# mixer passes: wave priority by item kind (RG-LRU items 2, retention 1, HGRN2 0), reset at pass end
# speedup vs baseline: 1.0048x; 1.0002x over previous
; __device__ __forceinline__ u32x4 pack8(const float (&v)[8]) { u32x4 w; w.x = pk2(v[0], v[1]); w.y = pk2(v[2], v[3]); w.z = pk2(v[4], v[5]); w.w = pk2(v[6], v[7]); return w; }
; __device__ __forceinline__ float gelu_tanh(float x) { const float z = 0.7978845608028654f * (x + 0.044715f * x * x * x); const float t = 1.0f - 2.0f * __builtin_amdgcn_rcpf(__expf(2.0f * z) + 1.0f); return 0.5f * x * (1.0f + t); }
; __device__ __forceinline__ void w_lru_m3(unsigned char* ws, const bf16_t* proj, bf16_t* y, int b, int ck_, int h, int lane) {
;     const int q = lane & 7, col = 64 * h + 8 * q;
;     const float* hinp = (const float*)(ws + WS_LRUIN) + (size_t)(b * NCH + ck_) * 512 + col;
;     const f32x4 h0 = *(const f32x4*)hinp, h1 = *(const f32x4*)(hinp + 4);
;     const float hin[8] = {h0[0], h0[1], h0[2], h0[3], h1[0], h1[1], h1[2], h1[3]};
; #pragma unroll
;     for (int i0 = 0; i0 < 8; i0 += 4) {
;         u32x4 rh[4], rp[4], rg[4];
; #pragma unroll
;         for (int i = 0; i < 4; ++i) { const size_t row = (size_t)b * SEQ + 64 * ck_ + (lane >> 3) + 8 * (i0 + i);
;             rh[i] = *(const u32x4*)(y + row * DM + col); rp[i] = *(const u32x4*)((const bf16_t*)(ws + WS_P) + row * 512 + col); rg[i] = *(const u32x4*)(proj + row * NIN + C_LG + col); }
; #pragma unroll
;         for (int i = 0; i < 4; ++i) { const size_t row = (size_t)b * SEQ + 64 * ck_ + (lane >> 3) + 8 * (i0 + i);
;             float hl[8], pv[8], g[8], o[8]; unpack8(rh[i], hl); unpack8(rp[i], pv); unpack8(rg[i], g);
; #pragma unroll
;             for (int j = 0; j < 8; ++j) o[j] = (hl[j] + pv[j] * hin[j]) * gelu_tanh(g[j]);
;             *(u32x4*)(y + row * DM + col) = pack8(o); }
.LBB0_184:
	s_setprio 2
	s_lshr_b32 s21, s20, 8
	s_lshr_b32 s24, s20, 9
	s_add_i32 s21, s21, s20
	s_and_b32 s24, s24, 12
	s_add_i32 s21, s21, s24
	s_and_b32 s21, s21, 15
	s_cmp_gt_u32 s21, 7
	s_cbranch_scc1 .LBB0_183
	s_ashr_i32 s24, s20, 31
	s_ashr_i32 s34, s20, 4
	s_lshr_b32 s24, s24, 25
	s_add_i32 s24, s34, s24
	s_ashr_i32 s40, s24, 7
	s_and_b32 s24, s24, 0x3ffff80
	v_mov_b32_e32 v12, v132
	s_ashr_i32 s35, s34, 31
	s_sub_i32 s24, s34, s24
	s_lshl_b32 s21, s21, 6
	v_lshlrev_b32_e32 v0, 3, v12
	s_lshl_b64 s[34:35], s[34:35], 11
	v_and_or_b32 v13, v0, 56, s21
	s_add_u32 s34, s7, s34
	s_addc_u32 s35, s28, s35
	v_lshlrev_b32_e32 v2, 2, v13
	s_ashr_i32 s41, s40, 31
	s_lshl_b32 s21, s24, 6
	v_lshl_add_u64 v[0:1], s[34:35], 0, v[2:3]
	s_lshl_b64 s[34:35], s[40:41], 13
	s_ashr_i32 s24, s21, 31
	global_load_dwordx4 v[8:11], v[0:1], off
	global_load_dwordx4 v[4:7], v[0:1], off offset:16
	s_add_u32 s34, s34, s21
	v_ashrrev_i32_e32 v0, 3, v12
	s_addc_u32 s35, s35, s24
	v_ashrrev_i32_e32 v1, 31, v0
	v_lshl_add_u64 v[60:61], s[34:35], 0, v[0:1]
	v_lshlrev_b32_e32 v2, 1, v13
	v_lshl_add_u64 v[62:63], s[10:11], 0, v[2:3]
	v_lshlrev_b64 v[12:13], 11, v[60:61]
	v_lshl_add_u64 v[0:1], s[82:83], 0, v[2:3]
	v_lshl_add_u64 v[72:73], v[62:63], 0, v[12:13]
	v_lshlrev_b64 v[12:13], 10, v[60:61]
	v_lshl_add_u64 v[12:13], v[0:1], 0, v[12:13]
	global_load_dwordx4 v[52:55], v[72:73], off
	global_load_dwordx4 v[56:59], v[12:13], off
	v_mov_b64_e32 v[12:13], s[8:9]
	v_mad_u64_u32 v[12:13], s[34:35], v60, s72, v[12:13]
	v_mad_i32_i24 v13, v61, s72, v13
	v_lshl_add_u64 v[64:65], v[12:13], 0, v[2:3]
	global_load_dwordx4 v[48:51], v[64:65], off offset:1024
	v_lshl_add_u64 v[12:13], v[60:61], 0, 8
	v_lshlrev_b64 v[14:15], 11, v[12:13]
	v_lshlrev_b64 v[12:13], 10, v[12:13]
	v_lshl_add_u64 v[12:13], v[0:1], 0, v[12:13]
	global_load_dwordx4 v[44:47], v[12:13], off
	v_add_co_u32_e32 v12, vcc, s97, v64
	v_lshl_add_u64 v[70:71], v[62:63], 0, v[14:15]
	s_nop 0
	v_addc_co_u32_e32 v13, vcc, 0, v65, vcc
	global_load_dwordx4 v[40:43], v[70:71], off
	global_load_dwordx4 v[36:39], v[12:13], off offset:1024
	v_lshl_add_u64 v[12:13], v[60:61], 0, 16
	v_lshlrev_b64 v[14:15], 11, v[12:13]
	v_lshlrev_b64 v[12:13], 10, v[12:13]
	v_lshl_add_u64 v[68:69], v[62:63], 0, v[14:15]
	v_lshl_add_u64 v[12:13], v[0:1], 0, v[12:13]
	global_load_dwordx4 v[28:31], v[68:69], off
	global_load_dwordx4 v[32:35], v[12:13], off
	v_add_co_u32_e32 v12, vcc, s13, v64
	v_lshl_add_u64 v[16:17], v[60:61], 0, 24
	s_nop 0
	v_addc_co_u32_e32 v13, vcc, 0, v65, vcc
	v_add_co_u32_e32 v20, vcc, s47, v64
	global_load_dwordx4 v[24:27], v[12:13], off offset:1024
	s_nop 0
	v_addc_co_u32_e32 v21, vcc, 0, v65, vcc
	global_load_dwordx4 v[20:23], v[20:21], off offset:1024
	v_lshlrev_b64 v[12:13], 11, v[16:17]
	v_lshlrev_b64 v[16:17], 10, v[16:17]
	v_lshl_add_u64 v[66:67], v[62:63], 0, v[12:13]
	v_lshl_add_u64 v[16:17], v[0:1], 0, v[16:17]
	global_load_dwordx4 v[12:15], v[66:67], off
	s_mov_b32 s21, 0x54000
	global_load_dwordx4 v[16:19], v[16:17], off
	v_lshl_add_u64 v[186:187], v[60:61], 0, 32
	v_lshlrev_b64 v[188:189], 11, v[186:187]
	v_lshl_add_u64 v[188:189], v[62:63], 0, v[188:189]
	global_load_dwordx4 v[222:225], v[188:189], off
	v_lshlrev_b64 v[188:189], 10, v[186:187]
	v_lshl_add_u64 v[188:189], v[0:1], 0, v[188:189]
	global_load_dwordx4 v[238:241], v[188:189], off
	v_mov_b32_e32 v190, s33
	v_mov_b32_e32 v191, 0
	v_lshl_add_u64 v[188:189], v[64:65], 0, v[190:191]
	global_load_dwordx4 v[134:137], v[188:189], off offset:1024
	v_lshl_add_u64 v[186:187], v[60:61], 0, 40
	v_lshlrev_b64 v[188:189], 11, v[186:187]
	v_lshl_add_u64 v[188:189], v[62:63], 0, v[188:189]
	global_load_dwordx4 v[226:229], v[188:189], off
	v_lshlrev_b64 v[188:189], 10, v[186:187]
	v_lshl_add_u64 v[188:189], v[0:1], 0, v[188:189]
	global_load_dwordx4 v[242:245], v[188:189], off
	v_mov_b32_e32 v190, s52
	v_mov_b32_e32 v191, 0
	v_lshl_add_u64 v[188:189], v[64:65], 0, v[190:191]
	global_load_dwordx4 v[138:141], v[188:189], off offset:1024
	v_lshl_add_u64 v[186:187], v[60:61], 0, 48
	v_lshlrev_b64 v[188:189], 11, v[186:187]
	v_lshl_add_u64 v[188:189], v[62:63], 0, v[188:189]
	global_load_dwordx4 v[230:233], v[188:189], off
	v_lshlrev_b64 v[188:189], 10, v[186:187]
	v_lshl_add_u64 v[188:189], v[0:1], 0, v[188:189]
	global_load_dwordx4 v[246:249], v[188:189], off
	v_mov_b32_e32 v190, s69
	v_mov_b32_e32 v191, 0
	v_lshl_add_u64 v[188:189], v[64:65], 0, v[190:191]
	global_load_dwordx4 v[146:149], v[188:189], off offset:1024
	v_lshl_add_u64 v[186:187], v[60:61], 0, 56
	v_lshlrev_b64 v[188:189], 11, v[186:187]
	v_lshl_add_u64 v[188:189], v[62:63], 0, v[188:189]
	global_load_dwordx4 v[234:237], v[188:189], off
	v_lshlrev_b64 v[188:189], 10, v[186:187]
	v_lshl_add_u64 v[188:189], v[0:1], 0, v[188:189]
	global_load_dwordx4 v[250:253], v[188:189], off
	v_mov_b32_e32 v190, s21
	v_mov_b32_e32 v191, 0
	v_lshl_add_u64 v[188:189], v[64:65], 0, v[190:191]
	global_load_dwordx4 v[150:153], v[188:189], off offset:1024
	s_waitcnt vmcnt(12) lgkmcnt(0)
; __device__ __forceinline__ u32x4 pack8(const float (&v)[8]) { u32x4 w; w.x = pk2(v[0], v[1]); w.y = pk2(v[2], v[3]); w.z = pk2(v[4], v[5]); w.w = pk2(v[6], v[7]); return w; }
; __device__ __forceinline__ float gelu_tanh(float x) { const float z = 0.7978845608028654f * (x + 0.044715f * x * x * x); const float t = 1.0f - 2.0f * __builtin_amdgcn_rcpf(__expf(2.0f * z) + 1.0f); return 0.5f * x * (1.0f + t); }
; __device__ __forceinline__ void w_lru_m3(unsigned char* ws, const bf16_t* proj, bf16_t* y, int b, int ck_, int h, int lane) {
;     ...
;     for (int i0 = 0; i0 < 8; i0 += 4) {
;         u32x4 rh[4], rp[4], rg[4];
; #pragma unroll
;         for (int i = 0; i < 4; ++i) { const size_t row = (size_t)b * SEQ + 64 * ck_ + (lane >> 3) + 8 * (i0 + i);
;             rh[i] = *(const u32x4*)(y + row * DM + col); rp[i] = *(const u32x4*)((const bf16_t*)(ws + WS_P) + row * 512 + col); rg[i] = *(const u32x4*)(proj + row * NIN + C_LG + col); }
; #pragma unroll
;         for (int i = 0; i < 4; ++i) { const size_t row = (size_t)b * SEQ + 64 * ck_ + (lane >> 3) + 8 * (i0 + i);
;             float hl[8], pv[8], g[8], o[8]; unpack8(rh[i], hl); unpack8(rp[i], pv); unpack8(rg[i], g);
; #pragma unroll
;             for (int j = 0; j < 8; ++j) o[j] = (hl[j] + pv[j] * hin[j]) * gelu_tanh(g[j]);
;             *(u32x4*)(y + row * DM + col) = pack8(o); }
	v_lshlrev_b32_e32 v74, 16, v52
	v_and_b32_e32 v75, 0xffff0000, v52
	v_lshlrev_b32_e32 v76, 16, v56
	v_and_b32_e32 v77, 0xffff0000, v56
	v_pk_fma_f32 v[74:75], v[8:9], v[76:77], v[74:75]
	v_lshlrev_b32_e32 v52, 16, v53
	v_and_b32_e32 v53, 0xffff0000, v53
	v_lshlrev_b32_e32 v78, 16, v48
	v_mul_f32_e32 v2, 0x3d372713, v78
	v_and_b32_e32 v79, 0xffff0000, v48
	v_mul_f32_e32 v2, v2, v78
	v_mov_b32_e32 v48, v78
	v_fmac_f32_e32 v48, v2, v48
	v_mul_f32_e32 v2, 0x3f4c422a, v48
	v_add_f32_e32 v2, v2, v2
	v_mul_f32_e32 v2, 0x3fb8aa3b, v2
	v_exp_f32_e32 v2, v2
	v_mov_b32_e32 v48, v79
	v_lshlrev_b32_e32 v56, 16, v57
	v_and_b32_e32 v57, 0xffff0000, v57
	v_add_f32_e32 v2, 1.0, v2
	v_rcp_f32_e32 v80, v2
	v_mul_f32_e32 v2, 0x3d372713, v79
	v_mul_f32_e32 v2, v2, v79
	v_fmac_f32_e32 v48, v2, v48
	v_mul_f32_e32 v2, 0x3f4c422a, v48
	v_add_f32_e32 v2, v2, v2
	v_mul_f32_e32 v2, 0x3fb8aa3b, v2
	v_exp_f32_e32 v2, v2
	v_pk_mul_f32 v[78:79], v[78:79], 0.5 op_sel_hi:[1,0]
	v_lshlrev_b32_e32 v48, 16, v49
	v_and_b32_e32 v49, 0xffff0000, v49
	v_add_f32_e32 v2, 1.0, v2
	v_rcp_f32_e32 v81, v2
	v_mul_f32_e32 v2, 0x3d372713, v48
	v_mul_f32_e32 v2, v2, v48
	v_pk_fma_f32 v[52:53], v[10:11], v[56:57], v[52:53]
	v_pk_fma_f32 v[76:77], v[80:81], 2.0, 1.0 op_sel_hi:[1,0,0] neg_lo:[1,0,0] neg_hi:[1,0,0]
	v_mov_b32_e32 v56, v49
	v_pk_add_f32 v[76:77], v[76:77], 1.0 op_sel_hi:[1,0]
	s_nop 0
	v_pk_mul_f32 v[76:77], v[78:79], v[76:77]
	s_nop 0
	v_pk_mul_f32 v[74:75], v[74:75], v[76:77]
	v_mov_b32_e32 v76, v48
	v_fmac_f32_e32 v76, v2, v76
	v_mul_f32_e32 v2, 0x3f4c422a, v76
	v_add_f32_e32 v2, v2, v2
	v_mul_f32_e32 v2, 0x3fb8aa3b, v2
	v_exp_f32_e32 v2, v2
	s_nop 0
	v_add_f32_e32 v2, 1.0, v2
	v_rcp_f32_e32 v76, v2
	v_mul_f32_e32 v2, 0x3d372713, v49
	v_mul_f32_e32 v2, v2, v49
	v_fmac_f32_e32 v56, v2, v56
	v_mul_f32_e32 v2, 0x3f4c422a, v56
	v_add_f32_e32 v2, v2, v2
	v_mul_f32_e32 v2, 0x3fb8aa3b, v2
	v_exp_f32_e32 v2, v2
	v_pk_mul_f32 v[48:49], v[48:49], 0.5 op_sel_hi:[1,0]
	v_add_f32_e32 v2, 1.0, v2
	v_rcp_f32_e32 v77, v2
	s_nop 0
	v_pk_fma_f32 v[56:57], v[76:77], 2.0, 1.0 op_sel_hi:[1,0,0] neg_lo:[1,0,0] neg_hi:[1,0,0]
	v_lshlrev_b32_e32 v76, 16, v50
	v_mul_f32_e32 v2, 0x3d372713, v76
	v_and_b32_e32 v77, 0xffff0000, v50
	v_mul_f32_e32 v2, v2, v76
	v_mov_b32_e32 v50, v76
	v_fmac_f32_e32 v50, v2, v50
	v_mul_f32_e32 v2, 0x3f4c422a, v50
	v_add_f32_e32 v2, v2, v2
	v_mul_f32_e32 v2, 0x3fb8aa3b, v2
	v_exp_f32_e32 v2, v2
	v_mov_b32_e32 v50, v77
	v_pk_add_f32 v[56:57], v[56:57], 1.0 op_sel_hi:[1,0]
	v_add_f32_e32 v2, 1.0, v2
	v_rcp_f32_e32 v78, v2
	v_mul_f32_e32 v2, 0x3d372713, v77
	v_mul_f32_e32 v2, v2, v77
	v_fmac_f32_e32 v50, v2, v50
	v_mul_f32_e32 v2, 0x3f4c422a, v50
	v_add_f32_e32 v2, v2, v2
	v_mul_f32_e32 v2, 0x3fb8aa3b, v2
	v_exp_f32_e32 v2, v2
	v_lshlrev_b32_e32 v50, 16, v51
	v_pk_mul_f32 v[48:49], v[48:49], v[56:57]
	v_lshlrev_b32_e32 v56, 16, v58
	v_add_f32_e32 v2, 1.0, v2
	v_rcp_f32_e32 v79, v2
	v_mul_f32_e32 v2, 0x3d372713, v50
	v_and_b32_e32 v57, 0xffff0000, v58
	v_mul_f32_e32 v2, v2, v50
	v_mov_b32_e32 v58, v50
	v_fmac_f32_e32 v58, v2, v58
	v_mul_f32_e32 v2, 0x3f4c422a, v58
	v_add_f32_e32 v2, v2, v2
	v_mul_f32_e32 v2, 0x3fb8aa3b, v2
	v_exp_f32_e32 v2, v2
	v_pk_mul_f32 v[52:53], v[52:53], v[48:49]
	v_lshlrev_b32_e32 v48, 16, v54
	v_and_b32_e32 v49, 0xffff0000, v54
	v_pk_fma_f32 v[48:49], v[4:5], v[56:57], v[48:49]
	v_pk_fma_f32 v[56:57], v[78:79], 2.0, 1.0 op_sel_hi:[1,0,0] neg_lo:[1,0,0] neg_hi:[1,0,0]
	v_pk_mul_f32 v[76:77], v[76:77], 0.5 op_sel_hi:[1,0]
	v_pk_add_f32 v[56:57], v[56:57], 1.0 op_sel_hi:[1,0]
	v_and_b32_e32 v51, 0xffff0000, v51
	v_pk_mul_f32 v[56:57], v[76:77], v[56:57]
	v_add_f32_e32 v2, 1.0, v2
	v_pk_mul_f32 v[56:57], v[48:49], v[56:57]
	v_lshlrev_b32_e32 v48, 16, v55
	v_and_b32_e32 v49, 0xffff0000, v55
	v_lshlrev_b32_e32 v54, 16, v59
	v_and_b32_e32 v55, 0xffff0000, v59
	v_rcp_f32_e32 v58, v2
	v_mul_f32_e32 v2, 0x3d372713, v51
	v_pk_fma_f32 v[48:49], v[6:7], v[54:55], v[48:49]
	v_mul_f32_e32 v2, v2, v51
	v_mov_b32_e32 v54, v51
	v_fmac_f32_e32 v54, v2, v54
	v_mul_f32_e32 v2, 0x3f4c422a, v54
	v_add_f32_e32 v2, v2, v2
	v_mul_f32_e32 v2, 0x3fb8aa3b, v2
	v_exp_f32_e32 v2, v2
	v_pk_mul_f32 v[50:51], v[50:51], 0.5 op_sel_hi:[1,0]
	v_add_f32_e32 v2, 1.0, v2
	v_rcp_f32_e32 v59, v2
	s_nop 0
	v_pk_fma_f32 v[54:55], v[58:59], 2.0, 1.0 op_sel_hi:[1,0,0] neg_lo:[1,0,0] neg_hi:[1,0,0]
	s_nop 0
	v_pk_add_f32 v[54:55], v[54:55], 1.0 op_sel_hi:[1,0]
	s_nop 0
	v_pk_mul_f32 v[50:51], v[50:51], v[54:55]
	s_nop 0
	v_pk_mul_f32 v[54:55], v[48:49], v[50:51]
	v_cvt_pk_bf16_f32 v49, v52, v53
	v_lshlrev_b32_e32 v52, 16, v36
	v_mul_f32_e32 v2, 0x3d372713, v52
	v_and_b32_e32 v53, 0xffff0000, v36
	v_mul_f32_e32 v2, v2, v52
	v_mov_b32_e32 v36, v52
	v_fmac_f32_e32 v36, v2, v36
	v_mul_f32_e32 v2, 0x3f4c422a, v36
	v_add_f32_e32 v2, v2, v2
	v_mul_f32_e32 v2, 0x3fb8aa3b, v2
	v_exp_f32_e32 v2, v2
	v_cvt_pk_bf16_f32 v51, v54, v55
	v_mov_b32_e32 v36, v53
	v_cvt_pk_bf16_f32 v48, v74, v75
	v_add_f32_e32 v2, 1.0, v2
	v_rcp_f32_e32 v54, v2
	v_mul_f32_e32 v2, 0x3d372713, v53
	v_mul_f32_e32 v2, v2, v53
	v_fmac_f32_e32 v36, v2, v36
	v_mul_f32_e32 v2, 0x3f4c422a, v36
	v_add_f32_e32 v2, v2, v2
	v_mul_f32_e32 v2, 0x3fb8aa3b, v2
	v_exp_f32_e32 v2, v2
	v_cvt_pk_bf16_f32 v50, v56, v57
	global_store_dwordx4 v[72:73], v[48:51], off
	v_pk_mul_f32 v[52:53], v[52:53], 0.5 op_sel_hi:[1,0]
	v_add_f32_e32 v2, 1.0, v2
	v_rcp_f32_e32 v55, v2
	v_lshlrev_b32_e32 v48, 16, v40
	v_and_b32_e32 v49, 0xffff0000, v40
	v_lshlrev_b32_e32 v50, 16, v44
	v_and_b32_e32 v51, 0xffff0000, v44
	v_pk_fma_f32 v[48:49], v[8:9], v[50:51], v[48:49]
	v_pk_fma_f32 v[50:51], v[54:55], 2.0, 1.0 op_sel_hi:[1,0,0] neg_lo:[1,0,0] neg_hi:[1,0,0]
; __device__ __forceinline__ u32x4 pack8(const float (&v)[8]) { u32x4 w; w.x = pk2(v[0], v[1]); w.y = pk2(v[2], v[3]); w.z = pk2(v[4], v[5]); w.w = pk2(v[6], v[7]); return w; }
; __device__ __forceinline__ float gelu_tanh(float x) { const float z = 0.7978845608028654f * (x + 0.044715f * x * x * x); const float t = 1.0f - 2.0f * __builtin_amdgcn_rcpf(__expf(2.0f * z) + 1.0f); return 0.5f * x * (1.0f + t); }
; __device__ __forceinline__ void w_lru_m3(unsigned char* ws, const bf16_t* proj, bf16_t* y, int b, int ck_, int h, int lane) {
;     ...
;     for (int i0 = 0; i0 < 8; i0 += 4) {
;         u32x4 rh[4], rp[4], rg[4];
; #pragma unroll
;         for (int i = 0; i < 4; ++i) { const size_t row = (size_t)b * SEQ + 64 * ck_ + (lane >> 3) + 8 * (i0 + i);
;             rh[i] = *(const u32x4*)(y + row * DM + col); rp[i] = *(const u32x4*)((const bf16_t*)(ws + WS_P) + row * 512 + col); rg[i] = *(const u32x4*)(proj + row * NIN + C_LG + col); }
; #pragma unroll
;         for (int i = 0; i < 4; ++i) { const size_t row = (size_t)b * SEQ + 64 * ck_ + (lane >> 3) + 8 * (i0 + i);
;             float hl[8], pv[8], g[8], o[8]; unpack8(rh[i], hl); unpack8(rp[i], pv); unpack8(rg[i], g);
; #pragma unroll
;             for (int j = 0; j < 8; ++j) o[j] = (hl[j] + pv[j] * hin[j]) * gelu_tanh(g[j]);
;             *(u32x4*)(y + row * DM + col) = pack8(o); }
	v_lshlrev_b32_e32 v36, 16, v37
	v_pk_add_f32 v[50:51], v[50:51], 1.0 op_sel_hi:[1,0]
	v_mul_f32_e32 v2, 0x3d372713, v36
	v_pk_mul_f32 v[50:51], v[52:53], v[50:51]
	v_mul_f32_e32 v2, v2, v36
	v_pk_mul_f32 v[48:49], v[48:49], v[50:51]
	v_mov_b32_e32 v50, v36
	v_fmac_f32_e32 v50, v2, v50
	v_mul_f32_e32 v2, 0x3f4c422a, v50
	v_add_f32_e32 v2, v2, v2
	v_mul_f32_e32 v2, 0x3fb8aa3b, v2
	v_exp_f32_e32 v2, v2
	v_and_b32_e32 v37, 0xffff0000, v37
	v_lshlrev_b32_e32 v40, 16, v41
	v_and_b32_e32 v41, 0xffff0000, v41
	v_add_f32_e32 v2, 1.0, v2
	v_lshlrev_b32_e32 v44, 16, v45
	v_and_b32_e32 v45, 0xffff0000, v45
	v_rcp_f32_e32 v50, v2
	v_mul_f32_e32 v2, 0x3d372713, v37
	v_pk_fma_f32 v[40:41], v[10:11], v[44:45], v[40:41]
	v_mul_f32_e32 v2, v2, v37
	v_mov_b32_e32 v44, v37
	v_fmac_f32_e32 v44, v2, v44
	v_mul_f32_e32 v2, 0x3f4c422a, v44
	v_add_f32_e32 v2, v2, v2
	v_mul_f32_e32 v2, 0x3fb8aa3b, v2
	v_exp_f32_e32 v2, v2
	v_pk_mul_f32 v[36:37], v[36:37], 0.5 op_sel_hi:[1,0]
	v_add_f32_e32 v2, 1.0, v2
	v_rcp_f32_e32 v51, v2
	s_nop 0
	v_pk_fma_f32 v[44:45], v[50:51], 2.0, 1.0 op_sel_hi:[1,0,0] neg_lo:[1,0,0] neg_hi:[1,0,0]
	v_lshlrev_b32_e32 v50, 16, v38
	v_mul_f32_e32 v2, 0x3d372713, v50
	v_and_b32_e32 v51, 0xffff0000, v38
	v_mul_f32_e32 v2, v2, v50
	v_mov_b32_e32 v38, v50
	v_fmac_f32_e32 v38, v2, v38
	v_mul_f32_e32 v2, 0x3f4c422a, v38
	v_add_f32_e32 v2, v2, v2
	v_mul_f32_e32 v2, 0x3fb8aa3b, v2
	v_exp_f32_e32 v2, v2
	v_mov_b32_e32 v38, v51
	v_pk_add_f32 v[44:45], v[44:45], 1.0 op_sel_hi:[1,0]
	v_add_f32_e32 v2, 1.0, v2
	v_rcp_f32_e32 v52, v2
	v_mul_f32_e32 v2, 0x3d372713, v51
	v_mul_f32_e32 v2, v2, v51
	v_fmac_f32_e32 v38, v2, v38
	v_mul_f32_e32 v2, 0x3f4c422a, v38
	v_add_f32_e32 v2, v2, v2
	v_mul_f32_e32 v2, 0x3fb8aa3b, v2
	v_exp_f32_e32 v2, v2
	v_lshlrev_b32_e32 v38, 16, v39
	v_pk_mul_f32 v[36:37], v[36:37], v[44:45]
	v_lshlrev_b32_e32 v44, 16, v46
	v_add_f32_e32 v2, 1.0, v2
	v_rcp_f32_e32 v53, v2
	v_mul_f32_e32 v2, 0x3d372713, v38
	v_and_b32_e32 v45, 0xffff0000, v46
	v_mul_f32_e32 v2, v2, v38
	v_mov_b32_e32 v46, v38
	v_fmac_f32_e32 v46, v2, v46
	v_mul_f32_e32 v2, 0x3f4c422a, v46
	v_add_f32_e32 v2, v2, v2
	v_mul_f32_e32 v2, 0x3fb8aa3b, v2
	v_exp_f32_e32 v2, v2
	v_pk_mul_f32 v[40:41], v[40:41], v[36:37]
	v_lshlrev_b32_e32 v36, 16, v42
	v_and_b32_e32 v37, 0xffff0000, v42
	v_pk_fma_f32 v[36:37], v[4:5], v[44:45], v[36:37]
	v_pk_fma_f32 v[44:45], v[52:53], 2.0, 1.0 op_sel_hi:[1,0,0] neg_lo:[1,0,0] neg_hi:[1,0,0]
	v_pk_mul_f32 v[50:51], v[50:51], 0.5 op_sel_hi:[1,0]
	v_pk_add_f32 v[44:45], v[44:45], 1.0 op_sel_hi:[1,0]
	v_and_b32_e32 v39, 0xffff0000, v39
	v_pk_mul_f32 v[44:45], v[50:51], v[44:45]
	v_add_f32_e32 v2, 1.0, v2
	v_pk_mul_f32 v[44:45], v[36:37], v[44:45]
	v_lshlrev_b32_e32 v36, 16, v43
	v_and_b32_e32 v37, 0xffff0000, v43
	v_lshlrev_b32_e32 v42, 16, v47
	v_and_b32_e32 v43, 0xffff0000, v47
	v_rcp_f32_e32 v46, v2
	v_mul_f32_e32 v2, 0x3d372713, v39
	v_pk_fma_f32 v[36:37], v[6:7], v[42:43], v[36:37]
	v_mul_f32_e32 v2, v2, v39
	v_mov_b32_e32 v42, v39
	v_fmac_f32_e32 v42, v2, v42
	v_mul_f32_e32 v2, 0x3f4c422a, v42
	v_add_f32_e32 v2, v2, v2
	v_mul_f32_e32 v2, 0x3fb8aa3b, v2
	v_exp_f32_e32 v2, v2
	v_pk_mul_f32 v[38:39], v[38:39], 0.5 op_sel_hi:[1,0]
	v_add_f32_e32 v2, 1.0, v2
	v_rcp_f32_e32 v47, v2
	s_nop 0
	v_pk_fma_f32 v[42:43], v[46:47], 2.0, 1.0 op_sel_hi:[1,0,0] neg_lo:[1,0,0] neg_hi:[1,0,0]
	s_nop 0
	v_pk_add_f32 v[42:43], v[42:43], 1.0 op_sel_hi:[1,0]
	s_nop 0
	v_pk_mul_f32 v[38:39], v[38:39], v[42:43]
	s_nop 0
	v_pk_mul_f32 v[42:43], v[36:37], v[38:39]
	v_cvt_pk_bf16_f32 v37, v40, v41
	v_lshlrev_b32_e32 v40, 16, v24
	v_mul_f32_e32 v2, 0x3d372713, v40
	v_and_b32_e32 v41, 0xffff0000, v24
	v_mul_f32_e32 v2, v2, v40
	v_mov_b32_e32 v24, v40
	v_fmac_f32_e32 v24, v2, v24
	v_mul_f32_e32 v2, 0x3f4c422a, v24
	v_add_f32_e32 v2, v2, v2
	v_mul_f32_e32 v2, 0x3fb8aa3b, v2
	v_exp_f32_e32 v2, v2
	v_cvt_pk_bf16_f32 v39, v42, v43
	v_mov_b32_e32 v24, v41
	v_cvt_pk_bf16_f32 v36, v48, v49
	v_add_f32_e32 v2, 1.0, v2
	v_rcp_f32_e32 v42, v2
	v_mul_f32_e32 v2, 0x3d372713, v41
	v_mul_f32_e32 v2, v2, v41
	v_fmac_f32_e32 v24, v2, v24
	v_mul_f32_e32 v2, 0x3f4c422a, v24
	v_add_f32_e32 v2, v2, v2
	v_mul_f32_e32 v2, 0x3fb8aa3b, v2
	v_exp_f32_e32 v2, v2
	v_cvt_pk_bf16_f32 v38, v44, v45
	global_store_dwordx4 v[70:71], v[36:39], off
	v_pk_mul_f32 v[40:41], v[40:41], 0.5 op_sel_hi:[1,0]
	v_add_f32_e32 v2, 1.0, v2
	v_rcp_f32_e32 v43, v2
	v_lshlrev_b32_e32 v36, 16, v28
	v_and_b32_e32 v37, 0xffff0000, v28
	v_lshlrev_b32_e32 v38, 16, v32
	v_and_b32_e32 v39, 0xffff0000, v32
	v_pk_fma_f32 v[36:37], v[8:9], v[38:39], v[36:37]
	v_pk_fma_f32 v[38:39], v[42:43], 2.0, 1.0 op_sel_hi:[1,0,0] neg_lo:[1,0,0] neg_hi:[1,0,0]
	v_lshlrev_b32_e32 v24, 16, v25
	v_pk_add_f32 v[38:39], v[38:39], 1.0 op_sel_hi:[1,0]
	v_mul_f32_e32 v2, 0x3d372713, v24
	v_pk_mul_f32 v[38:39], v[40:41], v[38:39]
	v_mul_f32_e32 v2, v2, v24
	v_pk_mul_f32 v[36:37], v[36:37], v[38:39]
	v_mov_b32_e32 v38, v24
	v_fmac_f32_e32 v38, v2, v38
	v_mul_f32_e32 v2, 0x3f4c422a, v38
	v_add_f32_e32 v2, v2, v2
	v_mul_f32_e32 v2, 0x3fb8aa3b, v2
	v_exp_f32_e32 v2, v2
	v_and_b32_e32 v25, 0xffff0000, v25
	v_lshlrev_b32_e32 v28, 16, v29
	v_and_b32_e32 v29, 0xffff0000, v29
	v_add_f32_e32 v2, 1.0, v2
	v_lshlrev_b32_e32 v32, 16, v33
	v_and_b32_e32 v33, 0xffff0000, v33
	v_rcp_f32_e32 v38, v2
	v_mul_f32_e32 v2, 0x3d372713, v25
	v_pk_fma_f32 v[28:29], v[10:11], v[32:33], v[28:29]
	v_mul_f32_e32 v2, v2, v25
	v_mov_b32_e32 v32, v25
	v_fmac_f32_e32 v32, v2, v32
	v_mul_f32_e32 v2, 0x3f4c422a, v32
	v_add_f32_e32 v2, v2, v2
	v_mul_f32_e32 v2, 0x3fb8aa3b, v2
	v_exp_f32_e32 v2, v2
	v_pk_mul_f32 v[24:25], v[24:25], 0.5 op_sel_hi:[1,0]
	v_add_f32_e32 v2, 1.0, v2
; __device__ __forceinline__ u32x4 pack8(const float (&v)[8]) { u32x4 w; w.x = pk2(v[0], v[1]); w.y = pk2(v[2], v[3]); w.z = pk2(v[4], v[5]); w.w = pk2(v[6], v[7]); return w; }
; __device__ __forceinline__ float gelu_tanh(float x) { const float z = 0.7978845608028654f * (x + 0.044715f * x * x * x); const float t = 1.0f - 2.0f * __builtin_amdgcn_rcpf(__expf(2.0f * z) + 1.0f); return 0.5f * x * (1.0f + t); }
; __device__ __forceinline__ void w_lru_m3(unsigned char* ws, const bf16_t* proj, bf16_t* y, int b, int ck_, int h, int lane) {
;     ...
;     for (int i0 = 0; i0 < 8; i0 += 4) {
;         u32x4 rh[4], rp[4], rg[4];
; #pragma unroll
;         for (int i = 0; i < 4; ++i) { const size_t row = (size_t)b * SEQ + 64 * ck_ + (lane >> 3) + 8 * (i0 + i);
;             rh[i] = *(const u32x4*)(y + row * DM + col); rp[i] = *(const u32x4*)((const bf16_t*)(ws + WS_P) + row * 512 + col); rg[i] = *(const u32x4*)(proj + row * NIN + C_LG + col); }
; #pragma unroll
;         for (int i = 0; i < 4; ++i) { const size_t row = (size_t)b * SEQ + 64 * ck_ + (lane >> 3) + 8 * (i0 + i);
;             float hl[8], pv[8], g[8], o[8]; unpack8(rh[i], hl); unpack8(rp[i], pv); unpack8(rg[i], g);
; #pragma unroll
;             for (int j = 0; j < 8; ++j) o[j] = (hl[j] + pv[j] * hin[j]) * gelu_tanh(g[j]);
;             *(u32x4*)(y + row * DM + col) = pack8(o); }
	v_rcp_f32_e32 v39, v2
	s_nop 0
	v_pk_fma_f32 v[32:33], v[38:39], 2.0, 1.0 op_sel_hi:[1,0,0] neg_lo:[1,0,0] neg_hi:[1,0,0]
	v_lshlrev_b32_e32 v38, 16, v26
	v_mul_f32_e32 v2, 0x3d372713, v38
	v_and_b32_e32 v39, 0xffff0000, v26
	v_mul_f32_e32 v2, v2, v38
	v_mov_b32_e32 v26, v38
	v_fmac_f32_e32 v26, v2, v26
	v_mul_f32_e32 v2, 0x3f4c422a, v26
	v_add_f32_e32 v2, v2, v2
	v_mul_f32_e32 v2, 0x3fb8aa3b, v2
	v_exp_f32_e32 v2, v2
	v_mov_b32_e32 v26, v39
	v_pk_add_f32 v[32:33], v[32:33], 1.0 op_sel_hi:[1,0]
	v_add_f32_e32 v2, 1.0, v2
	v_rcp_f32_e32 v40, v2
	v_mul_f32_e32 v2, 0x3d372713, v39
	v_mul_f32_e32 v2, v2, v39
	v_fmac_f32_e32 v26, v2, v26
	v_mul_f32_e32 v2, 0x3f4c422a, v26
	v_add_f32_e32 v2, v2, v2
	v_mul_f32_e32 v2, 0x3fb8aa3b, v2
	v_exp_f32_e32 v2, v2
	v_lshlrev_b32_e32 v26, 16, v27
	v_pk_mul_f32 v[24:25], v[24:25], v[32:33]
	v_lshlrev_b32_e32 v32, 16, v34
	v_add_f32_e32 v2, 1.0, v2
	v_rcp_f32_e32 v41, v2
	v_mul_f32_e32 v2, 0x3d372713, v26
	v_and_b32_e32 v33, 0xffff0000, v34
	v_mul_f32_e32 v2, v2, v26
	v_mov_b32_e32 v34, v26
	v_fmac_f32_e32 v34, v2, v34
	v_mul_f32_e32 v2, 0x3f4c422a, v34
	v_add_f32_e32 v2, v2, v2
	v_mul_f32_e32 v2, 0x3fb8aa3b, v2
	v_exp_f32_e32 v2, v2
	v_pk_mul_f32 v[28:29], v[28:29], v[24:25]
	v_lshlrev_b32_e32 v24, 16, v30
	v_and_b32_e32 v25, 0xffff0000, v30
	v_pk_fma_f32 v[24:25], v[4:5], v[32:33], v[24:25]
	v_pk_fma_f32 v[32:33], v[40:41], 2.0, 1.0 op_sel_hi:[1,0,0] neg_lo:[1,0,0] neg_hi:[1,0,0]
	v_pk_mul_f32 v[38:39], v[38:39], 0.5 op_sel_hi:[1,0]
	v_pk_add_f32 v[32:33], v[32:33], 1.0 op_sel_hi:[1,0]
	v_and_b32_e32 v27, 0xffff0000, v27
	v_pk_mul_f32 v[32:33], v[38:39], v[32:33]
	v_add_f32_e32 v2, 1.0, v2
	v_pk_mul_f32 v[32:33], v[24:25], v[32:33]
	v_lshlrev_b32_e32 v24, 16, v31
	v_and_b32_e32 v25, 0xffff0000, v31
	v_lshlrev_b32_e32 v30, 16, v35
	v_and_b32_e32 v31, 0xffff0000, v35
	v_rcp_f32_e32 v34, v2
	v_mul_f32_e32 v2, 0x3d372713, v27
	v_pk_fma_f32 v[24:25], v[6:7], v[30:31], v[24:25]
	v_mul_f32_e32 v2, v2, v27
	v_mov_b32_e32 v30, v27
	v_fmac_f32_e32 v30, v2, v30
	v_mul_f32_e32 v2, 0x3f4c422a, v30
	v_add_f32_e32 v2, v2, v2
	v_mul_f32_e32 v2, 0x3fb8aa3b, v2
	v_exp_f32_e32 v2, v2
	v_pk_mul_f32 v[26:27], v[26:27], 0.5 op_sel_hi:[1,0]
	v_add_f32_e32 v2, 1.0, v2
	v_rcp_f32_e32 v35, v2
	s_nop 0
	v_pk_fma_f32 v[30:31], v[34:35], 2.0, 1.0 op_sel_hi:[1,0,0] neg_lo:[1,0,0] neg_hi:[1,0,0]
	s_nop 0
	v_pk_add_f32 v[30:31], v[30:31], 1.0 op_sel_hi:[1,0]
	s_nop 0
	v_pk_mul_f32 v[26:27], v[26:27], v[30:31]
	s_nop 0
	v_pk_mul_f32 v[30:31], v[24:25], v[26:27]
	v_cvt_pk_bf16_f32 v25, v28, v29
	v_lshlrev_b32_e32 v28, 16, v20
	v_cvt_pk_bf16_f32 v24, v36, v37
	v_cvt_pk_bf16_f32 v26, v32, v33
	v_cvt_pk_bf16_f32 v27, v30, v31
	v_mul_f32_e32 v2, 0x3d372713, v28
	global_store_dwordx4 v[68:69], v[24:27], off
	v_mul_f32_e32 v2, v2, v28
	v_and_b32_e32 v29, 0xffff0000, v20
	v_lshlrev_b32_e32 v24, 16, v12
	v_and_b32_e32 v25, 0xffff0000, v12
	v_mov_b32_e32 v12, v28
	v_fmac_f32_e32 v12, v2, v12
	v_mul_f32_e32 v2, 0x3f4c422a, v12
	v_add_f32_e32 v2, v2, v2
	v_mul_f32_e32 v2, 0x3fb8aa3b, v2
	v_exp_f32_e32 v2, v2
	v_mov_b32_e32 v12, v29
	v_lshlrev_b32_e32 v26, 16, v16
	v_and_b32_e32 v27, 0xffff0000, v16
	v_add_f32_e32 v2, 1.0, v2
	v_rcp_f32_e32 v30, v2
	v_mul_f32_e32 v2, 0x3d372713, v29
	v_mul_f32_e32 v2, v2, v29
	v_fmac_f32_e32 v12, v2, v12
	v_mul_f32_e32 v2, 0x3f4c422a, v12
	v_add_f32_e32 v2, v2, v2
	v_mul_f32_e32 v2, 0x3fb8aa3b, v2
	v_exp_f32_e32 v2, v2
	v_pk_fma_f32 v[24:25], v[8:9], v[26:27], v[24:25]
	v_pk_mul_f32 v[28:29], v[28:29], 0.5 op_sel_hi:[1,0]
	v_lshlrev_b32_e32 v20, 16, v21
	v_add_f32_e32 v2, 1.0, v2
	v_rcp_f32_e32 v31, v2
	v_mul_f32_e32 v2, 0x3d372713, v20
	v_mul_f32_e32 v2, v2, v20
	v_and_b32_e32 v21, 0xffff0000, v21
	v_pk_fma_f32 v[26:27], v[30:31], 2.0, 1.0 op_sel_hi:[1,0,0] neg_lo:[1,0,0] neg_hi:[1,0,0]
	v_lshlrev_b32_e32 v12, 16, v13
	v_pk_add_f32 v[26:27], v[26:27], 1.0 op_sel_hi:[1,0]
	v_and_b32_e32 v13, 0xffff0000, v13
	v_pk_mul_f32 v[26:27], v[28:29], v[26:27]
	v_lshlrev_b32_e32 v16, 16, v17
	v_pk_mul_f32 v[24:25], v[24:25], v[26:27]
	v_mov_b32_e32 v26, v20
	v_fmac_f32_e32 v26, v2, v26
	v_mul_f32_e32 v2, 0x3f4c422a, v26
	v_add_f32_e32 v2, v2, v2
	v_mul_f32_e32 v2, 0x3fb8aa3b, v2
	v_exp_f32_e32 v2, v2
	v_and_b32_e32 v17, 0xffff0000, v17
	v_pk_fma_f32 v[12:13], v[10:11], v[16:17], v[12:13]
	v_mov_b32_e32 v16, v21
	v_add_f32_e32 v2, 1.0, v2
	v_rcp_f32_e32 v26, v2
	v_mul_f32_e32 v2, 0x3d372713, v21
	v_mul_f32_e32 v2, v2, v21
	v_fmac_f32_e32 v16, v2, v16
	v_mul_f32_e32 v2, 0x3f4c422a, v16
	v_add_f32_e32 v2, v2, v2
	v_mul_f32_e32 v2, 0x3fb8aa3b, v2
	v_exp_f32_e32 v2, v2
	v_pk_mul_f32 v[20:21], v[20:21], 0.5 op_sel_hi:[1,0]
	v_add_f32_e32 v2, 1.0, v2
	v_rcp_f32_e32 v27, v2
	s_nop 0
	v_pk_fma_f32 v[16:17], v[26:27], 2.0, 1.0 op_sel_hi:[1,0,0] neg_lo:[1,0,0] neg_hi:[1,0,0]
	s_nop 0
	v_pk_add_f32 v[16:17], v[16:17], 1.0 op_sel_hi:[1,0]
	v_lshlrev_b32_e32 v26, 16, v22
	v_pk_mul_f32 v[16:17], v[20:21], v[16:17]
	v_mul_f32_e32 v2, 0x3d372713, v26
	v_pk_mul_f32 v[16:17], v[12:13], v[16:17]
	v_lshlrev_b32_e32 v12, 16, v14
	v_and_b32_e32 v13, 0xffff0000, v14
	v_mul_f32_e32 v2, v2, v26
	v_mov_b32_e32 v14, v26
	v_fmac_f32_e32 v14, v2, v14
	v_mul_f32_e32 v2, 0x3f4c422a, v14
	v_add_f32_e32 v2, v2, v2
	v_mul_f32_e32 v2, 0x3fb8aa3b, v2
	v_exp_f32_e32 v2, v2
	v_and_b32_e32 v27, 0xffff0000, v22
	v_mov_b32_e32 v14, v27
	v_lshlrev_b32_e32 v20, 16, v18
	v_add_f32_e32 v2, 1.0, v2
	v_rcp_f32_e32 v28, v2
	v_mul_f32_e32 v2, 0x3d372713, v27
	v_mul_f32_e32 v2, v2, v27
	v_fmac_f32_e32 v14, v2, v14
	v_mul_f32_e32 v2, 0x3f4c422a, v14
	v_add_f32_e32 v2, v2, v2
	v_mul_f32_e32 v2, 0x3fb8aa3b, v2
	v_exp_f32_e32 v2, v2
	v_and_b32_e32 v21, 0xffff0000, v18
; __device__ __forceinline__ u32x4 pack8(const float (&v)[8]) { u32x4 w; w.x = pk2(v[0], v[1]); w.y = pk2(v[2], v[3]); w.z = pk2(v[4], v[5]); w.w = pk2(v[6], v[7]); return w; }
; __device__ __forceinline__ float gelu_tanh(float x) { const float z = 0.7978845608028654f * (x + 0.044715f * x * x * x); const float t = 1.0f - 2.0f * __builtin_amdgcn_rcpf(__expf(2.0f * z) + 1.0f); return 0.5f * x * (1.0f + t); }
; __device__ __forceinline__ void w_lru_m3(unsigned char* ws, const bf16_t* proj, bf16_t* y, int b, int ck_, int h, int lane) {
;     ...
;     for (int i0 = 0; i0 < 8; i0 += 4) {
;         u32x4 rh[4], rp[4], rg[4];
; #pragma unroll
;         for (int i = 0; i < 4; ++i) { const size_t row = (size_t)b * SEQ + 64 * ck_ + (lane >> 3) + 8 * (i0 + i);
;             rh[i] = *(const u32x4*)(y + row * DM + col); rp[i] = *(const u32x4*)((const bf16_t*)(ws + WS_P) + row * 512 + col); rg[i] = *(const u32x4*)(proj + row * NIN + C_LG + col); }
; #pragma unroll
;         for (int i = 0; i < 4; ++i) { const size_t row = (size_t)b * SEQ + 64 * ck_ + (lane >> 3) + 8 * (i0 + i);
;             float hl[8], pv[8], g[8], o[8]; unpack8(rh[i], hl); unpack8(rp[i], pv); unpack8(rg[i], g);
; #pragma unroll
;             for (int j = 0; j < 8; ++j) o[j] = (hl[j] + pv[j] * hin[j]) * gelu_tanh(g[j]);
;             *(u32x4*)(y + row * DM + col) = pack8(o); }
	v_lshlrev_b32_e32 v18, 16, v23
	v_mov_b32_e32 v22, v18
	v_add_f32_e32 v2, 1.0, v2
	v_rcp_f32_e32 v29, v2
	v_mul_f32_e32 v2, 0x3d372713, v18
	v_mul_f32_e32 v2, v2, v18
	v_fmac_f32_e32 v22, v2, v22
	v_mul_f32_e32 v2, 0x3f4c422a, v22
	v_add_f32_e32 v2, v2, v2
	v_mul_f32_e32 v2, 0x3fb8aa3b, v2
	v_exp_f32_e32 v2, v2
	v_pk_fma_f32 v[12:13], v[4:5], v[20:21], v[12:13]
	v_pk_fma_f32 v[20:21], v[28:29], 2.0, 1.0 op_sel_hi:[1,0,0] neg_lo:[1,0,0] neg_hi:[1,0,0]
	v_pk_mul_f32 v[26:27], v[26:27], 0.5 op_sel_hi:[1,0]
	v_pk_add_f32 v[20:21], v[20:21], 1.0 op_sel_hi:[1,0]
	v_lshlrev_b32_e32 v14, 16, v19
	v_pk_mul_f32 v[20:21], v[26:27], v[20:21]
	v_add_f32_e32 v2, 1.0, v2
	v_pk_mul_f32 v[20:21], v[12:13], v[20:21]
	v_lshlrev_b32_e32 v12, 16, v15
	v_and_b32_e32 v13, 0xffff0000, v15
	v_and_b32_e32 v15, 0xffff0000, v19
	v_and_b32_e32 v19, 0xffff0000, v23
	v_rcp_f32_e32 v22, v2
	v_mul_f32_e32 v2, 0x3d372713, v19
	v_pk_fma_f32 v[12:13], v[6:7], v[14:15], v[12:13]
	v_mul_f32_e32 v2, v2, v19
	v_mov_b32_e32 v14, v19
	v_fmac_f32_e32 v14, v2, v14
	v_mul_f32_e32 v2, 0x3f4c422a, v14
	v_add_f32_e32 v2, v2, v2
	v_mul_f32_e32 v2, 0x3fb8aa3b, v2
	v_exp_f32_e32 v2, v2
	v_pk_mul_f32 v[18:19], v[18:19], 0.5 op_sel_hi:[1,0]
	v_add_f32_e32 v2, 1.0, v2
	v_rcp_f32_e32 v23, v2
	s_nop 0
	v_pk_fma_f32 v[14:15], v[22:23], 2.0, 1.0 op_sel_hi:[1,0,0] neg_lo:[1,0,0] neg_hi:[1,0,0]
	s_nop 0
	v_pk_add_f32 v[14:15], v[14:15], 1.0 op_sel_hi:[1,0]
	s_nop 0
	v_pk_mul_f32 v[14:15], v[18:19], v[14:15]
	s_nop 0
	v_pk_mul_f32 v[18:19], v[12:13], v[14:15]
	v_cvt_pk_bf16_f32 v12, v24, v25
	v_cvt_pk_bf16_f32 v13, v16, v17
	v_cvt_pk_bf16_f32 v14, v20, v21
	v_cvt_pk_bf16_f32 v15, v18, v19
	global_store_dwordx4 v[66:67], v[12:15], off
	s_nop 1
	v_lshl_add_u64 v[12:13], v[60:61], 0, 32
	v_lshlrev_b64 v[14:15], 11, v[12:13]
	v_lshlrev_b64 v[12:13], 10, v[12:13]
	v_lshl_add_u64 v[70:71], v[62:63], 0, v[14:15]
	v_lshl_add_u64 v[12:13], v[0:1], 0, v[12:13]
	s_waitcnt vmcnt(4)
	v_mov_b64_e32 v[48:49], v[222:223]
	v_mov_b64_e32 v[50:51], v[224:225]
	v_mov_b64_e32 v[56:57], v[238:239]
	v_mov_b64_e32 v[58:59], v[240:241]
	v_add_co_u32_e32 v12, vcc, s33, v64
	s_nop 1
	v_addc_co_u32_e32 v13, vcc, 0, v65, vcc
	v_mov_b64_e32 v[52:53], v[134:135]
	v_mov_b64_e32 v[54:55], v[136:137]
	v_lshl_add_u64 v[12:13], v[60:61], 0, 40
	v_lshlrev_b64 v[14:15], 11, v[12:13]
	v_lshlrev_b64 v[12:13], 10, v[12:13]
	v_lshl_add_u64 v[68:69], v[62:63], 0, v[14:15]
	v_lshl_add_u64 v[12:13], v[0:1], 0, v[12:13]
	v_mov_b64_e32 v[40:41], v[226:227]
	v_mov_b64_e32 v[42:43], v[228:229]
	v_mov_b64_e32 v[44:45], v[242:243]
	v_mov_b64_e32 v[46:47], v[244:245]
	v_add_co_u32_e32 v12, vcc, s52, v64
	s_nop 1
	v_addc_co_u32_e32 v13, vcc, 0, v65, vcc
	v_mov_b64_e32 v[36:37], v[138:139]
	v_mov_b64_e32 v[38:39], v[140:141]
	v_lshl_add_u64 v[12:13], v[60:61], 0, 48
	v_lshlrev_b64 v[14:15], 11, v[12:13]
	v_lshlrev_b64 v[12:13], 10, v[12:13]
	v_lshl_add_u64 v[66:67], v[62:63], 0, v[14:15]
	v_lshl_add_u64 v[12:13], v[0:1], 0, v[12:13]
	v_mov_b64_e32 v[28:29], v[230:231]
	v_mov_b64_e32 v[30:31], v[232:233]
	v_mov_b64_e32 v[32:33], v[246:247]
	v_mov_b64_e32 v[34:35], v[248:249]
	v_add_co_u32_e32 v12, vcc, s69, v64
	s_nop 1
	v_addc_co_u32_e32 v13, vcc, 0, v65, vcc
	v_mov_b64_e32 v[24:25], v[146:147]
	v_mov_b64_e32 v[26:27], v[148:149]
	v_lshl_add_u64 v[12:13], v[60:61], 0, 56
	v_lshlrev_b64 v[14:15], 11, v[12:13]
	v_lshlrev_b64 v[12:13], 10, v[12:13]
	v_lshl_add_u64 v[60:61], v[62:63], 0, v[14:15]
	v_lshl_add_u64 v[0:1], v[0:1], 0, v[12:13]
	v_mov_b64_e32 v[16:17], v[234:235]
	v_mov_b64_e32 v[18:19], v[236:237]
	v_mov_b64_e32 v[20:21], v[250:251]
	v_mov_b64_e32 v[22:23], v[252:253]
	v_add_co_u32_e32 v0, vcc, s21, v64
	s_waitcnt lgkmcnt(0)
	v_lshlrev_b32_e32 v62, 16, v56
	v_addc_co_u32_e32 v1, vcc, 0, v65, vcc
	v_mov_b64_e32 v[12:13], v[150:151]
	v_mov_b64_e32 v[14:15], v[152:153]
	v_lshlrev_b32_e32 v0, 16, v48
	v_and_b32_e32 v1, 0xffff0000, v48
	v_lshlrev_b32_e32 v64, 16, v52
	v_mul_f32_e32 v2, 0x3d372713, v64
	v_mul_f32_e32 v2, v2, v64
	v_mov_b32_e32 v48, v64
	v_fmac_f32_e32 v48, v2, v48
	v_mul_f32_e32 v2, 0x3f4c422a, v48
	v_add_f32_e32 v2, v2, v2
	v_mul_f32_e32 v2, 0x3fb8aa3b, v2
	v_exp_f32_e32 v2, v2
	v_and_b32_e32 v65, 0xffff0000, v52
	v_mov_b32_e32 v48, v65
	v_and_b32_e32 v63, 0xffff0000, v56
	v_add_f32_e32 v2, 1.0, v2
	v_rcp_f32_e32 v72, v2
	v_mul_f32_e32 v2, 0x3d372713, v65
	v_mul_f32_e32 v2, v2, v65
	v_fmac_f32_e32 v48, v2, v48
	v_mul_f32_e32 v2, 0x3f4c422a, v48
	v_add_f32_e32 v2, v2, v2
	v_mul_f32_e32 v2, 0x3fb8aa3b, v2
	v_exp_f32_e32 v2, v2
	v_pk_fma_f32 v[0:1], v[8:9], v[62:63], v[0:1]
	v_pk_mul_f32 v[64:65], v[64:65], 0.5 op_sel_hi:[1,0]
	v_lshlrev_b32_e32 v52, 16, v53
	v_add_f32_e32 v2, 1.0, v2
	v_rcp_f32_e32 v73, v2
	v_mul_f32_e32 v2, 0x3d372713, v52
	v_mul_f32_e32 v2, v2, v52
	v_and_b32_e32 v53, 0xffff0000, v53
	v_pk_fma_f32 v[62:63], v[72:73], 2.0, 1.0 op_sel_hi:[1,0,0] neg_lo:[1,0,0] neg_hi:[1,0,0]
	v_lshlrev_b32_e32 v48, 16, v49
	v_pk_add_f32 v[62:63], v[62:63], 1.0 op_sel_hi:[1,0]
	v_and_b32_e32 v49, 0xffff0000, v49
	v_pk_mul_f32 v[62:63], v[64:65], v[62:63]
	v_lshlrev_b32_e32 v56, 16, v57
	v_pk_mul_f32 v[0:1], v[0:1], v[62:63]
	v_mov_b32_e32 v62, v52
	v_fmac_f32_e32 v62, v2, v62
	v_mul_f32_e32 v2, 0x3f4c422a, v62
	v_add_f32_e32 v2, v2, v2
	v_mul_f32_e32 v2, 0x3fb8aa3b, v2
	v_exp_f32_e32 v2, v2
	v_and_b32_e32 v57, 0xffff0000, v57
	v_pk_fma_f32 v[48:49], v[10:11], v[56:57], v[48:49]
	v_mov_b32_e32 v56, v53
	v_add_f32_e32 v2, 1.0, v2
	v_rcp_f32_e32 v62, v2
	v_mul_f32_e32 v2, 0x3d372713, v53
	v_mul_f32_e32 v2, v2, v53
	v_fmac_f32_e32 v56, v2, v56
	v_mul_f32_e32 v2, 0x3f4c422a, v56
	v_add_f32_e32 v2, v2, v2
	v_mul_f32_e32 v2, 0x3fb8aa3b, v2
; __device__ __forceinline__ u32x4 pack8(const float (&v)[8]) { u32x4 w; w.x = pk2(v[0], v[1]); w.y = pk2(v[2], v[3]); w.z = pk2(v[4], v[5]); w.w = pk2(v[6], v[7]); return w; }
; __device__ __forceinline__ float gelu_tanh(float x) { const float z = 0.7978845608028654f * (x + 0.044715f * x * x * x); const float t = 1.0f - 2.0f * __builtin_amdgcn_rcpf(__expf(2.0f * z) + 1.0f); return 0.5f * x * (1.0f + t); }
; __device__ __forceinline__ void w_lru_m3(unsigned char* ws, const bf16_t* proj, bf16_t* y, int b, int ck_, int h, int lane) {
;     ...
;     for (int i0 = 0; i0 < 8; i0 += 4) {
;         u32x4 rh[4], rp[4], rg[4];
; #pragma unroll
;         for (int i = 0; i < 4; ++i) { const size_t row = (size_t)b * SEQ + 64 * ck_ + (lane >> 3) + 8 * (i0 + i);
;             rh[i] = *(const u32x4*)(y + row * DM + col); rp[i] = *(const u32x4*)((const bf16_t*)(ws + WS_P) + row * 512 + col); rg[i] = *(const u32x4*)(proj + row * NIN + C_LG + col); }
; #pragma unroll
;         for (int i = 0; i < 4; ++i) { const size_t row = (size_t)b * SEQ + 64 * ck_ + (lane >> 3) + 8 * (i0 + i);
;             float hl[8], pv[8], g[8], o[8]; unpack8(rh[i], hl); unpack8(rp[i], pv); unpack8(rg[i], g);
; #pragma unroll
;             for (int j = 0; j < 8; ++j) o[j] = (hl[j] + pv[j] * hin[j]) * gelu_tanh(g[j]);
;             *(u32x4*)(y + row * DM + col) = pack8(o); }
	v_exp_f32_e32 v2, v2
	v_pk_mul_f32 v[52:53], v[52:53], 0.5 op_sel_hi:[1,0]
	v_add_f32_e32 v2, 1.0, v2
	v_rcp_f32_e32 v63, v2
	s_nop 0
	v_pk_fma_f32 v[56:57], v[62:63], 2.0, 1.0 op_sel_hi:[1,0,0] neg_lo:[1,0,0] neg_hi:[1,0,0]
	s_nop 0
	v_pk_add_f32 v[56:57], v[56:57], 1.0 op_sel_hi:[1,0]
	v_lshlrev_b32_e32 v62, 16, v54
	v_pk_mul_f32 v[52:53], v[52:53], v[56:57]
	v_mul_f32_e32 v2, 0x3d372713, v62
	v_pk_mul_f32 v[52:53], v[48:49], v[52:53]
	v_lshlrev_b32_e32 v48, 16, v50
	v_and_b32_e32 v49, 0xffff0000, v50
	v_mul_f32_e32 v2, v2, v62
	v_mov_b32_e32 v50, v62
	v_fmac_f32_e32 v50, v2, v50
	v_mul_f32_e32 v2, 0x3f4c422a, v50
	v_add_f32_e32 v2, v2, v2
	v_mul_f32_e32 v2, 0x3fb8aa3b, v2
	v_exp_f32_e32 v2, v2
	v_and_b32_e32 v63, 0xffff0000, v54
	v_mov_b32_e32 v50, v63
	v_lshlrev_b32_e32 v54, 16, v55
	v_add_f32_e32 v2, 1.0, v2
	v_rcp_f32_e32 v64, v2
	v_mul_f32_e32 v2, 0x3d372713, v63
	v_mul_f32_e32 v2, v2, v63
	v_fmac_f32_e32 v50, v2, v50
	v_mul_f32_e32 v2, 0x3f4c422a, v50
	v_add_f32_e32 v2, v2, v2
	v_mul_f32_e32 v2, 0x3fb8aa3b, v2
	v_exp_f32_e32 v2, v2
	v_lshlrev_b32_e32 v56, 16, v58
	v_and_b32_e32 v57, 0xffff0000, v58
	v_mov_b32_e32 v58, v54
	v_add_f32_e32 v2, 1.0, v2
	v_rcp_f32_e32 v65, v2
	v_mul_f32_e32 v2, 0x3d372713, v54
	v_mul_f32_e32 v2, v2, v54
	v_fmac_f32_e32 v58, v2, v58
	v_mul_f32_e32 v2, 0x3f4c422a, v58
	v_add_f32_e32 v2, v2, v2
	v_mul_f32_e32 v2, 0x3fb8aa3b, v2
	v_exp_f32_e32 v2, v2
	v_pk_fma_f32 v[48:49], v[4:5], v[56:57], v[48:49]
	v_pk_fma_f32 v[56:57], v[64:65], 2.0, 1.0 op_sel_hi:[1,0,0] neg_lo:[1,0,0] neg_hi:[1,0,0]
	v_pk_mul_f32 v[62:63], v[62:63], 0.5 op_sel_hi:[1,0]
	v_pk_add_f32 v[56:57], v[56:57], 1.0 op_sel_hi:[1,0]
	v_and_b32_e32 v55, 0xffff0000, v55
	v_pk_mul_f32 v[56:57], v[62:63], v[56:57]
	v_add_f32_e32 v2, 1.0, v2
	v_pk_mul_f32 v[56:57], v[48:49], v[56:57]
	v_lshlrev_b32_e32 v48, 16, v51
	v_and_b32_e32 v49, 0xffff0000, v51
	v_lshlrev_b32_e32 v50, 16, v59
	v_and_b32_e32 v51, 0xffff0000, v59
	v_rcp_f32_e32 v58, v2
	v_mul_f32_e32 v2, 0x3d372713, v55
	v_pk_fma_f32 v[48:49], v[6:7], v[50:51], v[48:49]
	v_mul_f32_e32 v2, v2, v55
	v_mov_b32_e32 v50, v55
	v_fmac_f32_e32 v50, v2, v50
	v_mul_f32_e32 v2, 0x3f4c422a, v50
	v_add_f32_e32 v2, v2, v2
	v_mul_f32_e32 v2, 0x3fb8aa3b, v2
	v_exp_f32_e32 v2, v2
	v_pk_mul_f32 v[54:55], v[54:55], 0.5 op_sel_hi:[1,0]
	v_add_f32_e32 v2, 1.0, v2
	v_rcp_f32_e32 v59, v2
	s_nop 0
	v_pk_fma_f32 v[50:51], v[58:59], 2.0, 1.0 op_sel_hi:[1,0,0] neg_lo:[1,0,0] neg_hi:[1,0,0]
	s_nop 0
	v_pk_add_f32 v[50:51], v[50:51], 1.0 op_sel_hi:[1,0]
	s_nop 0
	v_pk_mul_f32 v[50:51], v[54:55], v[50:51]
	s_nop 0
	v_pk_mul_f32 v[54:55], v[48:49], v[50:51]
	v_cvt_pk_bf16_f32 v48, v0, v1
	v_cvt_pk_bf16_f32 v49, v52, v53
	v_cvt_pk_bf16_f32 v50, v56, v57
	v_cvt_pk_bf16_f32 v51, v54, v55
	global_store_dwordx4 v[70:71], v[48:51], off
	v_lshlrev_b32_e32 v0, 16, v40
	v_and_b32_e32 v1, 0xffff0000, v40
	v_lshlrev_b32_e32 v50, 16, v36
	v_mul_f32_e32 v2, 0x3d372713, v50
	v_and_b32_e32 v51, 0xffff0000, v36
	v_mul_f32_e32 v2, v2, v50
	v_mov_b32_e32 v36, v50
	v_fmac_f32_e32 v36, v2, v36
	v_mul_f32_e32 v2, 0x3f4c422a, v36
	v_add_f32_e32 v2, v2, v2
	v_mul_f32_e32 v2, 0x3fb8aa3b, v2
	v_exp_f32_e32 v2, v2
	v_mov_b32_e32 v36, v51
	v_lshlrev_b32_e32 v48, 16, v44
	v_and_b32_e32 v49, 0xffff0000, v44
	v_add_f32_e32 v2, 1.0, v2
	v_rcp_f32_e32 v52, v2
	v_mul_f32_e32 v2, 0x3d372713, v51
	v_mul_f32_e32 v2, v2, v51
	v_fmac_f32_e32 v36, v2, v36
	v_mul_f32_e32 v2, 0x3f4c422a, v36
	v_add_f32_e32 v2, v2, v2
	v_mul_f32_e32 v2, 0x3fb8aa3b, v2
	v_exp_f32_e32 v2, v2
	v_pk_fma_f32 v[0:1], v[8:9], v[48:49], v[0:1]
	v_pk_mul_f32 v[50:51], v[50:51], 0.5 op_sel_hi:[1,0]
	v_lshlrev_b32_e32 v36, 16, v37
	v_add_f32_e32 v2, 1.0, v2
	v_rcp_f32_e32 v53, v2
	v_mul_f32_e32 v2, 0x3d372713, v36
	v_mul_f32_e32 v2, v2, v36
	v_and_b32_e32 v37, 0xffff0000, v37
	v_pk_fma_f32 v[48:49], v[52:53], 2.0, 1.0 op_sel_hi:[1,0,0] neg_lo:[1,0,0] neg_hi:[1,0,0]
	v_lshlrev_b32_e32 v40, 16, v41
	v_pk_add_f32 v[48:49], v[48:49], 1.0 op_sel_hi:[1,0]
	v_and_b32_e32 v41, 0xffff0000, v41
	v_pk_mul_f32 v[48:49], v[50:51], v[48:49]
	v_lshlrev_b32_e32 v44, 16, v45
	v_pk_mul_f32 v[0:1], v[0:1], v[48:49]
	v_mov_b32_e32 v48, v36
	v_fmac_f32_e32 v48, v2, v48
	v_mul_f32_e32 v2, 0x3f4c422a, v48
	v_add_f32_e32 v2, v2, v2
	v_mul_f32_e32 v2, 0x3fb8aa3b, v2
	v_exp_f32_e32 v2, v2
	v_and_b32_e32 v45, 0xffff0000, v45
	v_pk_fma_f32 v[40:41], v[10:11], v[44:45], v[40:41]
	v_mov_b32_e32 v44, v37
	v_add_f32_e32 v2, 1.0, v2
	v_rcp_f32_e32 v48, v2
	v_mul_f32_e32 v2, 0x3d372713, v37
	v_mul_f32_e32 v2, v2, v37
	v_fmac_f32_e32 v44, v2, v44
	v_mul_f32_e32 v2, 0x3f4c422a, v44
	v_add_f32_e32 v2, v2, v2
	v_mul_f32_e32 v2, 0x3fb8aa3b, v2
	v_exp_f32_e32 v2, v2
	v_pk_mul_f32 v[36:37], v[36:37], 0.5 op_sel_hi:[1,0]
	v_add_f32_e32 v2, 1.0, v2
	v_rcp_f32_e32 v49, v2
	s_nop 0
	v_pk_fma_f32 v[44:45], v[48:49], 2.0, 1.0 op_sel_hi:[1,0,0] neg_lo:[1,0,0] neg_hi:[1,0,0]
	v_lshlrev_b32_e32 v48, 16, v38
	v_mul_f32_e32 v2, 0x3d372713, v48
	v_and_b32_e32 v49, 0xffff0000, v38
	v_mul_f32_e32 v2, v2, v48
	v_mov_b32_e32 v38, v48
	v_fmac_f32_e32 v38, v2, v38
	v_mul_f32_e32 v2, 0x3f4c422a, v38
	v_add_f32_e32 v2, v2, v2
	v_mul_f32_e32 v2, 0x3fb8aa3b, v2
	v_exp_f32_e32 v2, v2
	v_mov_b32_e32 v38, v49
	v_pk_add_f32 v[44:45], v[44:45], 1.0 op_sel_hi:[1,0]
	v_add_f32_e32 v2, 1.0, v2
	v_rcp_f32_e32 v50, v2
	v_mul_f32_e32 v2, 0x3d372713, v49
	v_mul_f32_e32 v2, v2, v49
	v_fmac_f32_e32 v38, v2, v38
	v_mul_f32_e32 v2, 0x3f4c422a, v38
	v_add_f32_e32 v2, v2, v2
	v_mul_f32_e32 v2, 0x3fb8aa3b, v2
	v_exp_f32_e32 v2, v2
	v_lshlrev_b32_e32 v38, 16, v39
	v_pk_mul_f32 v[36:37], v[36:37], v[44:45]
	v_lshlrev_b32_e32 v44, 16, v46
	v_add_f32_e32 v2, 1.0, v2
; __device__ __forceinline__ u32x4 pack8(const float (&v)[8]) { u32x4 w; w.x = pk2(v[0], v[1]); w.y = pk2(v[2], v[3]); w.z = pk2(v[4], v[5]); w.w = pk2(v[6], v[7]); return w; }
; __device__ __forceinline__ float gelu_tanh(float x) { const float z = 0.7978845608028654f * (x + 0.044715f * x * x * x); const float t = 1.0f - 2.0f * __builtin_amdgcn_rcpf(__expf(2.0f * z) + 1.0f); return 0.5f * x * (1.0f + t); }
; __device__ __forceinline__ void w_lru_m3(unsigned char* ws, const bf16_t* proj, bf16_t* y, int b, int ck_, int h, int lane) {
;     ...
;     for (int i0 = 0; i0 < 8; i0 += 4) {
;         u32x4 rh[4], rp[4], rg[4];
; #pragma unroll
;         for (int i = 0; i < 4; ++i) { const size_t row = (size_t)b * SEQ + 64 * ck_ + (lane >> 3) + 8 * (i0 + i);
;             rh[i] = *(const u32x4*)(y + row * DM + col); rp[i] = *(const u32x4*)((const bf16_t*)(ws + WS_P) + row * 512 + col); rg[i] = *(const u32x4*)(proj + row * NIN + C_LG + col); }
; #pragma unroll
;         for (int i = 0; i < 4; ++i) { const size_t row = (size_t)b * SEQ + 64 * ck_ + (lane >> 3) + 8 * (i0 + i);
;             float hl[8], pv[8], g[8], o[8]; unpack8(rh[i], hl); unpack8(rp[i], pv); unpack8(rg[i], g);
; #pragma unroll
;             for (int j = 0; j < 8; ++j) o[j] = (hl[j] + pv[j] * hin[j]) * gelu_tanh(g[j]);
;             *(u32x4*)(y + row * DM + col) = pack8(o); }
	v_rcp_f32_e32 v51, v2
	v_mul_f32_e32 v2, 0x3d372713, v38
	v_and_b32_e32 v45, 0xffff0000, v46
	v_mul_f32_e32 v2, v2, v38
	v_mov_b32_e32 v46, v38
	v_fmac_f32_e32 v46, v2, v46
	v_mul_f32_e32 v2, 0x3f4c422a, v46
	v_add_f32_e32 v2, v2, v2
	v_mul_f32_e32 v2, 0x3fb8aa3b, v2
	v_exp_f32_e32 v2, v2
	v_pk_mul_f32 v[40:41], v[40:41], v[36:37]
	v_lshlrev_b32_e32 v36, 16, v42
	v_and_b32_e32 v37, 0xffff0000, v42
	v_pk_fma_f32 v[36:37], v[4:5], v[44:45], v[36:37]
	v_pk_fma_f32 v[44:45], v[50:51], 2.0, 1.0 op_sel_hi:[1,0,0] neg_lo:[1,0,0] neg_hi:[1,0,0]
	v_pk_mul_f32 v[48:49], v[48:49], 0.5 op_sel_hi:[1,0]
	v_pk_add_f32 v[44:45], v[44:45], 1.0 op_sel_hi:[1,0]
	v_and_b32_e32 v39, 0xffff0000, v39
	v_pk_mul_f32 v[44:45], v[48:49], v[44:45]
	v_add_f32_e32 v2, 1.0, v2
	v_pk_mul_f32 v[44:45], v[36:37], v[44:45]
	v_lshlrev_b32_e32 v36, 16, v43
	v_and_b32_e32 v37, 0xffff0000, v43
	v_lshlrev_b32_e32 v42, 16, v47
	v_and_b32_e32 v43, 0xffff0000, v47
	v_rcp_f32_e32 v46, v2
	v_mul_f32_e32 v2, 0x3d372713, v39
	v_pk_fma_f32 v[36:37], v[6:7], v[42:43], v[36:37]
	v_mul_f32_e32 v2, v2, v39
	v_mov_b32_e32 v42, v39
	v_fmac_f32_e32 v42, v2, v42
	v_mul_f32_e32 v2, 0x3f4c422a, v42
	v_add_f32_e32 v2, v2, v2
	v_mul_f32_e32 v2, 0x3fb8aa3b, v2
	v_exp_f32_e32 v2, v2
	v_pk_mul_f32 v[38:39], v[38:39], 0.5 op_sel_hi:[1,0]
	v_add_f32_e32 v2, 1.0, v2
	v_rcp_f32_e32 v47, v2
	s_nop 0
	v_pk_fma_f32 v[42:43], v[46:47], 2.0, 1.0 op_sel_hi:[1,0,0] neg_lo:[1,0,0] neg_hi:[1,0,0]
	s_nop 0
	v_pk_add_f32 v[42:43], v[42:43], 1.0 op_sel_hi:[1,0]
	s_nop 0
	v_pk_mul_f32 v[38:39], v[38:39], v[42:43]
	s_nop 0
	v_pk_mul_f32 v[42:43], v[36:37], v[38:39]
	v_cvt_pk_bf16_f32 v36, v0, v1
	v_cvt_pk_bf16_f32 v37, v40, v41
	v_cvt_pk_bf16_f32 v38, v44, v45
	v_cvt_pk_bf16_f32 v39, v42, v43
	global_store_dwordx4 v[68:69], v[36:39], off
	v_lshlrev_b32_e32 v0, 16, v28
	v_and_b32_e32 v1, 0xffff0000, v28
	v_lshlrev_b32_e32 v38, 16, v24
	v_mul_f32_e32 v2, 0x3d372713, v38
	v_and_b32_e32 v39, 0xffff0000, v24
	v_mul_f32_e32 v2, v2, v38
	v_mov_b32_e32 v24, v38
	v_fmac_f32_e32 v24, v2, v24
	v_mul_f32_e32 v2, 0x3f4c422a, v24
	v_add_f32_e32 v2, v2, v2
	v_mul_f32_e32 v2, 0x3fb8aa3b, v2
	v_exp_f32_e32 v2, v2
	v_mov_b32_e32 v24, v39
	v_lshlrev_b32_e32 v36, 16, v32
	v_and_b32_e32 v37, 0xffff0000, v32
	v_add_f32_e32 v2, 1.0, v2
	v_rcp_f32_e32 v40, v2
	v_mul_f32_e32 v2, 0x3d372713, v39
	v_mul_f32_e32 v2, v2, v39
	v_fmac_f32_e32 v24, v2, v24
	v_mul_f32_e32 v2, 0x3f4c422a, v24
	v_add_f32_e32 v2, v2, v2
	v_mul_f32_e32 v2, 0x3fb8aa3b, v2
	v_exp_f32_e32 v2, v2
	v_pk_fma_f32 v[0:1], v[8:9], v[36:37], v[0:1]
	v_pk_mul_f32 v[38:39], v[38:39], 0.5 op_sel_hi:[1,0]
	v_lshlrev_b32_e32 v24, 16, v25
	v_add_f32_e32 v2, 1.0, v2
	v_rcp_f32_e32 v41, v2
	v_mul_f32_e32 v2, 0x3d372713, v24
	v_mul_f32_e32 v2, v2, v24
	v_and_b32_e32 v25, 0xffff0000, v25
	v_pk_fma_f32 v[36:37], v[40:41], 2.0, 1.0 op_sel_hi:[1,0,0] neg_lo:[1,0,0] neg_hi:[1,0,0]
	v_lshlrev_b32_e32 v28, 16, v29
	v_pk_add_f32 v[36:37], v[36:37], 1.0 op_sel_hi:[1,0]
	v_and_b32_e32 v29, 0xffff0000, v29
	v_pk_mul_f32 v[36:37], v[38:39], v[36:37]
	v_lshlrev_b32_e32 v32, 16, v33
	v_pk_mul_f32 v[0:1], v[0:1], v[36:37]
	v_mov_b32_e32 v36, v24
	v_fmac_f32_e32 v36, v2, v36
	v_mul_f32_e32 v2, 0x3f4c422a, v36
	v_add_f32_e32 v2, v2, v2
	v_mul_f32_e32 v2, 0x3fb8aa3b, v2
	v_exp_f32_e32 v2, v2
	v_and_b32_e32 v33, 0xffff0000, v33
	v_pk_fma_f32 v[28:29], v[10:11], v[32:33], v[28:29]
	v_mov_b32_e32 v32, v25
	v_add_f32_e32 v2, 1.0, v2
	v_rcp_f32_e32 v36, v2
	v_mul_f32_e32 v2, 0x3d372713, v25
	v_mul_f32_e32 v2, v2, v25
	v_fmac_f32_e32 v32, v2, v32
	v_mul_f32_e32 v2, 0x3f4c422a, v32
	v_add_f32_e32 v2, v2, v2
	v_mul_f32_e32 v2, 0x3fb8aa3b, v2
	v_exp_f32_e32 v2, v2
	v_pk_mul_f32 v[24:25], v[24:25], 0.5 op_sel_hi:[1,0]
	v_add_f32_e32 v2, 1.0, v2
	v_rcp_f32_e32 v37, v2
	s_nop 0
	v_pk_fma_f32 v[32:33], v[36:37], 2.0, 1.0 op_sel_hi:[1,0,0] neg_lo:[1,0,0] neg_hi:[1,0,0]
	v_lshlrev_b32_e32 v36, 16, v26
	v_mul_f32_e32 v2, 0x3d372713, v36
	v_and_b32_e32 v37, 0xffff0000, v26
	v_mul_f32_e32 v2, v2, v36
	v_mov_b32_e32 v26, v36
	v_fmac_f32_e32 v26, v2, v26
	v_mul_f32_e32 v2, 0x3f4c422a, v26
	v_add_f32_e32 v2, v2, v2
	v_mul_f32_e32 v2, 0x3fb8aa3b, v2
	v_exp_f32_e32 v2, v2
	v_mov_b32_e32 v26, v37
	v_pk_add_f32 v[32:33], v[32:33], 1.0 op_sel_hi:[1,0]
	v_add_f32_e32 v2, 1.0, v2
	v_rcp_f32_e32 v38, v2
	v_mul_f32_e32 v2, 0x3d372713, v37
	v_mul_f32_e32 v2, v2, v37
	v_fmac_f32_e32 v26, v2, v26
	v_mul_f32_e32 v2, 0x3f4c422a, v26
	v_add_f32_e32 v2, v2, v2
	v_mul_f32_e32 v2, 0x3fb8aa3b, v2
	v_exp_f32_e32 v2, v2
	v_lshlrev_b32_e32 v26, 16, v27
	v_pk_mul_f32 v[24:25], v[24:25], v[32:33]
	v_lshlrev_b32_e32 v32, 16, v34
	v_add_f32_e32 v2, 1.0, v2
	v_rcp_f32_e32 v39, v2
	v_mul_f32_e32 v2, 0x3d372713, v26
	v_and_b32_e32 v33, 0xffff0000, v34
	v_mul_f32_e32 v2, v2, v26
	v_mov_b32_e32 v34, v26
	v_fmac_f32_e32 v34, v2, v34
	v_mul_f32_e32 v2, 0x3f4c422a, v34
	v_add_f32_e32 v2, v2, v2
	v_mul_f32_e32 v2, 0x3fb8aa3b, v2
	v_exp_f32_e32 v2, v2
	v_pk_mul_f32 v[28:29], v[28:29], v[24:25]
	v_lshlrev_b32_e32 v24, 16, v30
	v_and_b32_e32 v25, 0xffff0000, v30
	v_pk_fma_f32 v[24:25], v[4:5], v[32:33], v[24:25]
	v_pk_fma_f32 v[32:33], v[38:39], 2.0, 1.0 op_sel_hi:[1,0,0] neg_lo:[1,0,0] neg_hi:[1,0,0]
	v_pk_mul_f32 v[36:37], v[36:37], 0.5 op_sel_hi:[1,0]
	v_pk_add_f32 v[32:33], v[32:33], 1.0 op_sel_hi:[1,0]
	v_and_b32_e32 v27, 0xffff0000, v27
	v_pk_mul_f32 v[32:33], v[36:37], v[32:33]
	v_add_f32_e32 v2, 1.0, v2
	v_pk_mul_f32 v[32:33], v[24:25], v[32:33]
	v_lshlrev_b32_e32 v24, 16, v31
	v_and_b32_e32 v25, 0xffff0000, v31
	v_lshlrev_b32_e32 v30, 16, v35
	v_and_b32_e32 v31, 0xffff0000, v35
	v_rcp_f32_e32 v34, v2
	v_mul_f32_e32 v2, 0x3d372713, v27
	v_pk_fma_f32 v[24:25], v[6:7], v[30:31], v[24:25]
	v_mul_f32_e32 v2, v2, v27
	v_mov_b32_e32 v30, v27
	v_fmac_f32_e32 v30, v2, v30
	v_mul_f32_e32 v2, 0x3f4c422a, v30
	v_add_f32_e32 v2, v2, v2
	v_mul_f32_e32 v2, 0x3fb8aa3b, v2
	v_exp_f32_e32 v2, v2
	v_pk_mul_f32 v[26:27], v[26:27], 0.5 op_sel_hi:[1,0]
	v_add_f32_e32 v2, 1.0, v2
	v_rcp_f32_e32 v35, v2
	s_nop 0
	v_pk_fma_f32 v[30:31], v[34:35], 2.0, 1.0 op_sel_hi:[1,0,0] neg_lo:[1,0,0] neg_hi:[1,0,0]
	s_nop 0
	v_pk_add_f32 v[30:31], v[30:31], 1.0 op_sel_hi:[1,0]
	s_nop 0
	v_pk_mul_f32 v[26:27], v[26:27], v[30:31]
	s_nop 0
	v_pk_mul_f32 v[30:31], v[24:25], v[26:27]
	v_cvt_pk_bf16_f32 v24, v0, v1
	v_cvt_pk_bf16_f32 v25, v28, v29
	v_cvt_pk_bf16_f32 v26, v32, v33
	v_cvt_pk_bf16_f32 v27, v30, v31
	global_store_dwordx4 v[66:67], v[24:27], off
	v_lshlrev_b32_e32 v0, 16, v16
	v_and_b32_e32 v1, 0xffff0000, v16
	s_waitcnt lgkmcnt(0)
; __device__ __forceinline__ u32x4 pack8(const float (&v)[8]) { u32x4 w; w.x = pk2(v[0], v[1]); w.y = pk2(v[2], v[3]); w.z = pk2(v[4], v[5]); w.w = pk2(v[6], v[7]); return w; }
; __device__ __forceinline__ float gelu_tanh(float x) { const float z = 0.7978845608028654f * (x + 0.044715f * x * x * x); const float t = 1.0f - 2.0f * __builtin_amdgcn_rcpf(__expf(2.0f * z) + 1.0f); return 0.5f * x * (1.0f + t); }
; __device__ __forceinline__ void w_lru_m3(unsigned char* ws, const bf16_t* proj, bf16_t* y, int b, int ck_, int h, int lane) {
;     ...
;     for (int i0 = 0; i0 < 8; i0 += 4) {
;         u32x4 rh[4], rp[4], rg[4];
; #pragma unroll
;         for (int i = 0; i < 4; ++i) { const size_t row = (size_t)b * SEQ + 64 * ck_ + (lane >> 3) + 8 * (i0 + i);
;             rh[i] = *(const u32x4*)(y + row * DM + col); rp[i] = *(const u32x4*)((const bf16_t*)(ws + WS_P) + row * 512 + col); rg[i] = *(const u32x4*)(proj + row * NIN + C_LG + col); }
; #pragma unroll
;         for (int i = 0; i < 4; ++i) { const size_t row = (size_t)b * SEQ + 64 * ck_ + (lane >> 3) + 8 * (i0 + i);
;             float hl[8], pv[8], g[8], o[8]; unpack8(rh[i], hl); unpack8(rp[i], pv); unpack8(rg[i], g);
; #pragma unroll
;             for (int j = 0; j < 8; ++j) o[j] = (hl[j] + pv[j] * hin[j]) * gelu_tanh(g[j]);
;             *(u32x4*)(y + row * DM + col) = pack8(o); }
	v_lshlrev_b32_e32 v26, 16, v12
	v_mul_f32_e32 v2, 0x3d372713, v26
	v_and_b32_e32 v27, 0xffff0000, v12
	v_mul_f32_e32 v2, v2, v26
	v_mov_b32_e32 v12, v26
	v_fmac_f32_e32 v12, v2, v12
	v_mul_f32_e32 v2, 0x3f4c422a, v12
	v_add_f32_e32 v2, v2, v2
	v_mul_f32_e32 v2, 0x3fb8aa3b, v2
	v_exp_f32_e32 v2, v2
	v_lshlrev_b32_e32 v24, 16, v20
	v_and_b32_e32 v25, 0xffff0000, v20
	v_pk_fma_f32 v[0:1], v[8:9], v[24:25], v[0:1]
	v_add_f32_e32 v2, 1.0, v2
	v_rcp_f32_e32 v28, v2
	v_mul_f32_e32 v2, 0x3d372713, v27
	v_mul_f32_e32 v2, v2, v27
	v_mov_b32_e32 v8, v27
	v_fmac_f32_e32 v8, v2, v8
	v_mul_f32_e32 v2, 0x3f4c422a, v8
	v_add_f32_e32 v2, v2, v2
	v_mul_f32_e32 v2, 0x3fb8aa3b, v2
	v_exp_f32_e32 v2, v2
	v_lshlrev_b32_e32 v12, 16, v13
	v_mov_b32_e32 v20, v12
	v_pk_mul_f32 v[24:25], v[26:27], 0.5 op_sel_hi:[1,0]
	v_add_f32_e32 v2, 1.0, v2
	v_rcp_f32_e32 v29, v2
	v_mul_f32_e32 v2, 0x3d372713, v12
	v_mul_f32_e32 v2, v2, v12
	v_fmac_f32_e32 v20, v2, v20
	v_mul_f32_e32 v2, 0x3f4c422a, v20
	v_add_f32_e32 v2, v2, v2
	v_mul_f32_e32 v2, 0x3fb8aa3b, v2
	v_exp_f32_e32 v2, v2
	v_pk_fma_f32 v[8:9], v[28:29], 2.0, 1.0 op_sel_hi:[1,0,0] neg_lo:[1,0,0] neg_hi:[1,0,0]
	v_and_b32_e32 v13, 0xffff0000, v13
	v_pk_add_f32 v[8:9], v[8:9], 1.0 op_sel_hi:[1,0]
	v_add_f32_e32 v2, 1.0, v2
	v_pk_mul_f32 v[8:9], v[24:25], v[8:9]
	v_lshlrev_b32_e32 v16, 16, v21
	v_pk_mul_f32 v[0:1], v[0:1], v[8:9]
	v_lshlrev_b32_e32 v8, 16, v17
	v_and_b32_e32 v9, 0xffff0000, v17
	v_and_b32_e32 v17, 0xffff0000, v21
	v_rcp_f32_e32 v20, v2
	v_mul_f32_e32 v2, 0x3d372713, v13
	v_pk_fma_f32 v[8:9], v[10:11], v[16:17], v[8:9]
	v_mul_f32_e32 v2, v2, v13
	v_mov_b32_e32 v10, v13
	v_fmac_f32_e32 v10, v2, v10
	v_mul_f32_e32 v2, 0x3f4c422a, v10
	v_add_f32_e32 v2, v2, v2
	v_mul_f32_e32 v2, 0x3fb8aa3b, v2
	v_exp_f32_e32 v2, v2
	v_lshlrev_b32_e32 v16, 16, v14
	v_and_b32_e32 v17, 0xffff0000, v14
	v_mov_b32_e32 v14, v16
	v_add_f32_e32 v2, 1.0, v2
	v_rcp_f32_e32 v21, v2
	v_mul_f32_e32 v2, 0x3d372713, v16
	v_mul_f32_e32 v2, v2, v16
	v_fmac_f32_e32 v14, v2, v14
	v_mul_f32_e32 v2, 0x3f4c422a, v14
	v_add_f32_e32 v2, v2, v2
	v_mul_f32_e32 v2, 0x3fb8aa3b, v2
	v_exp_f32_e32 v2, v2
	v_pk_fma_f32 v[10:11], v[20:21], 2.0, 1.0 op_sel_hi:[1,0,0] neg_lo:[1,0,0] neg_hi:[1,0,0]
	v_pk_mul_f32 v[12:13], v[12:13], 0.5 op_sel_hi:[1,0]
	v_pk_add_f32 v[10:11], v[10:11], 1.0 op_sel_hi:[1,0]
	v_add_f32_e32 v2, 1.0, v2
	v_pk_mul_f32 v[10:11], v[12:13], v[10:11]
	v_lshlrev_b32_e32 v12, 16, v22
	v_pk_mul_f32 v[8:9], v[8:9], v[10:11]
	v_lshlrev_b32_e32 v10, 16, v18
	v_and_b32_e32 v11, 0xffff0000, v18
	v_and_b32_e32 v13, 0xffff0000, v22
	v_rcp_f32_e32 v20, v2
	v_mul_f32_e32 v2, 0x3d372713, v17
	v_pk_fma_f32 v[4:5], v[4:5], v[12:13], v[10:11]
	v_mul_f32_e32 v2, v2, v17
	v_mov_b32_e32 v10, v17
	v_fmac_f32_e32 v10, v2, v10
	v_mul_f32_e32 v2, 0x3f4c422a, v10
	v_add_f32_e32 v2, v2, v2
	v_mul_f32_e32 v2, 0x3fb8aa3b, v2
	v_exp_f32_e32 v2, v2
	v_lshlrev_b32_e32 v14, 16, v15
	v_pk_mul_f32 v[12:13], v[16:17], 0.5 op_sel_hi:[1,0]
	v_mov_b32_e32 v16, v14
	v_add_f32_e32 v2, 1.0, v2
	v_rcp_f32_e32 v21, v2
	v_mul_f32_e32 v2, 0x3d372713, v14
	v_mul_f32_e32 v2, v2, v14
	v_fmac_f32_e32 v16, v2, v16
	v_mul_f32_e32 v2, 0x3f4c422a, v16
	v_add_f32_e32 v2, v2, v2
	v_mul_f32_e32 v2, 0x3fb8aa3b, v2
	v_exp_f32_e32 v2, v2
	v_pk_fma_f32 v[10:11], v[20:21], 2.0, 1.0 op_sel_hi:[1,0,0] neg_lo:[1,0,0] neg_hi:[1,0,0]
	v_and_b32_e32 v15, 0xffff0000, v15
	v_pk_add_f32 v[10:11], v[10:11], 1.0 op_sel_hi:[1,0]
	v_add_f32_e32 v2, 1.0, v2
	v_pk_mul_f32 v[10:11], v[12:13], v[10:11]
	v_lshlrev_b32_e32 v12, 16, v23
	v_pk_mul_f32 v[10:11], v[4:5], v[10:11]
	v_lshlrev_b32_e32 v4, 16, v19
	v_and_b32_e32 v5, 0xffff0000, v19
	v_and_b32_e32 v13, 0xffff0000, v23
	v_rcp_f32_e32 v16, v2
	v_mul_f32_e32 v2, 0x3d372713, v15
	v_pk_fma_f32 v[4:5], v[6:7], v[12:13], v[4:5]
	v_mul_f32_e32 v2, v2, v15
	v_mov_b32_e32 v6, v15
	v_fmac_f32_e32 v6, v2, v6
	v_mul_f32_e32 v2, 0x3f4c422a, v6
	v_add_f32_e32 v2, v2, v2
	v_mul_f32_e32 v2, 0x3fb8aa3b, v2
	v_exp_f32_e32 v2, v2
	v_pk_mul_f32 v[12:13], v[14:15], 0.5 op_sel_hi:[1,0]
	v_add_f32_e32 v2, 1.0, v2
	v_rcp_f32_e32 v17, v2
	s_nop 0
	v_pk_fma_f32 v[6:7], v[16:17], 2.0, 1.0 op_sel_hi:[1,0,0] neg_lo:[1,0,0] neg_hi:[1,0,0]
	s_nop 0
	v_pk_add_f32 v[6:7], v[6:7], 1.0 op_sel_hi:[1,0]
	s_nop 0
	v_pk_mul_f32 v[6:7], v[12:13], v[6:7]
	s_nop 0
	v_pk_mul_f32 v[12:13], v[4:5], v[6:7]
	v_cvt_pk_bf16_f32 v4, v0, v1
	v_cvt_pk_bf16_f32 v5, v8, v9
	v_cvt_pk_bf16_f32 v6, v10, v11
	v_cvt_pk_bf16_f32 v7, v12, v13
	global_store_dwordx4 v[60:61], v[4:7], off
	s_branch .LBB0_183

; #define LAS __attribute__((address_space(3)))
; __device__ __forceinline__ void ld8bf(const bf16_t* p, float (&o)[8]) { unpack8(*(const u32x4*)p, o); }
; __device__ __forceinline__ float ret_lg(int h) { return log1pf(-exp2f(-5.0f - (float)h)); }
; __device__ __forceinline__ void w_ret_m3(const Args& a, int l, unsigned char* ws, const bf16_t* proj, bf16_t* y, LAS unsigned char* wl, int b, int ck_, int h, int lane) {
;     LAS bf16_t* vT = (LAS bf16_t*)wl;
;     const int row0 = b * SEQ + 64 * ck_, lo = lane & 15, fq = lane >> 4; const float lg = ret_lg(h);
;     const float* cosT = (const float*)(ws + WS_ROPE); const float* sinT = cosT + SEQ * 32;
;     w_store_vT(vT, proj + (size_t)row0 * NIN + C_RV + 64 * h, lane);
;     bf16x8 Qf[4][2], Kf[4][2], Sf[4][2];
; #pragma unroll
;     for (int tb = 0; tb < 4; ++tb) { const int n = 16 * tb + lo; float x1[8], x2[8], o1[8], o2[8], cs[8], sn[8];
;         const float* cp_ = cosT + (64 * ck_ + n) * 32 + 8 * fq; const float* sp_ = sinT + (64 * ck_ + n) * 32 + 8 * fq;
; #pragma unroll
;         for (int j = 0; j < 8; ++j) { cs[j] = cp_[j]; sn[j] = sp_[j]; }
;         const bf16_t* qs = proj + (size_t)(row0 + n) * NIN + C_RQ + 64 * h + 8 * fq;
;         ld8bf(qs, x1); ld8bf(qs + 32, x2);
.LBB0_187:
	s_setprio 1
	s_lshr_b32 s20, s46, 8
	s_lshr_b32 s21, s46, 9
	s_add_i32 s20, s20, s46
	s_and_b32 s21, s21, 12
	s_add_i32 s20, s20, s21
	s_and_b32 s21, s20, 12
	s_cmp_lg_u32 s21, 8
	s_cbranch_scc1 .LBB0_186
	s_and_b32 s27, s20, 11
	s_ashr_i32 s20, s46, 31
	s_ashr_i32 s21, s46, 4
	s_lshr_b32 s20, s20, 25
	s_add_i32 s27, s27, -8
	s_add_i32 s24, s21, s20
	v_cvt_f32_u32_e32 v0, s27
	s_ashr_i32 s20, s24, 7
	s_and_b32 s24, s24, 0xffffff80
	s_sub_i32 s21, s21, s24
	s_lshl_b32 s24, s20, 13
	s_lshl_b32 s38, s21, 6
	s_add_i32 s34, s38, s24
	v_sub_f32_e32 v0, 0xc0a00000, v0
	s_mov_b32 s24, 0xc2fc0000
	v_cmp_gt_f32_e32 vcc, s24, v0
	s_and_b64 s[40:41], vcc, exec
	s_cselect_b32 s24, 0xffffffc0, 0
	v_cndmask_b32_e32 v1, 0, v204, vcc
	v_add_f32_e32 v0, v0, v1
	v_exp_f32_e32 v0, v0
	s_ashr_i32 s35, s34, 31
	s_mul_i32 s39, s34, 0x1800
	s_add_u32 s39, s8, s39
	v_ldexp_f32 v102, v0, s24
	v_sub_f32_e32 v2, 1.0, v102
	v_add_f32_e32 v0, -1.0, v2
	v_sub_f32_e32 v1, v0, v2
	v_add_f32_e32 v1, 1.0, v1
	v_sub_f32_e64 v0, -v102, v0
	v_add_f32_e32 v4, v0, v1
	v_frexp_mant_f32_e32 v0, v2
	v_cmp_gt_f32_e32 vcc, s77, v0
	v_cvt_f64_f32_e32 v[0:1], v2
	v_frexp_exp_i32_f64_e32 v0, v[0:1]
	v_subbrev_co_u32_e32 v10, vcc, 0, v0, vcc
	v_sub_u32_e32 v0, 0, v10
	v_ldexp_f32 v1, v2, v0
	v_add_f32_e32 v2, -1.0, v1
	v_add_f32_e32 v5, 1.0, v1
	v_ldexp_f32 v0, v4, v0
	v_add_f32_e32 v4, 1.0, v2
	v_add_f32_e32 v6, -1.0, v5
	v_sub_f32_e32 v4, v1, v4
	v_sub_f32_e32 v1, v1, v6
	v_add_f32_e32 v4, v0, v4
	v_add_f32_e32 v0, v0, v1
	v_add_f32_e32 v11, v5, v0
	v_rcp_f32_e32 v13, v11
	v_sub_f32_e32 v1, v11, v5
	v_sub_f32_e32 v12, v0, v1
	v_add_f32_e32 v1, v2, v4
	v_sub_f32_e32 v0, v1, v2
	v_mul_f32_e32 v14, v1, v13
	v_sub_f32_e32 v2, v4, v0
	v_mul_f32_e32 v4, v11, v14
	v_fma_f32 v6, v14, v11, -v4
	v_fmac_f32_e32 v6, v14, v12
	v_add_f32_e32 v0, v4, v6
	v_sub_f32_e32 v5, v1, v0
	v_pk_add_f32 v[8:9], v[0:1], v[4:5] neg_lo:[0,1] neg_hi:[0,1]
	v_mov_b32_e32 v7, v0
	v_pk_add_f32 v[0:1], v[8:9], v[6:7] neg_lo:[0,1] neg_hi:[0,1]
	s_mul_hi_i32 s24, s34, 0x1800
	v_add_f32_e32 v1, v2, v1
	v_add_f32_e32 v0, v0, v1
	v_add_f32_e32 v1, v5, v0
	v_mul_f32_e32 v2, v13, v1
	v_mul_f32_e32 v4, v11, v2
	v_fma_f32 v6, v2, v11, -v4
	v_fmac_f32_e32 v6, v2, v12
	v_sub_f32_e32 v5, v5, v1
	v_add_f32_e32 v11, v0, v5
	v_add_f32_e32 v0, v4, v6
	v_sub_f32_e32 v5, v1, v0
	v_pk_add_f32 v[8:9], v[0:1], v[4:5] neg_lo:[0,1] neg_hi:[0,1]
	v_mov_b32_e32 v7, v0
	v_pk_add_f32 v[0:1], v[8:9], v[6:7] neg_lo:[0,1] neg_hi:[0,1]
	v_mov_b32_e32 v101, v132
	v_add_f32_e32 v1, v11, v1
	v_add_f32_e32 v0, v0, v1
	v_add_f32_e32 v1, v14, v2
	v_add_f32_e32 v0, v5, v0
	v_sub_f32_e32 v4, v1, v14
	v_mul_f32_e32 v0, v13, v0
	v_sub_f32_e32 v2, v2, v4
	v_add_f32_e32 v2, v2, v0
	v_add_f32_e32 v4, v1, v2
	v_mul_f32_e32 v6, v4, v4
	v_fmamk_f32 v0, v6, 0x3e9b6dac, v201
	v_fmaak_f32 v169, v6, v0, 0x3f2aaada
	v_cvt_f32_i32_e32 v0, v10
	v_sub_f32_e32 v1, v4, v1
	v_sub_f32_e32 v1, v2, v1
	v_ldexp_f32 v2, v1, 1
	v_mul_f32_e32 v1, v4, v6
	v_pk_mul_f32 v[6:7], v[0:1], v[168:169]
	v_ldexp_f32 v5, v4, 1
	v_fma_f32 v4, v0, s94, -v6
	v_fmac_f32_e32 v4, 0xb102e308, v0
	v_pk_add_f32 v[8:9], v[6:7], v[4:5]
	v_mov_b32_e32 v10, v6
	v_sub_f32_e32 v0, v9, v5
	v_sub_f32_e32 v0, v7, v0
	v_add_f32_e32 v11, v2, v0
	v_pk_add_f32 v[6:7], v[8:9], v[6:7] neg_lo:[0,1] neg_hi:[0,1]
	v_pk_add_f32 v[12:13], v[8:9], v[10:11]
	v_mov_b32_e32 v5, v8
	v_mov_b32_e32 v7, v13
	v_pk_add_f32 v[0:1], v[4:5], v[6:7] neg_lo:[0,1] neg_hi:[0,1]
	v_pk_add_f32 v[4:5], v[4:5], v[6:7]
	v_mov_b32_e32 v16, v9
	v_pk_add_f32 v[6:7], v[4:5], v[8:9] op_sel:[1,0] op_sel_hi:[0,1] neg_lo:[0,1] neg_hi:[0,1]
	v_pk_add_f32 v[14:15], v[12:13], v[6:7] op_sel_hi:[1,0] neg_lo:[0,1] neg_hi:[0,1]
	v_mov_b32_e32 v12, v13
	v_mov_b32_e32 v13, v5
	v_mov_b32_e32 v17, v6
	v_pk_add_f32 v[6:7], v[12:13], v[16:17] neg_lo:[0,1] neg_hi:[0,1]
	v_mov_b32_e32 v10, v11
	v_mov_b32_e32 v11, v8
	v_pk_add_f32 v[6:7], v[10:11], v[6:7] neg_lo:[0,1] neg_hi:[0,1]
	v_mov_b32_e32 v14, v0
	v_pk_add_f32 v[14:15], v[14:15], v[6:7]
	s_addc_u32 s43, s9, s24
	s_lshl_b32 s24, s27, 6
	s_lshl_b32 s40, s27, 7
	v_pk_add_f32 v[8:9], v[14:15], v[14:15] op_sel:[0,1] op_sel_hi:[1,0]
	s_add_u32 s42, s39, s40
	v_lshlrev_b32_e32 v2, 4, v101
	v_pk_add_f32 v[12:13], v[4:5], v[8:9] op_sel:[1,0] op_sel_hi:[0,1]
	s_addc_u32 s43, s43, 0
	v_and_b32_e32 v2, 0x70, v2
	v_mov_b32_e32 v1, v5
	v_mov_b32_e32 v15, v12
	v_mov_b32_e32 v7, v8
	v_ashrrev_i32_e32 v10, 3, v101
	v_lshl_add_u64 v[8:9], s[42:43], 0, v[2:3]
	v_pk_add_f32 v[18:19], v[14:15], v[0:1] neg_lo:[0,1] neg_hi:[0,1]
	v_mad_i64_i32 v[4:5], s[44:45], v10, s72, v[8:9]
	v_pk_add_f32 v[16:17], v[6:7], v[18:19] neg_lo:[0,1] neg_hi:[0,1]
	global_load_dwordx4 v[222:225], v[4:5], off offset:3072
	v_add_u32_e32 v4, 8, v10
	v_mad_i64_i32 v[4:5], s[44:45], v4, s72, v[8:9]
	global_load_dwordx4 v[226:229], v[4:5], off offset:3072
	v_add_u32_e32 v4, 16, v10
	v_mad_i64_i32 v[4:5], s[44:45], v4, s72, v[8:9]
	global_load_dwordx4 v[230:233], v[4:5], off offset:3072
	v_add_u32_e32 v4, 24, v10
	v_mad_i64_i32 v[4:5], s[44:45], v4, s72, v[8:9]
	global_load_dwordx4 v[234:237], v[4:5], off offset:3072
	v_add_u32_e32 v4, 32, v10
	v_mad_i64_i32 v[4:5], s[44:45], v4, s72, v[8:9]
	global_load_dwordx4 v[238:241], v[4:5], off offset:3072
	v_add_u32_e32 v4, 40, v10
	v_mad_i64_i32 v[4:5], s[44:45], v4, s72, v[8:9]
	global_load_dwordx4 v[242:245], v[4:5], off offset:3072
	v_add_u32_e32 v4, 48, v10
	v_mad_i64_i32 v[4:5], s[44:45], v4, s72, v[8:9]
	global_load_dwordx4 v[246:249], v[4:5], off offset:3072
	v_add_u32_e32 v4, 56, v10
	v_mad_i64_i32 v[4:5], s[44:45], v4, s72, v[8:9]
	global_load_dwordx4 v[250:253], v[4:5], off offset:3072
	v_mul_lo_u32 v11, v10, s23
	v_add3_u32 v2, s2, v2, v11
	v_and_b32_e32 v133, 15, v101
	v_ashrrev_i32_e32 v100, 4, v101
	s_mov_b32 s41, s25
	v_or_b32_e32 v144, 16, v133
	v_or_b32_e32 v136, 32, v133
	v_or_b32_e32 v134, 48, v133
	s_lshl_b32 s20, s20, 9
	s_lshl_b32 s21, s21, 2
	s_add_i32 s21, s21, s20
	s_or_b32 s20, s27, s21
	s_ashr_i32 s21, s20, 31
	s_lshl_b64 s[20:21], s[20:21], 13
	s_waitcnt lgkmcnt(0)
; #define LAS __attribute__((address_space(3)))
; __device__ __forceinline__ void ld8bf(const bf16_t* p, float (&o)[8]) { unpack8(*(const u32x4*)p, o); }
; __device__ __forceinline__ float ret_lg(int h) { return log1pf(-exp2f(-5.0f - (float)h)); }
; __device__ __forceinline__ bf16x8 pack_frag(const float (&v)[8]) { return __builtin_bit_cast(bf16x8, pack8(v)); }
; __device__ __forceinline__ void w_store_vT(LAS bf16_t* vN, const bf16_t* src, int lane) {
;     ...
;     for (int i = 0; i < 8; ++i) { const int m = (lane >> 3) + 8 * i, e0 = 8 * (lane & 7); *(LAS u32x4*)(vN + m * LD + e0) = *(const u32x4*)(src + (size_t)m * NIN + e0); }
; __device__ __forceinline__ void w_ret_m3(const Args& a, int l, unsigned char* ws, const bf16_t* proj, bf16_t* y, LAS unsigned char* wl, int b, int ck_, int h, int lane) {
;     LAS bf16_t* vT = (LAS bf16_t*)wl;
;     const int row0 = b * SEQ + 64 * ck_, lo = lane & 15, fq = lane >> 4; const float lg = ret_lg(h);
;     const float* cosT = (const float*)(ws + WS_ROPE); const float* sinT = cosT + SEQ * 32;
;     w_store_vT(vT, proj + (size_t)row0 * NIN + C_RV + 64 * h, lane);
;     bf16x8 Qf[4][2], Kf[4][2], Sf[4][2];
; #pragma unroll
;     for (int tb = 0; tb < 4; ++tb) { const int n = 16 * tb + lo; float x1[8], x2[8], o1[8], o2[8], cs[8], sn[8];
;         const float* cp_ = cosT + (64 * ck_ + n) * 32 + 8 * fq; const float* sp_ = sinT + (64 * ck_ + n) * 32 + 8 * fq;
; #pragma unroll
;         for (int j = 0; j < 8; ++j) { cs[j] = cp_[j]; sn[j] = sp_[j]; }
;         const bf16_t* qs = proj + (size_t)(row0 + n) * NIN + C_RQ + 64 * h + 8 * fq;
;         ld8bf(qs, x1); ld8bf(qs + 32, x2);
; #pragma unroll
;         for (int j = 0; j < 8; ++j) { o1[j] = x1[j] * cs[j] - x2[j] * sn[j]; o2[j] = x2[j] * cs[j] + x1[j] * sn[j]; }
;         Qf[tb][0] = pack_frag(o1); Qf[tb][1] = pack_frag(o2);
;         const bf16_t* ks = proj + (size_t)(row0 + n) * NIN + C_RK + 64 * h + 8 * fq;
;         ld8bf(ks, x1); ld8bf(ks + 32, x2);
; #pragma unroll
;         for (int j = 0; j < 8; ++j) { o1[j] = (x1[j] * cs[j] - x2[j] * sn[j]) * 0.125f; o2[j] = (x2[j] * cs[j] + x1[j] * sn[j]) * 0.125f; }
;         Kf[tb][0] = pack_frag(o1); Kf[tb][1] = pack_frag(o2);
;     }
	s_add_u32 s20, s48, s20
	s_addc_u32 s21, s49, s21
	v_cmp_gt_f32_e32 vcc, s95, v102
	v_lshlrev_b32_e32 v124, 2, v100
	v_add_u32_e32 v140, 16, v124
	v_lshlrev_b32_e32 v1, 3, v101
	v_not_b32_e32 v143, v124
	v_and_b32_e32 v1, 24, v1
	v_or_b32_e32 v141, 3, v124
	v_or_b32_e32 v142, 2, v124
	v_add_u32_e32 v104, s2, v1
	v_sub_u32_e32 v1, v133, v141
	v_cvt_f32_i32_e32 v1, v1
	v_ashrrev_i32_e32 v125, 31, v124
	v_mov_b32_e32 v186, v2
	v_lshlrev_b32_e32 v10, 3, v100
	v_ashrrev_i32_e32 v11, 31, v10
	v_or_b32_e32 v2, s38, v133
	v_lshlrev_b32_e32 v8, 5, v2
	v_lshlrev_b64 v[6:7], 2, v[10:11]
	v_ashrrev_i32_e32 v9, 31, v8
	v_lshl_add_u64 v[4:5], s[60:61], 0, v[6:7]
	v_lshl_add_u64 v[6:7], s[62:63], 0, v[6:7]
	v_lshlrev_b64 v[8:9], 2, v[8:9]
	v_lshl_add_u64 v[46:47], v[4:5], 0, v[8:9]
	v_lshl_add_u64 v[48:49], v[6:7], 0, v[8:9]
	v_or_b32_e32 v2, s34, v133
	v_mov_b64_e32 v[8:9], s[8:9]
	v_mad_i64_i32 v[20:21], s[44:45], v2, s72, v[8:9]
	v_lshl_add_u64 v[22:23], v[20:21], 0, s[40:41]
	v_lshlrev_b64 v[20:21], 1, v[10:11]
	v_lshl_add_u64 v[10:11], v[22:23], 0, v[20:21]
	global_load_dwordx4 v[22:25], v[10:11], off offset:2048
	global_load_dwordx4 v[26:29], v[10:11], off offset:2112
	global_load_dwordx4 v[30:33], v[10:11], off offset:2560
	global_load_dwordx4 v[34:37], v[10:11], off offset:2624
	global_load_dwordx4 v[38:41], v[46:47], off
	global_load_dwordx4 v[42:45], v[48:49], off
	global_load_dwordx4 v[174:177], v[46:47], off offset:16
	global_load_dwordx4 v[178:181], v[48:49], off offset:16
	s_waitcnt vmcnt(8)
	ds_write_b128 v186, v[222:225]
	ds_write_b128 v186, v[226:229] offset:1152
	ds_write_b128 v186, v[230:233] offset:2304
	ds_write_b128 v186, v[234:237] offset:3456
	ds_write_b128 v186, v[238:241] offset:4608
	ds_write_b128 v186, v[242:245] offset:5760
	ds_write_b128 v186, v[246:249] offset:6912
	ds_write_b128 v186, v[250:253] offset:8064
	v_lshlrev_b64 v[182:183], 1, v[124:125]
	v_lshl_add_u64 v[182:183], s[42:43], 0, v[182:183]
	v_and_b32_e32 v184, 16, v132
	v_lshrrev_b32_e32 v185, 1, v184
	v_add_u32_e32 v184, v184, v185
	v_mov_b32_e32 v185, 0
	v_lshl_add_u64 v[182:183], v[182:183], 0, v[184:185]
	v_mad_u64_u32 v[184:185], s[44:45], v133, s72, v[182:183]
	global_load_dwordx4 v[222:225], v[184:185], off offset:3584
	global_load_dwordx4 v[226:229], v[184:185], off offset:3648
	v_mad_u64_u32 v[184:185], s[44:45], v144, s72, v[182:183]
	global_load_dwordx4 v[230:233], v[184:185], off offset:3584
	global_load_dwordx4 v[234:237], v[184:185], off offset:3648
	v_mad_u64_u32 v[184:185], s[44:45], v136, s72, v[182:183]
	global_load_dwordx4 v[238:241], v[184:185], off offset:3584
	global_load_dwordx4 v[242:245], v[184:185], off offset:3648
	v_mad_u64_u32 v[184:185], s[44:45], v134, s72, v[182:183]
	global_load_dwordx4 v[246:249], v[184:185], off offset:3584
	global_load_dwordx4 v[250:253], v[184:185], off offset:3648
	v_mov_b32_e32 v184, 0x18000
	v_mov_b32_e32 v185, 0
	v_lshl_add_u64 v[182:183], v[10:11], 0, v[184:185]
	global_load_dwordx4 v[108:111], v[182:183], off offset:2048
	global_load_dwordx4 v[112:115], v[182:183], off offset:2112
	global_load_dwordx4 v[116:119], v[182:183], off offset:2560
	global_load_dwordx4 v[120:123], v[182:183], off offset:2624
	v_lshl_add_u64 v[182:183], v[182:183], 0, v[184:185]
	global_load_dwordx4 v[126:129], v[182:183], off offset:2048
	global_load_dwordx4 v[146:149], v[182:183], off offset:2112
	global_load_dwordx4 v[150:153], v[182:183], off offset:2560
	global_load_dwordx4 v[154:157], v[182:183], off offset:2624
	v_lshl_add_u64 v[182:183], v[182:183], 0, v[184:185]
	global_load_dwordx4 v[158:161], v[182:183], off offset:2048
	global_load_dwordx4 v[188:191], v[182:183], off offset:2112
	global_load_dwordx4 v[192:195], v[182:183], off offset:2560
	global_load_dwordx4 v[196:199], v[182:183], off offset:2624
	v_or_b32_e32 v2, s38, v144
	s_waitcnt vmcnt(20) lgkmcnt(0)
	v_lshlrev_b32_e32 v10, 16, v22
	v_lshlrev_b32_e32 v50, 16, v26
	v_and_b32_e32 v51, 0xffff0000, v26
	v_and_b32_e32 v11, 0xffff0000, v22
	v_pk_mul_f32 v[52:53], v[38:39], v[50:51]
	v_pk_mul_f32 v[50:51], v[42:43], v[50:51]
	v_pk_fma_f32 v[52:53], v[42:43], v[10:11], v[52:53]
	v_pk_fma_f32 v[10:11], v[38:39], v[10:11], v[50:51] neg_lo:[0,0,1] neg_hi:[0,0,1]
	v_lshlrev_b32_e32 v50, 16, v34
	v_and_b32_e32 v51, 0xffff0000, v34
	v_cvt_pk_bf16_f32 v96, v10, v11
	v_cvt_pk_bf16_f32 v92, v52, v53
	v_lshlrev_b32_e32 v10, 16, v30
	v_and_b32_e32 v11, 0xffff0000, v30
	v_pk_mul_f32 v[52:53], v[38:39], v[50:51]
	v_lshlrev_b32_e32 v26, 16, v27
	v_pk_fma_f32 v[52:53], v[42:43], v[10:11], v[52:53]
	v_pk_mul_f32 v[42:43], v[42:43], v[50:51]
	v_and_b32_e32 v27, 0xffff0000, v27
	v_pk_fma_f32 v[10:11], v[38:39], v[10:11], v[42:43] neg_lo:[0,0,1] neg_hi:[0,0,1]
	v_lshlrev_b32_e32 v22, 16, v23
	v_and_b32_e32 v23, 0xffff0000, v23
	v_pk_mul_f32 v[38:39], v[40:41], v[26:27]
	v_pk_mul_f32 v[26:27], v[44:45], v[26:27]
	v_pk_fma_f32 v[38:39], v[44:45], v[22:23], v[38:39]
	v_pk_fma_f32 v[22:23], v[40:41], v[22:23], v[26:27] neg_lo:[0,0,1] neg_hi:[0,0,1]
	v_lshlrev_b32_e32 v26, 16, v35
	v_and_b32_e32 v27, 0xffff0000, v35
	v_cvt_pk_bf16_f32 v97, v22, v23
	v_lshlrev_b32_e32 v22, 16, v31
	v_and_b32_e32 v23, 0xffff0000, v31
	v_pk_mul_f32 v[30:31], v[40:41], v[26:27]
	v_pk_mul_f32 v[26:27], v[44:45], v[26:27]
	v_cvt_pk_bf16_f32 v93, v38, v39
	v_pk_fma_f32 v[30:31], v[44:45], v[22:23], v[30:31]
	v_pk_fma_f32 v[22:23], v[40:41], v[22:23], v[26:27] neg_lo:[0,0,1] neg_hi:[0,0,1]
	v_mov_b64_e32 v[38:39], v[174:175]
	v_mov_b64_e32 v[40:41], v[176:177]
	v_mov_b64_e32 v[42:43], v[178:179]
	v_mov_b64_e32 v[44:45], v[180:181]
	v_lshlrev_b32_e32 v34, 16, v28
	v_and_b32_e32 v35, 0xffff0000, v28
	v_lshlrev_b32_e32 v26, 16, v24
	v_and_b32_e32 v27, 0xffff0000, v24
	v_lshlrev_b32_e32 v28, 16, v29
	v_and_b32_e32 v29, 0xffff0000, v29
	v_pk_mul_f32 v[10:11], v[10:11], s[16:17] op_sel_hi:[1,0]
	v_lshlrev_b32_e32 v24, 16, v25
	v_and_b32_e32 v25, 0xffff0000, v25
	v_pk_mul_f32 v[22:23], v[22:23], s[16:17] op_sel_hi:[1,0]
	v_cvt_pk_bf16_f32 v64, v10, v11
	v_lshlrev_b32_e32 v10, 5, v2
	v_or_b32_e32 v2, s34, v144
	v_cvt_pk_bf16_f32 v65, v22, v23
	v_mad_i64_i32 v[22:23], s[44:45], v2, s72, v[8:9]
	v_ashrrev_i32_e32 v11, 31, v10
	v_lshl_add_u64 v[22:23], v[22:23], 0, s[40:41]
	v_pk_mul_f32 v[30:31], v[30:31], s[16:17] op_sel_hi:[1,0]
	v_lshlrev_b64 v[10:11], 2, v[10:11]
	v_cvt_pk_bf16_f32 v73, v30, v31
	v_or_b32_e32 v2, s38, v136
	v_pk_mul_f32 v[52:53], v[52:53], s[16:17] op_sel_hi:[1,0]
	s_waitcnt vmcnt(0) lgkmcnt(0)
; __device__ __forceinline__ void ld8bf(const bf16_t* p, float (&o)[8]) { unpack8(*(const u32x4*)p, o); }
; __device__ __forceinline__ bf16x8 pack_frag(const float (&v)[8]) { return __builtin_bit_cast(bf16x8, pack8(v)); }
; __device__ __forceinline__ void w_ret_m3(const Args& a, int l, unsigned char* ws, const bf16_t* proj, bf16_t* y, LAS unsigned char* wl, int b, int ck_, int h, int lane) {
;     ...
;     for (int tb = 0; tb < 4; ++tb) { const int n = 16 * tb + lo; float x1[8], x2[8], o1[8], o2[8], cs[8], sn[8];
;         const float* cp_ = cosT + (64 * ck_ + n) * 32 + 8 * fq; const float* sp_ = sinT + (64 * ck_ + n) * 32 + 8 * fq;
; #pragma unroll
;         for (int j = 0; j < 8; ++j) { cs[j] = cp_[j]; sn[j] = sp_[j]; }
;         const bf16_t* qs = proj + (size_t)(row0 + n) * NIN + C_RQ + 64 * h + 8 * fq;
;         ld8bf(qs, x1); ld8bf(qs + 32, x2);
; #pragma unroll
;         for (int j = 0; j < 8; ++j) { o1[j] = x1[j] * cs[j] - x2[j] * sn[j]; o2[j] = x2[j] * cs[j] + x1[j] * sn[j]; }
;         Qf[tb][0] = pack_frag(o1); Qf[tb][1] = pack_frag(o2);
;         const bf16_t* ks = proj + (size_t)(row0 + n) * NIN + C_RK + 64 * h + 8 * fq;
;         ld8bf(ks, x1); ld8bf(ks + 32, x2);
; #pragma unroll
;         for (int j = 0; j < 8; ++j) { o1[j] = (x1[j] * cs[j] - x2[j] * sn[j]) * 0.125f; o2[j] = (x2[j] * cs[j] + x1[j] * sn[j]) * 0.125f; }
;         Kf[tb][0] = pack_frag(o1); Kf[tb][1] = pack_frag(o2);
;     }
	v_pk_mul_f32 v[46:47], v[38:39], v[34:35]
	v_pk_mul_f32 v[34:35], v[42:43], v[34:35]
	v_pk_fma_f32 v[46:47], v[42:43], v[26:27], v[46:47]
	v_pk_fma_f32 v[26:27], v[38:39], v[26:27], v[34:35] neg_lo:[0,0,1] neg_hi:[0,0,1]
	v_lshlrev_b32_e32 v34, 16, v36
	v_and_b32_e32 v35, 0xffff0000, v36
	v_cvt_pk_bf16_f32 v98, v26, v27
	v_cvt_pk_bf16_f32 v94, v46, v47
	v_lshlrev_b32_e32 v26, 16, v32
	v_and_b32_e32 v27, 0xffff0000, v32
	v_pk_mul_f32 v[46:47], v[38:39], v[34:35]
	v_pk_mul_f32 v[34:35], v[42:43], v[34:35]
	v_pk_fma_f32 v[46:47], v[42:43], v[26:27], v[46:47]
	v_pk_fma_f32 v[26:27], v[38:39], v[26:27], v[34:35] neg_lo:[0,0,1] neg_hi:[0,0,1]
	v_pk_mul_f32 v[34:35], v[40:41], v[28:29]
	v_pk_mul_f32 v[28:29], v[44:45], v[28:29]
	v_pk_fma_f32 v[34:35], v[44:45], v[24:25], v[34:35]
	v_pk_fma_f32 v[24:25], v[40:41], v[24:25], v[28:29] neg_lo:[0,0,1] neg_hi:[0,0,1]
	v_lshlrev_b32_e32 v28, 16, v37
	v_and_b32_e32 v29, 0xffff0000, v37
	v_cvt_pk_bf16_f32 v99, v24, v25
	v_lshlrev_b32_e32 v24, 16, v33
	v_and_b32_e32 v25, 0xffff0000, v33
	v_pk_mul_f32 v[32:33], v[40:41], v[28:29]
	v_pk_mul_f32 v[28:29], v[44:45], v[28:29]
	v_pk_fma_f32 v[32:33], v[44:45], v[24:25], v[32:33]
	v_pk_fma_f32 v[24:25], v[40:41], v[24:25], v[28:29] neg_lo:[0,0,1] neg_hi:[0,0,1]
	v_pk_mul_f32 v[46:47], v[46:47], s[16:17] op_sel_hi:[1,0]
	v_pk_mul_f32 v[26:27], v[26:27], s[16:17] op_sel_hi:[1,0]
	v_cvt_pk_bf16_f32 v95, v34, v35
	v_pk_mul_f32 v[32:33], v[32:33], s[16:17] op_sel_hi:[1,0]
	v_pk_mul_f32 v[24:25], v[24:25], s[16:17] op_sel_hi:[1,0]
	v_lshl_add_u64 v[34:35], v[22:23], 0, v[20:21]
	v_cvt_pk_bf16_f32 v66, v26, v27
	v_cvt_pk_bf16_f32 v67, v24, v25
	v_cvt_pk_bf16_f32 v74, v46, v47
	v_cvt_pk_bf16_f32 v75, v32, v33
	v_lshl_add_u64 v[46:47], v[4:5], 0, v[10:11]
	v_lshl_add_u64 v[10:11], v[6:7], 0, v[10:11]
	v_mov_b64_e32 v[22:23], v[108:109]
	v_mov_b64_e32 v[24:25], v[110:111]
	v_mov_b64_e32 v[26:27], v[112:113]
	v_mov_b64_e32 v[28:29], v[114:115]
	v_mov_b64_e32 v[30:31], v[116:117]
	v_mov_b64_e32 v[32:33], v[118:119]
	s_nop 0
	v_mov_b64_e32 v[34:35], v[120:121]
	v_mov_b64_e32 v[36:37], v[122:123]
	s_nop 0
	global_load_dwordx2 v[42:43], v[46:47], off
	global_load_dwordx4 v[38:41], v[10:11], off
	global_load_dwordx4 v[174:177], v[46:47], off offset:8
	global_load_dwordx4 v[178:181], v[10:11], off offset:16
	global_load_dwordx2 v[182:183], v[46:47], off offset:24
	v_cvt_pk_bf16_f32 v72, v52, v53
	s_waitcnt vmcnt(0) lgkmcnt(0)
	v_lshlrev_b32_e32 v44, 16, v22
	v_lshlrev_b32_e32 v48, 16, v26
	v_and_b32_e32 v49, 0xffff0000, v26
	v_and_b32_e32 v45, 0xffff0000, v22
	v_pk_mul_f32 v[50:51], v[42:43], v[48:49]
	v_pk_mul_f32 v[48:49], v[38:39], v[48:49]
	v_pk_fma_f32 v[50:51], v[38:39], v[44:45], v[50:51]
	v_pk_fma_f32 v[44:45], v[42:43], v[44:45], v[48:49] neg_lo:[0,0,1] neg_hi:[0,0,1]
	v_lshlrev_b32_e32 v48, 16, v34
	v_and_b32_e32 v49, 0xffff0000, v34
	v_cvt_pk_bf16_f32 v88, v44, v45
	v_cvt_pk_bf16_f32 v84, v50, v51
	v_lshlrev_b32_e32 v44, 16, v30
	v_and_b32_e32 v45, 0xffff0000, v30
	v_pk_mul_f32 v[50:51], v[42:43], v[48:49]
	v_lshlrev_b32_e32 v26, 16, v27
	v_pk_fma_f32 v[50:51], v[38:39], v[44:45], v[50:51]
	v_pk_mul_f32 v[38:39], v[38:39], v[48:49]
	v_and_b32_e32 v27, 0xffff0000, v27
	v_pk_fma_f32 v[38:39], v[42:43], v[44:45], v[38:39] neg_lo:[0,0,1] neg_hi:[0,0,1]
	v_mov_b64_e32 v[42:43], v[174:175]
	v_mov_b64_e32 v[44:45], v[176:177]
	v_pk_mul_f32 v[48:49], v[38:39], s[16:17] op_sel_hi:[1,0]
	v_lshlrev_b32_e32 v22, 16, v23
	v_and_b32_e32 v23, 0xffff0000, v23
	v_pk_mul_f32 v[50:51], v[50:51], s[16:17] op_sel_hi:[1,0]
	v_cvt_pk_bf16_f32 v60, v48, v49
	v_cvt_pk_bf16_f32 v68, v50, v51
	s_waitcnt vmcnt(0) lgkmcnt(0)
	v_pk_mul_f32 v[38:39], v[42:43], v[26:27]
	v_pk_mul_f32 v[26:27], v[40:41], v[26:27]
	v_pk_fma_f32 v[38:39], v[40:41], v[22:23], v[38:39]
	v_pk_fma_f32 v[22:23], v[42:43], v[22:23], v[26:27] neg_lo:[0,0,1] neg_hi:[0,0,1]
	v_lshlrev_b32_e32 v26, 16, v35
	v_and_b32_e32 v27, 0xffff0000, v35
	v_cvt_pk_bf16_f32 v89, v22, v23
	v_lshlrev_b32_e32 v22, 16, v31
	v_and_b32_e32 v23, 0xffff0000, v31
	v_pk_mul_f32 v[30:31], v[42:43], v[26:27]
	v_cvt_pk_bf16_f32 v85, v38, v39
	v_pk_fma_f32 v[30:31], v[40:41], v[22:23], v[30:31]
	v_pk_mul_f32 v[26:27], v[40:41], v[26:27]
	v_mov_b64_e32 v[38:39], v[178:179]
	v_mov_b64_e32 v[40:41], v[180:181]
	v_pk_fma_f32 v[22:23], v[42:43], v[22:23], v[26:27] neg_lo:[0,0,1] neg_hi:[0,0,1]
	v_lshlrev_b32_e32 v26, 16, v28
	v_and_b32_e32 v27, 0xffff0000, v28
	v_lshlrev_b32_e32 v10, 16, v24
	v_and_b32_e32 v11, 0xffff0000, v24
	v_pk_mul_f32 v[34:35], v[44:45], v[26:27]
	v_lshlrev_b32_e32 v28, 16, v29
	v_and_b32_e32 v29, 0xffff0000, v29
	v_lshlrev_b32_e32 v24, 16, v25
	v_and_b32_e32 v25, 0xffff0000, v25
	v_pk_mul_f32 v[22:23], v[22:23], s[16:17] op_sel_hi:[1,0]
	v_pk_mul_f32 v[30:31], v[30:31], s[16:17] op_sel_hi:[1,0]
	v_cvt_pk_bf16_f32 v61, v22, v23
	v_cvt_pk_bf16_f32 v69, v30, v31
	s_waitcnt vmcnt(0) lgkmcnt(0)
	v_pk_mul_f32 v[26:27], v[38:39], v[26:27]
	v_pk_fma_f32 v[34:35], v[38:39], v[10:11], v[34:35]
	v_pk_fma_f32 v[10:11], v[44:45], v[10:11], v[26:27] neg_lo:[0,0,1] neg_hi:[0,0,1]
	v_lshlrev_b32_e32 v26, 16, v36
	v_and_b32_e32 v27, 0xffff0000, v36
	v_cvt_pk_bf16_f32 v90, v10, v11
	v_cvt_pk_bf16_f32 v86, v34, v35
	v_lshlrev_b32_e32 v10, 16, v32
	v_and_b32_e32 v11, 0xffff0000, v32
	v_pk_mul_f32 v[34:35], v[44:45], v[26:27]
	v_pk_mul_f32 v[26:27], v[38:39], v[26:27]
	v_pk_fma_f32 v[34:35], v[38:39], v[10:11], v[34:35]
	v_pk_fma_f32 v[10:11], v[44:45], v[10:11], v[26:27] neg_lo:[0,0,1] neg_hi:[0,0,1]
	v_mov_b64_e32 v[26:27], v[182:183]
	v_pk_mul_f32 v[10:11], v[10:11], s[16:17] op_sel_hi:[1,0]
	v_pk_mul_f32 v[34:35], v[34:35], s[16:17] op_sel_hi:[1,0]
	v_cvt_pk_bf16_f32 v62, v10, v11
	v_lshlrev_b32_e32 v10, 5, v2
	v_or_b32_e32 v2, s34, v136
	v_mad_i64_i32 v[22:23], s[44:45], v2, s72, v[8:9]
	v_ashrrev_i32_e32 v11, 31, v10
	v_lshl_add_u64 v[22:23], v[22:23], 0, s[40:41]
	v_cvt_pk_bf16_f32 v70, v34, v35
	v_lshlrev_b64 v[10:11], 2, v[10:11]
	v_lshl_add_u64 v[34:35], v[22:23], 0, v[20:21]
	v_lshl_add_u64 v[46:47], v[4:5], 0, v[10:11]
	v_lshl_add_u64 v[10:11], v[6:7], 0, v[10:11]
	v_or_b32_e32 v2, s38, v134
	s_waitcnt vmcnt(0) lgkmcnt(0)
; __device__ __forceinline__ void ld8bf(const bf16_t* p, float (&o)[8]) { unpack8(*(const u32x4*)p, o); }
; __device__ __forceinline__ bf16x8 pack_frag(const float (&v)[8]) { return __builtin_bit_cast(bf16x8, pack8(v)); }
; __device__ __forceinline__ float ret_lg(int h) { return log1pf(-exp2f(-5.0f - (float)h)); }
; __device__ __forceinline__ void w_ret_m3(const Args& a, int l, unsigned char* ws, const bf16_t* proj, bf16_t* y, LAS unsigned char* wl, int b, int ck_, int h, int lane) {
;     ...
;     for (int tb = 0; tb < 4; ++tb) { const int n = 16 * tb + lo; float x1[8], x2[8], o1[8], o2[8], cs[8], sn[8];
;         const float* cp_ = cosT + (64 * ck_ + n) * 32 + 8 * fq; const float* sp_ = sinT + (64 * ck_ + n) * 32 + 8 * fq;
; #pragma unroll
;         for (int j = 0; j < 8; ++j) { cs[j] = cp_[j]; sn[j] = sp_[j]; }
;         const bf16_t* qs = proj + (size_t)(row0 + n) * NIN + C_RQ + 64 * h + 8 * fq;
;         ld8bf(qs, x1); ld8bf(qs + 32, x2);
; #pragma unroll
;         for (int j = 0; j < 8; ++j) { o1[j] = x1[j] * cs[j] - x2[j] * sn[j]; o2[j] = x2[j] * cs[j] + x1[j] * sn[j]; }
;         Qf[tb][0] = pack_frag(o1); Qf[tb][1] = pack_frag(o2);
;         const bf16_t* ks = proj + (size_t)(row0 + n) * NIN + C_RK + 64 * h + 8 * fq;
;         ld8bf(ks, x1); ld8bf(ks + 32, x2);
; #pragma unroll
;         for (int j = 0; j < 8; ++j) { o1[j] = (x1[j] * cs[j] - x2[j] * sn[j]) * 0.125f; o2[j] = (x2[j] * cs[j] + x1[j] * sn[j]) * 0.125f; }
;         Kf[tb][0] = pack_frag(o1); Kf[tb][1] = pack_frag(o2);
;     }
	v_pk_mul_f32 v[38:39], v[26:27], v[28:29]
	v_pk_mul_f32 v[28:29], v[40:41], v[28:29]
	v_pk_fma_f32 v[38:39], v[40:41], v[24:25], v[38:39]
	v_pk_fma_f32 v[24:25], v[26:27], v[24:25], v[28:29] neg_lo:[0,0,1] neg_hi:[0,0,1]
	v_lshlrev_b32_e32 v28, 16, v37
	v_and_b32_e32 v29, 0xffff0000, v37
	v_cvt_pk_bf16_f32 v91, v24, v25
	v_lshlrev_b32_e32 v24, 16, v33
	v_and_b32_e32 v25, 0xffff0000, v33
	v_pk_mul_f32 v[32:33], v[26:27], v[28:29]
	v_pk_mul_f32 v[28:29], v[40:41], v[28:29]
	v_pk_fma_f32 v[32:33], v[40:41], v[24:25], v[32:33]
	v_pk_fma_f32 v[24:25], v[26:27], v[24:25], v[28:29] neg_lo:[0,0,1] neg_hi:[0,0,1]
	v_pk_mul_f32 v[32:33], v[32:33], s[16:17] op_sel_hi:[1,0]
	v_pk_mul_f32 v[24:25], v[24:25], s[16:17] op_sel_hi:[1,0]
	v_cvt_pk_bf16_f32 v87, v38, v39
	v_cvt_pk_bf16_f32 v63, v24, v25
	v_cvt_pk_bf16_f32 v71, v32, v33
	v_mov_b64_e32 v[22:23], v[126:127]
	v_mov_b64_e32 v[24:25], v[128:129]
	v_mov_b64_e32 v[26:27], v[146:147]
	v_mov_b64_e32 v[28:29], v[148:149]
	v_mov_b64_e32 v[30:31], v[150:151]
	v_mov_b64_e32 v[32:33], v[152:153]
	s_nop 0
	v_mov_b64_e32 v[34:35], v[154:155]
	v_mov_b64_e32 v[36:37], v[156:157]
	s_nop 0
	global_load_dwordx4 v[38:41], v[46:47], off
	global_load_dwordx4 v[42:45], v[10:11], off
	global_load_dwordx4 v[174:177], v[46:47], off offset:16
	global_load_dwordx4 v[178:181], v[10:11], off offset:16
	s_waitcnt vmcnt(0) lgkmcnt(0)
	v_lshlrev_b32_e32 v48, 16, v22
	v_lshlrev_b32_e32 v50, 16, v26
	v_and_b32_e32 v51, 0xffff0000, v26
	v_and_b32_e32 v49, 0xffff0000, v22
	v_pk_mul_f32 v[52:53], v[38:39], v[50:51]
	v_pk_mul_f32 v[50:51], v[42:43], v[50:51]
	v_pk_fma_f32 v[52:53], v[42:43], v[48:49], v[52:53]
	v_pk_fma_f32 v[48:49], v[38:39], v[48:49], v[50:51] neg_lo:[0,0,1] neg_hi:[0,0,1]
	v_lshlrev_b32_e32 v50, 16, v34
	v_and_b32_e32 v51, 0xffff0000, v34
	v_cvt_pk_bf16_f32 v80, v48, v49
	v_cvt_pk_bf16_f32 v76, v52, v53
	v_lshlrev_b32_e32 v48, 16, v30
	v_and_b32_e32 v49, 0xffff0000, v30
	v_pk_mul_f32 v[52:53], v[38:39], v[50:51]
	v_lshlrev_b32_e32 v26, 16, v27
	v_pk_fma_f32 v[52:53], v[42:43], v[48:49], v[52:53]
	v_pk_mul_f32 v[42:43], v[42:43], v[50:51]
	v_and_b32_e32 v27, 0xffff0000, v27
	v_pk_fma_f32 v[38:39], v[38:39], v[48:49], v[42:43] neg_lo:[0,0,1] neg_hi:[0,0,1]
	v_lshlrev_b32_e32 v22, 16, v23
	v_pk_mul_f32 v[48:49], v[38:39], s[16:17] op_sel_hi:[1,0]
	v_and_b32_e32 v23, 0xffff0000, v23
	v_pk_mul_f32 v[38:39], v[40:41], v[26:27]
	v_pk_mul_f32 v[26:27], v[44:45], v[26:27]
	v_pk_fma_f32 v[38:39], v[44:45], v[22:23], v[38:39]
	v_pk_fma_f32 v[22:23], v[40:41], v[22:23], v[26:27] neg_lo:[0,0,1] neg_hi:[0,0,1]
	v_lshlrev_b32_e32 v26, 16, v35
	v_and_b32_e32 v27, 0xffff0000, v35
	v_cvt_pk_bf16_f32 v81, v22, v23
	v_lshlrev_b32_e32 v22, 16, v31
	v_and_b32_e32 v23, 0xffff0000, v31
	v_pk_mul_f32 v[30:31], v[40:41], v[26:27]
	v_pk_mul_f32 v[26:27], v[44:45], v[26:27]
	v_cvt_pk_bf16_f32 v77, v38, v39
	v_pk_fma_f32 v[30:31], v[44:45], v[22:23], v[30:31]
	v_pk_fma_f32 v[22:23], v[40:41], v[22:23], v[26:27] neg_lo:[0,0,1] neg_hi:[0,0,1]
	v_mov_b64_e32 v[38:39], v[174:175]
	v_mov_b64_e32 v[40:41], v[176:177]
	v_mov_b64_e32 v[42:43], v[178:179]
	v_mov_b64_e32 v[44:45], v[180:181]
	v_lshlrev_b32_e32 v26, 16, v28
	v_and_b32_e32 v27, 0xffff0000, v28
	v_lshlrev_b32_e32 v10, 16, v24
	v_and_b32_e32 v11, 0xffff0000, v24
	v_lshlrev_b32_e32 v24, 16, v25
	v_and_b32_e32 v25, 0xffff0000, v25
	v_pk_mul_f32 v[30:31], v[30:31], s[16:17] op_sel_hi:[1,0]
	v_pk_mul_f32 v[22:23], v[22:23], s[16:17] op_sel_hi:[1,0]
	v_pk_mul_f32 v[52:53], v[52:53], s[16:17] op_sel_hi:[1,0]
	s_waitcnt vmcnt(0) lgkmcnt(0)
	v_pk_mul_f32 v[34:35], v[38:39], v[26:27]
	v_pk_mul_f32 v[26:27], v[42:43], v[26:27]
	v_pk_fma_f32 v[34:35], v[42:43], v[10:11], v[34:35]
	v_pk_fma_f32 v[10:11], v[38:39], v[10:11], v[26:27] neg_lo:[0,0,1] neg_hi:[0,0,1]
	v_lshlrev_b32_e32 v26, 16, v36
	v_and_b32_e32 v27, 0xffff0000, v36
	v_cvt_pk_bf16_f32 v82, v10, v11
	v_cvt_pk_bf16_f32 v78, v34, v35
	v_lshlrev_b32_e32 v10, 16, v32
	v_and_b32_e32 v11, 0xffff0000, v32
	v_pk_mul_f32 v[34:35], v[38:39], v[26:27]
	v_pk_mul_f32 v[26:27], v[42:43], v[26:27]
	v_pk_fma_f32 v[34:35], v[42:43], v[10:11], v[34:35]
	v_pk_fma_f32 v[10:11], v[38:39], v[10:11], v[26:27] neg_lo:[0,0,1] neg_hi:[0,0,1]
	v_lshlrev_b32_e32 v26, 16, v29
	v_pk_mul_f32 v[10:11], v[10:11], s[16:17] op_sel_hi:[1,0]
	v_and_b32_e32 v27, 0xffff0000, v29
	v_cvt_pk_bf16_f32 v46, v10, v11
	v_lshlrev_b32_e32 v10, 5, v2
	v_pk_mul_f32 v[28:29], v[40:41], v[26:27]
	v_pk_mul_f32 v[26:27], v[44:45], v[26:27]
	v_ashrrev_i32_e32 v11, 31, v10
	v_pk_fma_f32 v[28:29], v[44:45], v[24:25], v[28:29]
	v_pk_fma_f32 v[24:25], v[40:41], v[24:25], v[26:27] neg_lo:[0,0,1] neg_hi:[0,0,1]
	v_lshlrev_b32_e32 v26, 16, v37
	v_and_b32_e32 v27, 0xffff0000, v37
	v_lshlrev_b64 v[10:11], 2, v[10:11]
	v_or_b32_e32 v2, s34, v134
	v_cvt_pk_bf16_f32 v83, v24, v25
	v_cvt_pk_bf16_f32 v79, v28, v29
	v_lshlrev_b32_e32 v24, 16, v33
	v_and_b32_e32 v25, 0xffff0000, v33
	v_pk_mul_f32 v[28:29], v[40:41], v[26:27]
	v_pk_mul_f32 v[26:27], v[44:45], v[26:27]
	v_lshl_add_u64 v[38:39], v[4:5], 0, v[10:11]
	v_mad_i64_i32 v[4:5], s[38:39], v2, s72, v[8:9]
	v_pk_fma_f32 v[28:29], v[44:45], v[24:25], v[28:29]
	v_pk_fma_f32 v[24:25], v[40:41], v[24:25], v[26:27] neg_lo:[0,0,1] neg_hi:[0,0,1]
	v_lshl_add_u64 v[4:5], v[4:5], 0, s[40:41]
	v_pk_mul_f32 v[34:35], v[34:35], s[16:17] op_sel_hi:[1,0]
	v_pk_mul_f32 v[28:29], v[28:29], s[16:17] op_sel_hi:[1,0]
	v_pk_mul_f32 v[24:25], v[24:25], s[16:17] op_sel_hi:[1,0]
	v_lshl_add_u64 v[26:27], v[4:5], 0, v[20:21]
	v_cvt_pk_bf16_f32 v44, v48, v49
	v_cvt_pk_bf16_f32 v45, v22, v23
	v_cvt_pk_bf16_f32 v47, v24, v25
	v_cvt_pk_bf16_f32 v49, v30, v31
	v_cvt_pk_bf16_f32 v50, v34, v35
	v_cvt_pk_bf16_f32 v51, v28, v29
	v_lshl_add_u64 v[40:41], v[6:7], 0, v[10:11]
	v_mov_b64_e32 v[4:5], v[158:159]
	v_mov_b64_e32 v[6:7], v[160:161]
	v_mov_b64_e32 v[8:9], v[188:189]
	v_mov_b64_e32 v[10:11], v[190:191]
	v_mov_b64_e32 v[22:23], v[192:193]
	v_mov_b64_e32 v[24:25], v[194:195]
	s_nop 0
	v_mov_b64_e32 v[26:27], v[196:197]
	v_mov_b64_e32 v[28:29], v[198:199]
	s_nop 0
	global_load_dwordx4 v[30:33], v[38:39], off
	global_load_dwordx4 v[34:37], v[40:41], off
	global_load_dwordx4 v[174:177], v[38:39], off offset:16
	global_load_dwordx4 v[178:181], v[40:41], off offset:16
	v_cvt_pk_bf16_f32 v48, v52, v53
	v_sub_f32_e32 v2, v14, v18
	v_sub_f32_e32 v0, v0, v2
	v_add_f32_e32 v0, v16, v0
	v_add_f32_e32 v0, v0, v17
	v_add_f32_e32 v0, v12, v0
	v_cmp_nlt_f32_e64 s[38:39], 1.0, v102
	v_lshl_add_u64 v[12:13], s[20:21], 0, v[20:21]
	v_lshlrev_b32_e32 v2, 7, v133
	v_cndmask_b32_e64 v0, v205, v0, s[38:39]
	v_cmp_neq_f32_e64 s[38:39], 1.0, v102
	s_mov_b32 s20, 10
	s_waitcnt vmcnt(0) lgkmcnt(0)
; __device__ __forceinline__ void ld8bf(const bf16_t* p, float (&o)[8]) { unpack8(*(const u32x4*)p, o); }
; __device__ __forceinline__ bf16x8 pack_frag(const float (&v)[8]) { return __builtin_bit_cast(bf16x8, pack8(v)); }
; template <int KIND>
; __device__ __forceinline__ void w_m3_core(const bf16x8 (&Qf)[4][2], const bf16x8 (&Kf)[4][2], const bf16x8 (&Sf)[4][2], const LAS bf16_t* vT, float lg,
;                                           const bf16_t* gsrc, const float* nw, bf16_t* ydst, int lo, int fq) {
;     ...
;                     s = __builtin_amdgcn_mfma_f32_16x16x32_bf16(Kf[mb][0], Qf[nb][0], s, 0, 0, 0); s = __builtin_amdgcn_mfma_f32_16x16x32_bf16(Kf[mb][1], Qf[nb][1], s, 0, 0, 0);
; #pragma unroll
;                     for (int r = 0; r < 4; ++r) { const int m = 16 * mb + 4 * fq + r, n = 16 * nb + lo; float v = s[r];
;                         if (KIND == 0) v *= __expf((float)(n - m) * lg);
; __device__ __forceinline__ void w_ret_m3(const Args& a, int l, unsigned char* ws, const bf16_t* proj, bf16_t* y, LAS unsigned char* wl, int b, int ck_, int h, int lane) {
;     ...
;         for (int j = 0; j < 8; ++j) { o1[j] = x1[j] * cs[j] - x2[j] * sn[j]; o2[j] = x2[j] * cs[j] + x1[j] * sn[j]; }
;         Qf[tb][0] = pack_frag(o1); Qf[tb][1] = pack_frag(o2);
;         const bf16_t* ks = proj + (size_t)(row0 + n) * NIN + C_RK + 64 * h + 8 * fq;
;         ld8bf(ks, x1); ld8bf(ks + 32, x2);
; #pragma unroll
;         for (int j = 0; j < 8; ++j) { o1[j] = (x1[j] * cs[j] - x2[j] * sn[j]) * 0.125f; o2[j] = (x2[j] * cs[j] + x1[j] * sn[j]) * 0.125f; }
;         Kf[tb][0] = pack_frag(o1); Kf[tb][1] = pack_frag(o2);
;     }
;     const bf16_t* Sb = (const bf16_t*)((const unsigned char*)a.out + OUT_SBR) + (size_t)((b * NCH + ck_) * 4 + h) * 4096;
; #pragma unroll
;     for (int eb = 0; eb < 4; ++eb)
; #pragma unroll
;         for (int kk = 0; kk < 2; ++kk) Sf[eb][kk] = *(const bf16x8*)(Sb + (16 * eb + lo) * 64 + 32 * kk + 8 * fq);
	v_lshlrev_b32_e32 v42, 16, v4
	v_lshlrev_b32_e32 v52, 16, v8
	v_and_b32_e32 v53, 0xffff0000, v8
	v_and_b32_e32 v43, 0xffff0000, v4
	v_pk_mul_f32 v[54:55], v[30:31], v[52:53]
	v_pk_mul_f32 v[52:53], v[34:35], v[52:53]
	v_pk_fma_f32 v[54:55], v[34:35], v[42:43], v[54:55]
	v_pk_fma_f32 v[42:43], v[30:31], v[42:43], v[52:53] neg_lo:[0,0,1] neg_hi:[0,0,1]
	v_lshlrev_b32_e32 v52, 16, v26
	v_and_b32_e32 v53, 0xffff0000, v26
	v_cvt_pk_bf16_f32 v8, v42, v43
	v_cvt_pk_bf16_f32 v4, v54, v55
	v_lshlrev_b32_e32 v42, 16, v22
	v_and_b32_e32 v43, 0xffff0000, v22
	v_pk_mul_f32 v[54:55], v[30:31], v[52:53]
	v_lshlrev_b32_e32 v26, 16, v27
	v_pk_fma_f32 v[54:55], v[34:35], v[42:43], v[54:55]
	v_pk_mul_f32 v[34:35], v[34:35], v[52:53]
	v_and_b32_e32 v27, 0xffff0000, v27
	v_pk_fma_f32 v[30:31], v[30:31], v[42:43], v[34:35] neg_lo:[0,0,1] neg_hi:[0,0,1]
	v_lshlrev_b32_e32 v34, 16, v9
	v_and_b32_e32 v35, 0xffff0000, v9
	v_pk_mul_f32 v[42:43], v[30:31], s[16:17] op_sel_hi:[1,0]
	v_lshlrev_b32_e32 v30, 16, v5
	v_and_b32_e32 v31, 0xffff0000, v5
	v_pk_mul_f32 v[52:53], v[32:33], v[34:35]
	v_pk_mul_f32 v[34:35], v[36:37], v[34:35]
	v_pk_fma_f32 v[52:53], v[36:37], v[30:31], v[52:53]
	v_pk_fma_f32 v[30:31], v[32:33], v[30:31], v[34:35] neg_lo:[0,0,1] neg_hi:[0,0,1]
	v_lshlrev_b32_e32 v22, 16, v23
	v_cvt_pk_bf16_f32 v9, v30, v31
	v_and_b32_e32 v23, 0xffff0000, v23
	v_pk_mul_f32 v[30:31], v[32:33], v[26:27]
	v_pk_mul_f32 v[26:27], v[36:37], v[26:27]
	v_pk_fma_f32 v[30:31], v[36:37], v[22:23], v[30:31]
	v_pk_fma_f32 v[22:23], v[32:33], v[22:23], v[26:27] neg_lo:[0,0,1] neg_hi:[0,0,1]
	v_pk_mul_f32 v[58:59], v[30:31], s[16:17] op_sel_hi:[1,0]
	v_mov_b64_e32 v[30:31], v[174:175]
	v_mov_b64_e32 v[32:33], v[176:177]
	v_mov_b64_e32 v[34:35], v[178:179]
	v_mov_b64_e32 v[36:37], v[180:181]
	v_lshlrev_b32_e32 v38, 16, v10
	v_and_b32_e32 v39, 0xffff0000, v10
	v_lshlrev_b32_e32 v26, 16, v6
	v_and_b32_e32 v27, 0xffff0000, v6
	v_cndmask_b32_e64 v0, v206, v0, s[38:39]
	v_pk_mul_f32 v[56:57], v[54:55], s[16:17] op_sel_hi:[1,0]
	v_pk_mul_f32 v[22:23], v[22:23], s[16:17] op_sel_hi:[1,0]
	v_cvt_pk_bf16_f32 v5, v52, v53
	v_cvt_pk_bf16_f32 v52, v42, v43
	v_cvt_pk_bf16_f32 v53, v22, v23
	v_cvt_pk_bf16_f32 v56, v56, v57
	v_cvt_pk_bf16_f32 v57, v58, v59
	v_cndmask_b32_e64 v135, v0, -v102, vcc
	v_bfe_u32 v0, v101, 2, 2
	v_or_b32_e32 v105, v124, v0
	v_or_b32_e32 v106, v140, v0
	v_lshlrev_b32_e32 v0, 6, v100
	v_mfma_f32_16x16x32_bf16 v[100:103], v[64:67], v[96:99], 0
	v_cmp_lt_i32_e32 vcc, v133, v124
	v_mul_f32_e32 v1, v135, v1
	v_mul_f32_e32 v1, 0x3fb8aa3b, v1
	v_mfma_f32_16x16x32_bf16 v[100:103], v[72:75], v[92:95], v[100:103]
	v_exp_f32_e32 v1, v1
	s_waitcnt vmcnt(0) lgkmcnt(0)
	v_pk_mul_f32 v[40:41], v[30:31], v[38:39]
	v_pk_mul_f32 v[38:39], v[34:35], v[38:39]
	v_pk_fma_f32 v[40:41], v[34:35], v[26:27], v[40:41]
	v_pk_fma_f32 v[26:27], v[30:31], v[26:27], v[38:39] neg_lo:[0,0,1] neg_hi:[0,0,1]
	v_lshlrev_b32_e32 v38, 16, v28
	v_and_b32_e32 v39, 0xffff0000, v28
	v_cvt_pk_bf16_f32 v10, v26, v27
	v_cvt_pk_bf16_f32 v6, v40, v41
	v_lshlrev_b32_e32 v26, 16, v24
	v_and_b32_e32 v27, 0xffff0000, v24
	v_pk_mul_f32 v[40:41], v[30:31], v[38:39]
	v_lshlrev_b32_e32 v28, 16, v29
	v_pk_fma_f32 v[40:41], v[34:35], v[26:27], v[40:41]
	v_pk_mul_f32 v[34:35], v[34:35], v[38:39]
	v_and_b32_e32 v29, 0xffff0000, v29
	v_pk_fma_f32 v[26:27], v[30:31], v[26:27], v[34:35] neg_lo:[0,0,1] neg_hi:[0,0,1]
	v_lshlrev_b32_e32 v34, 16, v11
	v_and_b32_e32 v35, 0xffff0000, v11
	v_lshlrev_b32_e32 v30, 16, v7
	v_and_b32_e32 v31, 0xffff0000, v7
	v_pk_mul_f32 v[38:39], v[32:33], v[34:35]
	v_pk_mul_f32 v[34:35], v[36:37], v[34:35]
	v_pk_fma_f32 v[38:39], v[36:37], v[30:31], v[38:39]
	v_pk_fma_f32 v[30:31], v[32:33], v[30:31], v[34:35] neg_lo:[0,0,1] neg_hi:[0,0,1]
	v_lshlrev_b32_e32 v24, 16, v25
	v_cvt_pk_bf16_f32 v11, v30, v31
	v_and_b32_e32 v25, 0xffff0000, v25
	v_pk_mul_f32 v[30:31], v[32:33], v[28:29]
	v_pk_mul_f32 v[28:29], v[36:37], v[28:29]
	v_pk_fma_f32 v[30:31], v[36:37], v[24:25], v[30:31]
	v_pk_fma_f32 v[24:25], v[32:33], v[24:25], v[28:29] neg_lo:[0,0,1] neg_hi:[0,0,1]
	v_lshl_add_u64 v[28:29], v[12:13], 0, v[2:3]
	v_add_co_u32_e64 v32, s[38:39], s73, v28
	v_pk_mul_f32 v[40:41], v[40:41], s[16:17] op_sel_hi:[1,0]
	v_pk_mul_f32 v[26:27], v[26:27], s[16:17] op_sel_hi:[1,0]
	v_pk_mul_f32 v[30:31], v[30:31], s[16:17] op_sel_hi:[1,0]
	v_pk_mul_f32 v[24:25], v[24:25], s[16:17] op_sel_hi:[1,0]
	v_addc_co_u32_e64 v33, s[38:39], 0, v29, s[38:39]
	v_cvt_pk_bf16_f32 v7, v38, v39
	v_cvt_pk_bf16_f32 v54, v26, v27
	v_cvt_pk_bf16_f32 v55, v24, v25
	v_cvt_pk_bf16_f32 v58, v40, v41
	v_cvt_pk_bf16_f32 v59, v30, v31
	global_load_dwordx4 v[20:23], v[28:29], off
	global_load_dwordx4 v[12:15], v[28:29], off offset:64
	global_load_dwordx4 v[24:27], v[28:29], off offset:2048
	global_load_dwordx4 v[16:19], v[28:29], off offset:2112
	global_load_dwordx4 v[36:39], v[32:33], off
	s_nop 0
	global_load_dwordx4 v[28:31], v[32:33], off offset:64
	global_load_dwordx4 v[40:43], v[32:33], off offset:2048
	s_nop 0
	global_load_dwordx4 v[32:35], v[32:33], off offset:2112
	v_lshlrev_b32_e32 v2, 2, v133
	v_bitop3_b32 v138, v0, 64, v2 bitop3:0x36
	v_bitop3_b32 v137, v0, s96, v2 bitop3:0x36
	v_sub_u32_e32 v0, v133, v124
	v_cvt_f32_i32_e32 v0, v0
	s_waitcnt lgkmcnt(0)
	s_ashr_i32 s21, s20, 31
	v_mul_f32_e32 v0, v135, v0
	v_mul_f32_e32 v0, 0x3fb8aa3b, v0
	v_exp_f32_e32 v139, v0
	s_lshl_b64 s[20:21], s[20:21], 3
	s_add_u32 s20, s0, s20
	s_addc_u32 s21, s1, s21
	v_mul_f32_e32 v0, v139, v100
	v_cndmask_b32_e64 v2, v0, 0, vcc
	v_add_u32_e32 v0, v133, v143
	v_cvt_f32_i32_e32 v0, v0
	s_load_dwordx2 s[20:21], s[20:21], 0x0
	s_lshl_b64 s[38:39], s[36:37], 2
	s_waitcnt vmcnt(7)
; __device__ __forceinline__ float bperm_f(int src_lane, float v) { return __builtin_bit_cast(float, __builtin_amdgcn_ds_bpermute(src_lane << 2, __builtin_bit_cast(int, v))); }
; template <int KIND>
; __device__ __forceinline__ void w_m3_core(const bf16x8 (&Qf)[4][2], const bf16x8 (&Kf)[4][2], const bf16x8 (&Sf)[4][2], const LAS bf16_t* vT, float lg,
;                                           const bf16_t* gsrc, const float* nw, bf16_t* ydst, int lo, int fq) {
;     ...
;             float pv[8];
; #pragma unroll
;             for (int hh = 0; hh < 2; ++hh) { const int mb = 2 * kk2 + hh;
;                 if (mb <= nb) { f32x4 s = {0.f, 0.f, 0.f, 0.f};
;                     s = __builtin_amdgcn_mfma_f32_16x16x32_bf16(Kf[mb][0], Qf[nb][0], s, 0, 0, 0); s = __builtin_amdgcn_mfma_f32_16x16x32_bf16(Kf[mb][1], Qf[nb][1], s, 0, 0, 0);
; #pragma unroll
;                     for (int r = 0; r < 4; ++r) { const int m = 16 * mb + 4 * fq + r, n = 16 * nb + lo; float v = s[r];
;                         if (KIND == 0) v *= __expf((float)(n - m) * lg);
;                         if (mb == nb) v = (m <= n) ? v : 0.f;
;                         pv[4 * hh + r] = v; }
;                 } else {
; #pragma unroll
;                     for (int r = 0; r < 4; ++r) pv[4 * hh + r] = 0.f; }
;             }
;             const bf16x8 Pf = pack_frag(pv);
; #pragma unroll
;             for (int eb = 0; eb < 4; ++eb)
;                 O[eb] = __builtin_amdgcn_mfma_f32_16x16x32_bf16(tr_frag(vT, 32 * kk2 + 4 * fq, 32 * kk2 + 16 + 4 * fq, 16 * eb, lo), Pf, O[eb], 0, 0, 0);
;         }
; #pragma unroll
;         for (int kk = 0; kk < 2; ++kk)
; #pragma unroll
;             for (int eb = 0; eb < 4; ++eb) O2[eb] = __builtin_amdgcn_mfma_f32_16x16x32_bf16(Sf[eb][kk], Qf[nb][kk], O2[eb], 0, 0, 0);
;         const float osc = KIND == 0 ? __expf((float)(16 * nb + lo + 1) * lg) : 1.0f;
; #pragma unroll
;         for (int eb = 0; eb < 4; ++eb) O[eb] = O[eb] + O2[eb] * osc;
;         float ss = 0.f;
; #pragma unroll
;         for (int eb = 0; eb < 4; ++eb) ss += (O[eb][0] * O[eb][0] + O[eb][1] * O[eb][1]) + (O[eb][2] * O[eb][2] + O[eb][3] * O[eb][3]);
;         { const int ln = (fq << 4) | lo; ss += bperm_f(ln ^ 16, ss); ss += bperm_f(ln ^ 32, ss); }
;         const float rs = rsqrtf(ss * (1.0f / 64.0f) + EPS);
	v_mfma_f32_16x16x32_bf16 v[116:119], v[20:23], v[96:99], 0
	v_mul_f32_e32 v0, v135, v0
	v_mul_f32_e32 v0, 0x3fb8aa3b, v0
	v_exp_f32_e32 v0, v0
	s_waitcnt lgkmcnt(0)
	s_add_u32 s27, s20, s38
	s_addc_u32 s38, s21, s39
	s_lshl_b64 s[20:21], s[24:25], 2
	s_add_u32 s44, s27, s20
	s_addc_u32 s45, s38, s21
	v_lshl_add_u64 v[182:183], v[124:125], 2, s[44:45]
	global_load_dwordx4 v[184:187], v[182:183], off
	global_load_dwordx4 v[188:191], v[182:183], off offset:64
	global_load_dwordx4 v[192:195], v[182:183], off offset:128
	global_load_dwordx4 v[196:199], v[182:183], off offset:192
	v_mul_f32_e32 v0, v0, v101
	v_cmp_gt_i32_e64 s[38:39], v133, v124
	s_lshl_b64 s[20:21], s[34:35], 11
	s_add_u32 s20, s10, s20
	v_cndmask_b32_e64 v107, 0, v0, s[38:39]
	v_sub_u32_e32 v0, v133, v142
	v_cvt_f32_i32_e32 v0, v0
	s_addc_u32 s21, s11, s21
	s_add_u32 s40, s20, s40
	s_addc_u32 s41, s21, 0
	v_mul_f32_e32 v0, v135, v0
	v_mul_f32_e32 v0, 0x3fb8aa3b, v0
	v_exp_f32_e32 v0, v0
	v_mad_u64_u32 v[126:127], s[20:21], v106, s23, v[104:105]
	v_mad_u64_u32 v[128:129], s[20:21], v105, s23, v[104:105]
	v_pk_mul_f32 v[100:101], v[0:1], v[102:103]
	v_cmp_ge_i32_e64 s[38:39], v133, v142
	v_cvt_pk_bf16_f32 v1, v100, v101
	ds_read_b64_tr_b16 v[102:103], v126
	ds_read_b64_tr_b16 v[110:111], v126 offset:32
	ds_read_b64_tr_b16 v[100:101], v128
	ds_read_b64_tr_b16 v[108:109], v128 offset:32
	v_cvt_pk_bf16_f32 v0, v2, v107
	v_cndmask_b32_e64 v2, 0, v1, s[38:39]
	v_lshrrev_b32_e32 v1, 16, v1
	v_cmp_ge_i32_e64 s[38:39], v133, v141
	s_waitcnt vmcnt(9)
	v_mfma_f32_16x16x32_bf16 v[146:149], v[24:27], v[96:99], 0
	v_cndmask_b32_e64 v1, 0, v1, s[38:39]
	v_perm_b32 v1, v1, v2, s53
	v_mov_b32_e32 v2, v3
	s_waitcnt vmcnt(7)
	v_mfma_f32_16x16x32_bf16 v[150:153], v[36:39], v[96:99], 0
	s_waitcnt lgkmcnt(1)
	v_mfma_f32_16x16x32_bf16 v[104:107], v[100:103], v[0:3], 0
	s_waitcnt lgkmcnt(0)
	v_mfma_f32_16x16x32_bf16 v[100:103], v[108:111], v[0:3], 0
	ds_read_b64_tr_b16 v[108:109], v128 offset:64
	ds_read_b64_tr_b16 v[110:111], v126 offset:64
	ds_read_b64_tr_b16 v[112:113], v128 offset:96
	ds_read_b64_tr_b16 v[114:115], v126 offset:96
	s_waitcnt lgkmcnt(2)
	v_mfma_f32_16x16x32_bf16 v[108:111], v[108:111], v[0:3], 0
	s_waitcnt lgkmcnt(0)
	v_mfma_f32_16x16x32_bf16 v[112:115], v[112:115], v[0:3], 0
	v_add_u32_e32 v0, 1, v133
	v_cvt_f32_ubyte0_e32 v0, v0
	v_mul_f32_e32 v0, v135, v0
	s_waitcnt vmcnt(5)
	v_mfma_f32_16x16x32_bf16 v[154:157], v[40:43], v[96:99], 0
	v_mul_f32_e32 v0, 0x3fb8aa3b, v0
	v_exp_f32_e32 v2, v0
	v_mfma_f32_16x16x32_bf16 v[120:123], v[12:15], v[92:95], v[116:119]
	v_mfma_f32_16x16x32_bf16 v[116:119], v[16:19], v[92:95], v[146:149]
	v_mfma_f32_16x16x32_bf16 v[96:99], v[28:31], v[92:95], v[150:153]
	s_nop 5
	v_fma_f32 v122, v2, v122, v106
	v_fma_f32 v123, v2, v123, v107
	v_pk_fma_f32 v[120:121], v[2:3], v[120:121], v[104:105] op_sel_hi:[0,1,1]
	v_pk_fma_f32 v[118:119], v[2:3], v[118:119], v[102:103] op_sel_hi:[0,1,1]
	s_waitcnt vmcnt(4)
	v_mfma_f32_16x16x32_bf16 v[92:95], v[32:35], v[92:95], v[154:157]
	v_fma_f32 v116, v2, v116, v100
	v_fma_f32 v117, v2, v117, v101
	v_pk_fma_f32 v[108:109], v[2:3], v[96:97], v[108:109] op_sel_hi:[0,1,1]
	v_pk_fma_f32 v[106:107], v[2:3], v[98:99], v[110:111] op_sel_hi:[0,1,1]
	v_lshl_add_u64 v[100:101], v[124:125], 2, s[44:45]
	s_nop 2
	v_pk_fma_f32 v[0:1], v[2:3], v[94:95], v[114:115] op_sel_hi:[0,1,1]
	v_pk_fma_f32 v[104:105], v[2:3], v[92:93], v[112:113] op_sel_hi:[0,1,1]
	v_pk_mul_f32 v[92:93], v[122:123], v[122:123]
	v_pk_mul_f32 v[94:95], v[120:121], v[120:121]
	v_mul_f32_e32 v2, v104, v104
	v_pk_mov_b32 v[96:97], v[94:95], v[92:93] op_sel:[1,0]
	v_mov_b32_e32 v95, v93
	v_pk_add_f32 v[92:93], v[96:97], v[94:95]
	v_pk_mul_f32 v[94:95], v[118:119], v[118:119]
	v_pk_mul_f32 v[96:97], v[116:117], v[116:117]
	v_pk_add_f32 v[92:93], v[92:93], v[92:93] op_sel:[0,1] op_sel_hi:[1,0]
	v_pk_mov_b32 v[98:99], v[96:97], v[94:95] op_sel:[1,0]
	v_mov_b32_e32 v97, v95
	v_pk_add_f32 v[94:95], v[98:99], v[96:97]
	v_mul_f32_e32 v96, v105, v105
	v_pk_add_f32 v[94:95], v[94:95], v[94:95] op_sel:[0,1] op_sel_hi:[1,0]
	v_mov_b32_e32 v93, v2
	v_mov_b32_e32 v95, v96
	v_mul_f32_e32 v2, v109, v109
	v_mul_f32_e32 v97, v0, v0
	v_pk_add_f32 v[92:93], v[92:93], v[94:95]
	v_pk_fma_f32 v[94:95], v[108:109], v[108:109], v[2:3] op_sel_hi:[1,1,0]
	v_mul_f32_e32 v2, v107, v107
	v_mul_f32_e32 v98, v1, v1
	v_mov_b32_e32 v95, v97
	v_pk_fma_f32 v[96:97], v[106:107], v[106:107], v[2:3] op_sel_hi:[1,1,0]
	s_nop 0
	v_mov_b32_e32 v97, v98
	v_pk_add_f32 v[94:95], v[94:95], v[96:97]
	v_mov_b64_e32 v[98:99], s[42:43]
	v_pk_add_f32 v[92:93], v[92:93], v[94:95]
	v_lshlrev_b64 v[96:97], 1, v[124:125]
	v_add_f32_e32 v2, v92, v93
	ds_bpermute_b32 v92, v138, v2
	s_waitcnt lgkmcnt(0)
	v_add_f32_e32 v2, v2, v92
	ds_bpermute_b32 v92, v137, v2
	s_waitcnt lgkmcnt(0)
	v_add_f32_e32 v2, v2, v92
	v_fmamk_f32 v2, v2, 0x3c800000, v200
	v_cmp_gt_f32_e64 s[38:39], s29, v2
	v_mul_f32_e32 v92, 0x4b800000, v2
	s_nop 0
	v_cndmask_b32_e64 v2, v2, v92, s[38:39]
	v_rsq_f32_e32 v2, v2
	s_nop 0
	v_mul_f32_e32 v92, 0x45800000, v2
	v_cndmask_b32_e64 v102, v2, v92, s[38:39]
	v_mad_u64_u32 v[92:93], s[20:21], v133, s72, v[98:99]
	v_lshl_add_u64 v[110:111], v[92:93], 0, v[96:97]
	s_waitcnt vmcnt(0)
; __device__ __forceinline__ unsigned pk2(float lo, float hi) { const f32x2_t v = {lo, hi}; const bf16x2_t b = __builtin_convertvector(v, bf16x2_t); return __builtin_bit_cast(unsigned, b); }
; __device__ __forceinline__ float sigmoidf_(float x) { return __builtin_amdgcn_rcpf(1.0f + __expf(-x)); }
; template <int KIND>
; __device__ __forceinline__ void w_m3_core(const bf16x8 (&Qf)[4][2], const bf16x8 (&Kf)[4][2], const bf16x8 (&Sf)[4][2], const LAS bf16_t* vT, float lg,
;                                           const bf16_t* gsrc, const float* nw, bf16_t* ydst, int lo, int fq) {
;     ...
;         const size_t n = 16 * nb + lo;
; #pragma unroll
;         for (int eb = 0; eb < 4; ++eb) { const int e0 = 16 * eb + 4 * fq;
;             const unsigned long long gw_ = *(const unsigned long long*)(gsrc + n * NIN + e0); const f32x4 w4 = *(const f32x4*)(nw + e0);
;             const float g0 = __uint_as_float((unsigned)gw_ << 16), g1 = __uint_as_float((unsigned)gw_ & 0xffff0000u), g2 = __uint_as_float((unsigned)(gw_ >> 32) << 16), g3 = __uint_as_float((unsigned)(gw_ >> 32) & 0xffff0000u);
;             const float o0 = O[eb][0] * rs * w4[0] * (g0 * sigmoidf_(g0)), o1 = O[eb][1] * rs * w4[1] * (g1 * sigmoidf_(g1));
;             const float o2 = O[eb][2] * rs * w4[2] * (g2 * sigmoidf_(g2)), o3 = O[eb][3] * rs * w4[3] * (g3 * sigmoidf_(g3));
;             *(unsigned long long*)(ydst + n * DM + e0) = (unsigned long long)pk2(o0, o1) | ((unsigned long long)pk2(o2, o3) << 32); }
	v_permlane16_swap_b32_e32 v222, v224
	v_permlane16_swap_b32_e32 v223, v225
	v_permlane16_swap_b32_e32 v226, v228
	v_permlane16_swap_b32_e32 v227, v229
	v_permlane16_swap_b32_e32 v230, v232
	v_permlane16_swap_b32_e32 v231, v233
	v_permlane16_swap_b32_e32 v234, v236
	v_permlane16_swap_b32_e32 v235, v237
	v_permlane16_swap_b32_e32 v238, v240
	v_permlane16_swap_b32_e32 v239, v241
	v_permlane16_swap_b32_e32 v242, v244
	v_permlane16_swap_b32_e32 v243, v245
	v_permlane16_swap_b32_e32 v246, v248
	v_permlane16_swap_b32_e32 v247, v249
	v_permlane16_swap_b32_e32 v250, v252
	v_permlane16_swap_b32_e32 v251, v253
	v_mov_b64_e32 v[114:115], v[222:223]
	v_mov_b64_e32 v[92:93], v[184:185]
	v_mov_b64_e32 v[94:95], v[186:187]
	v_lshlrev_b32_e32 v2, 11, v133
	v_lshl_add_u64 v[112:113], s[40:41], 0, v[2:3]
	v_pk_mul_f32 v[120:121], v[120:121], v[102:103] op_sel_hi:[1,0]
	v_pk_mul_f32 v[122:123], v[122:123], v[102:103] op_sel_hi:[1,0]
	v_lshl_add_u64 v[112:113], v[112:113], 0, v[96:97]
	v_pk_mul_f32 v[116:117], v[116:117], v[102:103] op_sel_hi:[1,0]
	v_pk_mul_f32 v[118:119], v[118:119], v[102:103] op_sel_hi:[1,0]
	v_pk_mul_f32 v[108:109], v[108:109], v[102:103] op_sel_hi:[1,0]
	s_waitcnt lgkmcnt(0)
	v_lshlrev_b32_e32 v130, 16, v114
	v_mul_f32_e32 v2, 0xbfb8aa3b, v130
	v_exp_f32_e32 v2, v2
	v_and_b32_e32 v131, 0xffff0000, v114
	v_lshlrev_b32_e32 v114, 16, v115
	v_and_b32_e32 v115, 0xffff0000, v115
	v_add_f32_e32 v2, 1.0, v2
	v_rcp_f32_e32 v146, v2
	v_mul_f32_e32 v2, 0xbfb8aa3b, v131
	v_exp_f32_e32 v2, v2
	v_pk_mul_f32 v[92:93], v[92:93], v[120:121]
	v_pk_mul_f32 v[94:95], v[94:95], v[122:123]
	v_add_f32_e32 v2, 1.0, v2
	v_rcp_f32_e32 v147, v2
	v_mul_f32_e32 v2, 0xbfb8aa3b, v114
	v_exp_f32_e32 v2, v2
	v_pk_mul_f32 v[120:121], v[146:147], v[130:131]
	s_nop 0
	v_pk_mul_f32 v[92:93], v[120:121], v[92:93]
	v_add_f32_e32 v2, 1.0, v2
	v_rcp_f32_e32 v120, v2
	v_mul_f32_e32 v2, 0xbfb8aa3b, v115
	v_exp_f32_e32 v2, v2
	v_cvt_pk_bf16_f32 v92, v92, v93
	v_add_f32_e32 v2, 1.0, v2
	v_rcp_f32_e32 v121, v2
	s_nop 0
	v_pk_mul_f32 v[114:115], v[120:121], v[114:115]
	s_nop 0
	v_pk_mul_f32 v[94:95], v[114:115], v[94:95]
	s_nop 0
	v_cvt_pk_bf16_f32 v93, v94, v95
	global_store_dwordx2 v[112:113], v[92:93], off offset:1024
	v_mov_b64_e32 v[114:115], v[224:225]
	s_nop 0
	v_mov_b64_e32 v[92:93], v[188:189]
	v_mov_b64_e32 v[94:95], v[190:191]
	s_waitcnt lgkmcnt(0)
	v_lshlrev_b32_e32 v120, 16, v114
	v_mul_f32_e32 v2, 0xbfb8aa3b, v120
	v_exp_f32_e32 v2, v2
	v_and_b32_e32 v121, 0xffff0000, v114
	v_lshlrev_b32_e32 v114, 16, v115
	v_and_b32_e32 v115, 0xffff0000, v115
	v_add_f32_e32 v2, 1.0, v2
	v_rcp_f32_e32 v122, v2
	v_mul_f32_e32 v2, 0xbfb8aa3b, v121
	v_exp_f32_e32 v2, v2
	v_pk_mul_f32 v[92:93], v[92:93], v[116:117]
	v_pk_mul_f32 v[94:95], v[94:95], v[118:119]
	v_add_f32_e32 v2, 1.0, v2
	v_rcp_f32_e32 v123, v2
	v_mul_f32_e32 v2, 0xbfb8aa3b, v114
	v_exp_f32_e32 v2, v2
	v_pk_mul_f32 v[116:117], v[122:123], v[120:121]
	s_nop 0
	v_pk_mul_f32 v[92:93], v[116:117], v[92:93]
	v_add_f32_e32 v2, 1.0, v2
	v_rcp_f32_e32 v116, v2
	v_mul_f32_e32 v2, 0xbfb8aa3b, v115
	v_exp_f32_e32 v2, v2
	v_cvt_pk_bf16_f32 v92, v92, v93
	v_add_f32_e32 v2, 1.0, v2
	v_rcp_f32_e32 v117, v2
	s_nop 0
	v_pk_mul_f32 v[114:115], v[116:117], v[114:115]
	s_nop 0
	v_pk_mul_f32 v[94:95], v[114:115], v[94:95]
	v_mul_f32_e32 v116, v106, v102
	v_cvt_pk_bf16_f32 v93, v94, v95
	global_store_dwordx2 v[112:113], v[92:93], off offset:1056
	v_mov_b64_e32 v[114:115], v[226:227]
	s_nop 0
	v_mov_b64_e32 v[92:93], v[192:193]
	v_mov_b64_e32 v[94:95], v[194:195]
	s_waitcnt lgkmcnt(0)
	v_lshlrev_b32_e32 v118, 16, v114
	v_mul_f32_e32 v2, 0xbfb8aa3b, v118
	v_exp_f32_e32 v2, v2
	v_and_b32_e32 v119, 0xffff0000, v114
	v_lshlrev_b32_e32 v117, 16, v115
	v_and_b32_e32 v115, 0xffff0000, v115
	v_add_f32_e32 v2, 1.0, v2
	v_rcp_f32_e32 v120, v2
	v_mul_f32_e32 v2, 0xbfb8aa3b, v119
	v_exp_f32_e32 v2, v2
	v_pk_mul_f32 v[92:93], v[92:93], v[108:109]
	v_mul_f32_e32 v114, v107, v102
	v_mov_b32_e32 v106, v95
	v_add_f32_e32 v2, 1.0, v2
	v_rcp_f32_e32 v121, v2
	v_mul_f32_e32 v2, 0xbfb8aa3b, v117
	v_exp_f32_e32 v2, v2
	v_pk_mul_f32 v[108:109], v[120:121], v[118:119]
	s_nop 0
	v_pk_mul_f32 v[92:93], v[108:109], v[92:93]
	v_add_f32_e32 v2, 1.0, v2
	v_rcp_f32_e32 v109, v2
	v_mul_f32_e32 v2, 0xbfb8aa3b, v115
	v_exp_f32_e32 v2, v2
	v_mov_b32_e32 v108, v94
	v_pk_mul_f32 v[108:109], v[108:109], v[116:117]
	v_cvt_pk_bf16_f32 v92, v92, v93
	v_add_f32_e32 v2, 1.0, v2
	v_rcp_f32_e32 v107, v2
	s_nop 0
	v_pk_mul_f32 v[94:95], v[106:107], v[114:115]
	v_mov_b32_e32 v106, v108
	v_mov_b32_e32 v107, v94
	v_mov_b32_e32 v94, v109
	v_pk_mul_f32 v[94:95], v[106:107], v[94:95]
	v_mul_f32_e32 v106, v0, v102
	v_cvt_pk_bf16_f32 v93, v94, v95
	global_store_dwordx2 v[112:113], v[92:93], off offset:1088
	v_mov_b64_e32 v[114:115], v[228:229]
	s_nop 0
	v_mov_b64_e32 v[92:93], v[196:197]
	v_mov_b64_e32 v[94:95], v[198:199]
	v_mul_f32_e32 v108, v105, v102
	v_mul_f32_e32 v110, v104, v102
	v_mul_f32_e32 v102, v1, v102
	s_waitcnt lgkmcnt(0)
; __device__ __forceinline__ float bperm_f(int src_lane, float v) { return __builtin_bit_cast(float, __builtin_amdgcn_ds_bpermute(src_lane << 2, __builtin_bit_cast(int, v))); }
; __device__ __forceinline__ bf16x8 pack_frag(const float (&v)[8]) { return __builtin_bit_cast(bf16x8, pack8(v)); }
; template <int KIND>
; __device__ __forceinline__ void w_m3_core(const bf16x8 (&Qf)[4][2], const bf16x8 (&Kf)[4][2], const bf16x8 (&Sf)[4][2], const LAS bf16_t* vT, float lg,
;                                           const bf16_t* gsrc, const float* nw, bf16_t* ydst, int lo, int fq) {
;     ...
;             for (int hh = 0; hh < 2; ++hh) { const int mb = 2 * kk2 + hh;
;                 if (mb <= nb) { f32x4 s = {0.f, 0.f, 0.f, 0.f};
;                     s = __builtin_amdgcn_mfma_f32_16x16x32_bf16(Kf[mb][0], Qf[nb][0], s, 0, 0, 0); s = __builtin_amdgcn_mfma_f32_16x16x32_bf16(Kf[mb][1], Qf[nb][1], s, 0, 0, 0);
; #pragma unroll
;                     for (int r = 0; r < 4; ++r) { const int m = 16 * mb + 4 * fq + r, n = 16 * nb + lo; float v = s[r];
;                         if (KIND == 0) v *= __expf((float)(n - m) * lg);
;                         if (mb == nb) v = (m <= n) ? v : 0.f;
;                         pv[4 * hh + r] = v; }
;                 } else {
; #pragma unroll
;                     for (int r = 0; r < 4; ++r) pv[4 * hh + r] = 0.f; }
;             }
;             const bf16x8 Pf = pack_frag(pv);
; #pragma unroll
;             for (int eb = 0; eb < 4; ++eb)
;                 O[eb] = __builtin_amdgcn_mfma_f32_16x16x32_bf16(tr_frag(vT, 32 * kk2 + 4 * fq, 32 * kk2 + 16 + 4 * fq, 16 * eb, lo), Pf, O[eb], 0, 0, 0);
;         }
; #pragma unroll
;         for (int kk = 0; kk < 2; ++kk)
; #pragma unroll
;             for (int eb = 0; eb < 4; ++eb) O2[eb] = __builtin_amdgcn_mfma_f32_16x16x32_bf16(Sf[eb][kk], Qf[nb][kk], O2[eb], 0, 0, 0);
;         const float osc = KIND == 0 ? __expf((float)(16 * nb + lo + 1) * lg) : 1.0f;
; #pragma unroll
;         for (int eb = 0; eb < 4; ++eb) O[eb] = O[eb] + O2[eb] * osc;
;         float ss = 0.f;
; #pragma unroll
;         for (int eb = 0; eb < 4; ++eb) ss += (O[eb][0] * O[eb][0] + O[eb][1] * O[eb][1]) + (O[eb][2] * O[eb][2] + O[eb][3] * O[eb][3]);
;         { const int ln = (fq << 4) | lo; ss += bperm_f(ln ^ 16, ss); ss += bperm_f(ln ^ 32, ss); }
	v_lshlrev_b32_e32 v111, 16, v114
	v_mul_f32_e32 v2, 0xbfb8aa3b, v111
	v_exp_f32_e32 v2, v2
	v_and_b32_e32 v109, 0xffff0000, v114
	v_lshlrev_b32_e32 v107, 16, v115
	v_and_b32_e32 v103, 0xffff0000, v115
	v_add_f32_e32 v2, 1.0, v2
	v_rcp_f32_e32 v115, v2
	v_mul_f32_e32 v2, 0xbfb8aa3b, v109
	v_exp_f32_e32 v2, v2
	v_mul_f32_e32 v0, 0xbfb8aa3b, v107
	v_exp_f32_e32 v0, v0
	v_mov_b32_e32 v104, v93
	v_add_f32_e32 v2, 1.0, v2
	v_rcp_f32_e32 v105, v2
	v_add_f32_e32 v0, 1.0, v0
	v_mov_b32_e32 v114, v92
	v_pk_mul_f32 v[110:111], v[114:115], v[110:111]
	v_pk_mul_f32 v[92:93], v[104:105], v[108:109]
	v_rcp_f32_e32 v105, v0
	v_mul_f32_e32 v0, 0xbfb8aa3b, v103
	v_exp_f32_e32 v0, v0
	v_mov_b32_e32 v104, v94
	v_pk_mul_f32 v[104:105], v[104:105], v[106:107]
	v_mov_b32_e32 v94, v110
	v_add_f32_e32 v0, 1.0, v0
	v_rcp_f32_e32 v1, v0
	v_mov_b32_e32 v0, v95
	v_mov_b32_e32 v95, v92
	v_mov_b32_e32 v92, v111
	v_pk_mul_f32 v[0:1], v[0:1], v[102:103]
	v_pk_mul_f32 v[92:93], v[94:95], v[92:93]
	v_mov_b32_e32 v94, v104
	v_mov_b32_e32 v95, v0
	v_mov_b32_e32 v0, v105
	v_pk_mul_f32 v[0:1], v[94:95], v[0:1]
	v_cvt_pk_bf16_f32 v92, v92, v93
	v_cvt_pk_bf16_f32 v93, v0, v1
	global_store_dwordx2 v[112:113], v[92:93], off offset:1120
	v_sub_u32_e32 v0, v144, v124
	v_add_u32_e32 v1, v144, v143
	v_cvt_f32_i32_e32 v0, v0
	v_cvt_f32_i32_e32 v1, v1
	v_mfma_f32_16x16x32_bf16 v[92:95], v[64:67], v[88:91], 0
	v_sub_u32_e32 v2, v144, v142
	v_mul_f32_e32 v0, v135, v0
	v_mul_f32_e32 v1, v135, v1
	v_cvt_f32_i32_e32 v2, v2
	v_mul_f32_e32 v0, 0x3fb8aa3b, v0
	v_mul_f32_e32 v1, 0x3fb8aa3b, v1
	v_mfma_f32_16x16x32_bf16 v[92:95], v[72:75], v[84:87], v[92:95]
	v_exp_f32_e32 v0, v0
	v_exp_f32_e32 v1, v1
	v_mul_f32_e32 v2, v135, v2
	v_mul_f32_e32 v2, 0x3fb8aa3b, v2
	v_add_u32_e32 v115, 17, v124
	s_nop 2
	v_pk_mul_f32 v[0:1], v[0:1], v[92:93]
	v_exp_f32_e32 v92, v2
	v_sub_u32_e32 v2, v144, v141
	v_cvt_f32_i32_e32 v2, v2
	v_cmp_ge_i32_e64 s[38:39], v144, v115
	v_add_u32_e32 v114, 19, v124
	v_add_u32_e32 v116, 18, v124
	v_mul_f32_e32 v2, v135, v2
	v_mul_f32_e32 v2, 0x3fb8aa3b, v2
	v_exp_f32_e32 v93, v2
	v_mfma_f32_16x16x32_bf16 v[110:113], v[36:39], v[88:91], 0
	v_mul_f32_e64 v102, v92, v94
	v_mul_f32_e64 v103, v93, v95
	v_mfma_f32_16x16x32_bf16 v[92:95], v[60:63], v[88:91], 0
	v_mfma_f32_16x16x32_bf16 v[92:95], v[68:71], v[84:87], v[92:95]
	v_mfma_f32_16x16x32_bf16 v[158:161], v[28:31], v[84:87], v[110:113]
	s_nop 6
	v_mul_f32_e32 v2, v139, v92
	v_sub_u32_e32 v92, v144, v115
	v_cvt_f32_i32_e32 v92, v92
	v_cndmask_b32_e64 v2, v2, 0, vcc
	v_mul_f32_e32 v92, v135, v92
	v_mul_f32_e32 v92, 0x3fb8aa3b, v92
	v_exp_f32_e32 v92, v92
	s_nop 0
	v_mul_f32_e32 v92, v92, v93
	v_cndmask_b32_e64 v106, 0, v92, s[38:39]
	v_sub_u32_e32 v92, v144, v116
	v_sub_u32_e32 v93, v144, v114
	v_cvt_f32_i32_e32 v92, v92
	v_cvt_f32_i32_e32 v93, v93
	v_cmp_ge_i32_e64 s[38:39], v144, v116
	v_mul_f32_e32 v92, v135, v92
	v_mul_f32_e32 v93, v135, v93
	v_mul_f32_e32 v92, 0x3fb8aa3b, v92
	v_mul_f32_e32 v93, 0x3fb8aa3b, v93
	v_exp_f32_e32 v92, v92
	v_exp_f32_e32 v93, v93
	s_nop 0
	v_pk_mul_f32 v[104:105], v[92:93], v[94:95]
	v_cvt_pk_bf16_f32 v92, v0, v1
	v_cvt_pk_bf16_f32 v93, v102, v103
	v_cvt_pk_bf16_f32 v94, v2, v106
	v_cvt_pk_bf16_f32 v0, v104, v105
	ds_read_b64_tr_b16 v[104:105], v126
	ds_read_b64_tr_b16 v[108:109], v126 offset:32
	ds_read_b64_tr_b16 v[102:103], v128
	ds_read_b64_tr_b16 v[106:107], v128 offset:32
	v_cndmask_b32_e64 v1, 0, v0, s[38:39]
	v_lshrrev_b32_e32 v0, 16, v0
	v_cmp_ge_i32_e64 s[38:39], v144, v114
	s_nop 1
	v_cndmask_b32_e64 v0, 0, v0, s[38:39]
	v_perm_b32 v95, v0, v1, s53
	v_add_u32_e32 v0, 17, v133
	v_cvt_f32_ubyte0_e32 v0, v0
	s_waitcnt lgkmcnt(0)
	v_mfma_f32_16x16x32_bf16 v[118:121], v[106:109], v[92:95], 0
	ds_read_b64_tr_b16 v[106:107], v128 offset:64
	ds_read_b64_tr_b16 v[108:109], v126 offset:64
	v_mul_f32_e32 v0, v135, v0
	v_mul_f32_e32 v0, 0x3fb8aa3b, v0
	s_waitcnt lgkmcnt(0)
	v_mfma_f32_16x16x32_bf16 v[146:149], v[106:109], v[92:95], 0
	ds_read_b64_tr_b16 v[106:107], v128 offset:96
	ds_read_b64_tr_b16 v[108:109], v126 offset:96
	v_exp_f32_e32 v2, v0
	v_mfma_f32_16x16x32_bf16 v[102:105], v[102:105], v[92:95], 0
	s_waitcnt lgkmcnt(0)
	v_mfma_f32_16x16x32_bf16 v[150:153], v[106:109], v[92:95], 0
	v_mfma_f32_16x16x32_bf16 v[92:95], v[20:23], v[88:91], 0
	v_mfma_f32_16x16x32_bf16 v[106:109], v[24:27], v[88:91], 0
	v_mfma_f32_16x16x32_bf16 v[88:91], v[40:43], v[88:91], 0
	v_mfma_f32_16x16x32_bf16 v[92:95], v[12:15], v[84:87], v[92:95]
	v_mfma_f32_16x16x32_bf16 v[154:157], v[16:19], v[84:87], v[106:109]
	v_mfma_f32_16x16x32_bf16 v[84:87], v[32:35], v[84:87], v[88:91]
	s_nop 5
	v_fma_f32 v108, v2, v94, v104
	v_fma_f32 v109, v2, v95, v105
	v_pk_fma_f32 v[110:111], v[2:3], v[92:93], v[102:103] op_sel_hi:[0,1,1]
	v_pk_fma_f32 v[102:103], v[2:3], v[156:157], v[120:121] op_sel_hi:[0,1,1]
	v_pk_fma_f32 v[106:107], v[2:3], v[154:155], v[118:119] op_sel_hi:[0,1,1]
	v_pk_fma_f32 v[92:93], v[2:3], v[160:161], v[148:149] op_sel_hi:[0,1,1]
	v_pk_fma_f32 v[0:1], v[2:3], v[86:87], v[152:153] op_sel_hi:[0,1,1]
	v_pk_fma_f32 v[90:91], v[2:3], v[84:85], v[150:151] op_sel_hi:[0,1,1]
	v_pk_mul_f32 v[84:85], v[108:109], v[108:109]
	v_pk_mul_f32 v[86:87], v[110:111], v[110:111]
	v_pk_fma_f32 v[94:95], v[2:3], v[158:159], v[146:147] op_sel_hi:[0,1,1]
	v_pk_mov_b32 v[88:89], v[86:87], v[84:85] op_sel:[1,0]
	v_mov_b32_e32 v87, v85
	v_pk_add_f32 v[84:85], v[88:89], v[86:87]
	v_pk_mul_f32 v[86:87], v[102:103], v[102:103]
	v_pk_mul_f32 v[88:89], v[106:107], v[106:107]
	v_mul_f32_e32 v2, v90, v90
	v_pk_mov_b32 v[104:105], v[88:89], v[86:87] op_sel:[1,0]
	v_mov_b32_e32 v89, v87
	v_pk_add_f32 v[86:87], v[104:105], v[88:89]
	v_mul_f32_e32 v88, v91, v91
	v_pk_add_f32 v[84:85], v[84:85], v[84:85] op_sel:[0,1] op_sel_hi:[1,0]
	v_pk_add_f32 v[86:87], v[86:87], v[86:87] op_sel:[0,1] op_sel_hi:[1,0]
	v_mov_b32_e32 v85, v2
	v_mov_b32_e32 v87, v88
	v_mul_f32_e32 v2, v95, v95
	v_mul_f32_e32 v89, v0, v0
	v_pk_add_f32 v[84:85], v[84:85], v[86:87]
	v_pk_fma_f32 v[86:87], v[94:95], v[94:95], v[2:3] op_sel_hi:[1,1,0]
	v_mul_f32_e32 v2, v93, v93
	v_mul_f32_e32 v104, v1, v1
	v_mov_b32_e32 v87, v89
	v_pk_fma_f32 v[88:89], v[92:93], v[92:93], v[2:3] op_sel_hi:[1,1,0]
	s_nop 0
	v_mov_b32_e32 v89, v104
	v_pk_add_f32 v[86:87], v[86:87], v[88:89]
	s_nop 0
	v_pk_add_f32 v[84:85], v[84:85], v[86:87]
	s_nop 0
	v_add_f32_e32 v2, v84, v85
	ds_bpermute_b32 v84, v138, v2
	s_waitcnt lgkmcnt(0)
; __device__ __forceinline__ unsigned pk2(float lo, float hi) { const f32x2_t v = {lo, hi}; const bf16x2_t b = __builtin_convertvector(v, bf16x2_t); return __builtin_bit_cast(unsigned, b); }
; __device__ __forceinline__ float sigmoidf_(float x) { return __builtin_amdgcn_rcpf(1.0f + __expf(-x)); }
; __device__ __forceinline__ float bperm_f(int src_lane, float v) { return __builtin_bit_cast(float, __builtin_amdgcn_ds_bpermute(src_lane << 2, __builtin_bit_cast(int, v))); }
; template <int KIND>
; __device__ __forceinline__ void w_m3_core(const bf16x8 (&Qf)[4][2], const bf16x8 (&Kf)[4][2], const bf16x8 (&Sf)[4][2], const LAS bf16_t* vT, float lg,
;                                           const bf16_t* gsrc, const float* nw, bf16_t* ydst, int lo, int fq) {
;     ...
;         const float osc = KIND == 0 ? __expf((float)(16 * nb + lo + 1) * lg) : 1.0f;
; #pragma unroll
;         for (int eb = 0; eb < 4; ++eb) O[eb] = O[eb] + O2[eb] * osc;
;         float ss = 0.f;
; #pragma unroll
;         for (int eb = 0; eb < 4; ++eb) ss += (O[eb][0] * O[eb][0] + O[eb][1] * O[eb][1]) + (O[eb][2] * O[eb][2] + O[eb][3] * O[eb][3]);
;         { const int ln = (fq << 4) | lo; ss += bperm_f(ln ^ 16, ss); ss += bperm_f(ln ^ 32, ss); }
;         const float rs = rsqrtf(ss * (1.0f / 64.0f) + EPS);
;         const size_t n = 16 * nb + lo;
; #pragma unroll
;         for (int eb = 0; eb < 4; ++eb) { const int e0 = 16 * eb + 4 * fq;
;             const unsigned long long gw_ = *(const unsigned long long*)(gsrc + n * NIN + e0); const f32x4 w4 = *(const f32x4*)(nw + e0);
;             const float g0 = __uint_as_float((unsigned)gw_ << 16), g1 = __uint_as_float((unsigned)gw_ & 0xffff0000u), g2 = __uint_as_float((unsigned)(gw_ >> 32) << 16), g3 = __uint_as_float((unsigned)(gw_ >> 32) & 0xffff0000u);
;             const float o0 = O[eb][0] * rs * w4[0] * (g0 * sigmoidf_(g0)), o1 = O[eb][1] * rs * w4[1] * (g1 * sigmoidf_(g1));
;             const float o2 = O[eb][2] * rs * w4[2] * (g2 * sigmoidf_(g2)), o3 = O[eb][3] * rs * w4[3] * (g3 * sigmoidf_(g3));
;             *(unsigned long long*)(ydst + n * DM + e0) = (unsigned long long)pk2(o0, o1) | ((unsigned long long)pk2(o2, o3) << 32); }
	v_add_f32_e32 v2, v2, v84
	ds_bpermute_b32 v84, v137, v2
	s_waitcnt lgkmcnt(0)
	v_add_f32_e32 v2, v2, v84
	v_fmamk_f32 v2, v2, 0x3c800000, v200
	v_cmp_gt_f32_e64 s[38:39], s29, v2
	v_mul_f32_e32 v84, 0x4b800000, v2
	s_nop 0
	v_cndmask_b32_e64 v2, v2, v84, s[38:39]
	v_rsq_f32_e32 v2, v2
	s_nop 0
	v_mul_f32_e32 v84, 0x45800000, v2
	v_cndmask_b32_e64 v88, v2, v84, s[38:39]
	v_mad_u64_u32 v[84:85], s[20:21], v144, s72, v[98:99]
	v_lshl_add_u64 v[104:105], v[84:85], 0, v[96:97]
	v_mov_b64_e32 v[118:119], v[230:231]
	v_mov_b64_e32 v[84:85], v[184:185]
	v_mov_b64_e32 v[86:87], v[186:187]
	v_lshlrev_b32_e32 v2, 11, v144
	v_lshl_add_u64 v[112:113], s[40:41], 0, v[2:3]
	v_pk_mul_f32 v[110:111], v[110:111], v[88:89] op_sel_hi:[1,0]
	v_pk_mul_f32 v[108:109], v[108:109], v[88:89] op_sel_hi:[1,0]
	v_pk_mul_f32 v[106:107], v[106:107], v[88:89] op_sel_hi:[1,0]
	v_pk_mul_f32 v[102:103], v[102:103], v[88:89] op_sel_hi:[1,0]
	v_pk_mul_f32 v[94:95], v[94:95], v[88:89] op_sel_hi:[1,0]
	s_waitcnt lgkmcnt(0)
	v_lshlrev_b32_e32 v120, 16, v118
	v_mul_f32_e32 v2, 0xbfb8aa3b, v120
	v_exp_f32_e32 v2, v2
	v_and_b32_e32 v121, 0xffff0000, v118
	v_lshlrev_b32_e32 v118, 16, v119
	v_and_b32_e32 v119, 0xffff0000, v119
	v_add_f32_e32 v2, 1.0, v2
	v_rcp_f32_e32 v122, v2
	v_mul_f32_e32 v2, 0xbfb8aa3b, v121
	v_exp_f32_e32 v2, v2
	v_pk_mul_f32 v[84:85], v[84:85], v[110:111]
	v_pk_mul_f32 v[86:87], v[86:87], v[108:109]
	v_add_f32_e32 v2, 1.0, v2
	v_rcp_f32_e32 v123, v2
	v_mul_f32_e32 v2, 0xbfb8aa3b, v118
	v_exp_f32_e32 v2, v2
	v_pk_mul_f32 v[110:111], v[122:123], v[120:121]
	s_nop 0
	v_pk_mul_f32 v[84:85], v[110:111], v[84:85]
	v_add_f32_e32 v2, 1.0, v2
	v_rcp_f32_e32 v110, v2
	v_mul_f32_e32 v2, 0xbfb8aa3b, v119
	v_exp_f32_e32 v2, v2
	s_nop 0
	v_add_f32_e32 v2, 1.0, v2
	v_rcp_f32_e32 v111, v2
	s_nop 0
	v_pk_mul_f32 v[108:109], v[110:111], v[118:119]
	s_nop 0
	v_pk_mul_f32 v[86:87], v[108:109], v[86:87]
	v_cvt_pk_bf16_f32 v108, v84, v85
	v_cvt_pk_bf16_f32 v109, v86, v87
	v_lshl_add_u64 v[84:85], v[112:113], 0, v[96:97]
	global_store_dwordx2 v[84:85], v[108:109], off offset:1024
	v_mov_b64_e32 v[86:87], v[232:233]
	s_nop 0
	v_mov_b64_e32 v[108:109], v[188:189]
	v_mov_b64_e32 v[110:111], v[190:191]
	s_waitcnt lgkmcnt(0)
	v_lshlrev_b32_e32 v112, 16, v86
	v_mul_f32_e32 v2, 0xbfb8aa3b, v112
	v_exp_f32_e32 v2, v2
	v_and_b32_e32 v113, 0xffff0000, v86
	v_lshlrev_b32_e32 v86, 16, v87
	v_and_b32_e32 v87, 0xffff0000, v87
	v_add_f32_e32 v2, 1.0, v2
	v_rcp_f32_e32 v118, v2
	v_mul_f32_e32 v2, 0xbfb8aa3b, v113
	v_exp_f32_e32 v2, v2
	v_pk_mul_f32 v[106:107], v[108:109], v[106:107]
	v_pk_mul_f32 v[102:103], v[110:111], v[102:103]
	v_mul_f32_e32 v110, v92, v88
	v_add_f32_e32 v2, 1.0, v2
	v_rcp_f32_e32 v119, v2
	v_mul_f32_e32 v2, 0xbfb8aa3b, v86
	v_exp_f32_e32 v2, v2
	v_pk_mul_f32 v[108:109], v[118:119], v[112:113]
	s_nop 0
	v_pk_mul_f32 v[106:107], v[108:109], v[106:107]
	v_add_f32_e32 v2, 1.0, v2
	v_rcp_f32_e32 v108, v2
	v_mul_f32_e32 v2, 0xbfb8aa3b, v87
	v_exp_f32_e32 v2, v2
	s_nop 0
	v_add_f32_e32 v2, 1.0, v2
	v_rcp_f32_e32 v109, v2
	s_nop 0
	v_pk_mul_f32 v[86:87], v[108:109], v[86:87]
	s_nop 0
	v_pk_mul_f32 v[86:87], v[86:87], v[102:103]
	v_cvt_pk_bf16_f32 v102, v106, v107
	v_cvt_pk_bf16_f32 v103, v86, v87
	global_store_dwordx2 v[84:85], v[102:103], off offset:1056
	v_mov_b64_e32 v[86:87], v[234:235]
	v_mov_b64_e32 v[106:107], v[192:193]
	v_mov_b64_e32 v[108:109], v[194:195]
	s_waitcnt lgkmcnt(0)
	v_lshlrev_b32_e32 v102, 16, v86
	v_mul_f32_e32 v2, 0xbfb8aa3b, v102
	v_exp_f32_e32 v2, v2
	v_and_b32_e32 v103, 0xffff0000, v86
	v_lshlrev_b32_e32 v111, 16, v87
	v_and_b32_e32 v87, 0xffff0000, v87
	v_add_f32_e32 v2, 1.0, v2
	v_rcp_f32_e32 v112, v2
	v_mul_f32_e32 v2, 0xbfb8aa3b, v103
	v_exp_f32_e32 v2, v2
	v_pk_mul_f32 v[94:95], v[106:107], v[94:95]
	v_mul_f32_e32 v86, v93, v88
	v_mov_b32_e32 v92, v109
	v_add_f32_e32 v2, 1.0, v2
	v_rcp_f32_e32 v113, v2
	v_mul_f32_e32 v2, 0xbfb8aa3b, v111
	v_exp_f32_e32 v2, v2
	v_mul_f32_e32 v106, v0, v88
	v_pk_mul_f32 v[102:103], v[112:113], v[102:103]
	v_add_f32_e32 v2, 1.0, v2
	v_pk_mul_f32 v[94:95], v[102:103], v[94:95]
	v_rcp_f32_e32 v103, v2
	v_mul_f32_e32 v2, 0xbfb8aa3b, v87
	v_exp_f32_e32 v2, v2
	v_mov_b32_e32 v102, v108
	v_pk_mul_f32 v[102:103], v[102:103], v[110:111]
	v_add_f32_e32 v2, 1.0, v2
	v_rcp_f32_e32 v93, v2
	s_nop 0
	v_pk_mul_f32 v[86:87], v[92:93], v[86:87]
	v_cvt_pk_bf16_f32 v92, v94, v95
	v_mov_b32_e32 v94, v102
	v_mov_b32_e32 v95, v86
	v_mov_b32_e32 v86, v103
	v_pk_mul_f32 v[86:87], v[94:95], v[86:87]
	v_mul_f32_e32 v102, v90, v88
	v_cvt_pk_bf16_f32 v93, v86, v87
	global_store_dwordx2 v[84:85], v[92:93], off offset:1088
	v_mov_b64_e32 v[86:87], v[236:237]
	s_nop 0
	v_mov_b64_e32 v[92:93], v[196:197]
	v_mov_b64_e32 v[94:95], v[198:199]
	v_mul_f32_e32 v104, v91, v88
	s_waitcnt lgkmcnt(0)
; __device__ __forceinline__ unsigned pk2(float lo, float hi) { const f32x2_t v = {lo, hi}; const bf16x2_t b = __builtin_convertvector(v, bf16x2_t); return __builtin_bit_cast(unsigned, b); }
; template <int KIND>
; __device__ __forceinline__ void w_m3_core(const bf16x8 (&Qf)[4][2], const bf16x8 (&Kf)[4][2], const bf16x8 (&Sf)[4][2], const LAS bf16_t* vT, float lg,
;                                           const bf16_t* gsrc, const float* nw, bf16_t* ydst, int lo, int fq) {
;     ...
;             for (int hh = 0; hh < 2; ++hh) { const int mb = 2 * kk2 + hh;
;                 if (mb <= nb) { f32x4 s = {0.f, 0.f, 0.f, 0.f};
;                     s = __builtin_amdgcn_mfma_f32_16x16x32_bf16(Kf[mb][0], Qf[nb][0], s, 0, 0, 0); s = __builtin_amdgcn_mfma_f32_16x16x32_bf16(Kf[mb][1], Qf[nb][1], s, 0, 0, 0);
; #pragma unroll
;                     for (int r = 0; r < 4; ++r) { const int m = 16 * mb + 4 * fq + r, n = 16 * nb + lo; float v = s[r];
;                         if (KIND == 0) v *= __expf((float)(n - m) * lg);
;                         if (mb == nb) v = (m <= n) ? v : 0.f;
;                         pv[4 * hh + r] = v; }
;                 } else {
; #pragma unroll
;                     for (int r = 0; r < 4; ++r) pv[4 * hh + r] = 0.f; }
;             }
;             const bf16x8 Pf = pack_frag(pv);
; #pragma unroll
;             for (int eb = 0; eb < 4; ++eb)
;                 O[eb] = __builtin_amdgcn_mfma_f32_16x16x32_bf16(tr_frag(vT, 32 * kk2 + 4 * fq, 32 * kk2 + 16 + 4 * fq, 16 * eb, lo), Pf, O[eb], 0, 0, 0);
;     ...
;         for (int eb = 0; eb < 4; ++eb) { const int e0 = 16 * eb + 4 * fq;
;             const unsigned long long gw_ = *(const unsigned long long*)(gsrc + n * NIN + e0); const f32x4 w4 = *(const f32x4*)(nw + e0);
;             const float g0 = __uint_as_float((unsigned)gw_ << 16), g1 = __uint_as_float((unsigned)gw_ & 0xffff0000u), g2 = __uint_as_float((unsigned)(gw_ >> 32) << 16), g3 = __uint_as_float((unsigned)(gw_ >> 32) & 0xffff0000u);
;             const float o0 = O[eb][0] * rs * w4[0] * (g0 * sigmoidf_(g0)), o1 = O[eb][1] * rs * w4[1] * (g1 * sigmoidf_(g1));
;             const float o2 = O[eb][2] * rs * w4[2] * (g2 * sigmoidf_(g2)), o3 = O[eb][3] * rs * w4[3] * (g3 * sigmoidf_(g3));
;             *(unsigned long long*)(ydst + n * DM + e0) = (unsigned long long)pk2(o0, o1) | ((unsigned long long)pk2(o2, o3) << 32); }
	v_lshlrev_b32_e32 v103, 16, v86
	v_lshlrev_b32_e32 v107, 16, v87
	v_mul_f32_e32 v2, 0xbfb8aa3b, v103
	v_mul_f32_e32 v0, 0xbfb8aa3b, v107
	v_exp_f32_e32 v2, v2
	v_exp_f32_e32 v0, v0
	v_and_b32_e32 v105, 0xffff0000, v86
	v_and_b32_e32 v87, 0xffff0000, v87
	v_add_f32_e32 v2, 1.0, v2
	v_add_f32_e32 v0, 1.0, v0
	v_rcp_f32_e32 v109, v2
	v_mul_f32_e32 v2, 0xbfb8aa3b, v105
	v_mov_b32_e32 v90, v93
	v_rcp_f32_e32 v93, v0
	v_mul_f32_e32 v0, 0xbfb8aa3b, v87
	v_exp_f32_e32 v2, v2
	v_exp_f32_e32 v0, v0
	v_mul_f32_e32 v86, v1, v88
	v_mov_b32_e32 v108, v92
	v_add_f32_e32 v2, 1.0, v2
	v_add_f32_e32 v0, 1.0, v0
	v_rcp_f32_e32 v91, v2
	v_rcp_f32_e32 v1, v0
	v_mov_b32_e32 v92, v94
	v_mov_b32_e32 v0, v95
	v_pk_mul_f32 v[102:103], v[108:109], v[102:103]
	v_pk_mul_f32 v[90:91], v[90:91], v[104:105]
	v_pk_mul_f32 v[92:93], v[92:93], v[106:107]
	v_pk_mul_f32 v[0:1], v[0:1], v[86:87]
	v_mov_b32_e32 v86, v102
	v_mov_b32_e32 v87, v90
	v_mov_b32_e32 v90, v103
	v_mov_b32_e32 v88, v92
	v_mov_b32_e32 v89, v0
	v_mov_b32_e32 v0, v93
	v_pk_mul_f32 v[86:87], v[86:87], v[90:91]
	v_pk_mul_f32 v[0:1], v[88:89], v[0:1]
	v_cvt_pk_bf16_f32 v86, v86, v87
	v_cvt_pk_bf16_f32 v87, v0, v1
	global_store_dwordx2 v[84:85], v[86:87], off offset:1120
	v_sub_u32_e32 v0, v136, v124
	v_add_u32_e32 v1, v136, v143
	v_cvt_f32_i32_e32 v0, v0
	v_cvt_f32_i32_e32 v1, v1
	v_mfma_f32_16x16x32_bf16 v[84:87], v[64:67], v[80:83], 0
	v_sub_u32_e32 v2, v136, v142
	v_mul_f32_e32 v0, v135, v0
	v_mul_f32_e32 v1, v135, v1
	v_cvt_f32_i32_e32 v2, v2
	v_mul_f32_e32 v0, 0x3fb8aa3b, v0
	v_mul_f32_e32 v1, 0x3fb8aa3b, v1
	v_mfma_f32_16x16x32_bf16 v[84:87], v[72:75], v[76:79], v[84:87]
	v_exp_f32_e32 v0, v0
	v_exp_f32_e32 v1, v1
	v_mul_f32_e32 v2, v135, v2
	v_mul_f32_e32 v2, 0x3fb8aa3b, v2
	s_nop 3
	v_pk_mul_f32 v[0:1], v[0:1], v[84:85]
	v_exp_f32_e32 v84, v2
	v_sub_u32_e32 v2, v136, v141
	v_cvt_f32_i32_e32 v2, v2
	v_mul_f32_e32 v2, v135, v2
	v_mul_f32_e32 v2, 0x3fb8aa3b, v2
	v_exp_f32_e32 v85, v2
	v_sub_u32_e32 v2, v136, v114
	v_cvt_f32_i32_e32 v2, v2
	v_pk_mul_f32 v[88:89], v[84:85], v[86:87]
	v_mfma_f32_16x16x32_bf16 v[84:87], v[60:63], v[80:83], 0
	v_mul_f32_e32 v2, v135, v2
	v_mul_f32_e32 v2, 0x3fb8aa3b, v2
	v_exp_f32_e32 v91, v2
	v_sub_u32_e32 v2, v136, v140
	v_cvt_f32_i32_e32 v2, v2
	v_mfma_f32_16x16x32_bf16 v[84:87], v[68:71], v[76:79], v[84:87]
	v_mul_f32_e32 v2, v135, v2
	v_mul_f32_e32 v2, 0x3fb8aa3b, v2
	v_exp_f32_e32 v92, v2
	v_sub_u32_e32 v2, v136, v115
	v_cvt_f32_i32_e32 v2, v2
	v_mul_f32_e32 v2, v135, v2
	v_mul_f32_e32 v2, 0x3fb8aa3b, v2
	v_exp_f32_e32 v93, v2
	v_sub_u32_e32 v2, v136, v116
	v_cvt_f32_i32_e32 v2, v2
	v_pk_mul_f32 v[92:93], v[92:93], v[84:85]
	v_cvt_pk_bf16_f32 v85, v88, v89
	v_mul_f32_e32 v2, v135, v2
	v_mul_f32_e32 v2, 0x3fb8aa3b, v2
	v_exp_f32_e32 v90, v2
	v_cvt_pk_bf16_f32 v84, v0, v1
	v_pk_mul_f32 v[90:91], v[90:91], v[86:87]
	v_cvt_pk_bf16_f32 v86, v92, v93
	v_cvt_pk_bf16_f32 v87, v90, v91
	ds_read_b64_tr_b16 v[90:91], v126
	ds_read_b64_tr_b16 v[94:95], v126 offset:32
	ds_read_b64_tr_b16 v[88:89], v128
	ds_read_b64_tr_b16 v[92:93], v128 offset:32
	ds_read_b64_tr_b16 v[102:103], v128 offset:64
	ds_read_b64_tr_b16 v[104:105], v126 offset:64
	ds_read_b64_tr_b16 v[106:107], v128 offset:96
	ds_read_b64_tr_b16 v[108:109], v126 offset:96
	s_waitcnt lgkmcnt(0)
	v_mfma_f32_16x16x32_bf16 v[88:91], v[88:91], v[84:87], 0
	v_mfma_f32_16x16x32_bf16 v[92:95], v[92:95], v[84:87], 0
	v_mfma_f32_16x16x32_bf16 v[102:105], v[102:105], v[84:87], 0
	v_mfma_f32_16x16x32_bf16 v[84:87], v[106:109], v[84:87], 0
	v_mfma_f32_16x16x32_bf16 v[106:109], v[44:47], v[80:83], 0
	v_mfma_f32_16x16x32_bf16 v[108:111], v[48:51], v[76:79], v[106:109]
	s_nop 6
	v_add_u32_e32 v107, 33, v124
	v_mul_f32_e32 v0, v139, v108
	v_cndmask_b32_e64 v2, v0, 0, vcc
	v_sub_u32_e32 v0, v136, v107
	v_cvt_f32_i32_e32 v0, v0
	v_cmp_ge_i32_e64 s[38:39], v136, v107
	v_add_u32_e32 v106, 35, v124
	v_add_u32_e32 v108, 34, v124
	v_mul_f32_e32 v0, v135, v0
	v_mul_f32_e32 v0, 0x3fb8aa3b, v0
	v_exp_f32_e32 v0, v0
	v_sub_u32_e32 v1, v136, v106
	v_cvt_f32_i32_e32 v1, v1
	v_mul_f32_e32 v0, v0, v109
	v_cndmask_b32_e64 v109, 0, v0, s[38:39]
	v_sub_u32_e32 v0, v136, v108
	v_cvt_f32_i32_e32 v0, v0
	v_mul_f32_e32 v1, v135, v1
	v_mul_f32_e32 v1, 0x3fb8aa3b, v1
	v_exp_f32_e32 v1, v1
	v_mul_f32_e32 v0, v135, v0
	v_mul_f32_e32 v0, 0x3fb8aa3b, v0
	v_exp_f32_e32 v0, v0
	v_cmp_ge_i32_e64 s[38:39], v136, v108
	v_pk_mul_f32 v[110:111], v[0:1], v[110:111]
	s_nop 0
	v_cvt_pk_bf16_f32 v1, v110, v111
	ds_read_b64_tr_b16 v[110:111], v128 offset:4608
	ds_read_b64_tr_b16 v[112:113], v126 offset:4608
	v_cvt_pk_bf16_f32 v0, v2, v109
	v_cndmask_b32_e64 v2, 0, v1, s[38:39]
	v_lshrrev_b32_e32 v1, 16, v1
	v_cmp_ge_i32_e64 s[38:39], v136, v106
	s_nop 1
	v_cndmask_b32_e64 v1, 0, v1, s[38:39]
	v_perm_b32 v1, v1, v2, s53
	v_mov_b32_e32 v2, v3
	s_waitcnt lgkmcnt(0)
	s_nop 0
	v_mfma_f32_16x16x32_bf16 v[88:91], v[110:113], v[0:3], v[88:91]
	ds_read_b64_tr_b16 v[110:111], v128 offset:4640
	ds_read_b64_tr_b16 v[112:113], v126 offset:4640
	s_waitcnt lgkmcnt(0)
	v_mfma_f32_16x16x32_bf16 v[110:113], v[110:113], v[0:3], v[92:95]
	s_nop 2
	ds_read_b64_tr_b16 v[92:93], v128 offset:4672
	ds_read_b64_tr_b16 v[94:95], v126 offset:4672
	s_waitcnt lgkmcnt(0)
	v_mfma_f32_16x16x32_bf16 v[118:121], v[92:95], v[0:3], v[102:105]
	ds_read_b64_tr_b16 v[92:93], v128 offset:4704
	ds_read_b64_tr_b16 v[94:95], v126 offset:4704
	s_waitcnt lgkmcnt(0)
; __device__ __forceinline__ unsigned pk2(float lo, float hi) { const f32x2_t v = {lo, hi}; const bf16x2_t b = __builtin_convertvector(v, bf16x2_t); return __builtin_bit_cast(unsigned, b); }
; __device__ __forceinline__ float sigmoidf_(float x) { return __builtin_amdgcn_rcpf(1.0f + __expf(-x)); }
; template <int KIND>
; __device__ __forceinline__ void w_m3_core(const bf16x8 (&Qf)[4][2], const bf16x8 (&Kf)[4][2], const bf16x8 (&Sf)[4][2], const LAS bf16_t* vT, float lg,
;                                           const bf16_t* gsrc, const float* nw, bf16_t* ydst, int lo, int fq) {
;     ...
;                 O[eb] = __builtin_amdgcn_mfma_f32_16x16x32_bf16(tr_frag(vT, 32 * kk2 + 4 * fq, 32 * kk2 + 16 + 4 * fq, 16 * eb, lo), Pf, O[eb], 0, 0, 0);
;         }
; #pragma unroll
;         for (int kk = 0; kk < 2; ++kk)
; #pragma unroll
;             for (int eb = 0; eb < 4; ++eb) O2[eb] = __builtin_amdgcn_mfma_f32_16x16x32_bf16(Sf[eb][kk], Qf[nb][kk], O2[eb], 0, 0, 0);
;         const float osc = KIND == 0 ? __expf((float)(16 * nb + lo + 1) * lg) : 1.0f;
; #pragma unroll
;         for (int eb = 0; eb < 4; ++eb) O[eb] = O[eb] + O2[eb] * osc;
;         float ss = 0.f;
; #pragma unroll
;         for (int eb = 0; eb < 4; ++eb) ss += (O[eb][0] * O[eb][0] + O[eb][1] * O[eb][1]) + (O[eb][2] * O[eb][2] + O[eb][3] * O[eb][3]);
;         { const int ln = (fq << 4) | lo; ss += bperm_f(ln ^ 16, ss); ss += bperm_f(ln ^ 32, ss); }
;         const float rs = rsqrtf(ss * (1.0f / 64.0f) + EPS);
;         const size_t n = 16 * nb + lo;
; #pragma unroll
;         for (int eb = 0; eb < 4; ++eb) { const int e0 = 16 * eb + 4 * fq;
;             const unsigned long long gw_ = *(const unsigned long long*)(gsrc + n * NIN + e0); const f32x4 w4 = *(const f32x4*)(nw + e0);
;             const float g0 = __uint_as_float((unsigned)gw_ << 16), g1 = __uint_as_float((unsigned)gw_ & 0xffff0000u), g2 = __uint_as_float((unsigned)(gw_ >> 32) << 16), g3 = __uint_as_float((unsigned)(gw_ >> 32) & 0xffff0000u);
;             const float o0 = O[eb][0] * rs * w4[0] * (g0 * sigmoidf_(g0)), o1 = O[eb][1] * rs * w4[1] * (g1 * sigmoidf_(g1));
;             const float o2 = O[eb][2] * rs * w4[2] * (g2 * sigmoidf_(g2)), o3 = O[eb][3] * rs * w4[3] * (g3 * sigmoidf_(g3));
;             *(unsigned long long*)(ydst + n * DM + e0) = (unsigned long long)pk2(o0, o1) | ((unsigned long long)pk2(o2, o3) << 32); }
	v_mfma_f32_16x16x32_bf16 v[144:147], v[92:95], v[0:3], v[84:87]
	v_add_u32_e32 v0, 33, v133
	v_cvt_f32_ubyte0_e32 v0, v0
	v_mul_f32_e32 v0, v135, v0
	v_mfma_f32_16x16x32_bf16 v[84:87], v[20:23], v[80:83], 0
	v_mul_f32_e32 v0, 0x3fb8aa3b, v0
	v_exp_f32_e32 v2, v0
	v_mfma_f32_16x16x32_bf16 v[92:95], v[24:27], v[80:83], 0
	v_mfma_f32_16x16x32_bf16 v[102:105], v[36:39], v[80:83], 0
	v_mfma_f32_16x16x32_bf16 v[80:83], v[40:43], v[80:83], 0
	v_mfma_f32_16x16x32_bf16 v[84:87], v[12:15], v[76:79], v[84:87]
	v_mfma_f32_16x16x32_bf16 v[148:151], v[16:19], v[76:79], v[92:95]
	v_mfma_f32_16x16x32_bf16 v[152:155], v[28:31], v[76:79], v[102:105]
	s_nop 5
	v_fma_f32 v94, v2, v86, v90
	v_fma_f32 v95, v2, v87, v91
	v_pk_fma_f32 v[92:93], v[2:3], v[148:149], v[110:111] op_sel_hi:[0,1,1]
	v_mfma_f32_16x16x32_bf16 v[76:79], v[32:35], v[76:79], v[80:83]
	v_fma_f32 v102, v2, v84, v88
	v_fma_f32 v103, v2, v85, v89
	v_pk_fma_f32 v[88:89], v[2:3], v[150:151], v[112:113] op_sel_hi:[0,1,1]
	v_pk_fma_f32 v[84:85], v[2:3], v[154:155], v[120:121] op_sel_hi:[0,1,1]
	v_pk_fma_f32 v[86:87], v[2:3], v[152:153], v[118:119] op_sel_hi:[0,1,1]
	s_nop 2
	v_pk_fma_f32 v[0:1], v[2:3], v[78:79], v[146:147] op_sel_hi:[0,1,1]
	v_pk_fma_f32 v[82:83], v[2:3], v[76:77], v[144:145] op_sel_hi:[0,1,1]
	v_pk_mul_f32 v[76:77], v[94:95], v[94:95]
	v_pk_mul_f32 v[78:79], v[102:103], v[102:103]
	v_mul_f32_e32 v2, v82, v82
	v_pk_mov_b32 v[80:81], v[78:79], v[76:77] op_sel:[1,0]
	v_mov_b32_e32 v79, v77
	v_pk_add_f32 v[76:77], v[80:81], v[78:79]
	v_pk_mul_f32 v[78:79], v[88:89], v[88:89]
	v_pk_mul_f32 v[80:81], v[92:93], v[92:93]
	v_pk_add_f32 v[76:77], v[76:77], v[76:77] op_sel:[0,1] op_sel_hi:[1,0]
	v_pk_mov_b32 v[90:91], v[80:81], v[78:79] op_sel:[1,0]
	v_mov_b32_e32 v81, v79
	v_pk_add_f32 v[78:79], v[90:91], v[80:81]
	v_mul_f32_e32 v80, v83, v83
	v_pk_add_f32 v[78:79], v[78:79], v[78:79] op_sel:[0,1] op_sel_hi:[1,0]
	v_mov_b32_e32 v77, v2
	v_mov_b32_e32 v79, v80
	v_mul_f32_e32 v2, v87, v87
	v_mul_f32_e32 v81, v0, v0
	v_pk_add_f32 v[76:77], v[76:77], v[78:79]
	v_pk_fma_f32 v[78:79], v[86:87], v[86:87], v[2:3] op_sel_hi:[1,1,0]
	v_mul_f32_e32 v2, v85, v85
	v_mul_f32_e32 v90, v1, v1
	v_mov_b32_e32 v79, v81
	v_pk_fma_f32 v[80:81], v[84:85], v[84:85], v[2:3] op_sel_hi:[1,1,0]
	s_nop 0
	v_mov_b32_e32 v81, v90
	v_pk_add_f32 v[78:79], v[78:79], v[80:81]
	s_nop 0
	v_pk_add_f32 v[76:77], v[76:77], v[78:79]
	s_nop 0
	v_add_f32_e32 v2, v76, v77
	ds_bpermute_b32 v76, v138, v2
	s_waitcnt lgkmcnt(0)
	v_add_f32_e32 v2, v2, v76
	ds_bpermute_b32 v76, v137, v2
	s_waitcnt lgkmcnt(0)
	v_add_f32_e32 v2, v2, v76
	v_fmamk_f32 v2, v2, 0x3c800000, v200
	v_cmp_gt_f32_e64 s[38:39], s29, v2
	v_mul_f32_e32 v76, 0x4b800000, v2
	s_nop 0
	v_cndmask_b32_e64 v2, v2, v76, s[38:39]
	v_rsq_f32_e32 v2, v2
	s_nop 0
	v_mul_f32_e32 v76, 0x45800000, v2
	v_cndmask_b32_e64 v80, v2, v76, s[38:39]
	v_mad_u64_u32 v[76:77], s[20:21], v136, s72, v[98:99]
	v_lshl_add_u64 v[90:91], v[76:77], 0, v[96:97]
	v_mov_b64_e32 v[110:111], v[238:239]
	v_mov_b64_e32 v[76:77], v[184:185]
	v_mov_b64_e32 v[78:79], v[186:187]
	v_lshlrev_b32_e32 v2, 11, v136
	v_lshl_add_u64 v[104:105], s[40:41], 0, v[2:3]
	v_pk_mul_f32 v[102:103], v[102:103], v[80:81] op_sel_hi:[1,0]
	v_pk_mul_f32 v[94:95], v[94:95], v[80:81] op_sel_hi:[1,0]
	v_pk_mul_f32 v[92:93], v[92:93], v[80:81] op_sel_hi:[1,0]
	v_pk_mul_f32 v[88:89], v[88:89], v[80:81] op_sel_hi:[1,0]
	v_pk_mul_f32 v[86:87], v[86:87], v[80:81] op_sel_hi:[1,0]
	s_waitcnt lgkmcnt(0)
	v_lshlrev_b32_e32 v112, 16, v110
	v_mul_f32_e32 v2, 0xbfb8aa3b, v112
	v_exp_f32_e32 v2, v2
	v_and_b32_e32 v113, 0xffff0000, v110
	v_lshlrev_b32_e32 v110, 16, v111
	v_and_b32_e32 v111, 0xffff0000, v111
	v_add_f32_e32 v2, 1.0, v2
	v_rcp_f32_e32 v118, v2
	v_mul_f32_e32 v2, 0xbfb8aa3b, v113
	v_exp_f32_e32 v2, v2
	v_pk_mul_f32 v[76:77], v[76:77], v[102:103]
	v_pk_mul_f32 v[78:79], v[78:79], v[94:95]
	v_add_f32_e32 v2, 1.0, v2
	v_rcp_f32_e32 v119, v2
	v_mul_f32_e32 v2, 0xbfb8aa3b, v110
	v_exp_f32_e32 v2, v2
	v_pk_mul_f32 v[102:103], v[118:119], v[112:113]
	s_nop 0
	v_pk_mul_f32 v[76:77], v[102:103], v[76:77]
	v_add_f32_e32 v2, 1.0, v2
	v_rcp_f32_e32 v102, v2
	v_mul_f32_e32 v2, 0xbfb8aa3b, v111
	v_exp_f32_e32 v2, v2
	s_nop 0
	v_add_f32_e32 v2, 1.0, v2
	v_rcp_f32_e32 v103, v2
	s_nop 0
	v_pk_mul_f32 v[94:95], v[102:103], v[110:111]
	s_nop 0
	v_pk_mul_f32 v[78:79], v[94:95], v[78:79]
	v_cvt_pk_bf16_f32 v94, v76, v77
	v_cvt_pk_bf16_f32 v95, v78, v79
	v_lshl_add_u64 v[76:77], v[104:105], 0, v[96:97]
	global_store_dwordx2 v[76:77], v[94:95], off offset:1024
	v_mov_b64_e32 v[78:79], v[240:241]
	v_mov_b64_e32 v[102:103], v[188:189]
	v_mov_b64_e32 v[104:105], v[190:191]
	s_waitcnt lgkmcnt(0)
	v_lshlrev_b32_e32 v94, 16, v78
	v_mul_f32_e32 v2, 0xbfb8aa3b, v94
	v_exp_f32_e32 v2, v2
	v_and_b32_e32 v95, 0xffff0000, v78
	v_lshlrev_b32_e32 v78, 16, v79
	v_and_b32_e32 v79, 0xffff0000, v79
	v_add_f32_e32 v2, 1.0, v2
	v_rcp_f32_e32 v110, v2
	v_mul_f32_e32 v2, 0xbfb8aa3b, v95
	v_exp_f32_e32 v2, v2
	v_pk_mul_f32 v[92:93], v[102:103], v[92:93]
	v_pk_mul_f32 v[88:89], v[104:105], v[88:89]
	v_mul_f32_e32 v102, v84, v80
	v_add_f32_e32 v2, 1.0, v2
	v_rcp_f32_e32 v111, v2
	v_mul_f32_e32 v2, 0xbfb8aa3b, v78
	v_exp_f32_e32 v2, v2
	v_pk_mul_f32 v[94:95], v[110:111], v[94:95]
	s_nop 0
	v_pk_mul_f32 v[92:93], v[94:95], v[92:93]
	v_add_f32_e32 v2, 1.0, v2
	v_rcp_f32_e32 v94, v2
	v_mul_f32_e32 v2, 0xbfb8aa3b, v79
	v_exp_f32_e32 v2, v2
	s_nop 0
	v_add_f32_e32 v2, 1.0, v2
	v_rcp_f32_e32 v95, v2
	s_nop 0
	v_pk_mul_f32 v[78:79], v[94:95], v[78:79]
	s_nop 0
	v_pk_mul_f32 v[78:79], v[78:79], v[88:89]
	v_cvt_pk_bf16_f32 v88, v92, v93
	v_cvt_pk_bf16_f32 v89, v78, v79
	global_store_dwordx2 v[76:77], v[88:89], off offset:1056
	v_mov_b64_e32 v[78:79], v[242:243]
	v_mov_b64_e32 v[92:93], v[192:193]
	v_mov_b64_e32 v[94:95], v[194:195]
	s_waitcnt lgkmcnt(0)
; __device__ __forceinline__ unsigned pk2(float lo, float hi) { const f32x2_t v = {lo, hi}; const bf16x2_t b = __builtin_convertvector(v, bf16x2_t); return __builtin_bit_cast(unsigned, b); }
; __device__ __forceinline__ float sigmoidf_(float x) { return __builtin_amdgcn_rcpf(1.0f + __expf(-x)); }
; template <int KIND>
; __device__ __forceinline__ void w_m3_core(const bf16x8 (&Qf)[4][2], const bf16x8 (&Kf)[4][2], const bf16x8 (&Sf)[4][2], const LAS bf16_t* vT, float lg,
;                                           const bf16_t* gsrc, const float* nw, bf16_t* ydst, int lo, int fq) {
;     ...
;             for (int hh = 0; hh < 2; ++hh) { const int mb = 2 * kk2 + hh;
;                 if (mb <= nb) { f32x4 s = {0.f, 0.f, 0.f, 0.f};
;                     s = __builtin_amdgcn_mfma_f32_16x16x32_bf16(Kf[mb][0], Qf[nb][0], s, 0, 0, 0); s = __builtin_amdgcn_mfma_f32_16x16x32_bf16(Kf[mb][1], Qf[nb][1], s, 0, 0, 0);
; #pragma unroll
;                     for (int r = 0; r < 4; ++r) { const int m = 16 * mb + 4 * fq + r, n = 16 * nb + lo; float v = s[r];
;                         if (KIND == 0) v *= __expf((float)(n - m) * lg);
;                         if (mb == nb) v = (m <= n) ? v : 0.f;
;                         pv[4 * hh + r] = v; }
;                 } else {
; #pragma unroll
;                     for (int r = 0; r < 4; ++r) pv[4 * hh + r] = 0.f; }
;             }
;     ...
;         for (int eb = 0; eb < 4; ++eb) { const int e0 = 16 * eb + 4 * fq;
;             const unsigned long long gw_ = *(const unsigned long long*)(gsrc + n * NIN + e0); const f32x4 w4 = *(const f32x4*)(nw + e0);
;             const float g0 = __uint_as_float((unsigned)gw_ << 16), g1 = __uint_as_float((unsigned)gw_ & 0xffff0000u), g2 = __uint_as_float((unsigned)(gw_ >> 32) << 16), g3 = __uint_as_float((unsigned)(gw_ >> 32) & 0xffff0000u);
;             const float o0 = O[eb][0] * rs * w4[0] * (g0 * sigmoidf_(g0)), o1 = O[eb][1] * rs * w4[1] * (g1 * sigmoidf_(g1));
;             const float o2 = O[eb][2] * rs * w4[2] * (g2 * sigmoidf_(g2)), o3 = O[eb][3] * rs * w4[3] * (g3 * sigmoidf_(g3));
;             *(unsigned long long*)(ydst + n * DM + e0) = (unsigned long long)pk2(o0, o1) | ((unsigned long long)pk2(o2, o3) << 32); }
	v_lshlrev_b32_e32 v88, 16, v78
	v_mul_f32_e32 v2, 0xbfb8aa3b, v88
	v_exp_f32_e32 v2, v2
	v_and_b32_e32 v89, 0xffff0000, v78
	v_lshlrev_b32_e32 v103, 16, v79
	v_and_b32_e32 v79, 0xffff0000, v79
	v_add_f32_e32 v2, 1.0, v2
	v_rcp_f32_e32 v104, v2
	v_mul_f32_e32 v2, 0xbfb8aa3b, v89
	v_exp_f32_e32 v2, v2
	v_pk_mul_f32 v[86:87], v[92:93], v[86:87]
	v_mul_f32_e32 v78, v85, v80
	v_mov_b32_e32 v84, v95
	v_add_f32_e32 v2, 1.0, v2
	v_rcp_f32_e32 v105, v2
	v_mul_f32_e32 v2, 0xbfb8aa3b, v103
	v_exp_f32_e32 v2, v2
	v_mul_f32_e32 v92, v0, v80
	v_pk_mul_f32 v[88:89], v[104:105], v[88:89]
	v_add_f32_e32 v2, 1.0, v2
	v_pk_mul_f32 v[86:87], v[88:89], v[86:87]
	v_rcp_f32_e32 v89, v2
	v_mul_f32_e32 v2, 0xbfb8aa3b, v79
	v_exp_f32_e32 v2, v2
	v_mov_b32_e32 v88, v94
	v_pk_mul_f32 v[88:89], v[88:89], v[102:103]
	v_add_f32_e32 v2, 1.0, v2
	v_rcp_f32_e32 v85, v2
	s_nop 0
	v_pk_mul_f32 v[78:79], v[84:85], v[78:79]
	v_cvt_pk_bf16_f32 v84, v86, v87
	v_mov_b32_e32 v86, v88
	v_mov_b32_e32 v87, v78
	v_mov_b32_e32 v78, v89
	v_pk_mul_f32 v[78:79], v[86:87], v[78:79]
	v_mul_f32_e32 v88, v82, v80
	v_cvt_pk_bf16_f32 v85, v78, v79
	global_store_dwordx2 v[76:77], v[84:85], off offset:1088
	v_mov_b64_e32 v[78:79], v[244:245]
	s_nop 0
	v_mov_b64_e32 v[84:85], v[196:197]
	v_mov_b64_e32 v[86:87], v[198:199]
	v_mul_f32_e32 v90, v83, v80
	s_waitcnt lgkmcnt(0)
	v_lshlrev_b32_e32 v89, 16, v78
	v_lshlrev_b32_e32 v93, 16, v79
	v_mul_f32_e32 v2, 0xbfb8aa3b, v89
	v_mul_f32_e32 v0, 0xbfb8aa3b, v93
	v_exp_f32_e32 v2, v2
	v_exp_f32_e32 v0, v0
	v_and_b32_e32 v91, 0xffff0000, v78
	v_and_b32_e32 v79, 0xffff0000, v79
	v_add_f32_e32 v2, 1.0, v2
	v_add_f32_e32 v0, 1.0, v0
	v_rcp_f32_e32 v95, v2
	v_mul_f32_e32 v2, 0xbfb8aa3b, v91
	v_mov_b32_e32 v82, v85
	v_rcp_f32_e32 v85, v0
	v_mul_f32_e32 v0, 0xbfb8aa3b, v79
	v_exp_f32_e32 v2, v2
	v_exp_f32_e32 v0, v0
	v_mul_f32_e32 v78, v1, v80
	v_mov_b32_e32 v94, v84
	v_add_f32_e32 v2, 1.0, v2
	v_add_f32_e32 v0, 1.0, v0
	v_rcp_f32_e32 v83, v2
	v_rcp_f32_e32 v1, v0
	v_mov_b32_e32 v84, v86
	v_mov_b32_e32 v0, v87
	v_pk_mul_f32 v[88:89], v[94:95], v[88:89]
	v_pk_mul_f32 v[82:83], v[82:83], v[90:91]
	v_pk_mul_f32 v[84:85], v[84:85], v[92:93]
	v_pk_mul_f32 v[0:1], v[0:1], v[78:79]
	v_mov_b32_e32 v78, v88
	v_mov_b32_e32 v79, v82
	v_mov_b32_e32 v82, v89
	v_mov_b32_e32 v80, v84
	v_mov_b32_e32 v81, v0
	v_mov_b32_e32 v0, v85
	v_pk_mul_f32 v[78:79], v[78:79], v[82:83]
	v_pk_mul_f32 v[0:1], v[80:81], v[0:1]
	v_cvt_pk_bf16_f32 v78, v78, v79
	v_cvt_pk_bf16_f32 v79, v0, v1
	global_store_dwordx2 v[76:77], v[78:79], off offset:1120
	v_sub_u32_e32 v2, v134, v124
	v_add_u32_e32 v1, v134, v143
	v_cvt_f32_i32_e32 v0, v2
	v_cvt_f32_i32_e32 v1, v1
	v_mfma_f32_16x16x32_bf16 v[64:67], v[64:67], v[8:11], 0
	v_mul_f32_e32 v0, v135, v0
	v_mul_f32_e32 v1, v135, v1
	v_mul_f32_e32 v0, 0x3fb8aa3b, v0
	v_mul_f32_e32 v1, 0x3fb8aa3b, v1
	v_mfma_f32_16x16x32_bf16 v[64:67], v[72:75], v[4:7], v[64:67]
	v_exp_f32_e32 v0, v0
	v_exp_f32_e32 v1, v1
	v_mfma_f32_16x16x32_bf16 v[60:63], v[60:63], v[8:11], 0
	v_mfma_f32_16x16x32_bf16 v[60:63], v[68:71], v[4:7], v[60:63]
	s_nop 3
	v_mul_f32_e64 v0, v0, v64
	v_mul_f32_e64 v1, v1, v65
	v_sub_u32_e32 v64, v134, v142
	v_cvt_pk_bf16_f32 v68, v0, v1
	v_subrev_u32_e32 v0, 32, v2
	v_sub_u32_e32 v1, v134, v107
	v_cvt_f32_i32_e32 v0, v0
	v_cvt_f32_i32_e32 v1, v1
	v_mfma_f32_16x16x32_bf16 v[44:47], v[44:47], v[8:11], 0
	v_sub_u32_e32 v2, v134, v108
	v_mul_f32_e32 v0, v135, v0
	v_mul_f32_e32 v1, v135, v1
	v_cvt_f32_i32_e32 v2, v2
	v_mul_f32_e32 v0, 0x3fb8aa3b, v0
	v_mul_f32_e32 v1, 0x3fb8aa3b, v1
	v_mfma_f32_16x16x32_bf16 v[44:47], v[48:51], v[4:7], v[44:47]
	v_exp_f32_e32 v0, v0
	v_exp_f32_e32 v1, v1
	v_mul_f32_e32 v2, v135, v2
	v_mul_f32_e32 v2, 0x3fb8aa3b, v2
	v_sub_u32_e32 v65, v134, v141
	s_nop 2
	v_pk_mul_f32 v[0:1], v[0:1], v[44:45]
	v_exp_f32_e32 v44, v2
	v_sub_u32_e32 v2, v134, v106
	v_cvt_f32_i32_e32 v2, v2
	v_cvt_f32_i32_e32 v64, v64
	v_cvt_f32_i32_e32 v65, v65
	v_mfma_f32_16x16x32_bf16 v[20:23], v[20:23], v[8:11], 0
	v_mul_f32_e32 v2, v135, v2
	v_mul_f32_e32 v2, 0x3fb8aa3b, v2
	v_exp_f32_e32 v45, v2
	v_mul_f32_e32 v64, v135, v64
	v_mul_f32_e32 v65, v135, v65
	v_mul_f32_e32 v64, 0x3fb8aa3b, v64
	v_pk_mul_f32 v[48:49], v[44:45], v[46:47]
	v_mfma_f32_16x16x32_bf16 v[44:47], v[52:55], v[8:11], 0
	v_mul_f32_e32 v65, 0x3fb8aa3b, v65
	v_exp_f32_e32 v64, v64
	v_exp_f32_e32 v65, v65
	v_mfma_f32_16x16x32_bf16 v[44:47], v[56:59], v[4:7], v[44:47]
	v_mul_f32_e64 v64, v64, v66
	v_mul_f32_e64 v65, v65, v67
	v_sub_u32_e32 v66, v134, v140
	v_sub_u32_e32 v67, v134, v115
	s_nop 3
	v_mul_f32_e32 v2, v139, v44
	v_add_u32_e32 v44, 49, v124
	v_sub_u32_e32 v50, v134, v44
	v_cvt_f32_i32_e32 v50, v50
	v_cvt_f32_i32_e32 v66, v66
	v_cvt_f32_i32_e32 v67, v67
	v_cndmask_b32_e64 v2, v2, 0, vcc
	v_mul_f32_e32 v50, v135, v50
	v_mul_f32_e32 v50, 0x3fb8aa3b, v50
	v_exp_f32_e32 v50, v50
	v_cmp_ge_i32_e32 vcc, v134, v44
	v_add_u32_e32 v44, 50, v124
	v_mul_f32_e32 v66, v135, v66
	v_mul_f32_e32 v45, v50, v45
	v_cndmask_b32_e32 v50, 0, v45, vcc
	v_sub_u32_e32 v45, v134, v44
	v_cvt_f32_i32_e32 v45, v45
	v_mul_f32_e32 v67, v135, v67
	v_mul_f32_e32 v66, 0x3fb8aa3b, v66
	v_mul_f32_e32 v67, 0x3fb8aa3b, v67
	v_exp_f32_e32 v66, v66
	v_exp_f32_e32 v67, v67
	v_mul_f32_e32 v45, v135, v45
	v_mul_f32_e32 v45, 0x3fb8aa3b, v45
	v_exp_f32_e32 v45, v45
	v_pk_mul_f32 v[60:61], v[66:67], v[60:61]
	v_sub_u32_e32 v66, v134, v116
	v_sub_u32_e32 v67, v134, v114
	v_cvt_f32_i32_e32 v66, v66
	v_cvt_f32_i32_e32 v67, v67
	v_mul_f32_e32 v45, v45, v46
	v_cmp_ge_i32_e32 vcc, v134, v44
	v_add_u32_e32 v44, 51, v124
	v_mul_f32_e32 v66, v135, v66
	v_cndmask_b32_e32 v51, 0, v45, vcc
	v_sub_u32_e32 v45, v134, v44
	v_mul_f32_e32 v67, v135, v67
	v_cvt_f32_i32_e32 v45, v45
	v_mul_f32_e32 v66, 0x3fb8aa3b, v66
	v_mul_f32_e32 v67, 0x3fb8aa3b, v67
	v_exp_f32_e32 v66, v66
	v_exp_f32_e32 v67, v67
	v_mul_f32_e32 v45, v135, v45
	v_mul_f32_e32 v45, 0x3fb8aa3b, v45
	v_exp_f32_e32 v45, v45
	v_pk_mul_f32 v[62:63], v[66:67], v[62:63]
	v_cvt_pk_bf16_f32 v69, v64, v65
	v_cvt_pk_bf16_f32 v70, v60, v61
	v_cvt_pk_bf16_f32 v71, v62, v63
	ds_read_b64_tr_b16 v[62:63], v126
	ds_read_b64_tr_b16 v[66:67], v126 offset:32
	ds_read_b64_tr_b16 v[60:61], v128
	ds_read_b64_tr_b16 v[64:65], v128 offset:32
	v_mul_f32_e32 v45, v45, v47
	v_cmp_ge_i32_e32 vcc, v134, v44
	s_waitcnt lgkmcnt(0)
; __device__ __forceinline__ float bperm_f(int src_lane, float v) { return __builtin_bit_cast(float, __builtin_amdgcn_ds_bpermute(src_lane << 2, __builtin_bit_cast(int, v))); }
; __device__ __forceinline__ bf16x8 pack_frag(const float (&v)[8]) { return __builtin_bit_cast(bf16x8, pack8(v)); }
; template <int KIND>
; __device__ __forceinline__ void w_m3_core(const bf16x8 (&Qf)[4][2], const bf16x8 (&Kf)[4][2], const bf16x8 (&Sf)[4][2], const LAS bf16_t* vT, float lg,
;                                           const bf16_t* gsrc, const float* nw, bf16_t* ydst, int lo, int fq) {
;     ...
;             const bf16x8 Pf = pack_frag(pv);
; #pragma unroll
;             for (int eb = 0; eb < 4; ++eb)
;                 O[eb] = __builtin_amdgcn_mfma_f32_16x16x32_bf16(tr_frag(vT, 32 * kk2 + 4 * fq, 32 * kk2 + 16 + 4 * fq, 16 * eb, lo), Pf, O[eb], 0, 0, 0);
;         }
; #pragma unroll
;         for (int kk = 0; kk < 2; ++kk)
; #pragma unroll
;             for (int eb = 0; eb < 4; ++eb) O2[eb] = __builtin_amdgcn_mfma_f32_16x16x32_bf16(Sf[eb][kk], Qf[nb][kk], O2[eb], 0, 0, 0);
;         const float osc = KIND == 0 ? __expf((float)(16 * nb + lo + 1) * lg) : 1.0f;
; #pragma unroll
;         for (int eb = 0; eb < 4; ++eb) O[eb] = O[eb] + O2[eb] * osc;
;         float ss = 0.f;
; #pragma unroll
;         for (int eb = 0; eb < 4; ++eb) ss += (O[eb][0] * O[eb][0] + O[eb][1] * O[eb][1]) + (O[eb][2] * O[eb][2] + O[eb][3] * O[eb][3]);
;         { const int ln = (fq << 4) | lo; ss += bperm_f(ln ^ 16, ss); ss += bperm_f(ln ^ 32, ss); }
;         const float rs = rsqrtf(ss * (1.0f / 64.0f) + EPS);
;         const size_t n = 16 * nb + lo;
; #pragma unroll
	v_mfma_f32_16x16x32_bf16 v[72:75], v[60:63], v[68:71], 0
	v_cndmask_b32_e32 v47, 0, v45, vcc
	v_cvt_pk_bf16_f32 v45, v48, v49
	v_cvt_pk_bf16_f32 v46, v2, v50
	v_mfma_f32_16x16x32_bf16 v[60:63], v[64:67], v[68:71], 0
	ds_read_b64_tr_b16 v[64:65], v128 offset:64
	ds_read_b64_tr_b16 v[66:67], v126 offset:64
	ds_read_b64_tr_b16 v[76:77], v128 offset:96
	ds_read_b64_tr_b16 v[78:79], v126 offset:96
	v_cvt_pk_bf16_f32 v47, v51, v47
	ds_read_b64_tr_b16 v[48:49], v128 offset:4608
	ds_read_b64_tr_b16 v[50:51], v126 offset:4608
	ds_read_b64_tr_b16 v[52:53], v128 offset:4640
	ds_read_b64_tr_b16 v[54:55], v126 offset:4640
	v_cvt_pk_bf16_f32 v44, v0, v1
	ds_read_b64_tr_b16 v[56:57], v128 offset:4672
	ds_read_b64_tr_b16 v[58:59], v126 offset:4672
	s_waitcnt lgkmcnt(0)
	v_mfma_f32_16x16x32_bf16 v[52:55], v[52:55], v[44:47], v[60:63]
	s_nop 2
	ds_read_b64_tr_b16 v[60:61], v128 offset:4704
	ds_read_b64_tr_b16 v[62:63], v126 offset:4704
	v_add_u32_e32 v0, 49, v133
	v_cvt_f32_ubyte0_e32 v0, v0
	v_mfma_f32_16x16x32_bf16 v[64:67], v[64:67], v[68:71], 0
	v_mul_f32_e32 v0, v135, v0
	v_mul_f32_e32 v0, 0x3fb8aa3b, v0
	v_exp_f32_e32 v2, v0
	v_mfma_f32_16x16x32_bf16 v[68:71], v[76:79], v[68:71], 0
	v_mfma_f32_16x16x32_bf16 v[24:27], v[24:27], v[8:11], 0
	v_mfma_f32_16x16x32_bf16 v[36:39], v[36:39], v[8:11], 0
	v_mfma_f32_16x16x32_bf16 v[8:11], v[40:43], v[8:11], 0
	v_mfma_f32_16x16x32_bf16 v[48:51], v[48:51], v[44:47], v[72:75]
	v_mfma_f32_16x16x32_bf16 v[12:15], v[12:15], v[4:7], v[20:23]
	v_mfma_f32_16x16x32_bf16 v[56:59], v[56:59], v[44:47], v[64:67]
	s_waitcnt lgkmcnt(0)
	v_mfma_f32_16x16x32_bf16 v[44:47], v[60:63], v[44:47], v[68:71]
	s_nop 4
	v_fma_f32 v22, v2, v14, v50
	v_fma_f32 v23, v2, v15, v51
	v_mfma_f32_16x16x32_bf16 v[18:21], v[16:19], v[4:7], v[24:27]
	v_mfma_f32_16x16x32_bf16 v[26:29], v[28:31], v[4:7], v[36:39]
	s_nop 1
	v_fma_f32 v24, v2, v12, v48
	v_fma_f32 v25, v2, v13, v49
	s_nop 2
	v_pk_fma_f32 v[16:17], v[2:3], v[20:21], v[54:55] op_sel_hi:[0,1,1]
	v_pk_fma_f32 v[18:19], v[2:3], v[18:19], v[52:53] op_sel_hi:[0,1,1]
	v_mfma_f32_16x16x32_bf16 v[4:7], v[32:35], v[4:7], v[8:11]
	v_fma_f32 v12, v2, v28, v58
	v_fma_f32 v13, v2, v29, v59
	s_nop 5
	v_pk_fma_f32 v[0:1], v[2:3], v[6:7], v[46:47] op_sel_hi:[0,1,1]
	v_pk_fma_f32 v[10:11], v[2:3], v[4:5], v[44:45] op_sel_hi:[0,1,1]
	v_pk_mul_f32 v[4:5], v[22:23], v[22:23]
	v_pk_mul_f32 v[6:7], v[24:25], v[24:25]
	v_pk_fma_f32 v[14:15], v[2:3], v[26:27], v[56:57] op_sel_hi:[0,1,1]
	v_pk_mov_b32 v[8:9], v[6:7], v[4:5] op_sel:[1,0]
	v_mov_b32_e32 v7, v5
	v_pk_add_f32 v[4:5], v[8:9], v[6:7]
	v_pk_mul_f32 v[6:7], v[16:17], v[16:17]
	v_pk_mul_f32 v[8:9], v[18:19], v[18:19]
	v_mul_f32_e32 v2, v10, v10
	v_pk_mov_b32 v[20:21], v[8:9], v[6:7] op_sel:[1,0]
	v_mov_b32_e32 v9, v7
	v_pk_add_f32 v[6:7], v[20:21], v[8:9]
	v_mul_f32_e32 v8, v11, v11
	v_pk_add_f32 v[4:5], v[4:5], v[4:5] op_sel:[0,1] op_sel_hi:[1,0]
	v_pk_add_f32 v[6:7], v[6:7], v[6:7] op_sel:[0,1] op_sel_hi:[1,0]
	v_mov_b32_e32 v5, v2
	v_mov_b32_e32 v7, v8
	v_mul_f32_e32 v2, v15, v15
	v_mul_f32_e32 v9, v0, v0
	v_pk_add_f32 v[4:5], v[4:5], v[6:7]
	v_pk_fma_f32 v[6:7], v[14:15], v[14:15], v[2:3] op_sel_hi:[1,1,0]
	v_mul_f32_e32 v2, v13, v13
	v_mul_f32_e32 v20, v1, v1
	v_mov_b32_e32 v7, v9
	v_pk_fma_f32 v[8:9], v[12:13], v[12:13], v[2:3] op_sel_hi:[1,1,0]
	s_nop 0
	v_mov_b32_e32 v9, v20
	v_pk_add_f32 v[6:7], v[6:7], v[8:9]
	s_nop 0
	v_pk_add_f32 v[4:5], v[4:5], v[6:7]
	s_nop 0
	v_add_f32_e32 v2, v4, v5
	ds_bpermute_b32 v4, v138, v2
	s_waitcnt lgkmcnt(0)
	v_add_f32_e32 v2, v2, v4
	ds_bpermute_b32 v4, v137, v2
	s_waitcnt lgkmcnt(0)
	v_add_f32_e32 v2, v2, v4
	v_fmamk_f32 v2, v2, 0x3c800000, v200
	v_cmp_gt_f32_e32 vcc, s29, v2
	v_mul_f32_e32 v4, 0x4b800000, v2
	s_nop 0
	v_cndmask_b32_e32 v2, v2, v4, vcc
	v_rsq_f32_e32 v2, v2
	s_nop 0
	v_mul_f32_e32 v4, 0x45800000, v2
	v_cndmask_b32_e32 v8, v2, v4, vcc
	v_mad_u64_u32 v[4:5], s[20:21], v134, s72, v[98:99]
	v_lshl_add_u64 v[20:21], v[4:5], 0, v[96:97]
	v_mov_b64_e32 v[28:29], v[246:247]
	v_mov_b64_e32 v[4:5], v[184:185]
	v_mov_b64_e32 v[6:7], v[186:187]
	v_lshlrev_b32_e32 v2, 11, v134
	v_lshl_add_u64 v[26:27], s[40:41], 0, v[2:3]
	v_pk_mul_f32 v[24:25], v[24:25], v[8:9] op_sel_hi:[1,0]
	v_pk_mul_f32 v[22:23], v[22:23], v[8:9] op_sel_hi:[1,0]
	v_pk_mul_f32 v[18:19], v[18:19], v[8:9] op_sel_hi:[1,0]
	v_pk_mul_f32 v[16:17], v[16:17], v[8:9] op_sel_hi:[1,0]
	v_pk_mul_f32 v[14:15], v[14:15], v[8:9] op_sel_hi:[1,0]
	s_waitcnt lgkmcnt(0)
; __device__ __forceinline__ unsigned pk2(float lo, float hi) { const f32x2_t v = {lo, hi}; const bf16x2_t b = __builtin_convertvector(v, bf16x2_t); return __builtin_bit_cast(unsigned, b); }
; __device__ __forceinline__ float sigmoidf_(float x) { return __builtin_amdgcn_rcpf(1.0f + __expf(-x)); }
; template <int KIND>
; __device__ __forceinline__ void w_m3_core(const bf16x8 (&Qf)[4][2], const bf16x8 (&Kf)[4][2], const bf16x8 (&Sf)[4][2], const LAS bf16_t* vT, float lg,
;                                           const bf16_t* gsrc, const float* nw, bf16_t* ydst, int lo, int fq) {
;     ...
;         for (int eb = 0; eb < 4; ++eb) { const int e0 = 16 * eb + 4 * fq;
;             const unsigned long long gw_ = *(const unsigned long long*)(gsrc + n * NIN + e0); const f32x4 w4 = *(const f32x4*)(nw + e0);
;             const float g0 = __uint_as_float((unsigned)gw_ << 16), g1 = __uint_as_float((unsigned)gw_ & 0xffff0000u), g2 = __uint_as_float((unsigned)(gw_ >> 32) << 16), g3 = __uint_as_float((unsigned)(gw_ >> 32) & 0xffff0000u);
;             const float o0 = O[eb][0] * rs * w4[0] * (g0 * sigmoidf_(g0)), o1 = O[eb][1] * rs * w4[1] * (g1 * sigmoidf_(g1));
;             const float o2 = O[eb][2] * rs * w4[2] * (g2 * sigmoidf_(g2)), o3 = O[eb][3] * rs * w4[3] * (g3 * sigmoidf_(g3));
;             *(unsigned long long*)(ydst + n * DM + e0) = (unsigned long long)pk2(o0, o1) | ((unsigned long long)pk2(o2, o3) << 32); }
;         asm volatile("" ::: "memory");
;         __builtin_amdgcn_sched_barrier(0);
	v_lshlrev_b32_e32 v30, 16, v28
	v_mul_f32_e32 v2, 0xbfb8aa3b, v30
	v_exp_f32_e32 v2, v2
	v_and_b32_e32 v31, 0xffff0000, v28
	v_lshlrev_b32_e32 v28, 16, v29
	v_and_b32_e32 v29, 0xffff0000, v29
	v_add_f32_e32 v2, 1.0, v2
	v_rcp_f32_e32 v32, v2
	v_mul_f32_e32 v2, 0xbfb8aa3b, v31
	v_exp_f32_e32 v2, v2
	v_pk_mul_f32 v[4:5], v[4:5], v[24:25]
	v_pk_mul_f32 v[6:7], v[6:7], v[22:23]
	v_add_f32_e32 v2, 1.0, v2
	v_rcp_f32_e32 v33, v2
	v_mul_f32_e32 v2, 0xbfb8aa3b, v28
	v_exp_f32_e32 v2, v2
	v_pk_mul_f32 v[24:25], v[32:33], v[30:31]
	s_nop 0
	v_pk_mul_f32 v[4:5], v[24:25], v[4:5]
	v_add_f32_e32 v2, 1.0, v2
	v_rcp_f32_e32 v24, v2
	v_mul_f32_e32 v2, 0xbfb8aa3b, v29
	v_exp_f32_e32 v2, v2
	s_nop 0
	v_add_f32_e32 v2, 1.0, v2
	v_rcp_f32_e32 v25, v2
	s_nop 0
	v_pk_mul_f32 v[22:23], v[24:25], v[28:29]
	s_nop 0
	v_pk_mul_f32 v[6:7], v[22:23], v[6:7]
	v_cvt_pk_bf16_f32 v22, v4, v5
	v_cvt_pk_bf16_f32 v23, v6, v7
	v_lshl_add_u64 v[4:5], v[26:27], 0, v[96:97]
	global_store_dwordx2 v[4:5], v[22:23], off offset:1024
	v_mov_b64_e32 v[6:7], v[248:249]
	s_nop 0
	v_mov_b64_e32 v[22:23], v[188:189]
	v_mov_b64_e32 v[24:25], v[190:191]
	s_waitcnt lgkmcnt(0)
	v_lshlrev_b32_e32 v26, 16, v6
	v_mul_f32_e32 v2, 0xbfb8aa3b, v26
	v_exp_f32_e32 v2, v2
	v_and_b32_e32 v27, 0xffff0000, v6
	v_lshlrev_b32_e32 v6, 16, v7
	v_and_b32_e32 v7, 0xffff0000, v7
	v_add_f32_e32 v2, 1.0, v2
	v_rcp_f32_e32 v28, v2
	v_mul_f32_e32 v2, 0xbfb8aa3b, v27
	v_exp_f32_e32 v2, v2
	v_pk_mul_f32 v[18:19], v[22:23], v[18:19]
	v_pk_mul_f32 v[16:17], v[24:25], v[16:17]
	v_mul_f32_e32 v24, v12, v8
	v_add_f32_e32 v2, 1.0, v2
	v_rcp_f32_e32 v29, v2
	v_mul_f32_e32 v2, 0xbfb8aa3b, v6
	v_exp_f32_e32 v2, v2
	v_pk_mul_f32 v[22:23], v[28:29], v[26:27]
	s_nop 0
	v_pk_mul_f32 v[18:19], v[22:23], v[18:19]
	v_add_f32_e32 v2, 1.0, v2
	v_rcp_f32_e32 v22, v2
	v_mul_f32_e32 v2, 0xbfb8aa3b, v7
	v_exp_f32_e32 v2, v2
	s_nop 0
	v_add_f32_e32 v2, 1.0, v2
	v_rcp_f32_e32 v23, v2
	s_nop 0
	v_pk_mul_f32 v[6:7], v[22:23], v[6:7]
	s_nop 0
	v_pk_mul_f32 v[6:7], v[6:7], v[16:17]
	v_cvt_pk_bf16_f32 v16, v18, v19
	v_cvt_pk_bf16_f32 v17, v6, v7
	global_store_dwordx2 v[4:5], v[16:17], off offset:1056
	v_mov_b64_e32 v[6:7], v[250:251]
	s_nop 0
	v_mov_b64_e32 v[16:17], v[192:193]
	v_mov_b64_e32 v[18:19], v[194:195]
	s_waitcnt lgkmcnt(0)
	v_lshlrev_b32_e32 v22, 16, v6
	v_mul_f32_e32 v2, 0xbfb8aa3b, v22
	v_exp_f32_e32 v2, v2
	v_and_b32_e32 v23, 0xffff0000, v6
	v_lshlrev_b32_e32 v25, 16, v7
	v_and_b32_e32 v7, 0xffff0000, v7
	v_add_f32_e32 v2, 1.0, v2
	v_rcp_f32_e32 v26, v2
	v_mul_f32_e32 v2, 0xbfb8aa3b, v23
	v_exp_f32_e32 v2, v2
	v_pk_mul_f32 v[14:15], v[16:17], v[14:15]
	v_mul_f32_e32 v6, v13, v8
	v_mov_b32_e32 v12, v19
	v_add_f32_e32 v2, 1.0, v2
	v_rcp_f32_e32 v27, v2
	v_mul_f32_e32 v2, 0xbfb8aa3b, v25
	v_exp_f32_e32 v2, v2
	v_pk_mul_f32 v[16:17], v[26:27], v[22:23]
	s_nop 0
	v_pk_mul_f32 v[14:15], v[16:17], v[14:15]
	v_add_f32_e32 v2, 1.0, v2
	v_rcp_f32_e32 v17, v2
	v_mul_f32_e32 v2, 0xbfb8aa3b, v7
	v_exp_f32_e32 v2, v2
	v_mov_b32_e32 v16, v18
	v_pk_mul_f32 v[16:17], v[16:17], v[24:25]
	v_mul_f32_e32 v18, v11, v8
	v_add_f32_e32 v2, 1.0, v2
	v_rcp_f32_e32 v13, v2
	s_nop 0
	v_pk_mul_f32 v[6:7], v[12:13], v[6:7]
	v_cvt_pk_bf16_f32 v12, v14, v15
	v_mov_b32_e32 v14, v16
	v_mov_b32_e32 v15, v6
	v_mov_b32_e32 v6, v17
	v_pk_mul_f32 v[6:7], v[14:15], v[6:7]
	v_mul_f32_e32 v16, v10, v8
	v_cvt_pk_bf16_f32 v13, v6, v7
	global_store_dwordx2 v[4:5], v[12:13], off offset:1088
	v_mov_b64_e32 v[6:7], v[252:253]
	s_nop 0
	v_mov_b64_e32 v[12:13], v[196:197]
	v_mov_b64_e32 v[14:15], v[198:199]
	v_mul_f32_e32 v20, v0, v8
	s_waitcnt lgkmcnt(0)
	v_lshlrev_b32_e32 v17, 16, v6
	v_lshlrev_b32_e32 v21, 16, v7
	v_mul_f32_e32 v2, 0xbfb8aa3b, v17
	v_mul_f32_e32 v0, 0xbfb8aa3b, v21
	v_exp_f32_e32 v2, v2
	v_exp_f32_e32 v0, v0
	v_and_b32_e32 v19, 0xffff0000, v6
	v_and_b32_e32 v7, 0xffff0000, v7
	v_add_f32_e32 v2, 1.0, v2
	v_add_f32_e32 v0, 1.0, v0
	v_rcp_f32_e32 v23, v2
	v_mul_f32_e32 v2, 0xbfb8aa3b, v19
	v_mov_b32_e32 v10, v13
	v_rcp_f32_e32 v13, v0
	v_mul_f32_e32 v0, 0xbfb8aa3b, v7
	v_exp_f32_e32 v2, v2
	v_exp_f32_e32 v0, v0
	v_mul_f32_e32 v6, v1, v8
	v_mov_b32_e32 v22, v12
	v_add_f32_e32 v2, 1.0, v2
	v_add_f32_e32 v0, 1.0, v0
	v_rcp_f32_e32 v11, v2
	v_rcp_f32_e32 v1, v0
	v_mov_b32_e32 v12, v14
	v_mov_b32_e32 v0, v15
	v_pk_mul_f32 v[16:17], v[22:23], v[16:17]
	v_pk_mul_f32 v[10:11], v[10:11], v[18:19]
	v_pk_mul_f32 v[12:13], v[12:13], v[20:21]
	v_pk_mul_f32 v[0:1], v[0:1], v[6:7]
	v_mov_b32_e32 v6, v16
	v_mov_b32_e32 v7, v10
	v_mov_b32_e32 v10, v17
	v_mov_b32_e32 v8, v12
	v_mov_b32_e32 v9, v0
	v_mov_b32_e32 v0, v13
	v_pk_mul_f32 v[6:7], v[6:7], v[10:11]
	v_pk_mul_f32 v[0:1], v[8:9], v[0:1]
	v_cvt_pk_bf16_f32 v6, v6, v7
	v_cvt_pk_bf16_f32 v7, v0, v1
	global_store_dwordx2 v[4:5], v[6:7], off offset:1120
	s_waitcnt lgkmcnt(0)
	s_branch .LBB0_186

; #define LAS __attribute__((address_space(3)))
; __device__ __forceinline__ void ld8bf(const bf16_t* p, float (&o)[8]) { unpack8(*(const u32x4*)p, o); }
; __device__ __forceinline__ void w_hg_m3(const Args& a, int l, unsigned char* ws, const bf16_t* proj, bf16_t* y, LAS unsigned char* wl, int b, int ck_, int h, int lane) {
;     LAS bf16_t* vT = (LAS bf16_t*)wl;
;     const int row0 = b * SEQ + 64 * ck_, lo = lane & 15, fq = lane >> 4;
;     w_store_vT(vT, proj + (size_t)row0 * NIN + C_HI + 64 * h, lane);
;     bf16x8 Qf[4][2], Kf[4][2], Sf[4][2]; float er[2][8];
;     const bf16_t* Sb = (const bf16_t*)((const unsigned char*)a.out + OUT_SBH) + (size_t)((b * NCH + ck_) * 4 + h) * 4096;
; #pragma unroll
;     for (int kk = 0; kk < 2; ++kk) { float bb[4][8], r31[8], r63[8], lbv[8];
; #pragma unroll
;         for (int j = 0; j < 8; ++j) lbv[j] = hg_lb(a, l, 64 * h + 32 * kk + 8 * fq + j);
;         const bf16_t* fsrc = proj + (size_t)row0 * NIN + C_HF + 64 * h + 32 * kk + 8 * fq;
;         w_hg_scan(lbv, fsrc, lane, bb, r31, r63);
; #pragma unroll
;         for (int tb = 0; tb < 4; ++tb) { float fp[8], qv[8], a1[8], a2[8];
;             ld8bf(fsrc + (size_t)(16 * tb + lo) * NIN, fp); ld8bf(proj + (size_t)(row0 + 16 * tb + lo) * NIN + C_HQ + 64 * h + 32 * kk + 8 * fq, qv);
.LBB0_191:
	s_setprio 0
	s_lshr_b32 s20, s66, 8
	s_lshr_b32 s21, s66, 9
	s_add_i32 s20, s20, s66
	s_and_b32 s21, s21, 12
	s_add_i32 s20, s20, s21
	s_and_b32 s70, s20, 15
	s_cmp_lt_u32 s70, 12
	s_cbranch_scc1 .LBB0_190
	s_ashr_i32 s21, s66, 31
	s_ashr_i32 s20, s66, 4
	s_lshr_b32 s21, s21, 25
	s_add_i32 s21, s20, s21
	s_ashr_i32 s71, s21, 7
	s_and_b32 s21, s21, 0xffffff80
	s_sub_i32 s90, s20, s21
	s_lshl_b32 s20, s71, 13
	s_lshl_b32 s21, s90, 6
	s_add_i32 s86, s21, s20
	s_add_i32 s70, s70, -12
	s_mul_i32 s21, s86, 0x1800
	s_mul_hi_i32 s20, s86, 0x1800
	s_add_u32 s67, s8, s21
	v_mov_b32_e32 v10, v132
	s_addc_u32 s68, s9, s20
	s_lshl_b32 s24, s70, 6
	s_lshl_b32 s20, s70, 7
	s_add_u32 s20, s67, s20
	v_lshlrev_b32_e32 v0, 4, v10
	s_addc_u32 s21, s68, 0
	v_and_b32_e32 v2, 0x70, v0
	v_lshl_add_u64 v[0:1], s[20:21], 0, v[2:3]
	s_mov_b64 s[20:21], 0x1400
	v_ashrrev_i32_e32 v8, 3, v10
	v_lshl_add_u64 v[0:1], v[0:1], 0, s[20:21]
	v_mad_i64_i32 v[4:5], s[20:21], v8, s72, v[0:1]
	global_load_dwordx4 v[60:63], v[4:5], off
	v_add_u32_e32 v4, 8, v8
	v_mad_i64_i32 v[4:5], s[20:21], v4, s72, v[0:1]
	global_load_dwordx4 v[64:67], v[4:5], off
	v_add_u32_e32 v4, 16, v8
	v_mad_i64_i32 v[4:5], s[20:21], v4, s72, v[0:1]
	global_load_dwordx4 v[70:73], v[4:5], off
	v_add_u32_e32 v4, 24, v8
	v_mad_i64_i32 v[4:5], s[20:21], v4, s72, v[0:1]
	global_load_dwordx4 v[74:77], v[4:5], off
	v_add_u32_e32 v4, 32, v8
	v_mad_i64_i32 v[4:5], s[20:21], v4, s72, v[0:1]
	global_load_dwordx4 v[78:81], v[4:5], off
	v_add_u32_e32 v4, 40, v8
	v_mad_i64_i32 v[4:5], s[20:21], v4, s72, v[0:1]
	global_load_dwordx4 v[88:91], v[4:5], off
	v_add_u32_e32 v4, 48, v8
	v_mad_i64_i32 v[4:5], s[20:21], v4, s72, v[0:1]
	global_load_dwordx4 v[92:95], v[4:5], off
	v_add_u32_e32 v4, 56, v8
	v_mad_i64_i32 v[0:1], s[20:21], v4, s72, v[0:1]
	global_load_dwordx4 v[96:99], v[0:1], off
	v_and_b32_e32 v196, 15, v10
	v_lshrrev_b32_e32 v197, 4, v10
	v_mul_u32_u24_e32 v196, 0x1800, v196
	v_lshl_add_u32 v196, v197, 4, v196
	s_lshl_b32 s20, s24, 1
	s_addk_i32 s20, 0x1200
	v_add_u32_e32 v196, s20, v196
	v_add_co_u32_e32 v198, vcc, s67, v196
	v_mov_b32_e32 v199, s68
	s_nop 0
	v_addc_co_u32_e32 v199, vcc, 0, v199, vcc
	global_load_dwordx4 v[222:225], v[198:199], off
	global_load_dwordx4 v[238:241], v[198:199], off offset:64
	v_add_u32_e32 v196, 0x18000, v196
	v_add_co_u32_e32 v198, vcc, s67, v196
	v_mov_b32_e32 v199, s68
	s_nop 0
	v_addc_co_u32_e32 v199, vcc, 0, v199, vcc
	global_load_dwordx4 v[226:229], v[198:199], off
	global_load_dwordx4 v[242:245], v[198:199], off offset:64
	v_add_u32_e32 v196, 0x18000, v196
	v_add_co_u32_e32 v198, vcc, s67, v196
	v_mov_b32_e32 v199, s68
	s_nop 0
	v_addc_co_u32_e32 v199, vcc, 0, v199, vcc
	global_load_dwordx4 v[230:233], v[198:199], off
	global_load_dwordx4 v[246:249], v[198:199], off offset:64
	v_add_u32_e32 v196, 0x18000, v196
	v_add_co_u32_e32 v198, vcc, s67, v196
	v_mov_b32_e32 v199, s68
	s_nop 0
	v_addc_co_u32_e32 v199, vcc, 0, v199, vcc
	global_load_dwordx4 v[234:237], v[198:199], off
	global_load_dwordx4 v[250:253], v[198:199], off offset:64
	v_mul_lo_u32 v9, v8, s23
	v_add3_u32 v2, s2, v2, v9
	v_ashrrev_i32_e32 v108, 4, v10
	v_mov_b32_e32 v43, 0
	s_and_b64 vcc, exec, s[14:15]
	v_mov_b32_e32 v42, 0
	v_mov_b32_e32 v154, v2
	v_lshlrev_b32_e32 v0, 3, v108
	v_add_u32_e32 v36, s24, v0
	v_ashrrev_i32_e32 v37, 31, v36
	s_cbranch_vccnz .LBB0_466
	v_cndmask_b32_e64 v1, 0, 1, s[14:15]
	v_cmp_ne_u32_e64 s[38:39], 1, v1
	s_andn2_b64 vcc, exec, s[14:15]
	s_cbranch_vccz .LBB0_467

; #define LAS __attribute__((address_space(3)))
; __device__ __forceinline__ u32x4 pack8(const float (&v)[8]) { u32x4 w; w.x = pk2(v[0], v[1]); w.y = pk2(v[2], v[3]); w.z = pk2(v[4], v[5]); w.w = pk2(v[6], v[7]); return w; }
; __device__ __forceinline__ void ld8bf(const bf16_t* p, float (&o)[8]) { unpack8(*(const u32x4*)p, o); }
; __device__ __forceinline__ float ret_lg(int h) { return log1pf(-exp2f(-5.0f - (float)h)); }
; __device__ __forceinline__ void w_ret_m1(unsigned char* ws, const bf16_t* proj, LAS unsigned char* wl, int b, int ck_, int h, int lane) {
;     LAS bf16_t* vT = (LAS bf16_t*)wl; LAS bf16_t* kT = (LAS bf16_t*)(wl + TILE_B);
;     const int row0 = b * SEQ + 64 * ck_, lo = lane & 15, fq = lane >> 4; const float lg = ret_lg(h);
;     const float* cosT = (const float*)(ws + WS_ROPE); const float* sinT = cosT + SEQ * 32;
; #pragma unroll
;     for (int i = 0; i < 4; ++i) { const int m = (lane >> 2) + 16 * i, cp = lane & 3; float x1[8], x2[8];
;         const bf16_t* src = proj + (size_t)(row0 + m) * NIN + C_RK + 64 * h; ld8bf(src + 8 * cp, x1); ld8bf(src + 32 + 8 * cp, x2);
;         const float* cp_ = cosT + (64 * ck_ + m) * 32 + 8 * cp; const float* sp_ = sinT + (64 * ck_ + m) * 32 + 8 * cp;
;         const float sc = 0.125f * __expf((float)(63 - m) * lg);
;         float o1[8], o2[8];
; #pragma unroll
;         for (int j = 0; j < 8; ++j) { const float cs = cp_[j], sn = sp_[j]; o1[j] = (x1[j] * cs - x2[j] * sn) * sc; o2[j] = (x2[j] * cs + x1[j] * sn) * sc; }
;         *(LAS u32x4*)(kT + m * LD + 8 * cp) = pack8(o1); *(LAS u32x4*)(kT + m * LD + 32 + 8 * cp) = pack8(o2); }
.LBB0_516:
	s_setprio 1
	s_lshr_b32 s21, s20, 8
	s_lshr_b32 s24, s20, 9
	s_add_i32 s21, s21, s20
	s_and_b32 s24, s24, 12
	s_add_i32 s21, s21, s24
	s_and_b32 s24, s21, 12
	s_cmp_lg_u32 s24, 8
	s_cbranch_scc1 .LBB0_515
	s_and_b32 s34, s21, 11
	s_ashr_i32 s21, s20, 31
	s_ashr_i32 s24, s20, 4
	s_lshr_b32 s21, s21, 25
	s_add_i32 s34, s34, -8
	s_add_i32 s27, s24, s21
	v_cvt_f32_u32_e32 v0, s34
	s_ashr_i32 s21, s27, 7
	s_and_b32 s27, s27, 0xffffff80
	s_sub_i32 s27, s24, s27
	s_lshl_b32 s24, s21, 13
	s_lshl_b32 s38, s27, 6
	s_add_i32 s35, s38, s24
	v_sub_f32_e32 v0, 0xc0a00000, v0
	s_mov_b32 s24, 0xc2fc0000
	v_cmp_gt_f32_e32 vcc, s24, v0
	s_and_b64 s[40:41], vcc, exec
	s_cselect_b32 s24, 0xffffffc0, 0
	v_cndmask_b32_e32 v1, 0, v204, vcc
	v_add_f32_e32 v0, v0, v1
	v_exp_f32_e32 v0, v0
	v_mov_b32_e32 v25, v144
	v_mov_b64_e32 v[22:23], s[8:9]
	v_ldexp_f32 v2, v0, s24
	v_sub_f32_e32 v4, 1.0, v2
	v_add_f32_e32 v0, -1.0, v4
	v_sub_f32_e32 v1, v0, v4
	v_add_f32_e32 v1, 1.0, v1
	v_sub_f32_e64 v0, -v2, v0
	v_add_f32_e32 v5, v0, v1
	v_frexp_mant_f32_e32 v0, v4
	v_cmp_gt_f32_e32 vcc, s77, v0
	v_cvt_f64_f32_e32 v[0:1], v4
	v_frexp_exp_i32_f64_e32 v0, v[0:1]
	v_subbrev_co_u32_e32 v10, vcc, 0, v0, vcc
	v_sub_u32_e32 v0, 0, v10
	v_ldexp_f32 v1, v4, v0
	v_add_f32_e32 v4, -1.0, v1
	v_add_f32_e32 v6, 1.0, v1
	v_ldexp_f32 v0, v5, v0
	v_add_f32_e32 v5, 1.0, v4
	v_add_f32_e32 v7, -1.0, v6
	v_sub_f32_e32 v5, v1, v5
	v_sub_f32_e32 v1, v1, v7
	v_add_f32_e32 v5, v0, v5
	v_add_f32_e32 v0, v0, v1
	v_add_f32_e32 v11, v6, v0
	v_rcp_f32_e32 v13, v11
	v_sub_f32_e32 v1, v11, v6
	v_sub_f32_e32 v12, v0, v1
	v_add_f32_e32 v1, v4, v5
	v_mul_f32_e32 v15, v1, v13
	v_sub_f32_e32 v0, v1, v4
	v_mul_f32_e32 v4, v11, v15
	v_fma_f32 v6, v15, v11, -v4
	v_fmac_f32_e32 v6, v15, v12
	v_sub_f32_e32 v14, v5, v0
	v_add_f32_e32 v0, v4, v6
	v_sub_f32_e32 v5, v1, v0
	v_pk_add_f32 v[8:9], v[0:1], v[4:5] neg_lo:[0,1] neg_hi:[0,1]
	v_mov_b32_e32 v7, v0
	v_pk_add_f32 v[0:1], v[8:9], v[6:7] neg_lo:[0,1] neg_hi:[0,1]
	v_cmp_nlt_f32_e32 vcc, 1.0, v2
	v_add_f32_e32 v1, v14, v1
	v_add_f32_e32 v0, v0, v1
	v_add_f32_e32 v1, v5, v0
	v_mul_f32_e32 v14, v13, v1
	v_mul_f32_e32 v4, v11, v14
	v_fma_f32 v6, v14, v11, -v4
	v_fmac_f32_e32 v6, v14, v12
	v_sub_f32_e32 v5, v5, v1
	v_add_f32_e32 v11, v0, v5
	v_add_f32_e32 v0, v4, v6
	v_sub_f32_e32 v5, v1, v0
	v_pk_add_f32 v[8:9], v[0:1], v[4:5] neg_lo:[0,1] neg_hi:[0,1]
	v_mov_b32_e32 v7, v0
	v_pk_add_f32 v[0:1], v[8:9], v[6:7] neg_lo:[0,1] neg_hi:[0,1]
	v_ashrrev_i32_e32 v36, 2, v25
	v_add_f32_e32 v1, v11, v1
	v_add_f32_e32 v0, v0, v1
	v_add_f32_e32 v1, v15, v14
	v_add_f32_e32 v0, v5, v0
	v_sub_f32_e32 v4, v1, v15
	v_mul_f32_e32 v0, v13, v0
	v_sub_f32_e32 v4, v14, v4
	v_add_f32_e32 v4, v4, v0
	v_add_f32_e32 v6, v1, v4
	v_mul_f32_e32 v7, v6, v6
	v_fmamk_f32 v0, v7, 0x3e9b6dac, v201
	v_fmaak_f32 v169, v7, v0, 0x3f2aaada
	v_cvt_f32_i32_e32 v0, v10
	v_sub_f32_e32 v1, v6, v1
	v_sub_f32_e32 v1, v4, v1
	v_ldexp_f32 v8, v1, 1
	v_mul_f32_e32 v1, v6, v7
	v_ldexp_f32 v5, v6, 1
	v_pk_mul_f32 v[6:7], v[0:1], v[168:169]
	s_lshl_b32 s24, s34, 7
	v_fma_f32 v4, v0, s94, -v6
	v_fmac_f32_e32 v4, 0xb102e308, v0
	v_pk_add_f32 v[0:1], v[6:7], v[4:5]
	s_nop 0
	v_sub_f32_e32 v5, v1, v5
	v_sub_f32_e32 v5, v7, v5
	v_add_f32_e32 v9, v8, v5
	v_mov_b32_e32 v8, v6
	v_pk_add_f32 v[6:7], v[0:1], v[6:7] neg_lo:[0,1] neg_hi:[0,1]
	v_pk_add_f32 v[10:11], v[0:1], v[8:9]
	v_mov_b32_e32 v5, v0
	v_mov_b32_e32 v7, v11
	v_pk_add_f32 v[12:13], v[4:5], v[6:7] neg_lo:[0,1] neg_hi:[0,1]
	v_pk_add_f32 v[4:5], v[4:5], v[6:7]
	v_mov_b32_e32 v16, v1
	v_pk_add_f32 v[6:7], v[4:5], v[0:1] op_sel:[1,0] op_sel_hi:[0,1] neg_lo:[0,1] neg_hi:[0,1]
	v_pk_add_f32 v[14:15], v[10:11], v[6:7] op_sel_hi:[1,0] neg_lo:[0,1] neg_hi:[0,1]
	v_mov_b32_e32 v10, v11
	v_mov_b32_e32 v11, v5
	v_mov_b32_e32 v17, v6
	v_pk_add_f32 v[6:7], v[10:11], v[16:17] neg_lo:[0,1] neg_hi:[0,1]
	v_mov_b32_e32 v8, v9
	v_mov_b32_e32 v9, v0
	v_pk_add_f32 v[0:1], v[8:9], v[6:7] neg_lo:[0,1] neg_hi:[0,1]
	v_mov_b32_e32 v14, v12
	v_pk_add_f32 v[6:7], v[14:15], v[0:1]
	v_mov_b32_e32 v13, v5
	v_pk_add_f32 v[8:9], v[6:7], v[6:7] op_sel:[0,1] op_sel_hi:[1,0]
	s_nop 0
	v_pk_add_f32 v[4:5], v[4:5], v[8:9] op_sel:[1,0] op_sel_hi:[0,1]
	v_mov_b32_e32 v7, v4
	v_pk_add_f32 v[10:11], v[6:7], v[12:13] neg_lo:[0,1] neg_hi:[0,1]
	v_mov_b32_e32 v1, v8
	v_sub_f32_e32 v5, v6, v10
	v_pk_add_f32 v[0:1], v[0:1], v[10:11] neg_lo:[0,1] neg_hi:[0,1]
	v_sub_f32_e32 v5, v12, v5
	v_add_f32_e32 v0, v0, v5
	v_add_f32_e32 v0, v0, v1
	v_add_f32_e32 v0, v4, v0
	v_cndmask_b32_e32 v0, v205, v0, vcc
	v_cmp_neq_f32_e32 vcc, 1.0, v2
	v_add_lshl_u32 v12, v36, s38, 5
	v_ashrrev_i32_e32 v13, 31, v12
	v_cndmask_b32_e32 v0, v206, v0, vcc
	v_cmp_gt_f32_e32 vcc, s95, v2
	v_lshlrev_b64 v[12:13], 2, v[12:13]
	s_nop 0
	v_cndmask_b32_e64 v35, v0, -v2, vcc
	v_lshlrev_b32_e32 v0, 3, v25
	v_and_b32_e32 v34, 24, v0
	v_lshlrev_b32_e32 v2, 2, v34
	v_lshl_add_u64 v[0:1], s[4:5], 0, v[2:3]
	v_lshl_add_u64 v[20:21], s[82:83], 0, v[2:3]
	v_lshl_add_u64 v[18:19], v[0:1], 0, v[12:13]
	v_lshl_add_u64 v[16:17], v[20:21], 0, v[12:13]
	v_sub_u32_e32 v12, 63, v36
	v_cvt_f32_i32_e32 v12, v12
	v_add_u32_e32 v2, s35, v36
	v_mad_i64_i32 v[4:5], s[40:41], v2, s72, v[22:23]
	v_mul_f32_e32 v12, v35, v12
	v_mul_f32_e32 v12, 0x3fb8aa3b, v12
	v_exp_f32_e32 v12, v12
	v_lshl_add_u64 v[4:5], v[4:5], 0, s[24:25]
	v_lshlrev_b32_e32 v2, 1, v34
	v_lshl_add_u64 v[4:5], v[4:5], 0, v[2:3]
	global_load_dwordx4 v[8:11], v[4:5], off offset:2560
	s_nop 0
	global_load_dwordx4 v[4:7], v[4:5], off offset:2624
	v_mul_f32_e32 v24, 0x3e000000, v12
	global_load_dwordx4 v[12:15], v[18:19], off
	global_load_dwordx4 v[28:31], v[16:17], off
	global_load_dwordx4 v[178:181], v[18:19], off offset:16
	global_load_dwordx4 v[182:185], v[16:17], off offset:16
	s_waitcnt vmcnt(0) lgkmcnt(0)
; #define LAS __attribute__((address_space(3)))
; __device__ __forceinline__ u32x4 pack8(const float (&v)[8]) { u32x4 w; w.x = pk2(v[0], v[1]); w.y = pk2(v[2], v[3]); w.z = pk2(v[4], v[5]); w.w = pk2(v[6], v[7]); return w; }
; __device__ __forceinline__ void ld8bf(const bf16_t* p, float (&o)[8]) { unpack8(*(const u32x4*)p, o); }
; __device__ __forceinline__ void w_ret_m1(unsigned char* ws, const bf16_t* proj, LAS unsigned char* wl, int b, int ck_, int h, int lane) {
;     ...
;     for (int i = 0; i < 4; ++i) { const int m = (lane >> 2) + 16 * i, cp = lane & 3; float x1[8], x2[8];
;         const bf16_t* src = proj + (size_t)(row0 + m) * NIN + C_RK + 64 * h; ld8bf(src + 8 * cp, x1); ld8bf(src + 32 + 8 * cp, x2);
;         const float* cp_ = cosT + (64 * ck_ + m) * 32 + 8 * cp; const float* sp_ = sinT + (64 * ck_ + m) * 32 + 8 * cp;
;         const float sc = 0.125f * __expf((float)(63 - m) * lg);
;         float o1[8], o2[8];
; #pragma unroll
;         for (int j = 0; j < 8; ++j) { const float cs = cp_[j], sn = sp_[j]; o1[j] = (x1[j] * cs - x2[j] * sn) * sc; o2[j] = (x2[j] * cs + x1[j] * sn) * sc; }
;         *(LAS u32x4*)(kT + m * LD + 8 * cp) = pack8(o1); *(LAS u32x4*)(kT + m * LD + 32 + 8 * cp) = pack8(o2); }
	v_lshlrev_b32_e32 v32, 16, v8
	v_and_b32_e32 v33, 0xffff0000, v8
	v_lshlrev_b32_e32 v38, 16, v4
	v_and_b32_e32 v39, 0xffff0000, v4
	v_pk_mul_f32 v[26:27], v[28:29], v[32:33]
	v_pk_mul_f32 v[28:29], v[28:29], v[38:39]
	v_pk_fma_f32 v[26:27], v[12:13], v[38:39], v[26:27]
	v_pk_fma_f32 v[12:13], v[12:13], v[32:33], v[28:29] neg_lo:[0,0,1] neg_hi:[0,0,1]
	v_lshlrev_b32_e32 v8, 16, v9
	v_and_b32_e32 v9, 0xffff0000, v9
	v_pk_mul_f32 v[28:29], v[24:25], v[12:13] op_sel_hi:[0,1]
	v_lshlrev_b32_e32 v12, 16, v5
	v_and_b32_e32 v13, 0xffff0000, v5
	v_pk_mul_f32 v[4:5], v[30:31], v[8:9]
	v_lshlrev_b32_e32 v32, 16, v6
	v_pk_fma_f32 v[4:5], v[14:15], v[12:13], v[4:5]
	v_pk_mul_f32 v[12:13], v[30:31], v[12:13]
	v_lshlrev_b32_e32 v30, 16, v10
	v_pk_fma_f32 v[8:9], v[14:15], v[8:9], v[12:13] neg_lo:[0,0,1] neg_hi:[0,0,1]
	v_mov_b64_e32 v[12:13], v[178:179]
	v_mov_b64_e32 v[14:15], v[180:181]
	s_nop 0
	v_mov_b64_e32 v[16:17], v[182:183]
	v_mov_b64_e32 v[18:19], v[184:185]
	v_and_b32_e32 v31, 0xffff0000, v10
	v_and_b32_e32 v33, 0xffff0000, v6
	v_lshlrev_b32_e32 v10, 16, v11
	v_and_b32_e32 v11, 0xffff0000, v11
	v_lshlrev_b32_e32 v6, 16, v7
	v_and_b32_e32 v7, 0xffff0000, v7
	v_pk_mul_f32 v[8:9], v[24:25], v[8:9] op_sel_hi:[0,1]
	v_pk_mul_f32 v[4:5], v[24:25], v[4:5] op_sel_hi:[0,1]
	v_pk_mul_f32 v[26:27], v[24:25], v[26:27] op_sel_hi:[0,1]
	s_waitcnt vmcnt(0) lgkmcnt(0)
	v_pk_mul_f32 v[38:39], v[16:17], v[30:31]
	v_pk_mul_f32 v[16:17], v[16:17], v[32:33]
	v_pk_fma_f32 v[38:39], v[12:13], v[32:33], v[38:39]
	v_pk_fma_f32 v[12:13], v[12:13], v[30:31], v[16:17] neg_lo:[0,0,1] neg_hi:[0,0,1]
	v_pk_mul_f32 v[16:17], v[18:19], v[10:11]
	v_pk_mul_f32 v[12:13], v[24:25], v[12:13] op_sel_hi:[0,1]
	v_pk_fma_f32 v[16:17], v[14:15], v[6:7], v[16:17]
	v_pk_mul_f32 v[6:7], v[18:19], v[6:7]
	v_pk_mul_f32 v[38:39], v[24:25], v[38:39] op_sel_hi:[0,1]
	v_pk_fma_f32 v[6:7], v[14:15], v[10:11], v[6:7] neg_lo:[0,0,1] neg_hi:[0,0,1]
	v_pk_mul_f32 v[16:17], v[24:25], v[16:17] op_sel_hi:[0,1]
	v_pk_mul_f32 v[10:11], v[24:25], v[6:7] op_sel_hi:[0,1]
	v_cvt_pk_bf16_f32 v7, v8, v9
	v_cvt_pk_bf16_f32 v9, v10, v11
	v_mul_lo_u32 v10, v36, s23
	v_cvt_pk_bf16_f32 v6, v28, v29
	v_cvt_pk_bf16_f32 v8, v12, v13
	v_add3_u32 v18, s6, v10, v2
	v_add_u32_e32 v12, 16, v36
	ds_write_b128 v18, v[6:9] offset:9216
	v_cvt_pk_bf16_f32 v7, v4, v5
	v_add_u32_e32 v4, s35, v12
	v_mad_i64_i32 v[4:5], s[40:41], v4, s72, v[22:23]
	v_add_lshl_u32 v12, v12, s38, 5
	v_cvt_pk_bf16_f32 v6, v26, v27
	v_cvt_pk_bf16_f32 v8, v38, v39
	v_cvt_pk_bf16_f32 v9, v16, v17
	v_lshl_add_u64 v[4:5], v[4:5], 0, s[24:25]
	v_ashrrev_i32_e32 v13, 31, v12
	ds_write_b128 v18, v[6:9] offset:9280
	v_lshl_add_u64 v[4:5], v[4:5], 0, v[2:3]
	v_lshlrev_b64 v[12:13], 2, v[12:13]
	global_load_dwordx4 v[8:11], v[4:5], off offset:2560
	s_nop 0
	global_load_dwordx4 v[4:7], v[4:5], off offset:2624
	v_lshl_add_u64 v[38:39], v[0:1], 0, v[12:13]
	v_lshl_add_u64 v[40:41], v[20:21], 0, v[12:13]
	global_load_dwordx4 v[26:29], v[38:39], off
	global_load_dwordx4 v[30:33], v[40:41], off
	global_load_dwordx4 v[178:181], v[38:39], off offset:16
	global_load_dwordx4 v[182:185], v[40:41], off offset:16
	v_sub_u32_e32 v12, 47, v36
	v_cvt_f32_i32_e32 v12, v12
	v_mul_f32_e32 v12, v35, v12
	v_mul_f32_e32 v12, 0x3fb8aa3b, v12
	v_exp_f32_e32 v12, v12
	s_waitcnt vmcnt(0) lgkmcnt(0)
	v_lshlrev_b32_e32 v16, 16, v8
	v_and_b32_e32 v17, 0xffff0000, v8
	v_lshlrev_b32_e32 v42, 16, v4
	v_and_b32_e32 v43, 0xffff0000, v4
	v_pk_mul_f32 v[14:15], v[30:31], v[16:17]
	v_pk_mul_f32 v[30:31], v[30:31], v[42:43]
	v_lshlrev_b32_e32 v8, 16, v9
	v_and_b32_e32 v9, 0xffff0000, v9
	v_pk_fma_f32 v[14:15], v[26:27], v[42:43], v[14:15]
	v_pk_fma_f32 v[16:17], v[26:27], v[16:17], v[30:31] neg_lo:[0,0,1] neg_hi:[0,0,1]
	v_lshlrev_b32_e32 v26, 16, v5
	v_and_b32_e32 v27, 0xffff0000, v5
	v_pk_mul_f32 v[4:5], v[32:33], v[8:9]
	v_lshlrev_b32_e32 v42, 16, v10
	v_pk_fma_f32 v[4:5], v[28:29], v[26:27], v[4:5]
	v_pk_mul_f32 v[26:27], v[32:33], v[26:27]
	v_and_b32_e32 v43, 0xffff0000, v10
	v_pk_fma_f32 v[8:9], v[28:29], v[8:9], v[26:27] neg_lo:[0,0,1] neg_hi:[0,0,1]
	v_mov_b64_e32 v[26:27], v[178:179]
	v_mov_b64_e32 v[28:29], v[180:181]
	v_mov_b64_e32 v[30:31], v[182:183]
	v_mov_b64_e32 v[32:33], v[184:185]
	v_lshlrev_b32_e32 v44, 16, v6
	v_and_b32_e32 v45, 0xffff0000, v6
	v_lshlrev_b32_e32 v10, 16, v11
	v_and_b32_e32 v11, 0xffff0000, v11
	v_lshlrev_b32_e32 v6, 16, v7
	v_and_b32_e32 v7, 0xffff0000, v7
	v_mul_f32_e32 v12, 0x3e000000, v12
	v_pk_mul_f32 v[16:17], v[12:13], v[16:17] op_sel_hi:[0,1]
	v_pk_mul_f32 v[8:9], v[12:13], v[8:9] op_sel_hi:[0,1]
	v_pk_mul_f32 v[14:15], v[12:13], v[14:15] op_sel_hi:[0,1]
	v_pk_mul_f32 v[4:5], v[12:13], v[4:5] op_sel_hi:[0,1]
	s_waitcnt vmcnt(0) lgkmcnt(0)
; #define LAS __attribute__((address_space(3)))
; __device__ __forceinline__ u32x4 pack8(const float (&v)[8]) { u32x4 w; w.x = pk2(v[0], v[1]); w.y = pk2(v[2], v[3]); w.z = pk2(v[4], v[5]); w.w = pk2(v[6], v[7]); return w; }
; __device__ __forceinline__ void ld8bf(const bf16_t* p, float (&o)[8]) { unpack8(*(const u32x4*)p, o); }
; __device__ __forceinline__ void w_ret_m1(unsigned char* ws, const bf16_t* proj, LAS unsigned char* wl, int b, int ck_, int h, int lane) {
;     ...
;     for (int i = 0; i < 4; ++i) { const int m = (lane >> 2) + 16 * i, cp = lane & 3; float x1[8], x2[8];
;         const bf16_t* src = proj + (size_t)(row0 + m) * NIN + C_RK + 64 * h; ld8bf(src + 8 * cp, x1); ld8bf(src + 32 + 8 * cp, x2);
;         const float* cp_ = cosT + (64 * ck_ + m) * 32 + 8 * cp; const float* sp_ = sinT + (64 * ck_ + m) * 32 + 8 * cp;
;         const float sc = 0.125f * __expf((float)(63 - m) * lg);
;         float o1[8], o2[8];
; #pragma unroll
;         for (int j = 0; j < 8; ++j) { const float cs = cp_[j], sn = sp_[j]; o1[j] = (x1[j] * cs - x2[j] * sn) * sc; o2[j] = (x2[j] * cs + x1[j] * sn) * sc; }
;         *(LAS u32x4*)(kT + m * LD + 8 * cp) = pack8(o1); *(LAS u32x4*)(kT + m * LD + 32 + 8 * cp) = pack8(o2); }
	v_pk_mul_f32 v[38:39], v[30:31], v[42:43]
	v_pk_mul_f32 v[30:31], v[30:31], v[44:45]
	v_pk_fma_f32 v[38:39], v[26:27], v[44:45], v[38:39]
	v_pk_fma_f32 v[26:27], v[26:27], v[42:43], v[30:31] neg_lo:[0,0,1] neg_hi:[0,0,1]
	v_pk_mul_f32 v[30:31], v[32:33], v[10:11]
	v_pk_mul_f32 v[26:27], v[12:13], v[26:27] op_sel_hi:[0,1]
	v_pk_fma_f32 v[30:31], v[28:29], v[6:7], v[30:31]
	v_pk_mul_f32 v[6:7], v[32:33], v[6:7]
	v_pk_mul_f32 v[38:39], v[12:13], v[38:39] op_sel_hi:[0,1]
	v_pk_fma_f32 v[6:7], v[28:29], v[10:11], v[6:7] neg_lo:[0,0,1] neg_hi:[0,0,1]
	v_pk_mul_f32 v[30:31], v[12:13], v[30:31] op_sel_hi:[0,1]
	v_pk_mul_f32 v[10:11], v[12:13], v[6:7] op_sel_hi:[0,1]
	v_cvt_pk_bf16_f32 v6, v16, v17
	v_cvt_pk_bf16_f32 v7, v8, v9
	v_cvt_pk_bf16_f32 v8, v26, v27
	v_cvt_pk_bf16_f32 v9, v10, v11
	v_add_u32_e32 v12, 32, v36
	ds_write_b128 v18, v[6:9] offset:11520
	v_cvt_pk_bf16_f32 v7, v4, v5
	v_add_u32_e32 v4, s35, v12
	v_mad_i64_i32 v[4:5], s[40:41], v4, s72, v[22:23]
	v_add_lshl_u32 v12, v12, s38, 5
	v_cvt_pk_bf16_f32 v6, v14, v15
	v_cvt_pk_bf16_f32 v8, v38, v39
	v_cvt_pk_bf16_f32 v9, v30, v31
	v_lshl_add_u64 v[4:5], v[4:5], 0, s[24:25]
	v_ashrrev_i32_e32 v13, 31, v12
	ds_write_b128 v18, v[6:9] offset:11584
	v_lshl_add_u64 v[4:5], v[4:5], 0, v[2:3]
	v_lshlrev_b64 v[12:13], 2, v[12:13]
	global_load_dwordx4 v[8:11], v[4:5], off offset:2560
	s_nop 0
	global_load_dwordx4 v[4:7], v[4:5], off offset:2624
	v_lshl_add_u64 v[38:39], v[0:1], 0, v[12:13]
	v_lshl_add_u64 v[40:41], v[20:21], 0, v[12:13]
	global_load_dwordx4 v[26:29], v[38:39], off
	global_load_dwordx4 v[30:33], v[40:41], off
	global_load_dwordx4 v[178:181], v[38:39], off offset:16
	global_load_dwordx4 v[182:185], v[40:41], off offset:16
	v_sub_u32_e32 v12, 31, v36
	v_cvt_f32_i32_e32 v12, v12
	v_mul_f32_e32 v12, v35, v12
	v_mul_f32_e32 v12, 0x3fb8aa3b, v12
	v_exp_f32_e32 v12, v12
	s_waitcnt vmcnt(0) lgkmcnt(0)
	v_lshlrev_b32_e32 v16, 16, v8
	v_and_b32_e32 v17, 0xffff0000, v8
	v_lshlrev_b32_e32 v42, 16, v4
	v_and_b32_e32 v43, 0xffff0000, v4
	v_pk_mul_f32 v[14:15], v[30:31], v[16:17]
	v_pk_mul_f32 v[30:31], v[30:31], v[42:43]
	v_lshlrev_b32_e32 v8, 16, v9
	v_and_b32_e32 v9, 0xffff0000, v9
	v_pk_fma_f32 v[14:15], v[26:27], v[42:43], v[14:15]
	v_pk_fma_f32 v[16:17], v[26:27], v[16:17], v[30:31] neg_lo:[0,0,1] neg_hi:[0,0,1]
	v_lshlrev_b32_e32 v26, 16, v5
	v_and_b32_e32 v27, 0xffff0000, v5
	v_pk_mul_f32 v[4:5], v[32:33], v[8:9]
	v_lshlrev_b32_e32 v42, 16, v10
	v_pk_fma_f32 v[4:5], v[28:29], v[26:27], v[4:5]
	v_pk_mul_f32 v[26:27], v[32:33], v[26:27]
	v_and_b32_e32 v43, 0xffff0000, v10
	v_pk_fma_f32 v[8:9], v[28:29], v[8:9], v[26:27] neg_lo:[0,0,1] neg_hi:[0,0,1]
	v_mov_b64_e32 v[26:27], v[178:179]
	v_mov_b64_e32 v[28:29], v[180:181]
	v_mov_b64_e32 v[30:31], v[182:183]
	v_mov_b64_e32 v[32:33], v[184:185]
	v_lshlrev_b32_e32 v44, 16, v6
	v_and_b32_e32 v45, 0xffff0000, v6
	v_lshlrev_b32_e32 v10, 16, v11
	v_and_b32_e32 v11, 0xffff0000, v11
	v_lshlrev_b32_e32 v6, 16, v7
	v_and_b32_e32 v7, 0xffff0000, v7
	v_mul_f32_e32 v12, 0x3e000000, v12
	v_pk_mul_f32 v[16:17], v[12:13], v[16:17] op_sel_hi:[0,1]
	v_pk_mul_f32 v[8:9], v[12:13], v[8:9] op_sel_hi:[0,1]
	v_pk_mul_f32 v[14:15], v[12:13], v[14:15] op_sel_hi:[0,1]
	v_pk_mul_f32 v[4:5], v[12:13], v[4:5] op_sel_hi:[0,1]
	s_waitcnt vmcnt(0) lgkmcnt(0)
	v_pk_mul_f32 v[38:39], v[30:31], v[42:43]
	v_pk_mul_f32 v[30:31], v[30:31], v[44:45]
	v_pk_fma_f32 v[38:39], v[26:27], v[44:45], v[38:39]
	v_pk_fma_f32 v[26:27], v[26:27], v[42:43], v[30:31] neg_lo:[0,0,1] neg_hi:[0,0,1]
	v_pk_mul_f32 v[30:31], v[32:33], v[10:11]
	v_pk_mul_f32 v[26:27], v[12:13], v[26:27] op_sel_hi:[0,1]
	v_pk_fma_f32 v[30:31], v[28:29], v[6:7], v[30:31]
	v_pk_mul_f32 v[6:7], v[32:33], v[6:7]
	v_pk_mul_f32 v[38:39], v[12:13], v[38:39] op_sel_hi:[0,1]
	v_pk_fma_f32 v[6:7], v[28:29], v[10:11], v[6:7] neg_lo:[0,0,1] neg_hi:[0,0,1]
	v_pk_mul_f32 v[30:31], v[12:13], v[30:31] op_sel_hi:[0,1]
	v_pk_mul_f32 v[10:11], v[12:13], v[6:7] op_sel_hi:[0,1]
	v_cvt_pk_bf16_f32 v6, v16, v17
	v_cvt_pk_bf16_f32 v7, v8, v9
	v_cvt_pk_bf16_f32 v8, v26, v27
	v_cvt_pk_bf16_f32 v9, v10, v11
	v_add_u32_e32 v12, 48, v36
	ds_write_b128 v18, v[6:9] offset:13824
	v_cvt_pk_bf16_f32 v7, v4, v5
	v_add_u32_e32 v4, s35, v12
	v_mad_i64_i32 v[4:5], s[40:41], v4, s72, v[22:23]
	v_add_lshl_u32 v12, v12, s38, 5
	v_cvt_pk_bf16_f32 v6, v14, v15
	v_cvt_pk_bf16_f32 v8, v38, v39
	v_cvt_pk_bf16_f32 v9, v30, v31
	v_lshl_add_u64 v[4:5], v[4:5], 0, s[24:25]
	v_ashrrev_i32_e32 v13, 31, v12
	ds_write_b128 v18, v[6:9] offset:13888
	v_lshl_add_u64 v[4:5], v[4:5], 0, v[2:3]
	v_lshlrev_b64 v[12:13], 2, v[12:13]
	global_load_dwordx4 v[8:11], v[4:5], off offset:2560
	s_nop 0
	global_load_dwordx4 v[4:7], v[4:5], off offset:2624
	v_lshl_add_u64 v[26:27], v[0:1], 0, v[12:13]
	v_lshl_add_u64 v[28:29], v[20:21], 0, v[12:13]
	global_load_dwordx4 v[14:17], v[26:27], off
	global_load_dwordx4 v[20:23], v[28:29], off
	global_load_dwordx4 v[178:181], v[26:27], off offset:16
	global_load_dwordx4 v[182:185], v[28:29], off offset:16
	v_sub_u32_e32 v0, 15, v36
	v_cvt_f32_i32_e32 v0, v0
	s_mul_hi_i32 s38, s35, 0x1800
	s_mulk_i32 s35, 0x1800
	s_add_u32 s35, s8, s35
	v_mul_f32_e32 v0, v35, v0
	v_mul_f32_e32 v0, 0x3fb8aa3b, v0
	v_exp_f32_e32 v0, v0
	s_addc_u32 s39, s9, s38
	s_add_u32 s38, s35, s24
	s_addc_u32 s39, s39, 0
	v_mul_f32_e32 v0, 0x3e000000, v0
	s_lshl_b32 s21, s21, 9
	s_lshl_b32 s24, s27, 2
	s_add_i32 s24, s24, s21
	s_or_b32 s34, s34, s24
	s_ashr_i32 s35, s34, 31
	s_lshl_b64 s[34:35], s[34:35], 13
	s_add_u32 s34, s67, s34
	s_addc_u32 s35, s28, s35
	s_waitcnt vmcnt(0) lgkmcnt(0)
; #define LAS __attribute__((address_space(3)))
; __device__ __forceinline__ void ld8bf(const bf16_t* p, float (&o)[8]) { unpack8(*(const u32x4*)p, o); }
; __device__ __forceinline__ void w_store_vT(LAS bf16_t* vN, const bf16_t* src, int lane) {
; #pragma unroll
;     for (int i = 0; i < 8; ++i) { const int m = (lane >> 3) + 8 * i, e0 = 8 * (lane & 7); *(LAS u32x4*)(vN + m * LD + e0) = *(const u32x4*)(src + (size_t)m * NIN + e0); }
; }
; __device__ __forceinline__ void w_kv(const LAS bf16_t* vN, const LAS bf16_t* kN, bf16_t* S, int lo, int fq) {
; #pragma unroll
;     for (int db = 0; db < 4; ++db) {
;         bf16x8 kf[2];
; #pragma unroll
;         for (int kk = 0; kk < 2; ++kk) kf[kk] = tr_frag(kN, 32 * kk + 8 * fq, 32 * kk + 8 * fq + 4, 16 * db, lo);
; #pragma unroll
;         for (int eb = 0; eb < 4; ++eb) { f32x4 acc = {0.f, 0.f, 0.f, 0.f};
; #pragma unroll
;             for (int kk = 0; kk < 2; ++kk) { const bf16x8 vf = tr_frag(vN, 32 * kk + 8 * fq, 32 * kk + 8 * fq + 4, 16 * eb, lo); acc = __builtin_amdgcn_mfma_f32_16x16x32_bf16(kf[kk], vf, acc, 0, 0, 0); }
;             *(unsigned long long*)(S + (16 * eb + lo) * 64 + 16 * db + 4 * fq) = (unsigned long long)pk2(acc[0], acc[1]) | ((unsigned long long)pk2(acc[2], acc[3]) << 32); }
; __device__ __forceinline__ void w_ret_m1(unsigned char* ws, const bf16_t* proj, LAS unsigned char* wl, int b, int ck_, int h, int lane) {
;     ...
;     for (int i = 0; i < 4; ++i) { const int m = (lane >> 2) + 16 * i, cp = lane & 3; float x1[8], x2[8];
;         const bf16_t* src = proj + (size_t)(row0 + m) * NIN + C_RK + 64 * h; ld8bf(src + 8 * cp, x1); ld8bf(src + 32 + 8 * cp, x2);
;         const float* cp_ = cosT + (64 * ck_ + m) * 32 + 8 * cp; const float* sp_ = sinT + (64 * ck_ + m) * 32 + 8 * cp;
;         const float sc = 0.125f * __expf((float)(63 - m) * lg);
;         float o1[8], o2[8];
; #pragma unroll
;         for (int j = 0; j < 8; ++j) { const float cs = cp_[j], sn = sp_[j]; o1[j] = (x1[j] * cs - x2[j] * sn) * sc; o2[j] = (x2[j] * cs + x1[j] * sn) * sc; }
;         *(LAS u32x4*)(kT + m * LD + 8 * cp) = pack8(o1); *(LAS u32x4*)(kT + m * LD + 32 + 8 * cp) = pack8(o2); }
;     w_store_vT(vT, proj + (size_t)row0 * NIN + C_RV + 64 * h, lane);
;     WAVE_LDS_FENCE();
;     w_kv(vT, kT, (bf16_t*)(ws + WS_SRET) + (size_t)((b * NCH + ck_) * 4 + h) * 4096, lo, fq);
;     WAVE_LDS_FENCE();
	v_lshlrev_b32_e32 v30, 16, v8
	v_and_b32_e32 v31, 0xffff0000, v8
	v_lshlrev_b32_e32 v32, 16, v4
	v_and_b32_e32 v33, 0xffff0000, v4
	v_pk_mul_f32 v[12:13], v[20:21], v[30:31]
	v_pk_mul_f32 v[20:21], v[20:21], v[32:33]
	v_lshlrev_b32_e32 v8, 16, v9
	v_and_b32_e32 v9, 0xffff0000, v9
	v_pk_fma_f32 v[12:13], v[14:15], v[32:33], v[12:13]
	v_pk_fma_f32 v[14:15], v[14:15], v[30:31], v[20:21] neg_lo:[0,0,1] neg_hi:[0,0,1]
	v_lshlrev_b32_e32 v20, 16, v5
	v_and_b32_e32 v21, 0xffff0000, v5
	v_pk_mul_f32 v[4:5], v[22:23], v[8:9]
	v_lshlrev_b32_e32 v30, 16, v6
	v_pk_fma_f32 v[4:5], v[16:17], v[20:21], v[4:5]
	v_pk_mul_f32 v[20:21], v[22:23], v[20:21]
	v_and_b32_e32 v31, 0xffff0000, v6
	v_pk_fma_f32 v[8:9], v[16:17], v[8:9], v[20:21] neg_lo:[0,0,1] neg_hi:[0,0,1]
	v_mov_b64_e32 v[20:21], v[178:179]
	v_mov_b64_e32 v[22:23], v[180:181]
	s_nop 0
	v_mov_b64_e32 v[26:27], v[182:183]
	v_mov_b64_e32 v[28:29], v[184:185]
	v_lshlrev_b32_e32 v16, 16, v10
	v_and_b32_e32 v17, 0xffff0000, v10
	v_lshlrev_b32_e32 v10, 16, v11
	v_and_b32_e32 v11, 0xffff0000, v11
	v_lshlrev_b32_e32 v6, 16, v7
	v_and_b32_e32 v7, 0xffff0000, v7
	v_pk_mul_f32 v[12:13], v[0:1], v[12:13] op_sel_hi:[0,1]
	v_pk_mul_f32 v[14:15], v[0:1], v[14:15] op_sel_hi:[0,1]
	v_pk_mul_f32 v[4:5], v[0:1], v[4:5] op_sel_hi:[0,1]
	v_pk_mul_f32 v[8:9], v[0:1], v[8:9] op_sel_hi:[0,1]
	s_waitcnt vmcnt(0) lgkmcnt(0)
	v_pk_mul_f32 v[32:33], v[26:27], v[16:17]
	v_pk_mul_f32 v[26:27], v[26:27], v[30:31]
	v_pk_fma_f32 v[32:33], v[20:21], v[30:31], v[32:33]
	v_pk_fma_f32 v[16:17], v[20:21], v[16:17], v[26:27] neg_lo:[0,0,1] neg_hi:[0,0,1]
	v_pk_mul_f32 v[20:21], v[28:29], v[10:11]
	v_pk_mul_f32 v[32:33], v[0:1], v[32:33] op_sel_hi:[0,1]
	v_pk_fma_f32 v[20:21], v[22:23], v[6:7], v[20:21]
	v_pk_mul_f32 v[6:7], v[28:29], v[6:7]
	v_pk_mul_f32 v[16:17], v[0:1], v[16:17] op_sel_hi:[0,1]
	v_pk_fma_f32 v[6:7], v[22:23], v[10:11], v[6:7] neg_lo:[0,0,1] neg_hi:[0,0,1]
	v_pk_mul_f32 v[20:21], v[0:1], v[20:21] op_sel_hi:[0,1]
	v_pk_mul_f32 v[0:1], v[0:1], v[6:7] op_sel_hi:[0,1]
	v_cvt_pk_bf16_f32 v6, v14, v15
	v_cvt_pk_bf16_f32 v7, v8, v9
	v_cvt_pk_bf16_f32 v8, v16, v17
	v_cvt_pk_bf16_f32 v9, v0, v1
	v_lshlrev_b32_e32 v0, 4, v25
	ds_write_b128 v18, v[6:9] offset:16128
	v_cvt_pk_bf16_f32 v6, v12, v13
	v_cvt_pk_bf16_f32 v7, v4, v5
	v_cvt_pk_bf16_f32 v8, v32, v33
	v_cvt_pk_bf16_f32 v9, v20, v21
	v_and_b32_e32 v2, 0x70, v0
	ds_write_b128 v18, v[6:9] offset:16192
	v_ashrrev_i32_e32 v9, 3, v25
	v_lshl_add_u64 v[0:1], s[38:39], 0, v[2:3]
	v_mad_i64_i32 v[4:5], s[38:39], v9, s72, v[0:1]
	global_load_dwordx4 v[224:227], v[4:5], off offset:3072
	v_add_u32_e32 v4, 8, v9
	v_mad_i64_i32 v[4:5], s[38:39], v4, s72, v[0:1]
	global_load_dwordx4 v[228:231], v[4:5], off offset:3072
	v_add_u32_e32 v4, 16, v9
	v_mad_i64_i32 v[4:5], s[38:39], v4, s72, v[0:1]
	global_load_dwordx4 v[232:235], v[4:5], off offset:3072
	v_add_u32_e32 v4, 24, v9
	v_mad_i64_i32 v[4:5], s[38:39], v4, s72, v[0:1]
	global_load_dwordx4 v[236:239], v[4:5], off offset:3072
	v_add_u32_e32 v4, 32, v9
	v_mad_i64_i32 v[4:5], s[38:39], v4, s72, v[0:1]
	global_load_dwordx4 v[240:243], v[4:5], off offset:3072
	v_add_u32_e32 v4, 40, v9
	v_mad_i64_i32 v[4:5], s[38:39], v4, s72, v[0:1]
	global_load_dwordx4 v[244:247], v[4:5], off offset:3072
	v_add_u32_e32 v4, 48, v9
	v_mad_i64_i32 v[4:5], s[38:39], v4, s72, v[0:1]
	global_load_dwordx4 v[248:251], v[4:5], off offset:3072
	v_add_u32_e32 v4, 56, v9
	v_mad_i64_i32 v[0:1], s[38:39], v4, s72, v[0:1]
	global_load_dwordx4 v[186:189], v[0:1], off offset:3072
	v_mul_lo_u32 v10, v9, s23
	v_add3_u32 v2, s6, v2, v10
	v_ashrrev_i32_e32 v8, 4, v25
	v_and_b32_e32 v17, 15, v25
	v_lshlrev_b32_e32 v0, 2, v8
	v_ashrrev_i32_e32 v1, 31, v0
	v_lshl_add_u64 v[0:1], v[0:1], 1, s[34:35]
	v_lshl_add_u64 v[26:27], v[0:1], 0, 32
	s_mov_b64 s[34:35], 0x60
	s_waitcnt vmcnt(0) lgkmcnt(0)
	ds_write_b128 v2, v[224:227]
	ds_write_b128 v2, v[228:231] offset:1152
	ds_write_b128 v2, v[232:235] offset:2304
	ds_write_b128 v2, v[236:239] offset:3456
	ds_write_b128 v2, v[240:243] offset:4608
	ds_write_b128 v2, v[244:247] offset:5760
	ds_write_b128 v2, v[248:251] offset:6912
	ds_write_b128 v2, v[186:189] offset:8064
	v_bfe_u32 v2, v25, 2, 2
	v_lshl_or_b32 v2, v8, 3, v2
	v_mul_lo_u32 v2, v2, s23
	s_waitcnt lgkmcnt(0)
	v_add3_u32 v16, s6, v34, v2
	ds_read_b64_tr_b16 v[8:9], v16 offset:9216
	ds_read_b64_tr_b16 v[10:11], v16 offset:9792
	ds_read_b64_tr_b16 v[4:5], v16 offset:13824
	ds_read_b64_tr_b16 v[6:7], v16 offset:14400
	ds_read_b64_tr_b16 v[12:13], v16
	ds_read_b64_tr_b16 v[14:15], v16 offset:576
	ds_read_b64_tr_b16 v[18:19], v16 offset:4608
	ds_read_b64_tr_b16 v[20:21], v16 offset:5184
	s_waitcnt lgkmcnt(2)
	v_mfma_f32_16x16x32_bf16 v[12:15], v[8:11], v[12:15], 0
	v_lshlrev_b32_e32 v2, 7, v17
	s_waitcnt lgkmcnt(0)
	v_mfma_f32_16x16x32_bf16 v[12:15], v[4:7], v[18:21], v[12:15]
	s_nop 7
	v_cvt_pk_bf16_f32 v18, v12, v13
	v_cvt_pk_bf16_f32 v19, v14, v15
	v_lshl_add_u64 v[12:13], v[0:1], 0, v[2:3]
	flat_store_dwordx2 v[12:13], v[18:19]
	ds_read_b64_tr_b16 v[18:19], v16 offset:32
	ds_read_b64_tr_b16 v[20:21], v16 offset:608
	ds_read_b64_tr_b16 v[22:23], v16 offset:4640
	ds_read_b64_tr_b16 v[24:25], v16 offset:5216
	s_waitcnt lgkmcnt(0)
	v_mfma_f32_16x16x32_bf16 v[18:21], v[8:11], v[18:21], 0
	v_mfma_f32_16x16x32_bf16 v[18:21], v[4:7], v[22:25], v[18:21]
	s_nop 7
	v_cvt_pk_bf16_f32 v14, v18, v19
	v_cvt_pk_bf16_f32 v15, v20, v21
	flat_store_dwordx2 v[12:13], v[14:15] offset:2048
	ds_read_b64_tr_b16 v[18:19], v16 offset:64
	ds_read_b64_tr_b16 v[20:21], v16 offset:640
	ds_read_b64_tr_b16 v[22:23], v16 offset:4672
	ds_read_b64_tr_b16 v[24:25], v16 offset:5248
	s_waitcnt lgkmcnt(0)
; #define LAS __attribute__((address_space(3)))
; __device__ __forceinline__ unsigned pk2(float lo, float hi) { const f32x2_t v = {lo, hi}; const bf16x2_t b = __builtin_convertvector(v, bf16x2_t); return __builtin_bit_cast(unsigned, b); }
; __device__ __forceinline__ void w_kv(const LAS bf16_t* vN, const LAS bf16_t* kN, bf16_t* S, int lo, int fq) {
; #pragma unroll
;     for (int db = 0; db < 4; ++db) {
;         bf16x8 kf[2];
; #pragma unroll
;         for (int kk = 0; kk < 2; ++kk) kf[kk] = tr_frag(kN, 32 * kk + 8 * fq, 32 * kk + 8 * fq + 4, 16 * db, lo);
; #pragma unroll
;         for (int eb = 0; eb < 4; ++eb) { f32x4 acc = {0.f, 0.f, 0.f, 0.f};
; #pragma unroll
;             for (int kk = 0; kk < 2; ++kk) { const bf16x8 vf = tr_frag(vN, 32 * kk + 8 * fq, 32 * kk + 8 * fq + 4, 16 * eb, lo); acc = __builtin_amdgcn_mfma_f32_16x16x32_bf16(kf[kk], vf, acc, 0, 0, 0); }
;             *(unsigned long long*)(S + (16 * eb + lo) * 64 + 16 * db + 4 * fq) = (unsigned long long)pk2(acc[0], acc[1]) | ((unsigned long long)pk2(acc[2], acc[3]) << 32); }
;     }
; }
	v_mfma_f32_16x16x32_bf16 v[18:21], v[8:11], v[18:21], 0
	v_or_b32_e32 v14, 0x1000, v2
	v_mov_b32_e32 v15, v3
	v_or_b32_e32 v2, 0x1800, v2
	v_mfma_f32_16x16x32_bf16 v[18:21], v[4:7], v[22:25], v[18:21]
	s_nop 7
	v_cvt_pk_bf16_f32 v18, v18, v19
	v_cvt_pk_bf16_f32 v19, v20, v21
	v_lshl_add_u64 v[20:21], v[0:1], 0, v[14:15]
	flat_store_dwordx2 v[20:21], v[18:19]
	ds_read_b64_tr_b16 v[18:19], v16 offset:96
	ds_read_b64_tr_b16 v[20:21], v16 offset:672
	s_waitcnt lgkmcnt(0)
	v_mfma_f32_16x16x32_bf16 v[8:11], v[8:11], v[18:21], 0
	ds_read_b64_tr_b16 v[18:19], v16 offset:4704
	ds_read_b64_tr_b16 v[20:21], v16 offset:5280
	s_waitcnt lgkmcnt(0)
	v_mfma_f32_16x16x32_bf16 v[4:7], v[4:7], v[18:21], v[8:11]
	s_nop 7
	v_cvt_pk_bf16_f32 v4, v4, v5
	v_cvt_pk_bf16_f32 v5, v6, v7
	v_lshl_add_u64 v[6:7], v[0:1], 0, v[2:3]
	flat_store_dwordx2 v[6:7], v[4:5]
	ds_read_b64_tr_b16 v[4:5], v16 offset:9248
	ds_read_b64_tr_b16 v[6:7], v16 offset:9824
	ds_read_b64_tr_b16 v[8:9], v16 offset:13856
	ds_read_b64_tr_b16 v[10:11], v16 offset:14432
	ds_read_b64_tr_b16 v[18:19], v16
	ds_read_b64_tr_b16 v[20:21], v16 offset:576
	ds_read_b64_tr_b16 v[22:23], v16 offset:4608
	ds_read_b64_tr_b16 v[24:25], v16 offset:5184
	s_waitcnt lgkmcnt(0)
	v_mfma_f32_16x16x32_bf16 v[18:21], v[4:7], v[18:21], 0
	v_mfma_f32_16x16x32_bf16 v[18:21], v[8:11], v[22:25], v[18:21]
	s_nop 7
	v_cvt_pk_bf16_f32 v18, v18, v19
	v_cvt_pk_bf16_f32 v19, v20, v21
	flat_store_dwordx2 v[12:13], v[18:19] offset:32
	ds_read_b64_tr_b16 v[18:19], v16 offset:32
	ds_read_b64_tr_b16 v[20:21], v16 offset:608
	ds_read_b64_tr_b16 v[22:23], v16 offset:4640
	ds_read_b64_tr_b16 v[24:25], v16 offset:5216
	s_waitcnt lgkmcnt(0)
	v_mfma_f32_16x16x32_bf16 v[18:21], v[4:7], v[18:21], 0
	v_mfma_f32_16x16x32_bf16 v[18:21], v[8:11], v[22:25], v[18:21]
	s_nop 7
	v_cvt_pk_bf16_f32 v18, v18, v19
	v_cvt_pk_bf16_f32 v19, v20, v21
	flat_store_dwordx2 v[12:13], v[18:19] offset:2080
	ds_read_b64_tr_b16 v[18:19], v16 offset:64
	ds_read_b64_tr_b16 v[20:21], v16 offset:640
	ds_read_b64_tr_b16 v[22:23], v16 offset:4672
	ds_read_b64_tr_b16 v[24:25], v16 offset:5248
	s_waitcnt lgkmcnt(0)
	v_mfma_f32_16x16x32_bf16 v[18:21], v[4:7], v[18:21], 0
	v_mfma_f32_16x16x32_bf16 v[18:21], v[8:11], v[22:25], v[18:21]
	s_nop 7
	v_cvt_pk_bf16_f32 v18, v18, v19
	v_cvt_pk_bf16_f32 v19, v20, v21
	v_lshl_add_u64 v[20:21], v[26:27], 0, v[14:15]
	flat_store_dwordx2 v[20:21], v[18:19]
	ds_read_b64_tr_b16 v[18:19], v16 offset:96
	ds_read_b64_tr_b16 v[20:21], v16 offset:672
	s_waitcnt lgkmcnt(0)
	v_mfma_f32_16x16x32_bf16 v[4:7], v[4:7], v[18:21], 0
	ds_read_b64_tr_b16 v[18:19], v16 offset:4704
	ds_read_b64_tr_b16 v[20:21], v16 offset:5280
	s_waitcnt lgkmcnt(0)
	v_mfma_f32_16x16x32_bf16 v[4:7], v[8:11], v[18:21], v[4:7]
	s_nop 7
	v_cvt_pk_bf16_f32 v4, v4, v5
	v_cvt_pk_bf16_f32 v5, v6, v7
	v_lshl_add_u64 v[6:7], v[26:27], 0, v[2:3]
	flat_store_dwordx2 v[6:7], v[4:5]
	ds_read_b64_tr_b16 v[4:5], v16 offset:9280
	ds_read_b64_tr_b16 v[6:7], v16 offset:9856
	ds_read_b64_tr_b16 v[8:9], v16 offset:13888
	ds_read_b64_tr_b16 v[10:11], v16 offset:14464
	ds_read_b64_tr_b16 v[18:19], v16
	ds_read_b64_tr_b16 v[20:21], v16 offset:576
	ds_read_b64_tr_b16 v[22:23], v16 offset:4608
	ds_read_b64_tr_b16 v[24:25], v16 offset:5184
	s_waitcnt lgkmcnt(0)
	v_mfma_f32_16x16x32_bf16 v[18:21], v[4:7], v[18:21], 0
	v_lshl_add_u64 v[26:27], v[0:1], 0, 64
	v_lshl_add_u64 v[0:1], v[0:1], 0, s[34:35]
	v_mfma_f32_16x16x32_bf16 v[18:21], v[8:11], v[22:25], v[18:21]
	s_nop 7
	v_cvt_pk_bf16_f32 v18, v18, v19
	v_cvt_pk_bf16_f32 v19, v20, v21
	flat_store_dwordx2 v[12:13], v[18:19] offset:64
	ds_read_b64_tr_b16 v[18:19], v16 offset:32
	ds_read_b64_tr_b16 v[20:21], v16 offset:608
	ds_read_b64_tr_b16 v[22:23], v16 offset:4640
	ds_read_b64_tr_b16 v[24:25], v16 offset:5216
	s_waitcnt lgkmcnt(0)
; #define LAS __attribute__((address_space(3)))
; __device__ __forceinline__ unsigned pk2(float lo, float hi) { const f32x2_t v = {lo, hi}; const bf16x2_t b = __builtin_convertvector(v, bf16x2_t); return __builtin_bit_cast(unsigned, b); }
; __device__ __forceinline__ void w_kv(const LAS bf16_t* vN, const LAS bf16_t* kN, bf16_t* S, int lo, int fq) {
; #pragma unroll
;     for (int db = 0; db < 4; ++db) {
;         bf16x8 kf[2];
; #pragma unroll
;         for (int kk = 0; kk < 2; ++kk) kf[kk] = tr_frag(kN, 32 * kk + 8 * fq, 32 * kk + 8 * fq + 4, 16 * db, lo);
; #pragma unroll
;         for (int eb = 0; eb < 4; ++eb) { f32x4 acc = {0.f, 0.f, 0.f, 0.f};
; #pragma unroll
;             for (int kk = 0; kk < 2; ++kk) { const bf16x8 vf = tr_frag(vN, 32 * kk + 8 * fq, 32 * kk + 8 * fq + 4, 16 * eb, lo); acc = __builtin_amdgcn_mfma_f32_16x16x32_bf16(kf[kk], vf, acc, 0, 0, 0); }
;             *(unsigned long long*)(S + (16 * eb + lo) * 64 + 16 * db + 4 * fq) = (unsigned long long)pk2(acc[0], acc[1]) | ((unsigned long long)pk2(acc[2], acc[3]) << 32); }
;     }
; }
	v_mfma_f32_16x16x32_bf16 v[18:21], v[4:7], v[18:21], 0
	v_mfma_f32_16x16x32_bf16 v[18:21], v[8:11], v[22:25], v[18:21]
	s_nop 7
	v_cvt_pk_bf16_f32 v18, v18, v19
	v_cvt_pk_bf16_f32 v19, v20, v21
	flat_store_dwordx2 v[12:13], v[18:19] offset:2112
	ds_read_b64_tr_b16 v[18:19], v16 offset:64
	ds_read_b64_tr_b16 v[20:21], v16 offset:640
	ds_read_b64_tr_b16 v[22:23], v16 offset:4672
	ds_read_b64_tr_b16 v[24:25], v16 offset:5248
	s_waitcnt lgkmcnt(0)
	v_mfma_f32_16x16x32_bf16 v[18:21], v[4:7], v[18:21], 0
	v_mfma_f32_16x16x32_bf16 v[18:21], v[8:11], v[22:25], v[18:21]
	s_nop 7
	v_cvt_pk_bf16_f32 v18, v18, v19
	v_cvt_pk_bf16_f32 v19, v20, v21
	v_lshl_add_u64 v[20:21], v[26:27], 0, v[14:15]
	flat_store_dwordx2 v[20:21], v[18:19]
	ds_read_b64_tr_b16 v[18:19], v16 offset:96
	ds_read_b64_tr_b16 v[20:21], v16 offset:672
	s_waitcnt lgkmcnt(0)
	v_mfma_f32_16x16x32_bf16 v[4:7], v[4:7], v[18:21], 0
	ds_read_b64_tr_b16 v[18:19], v16 offset:4704
	ds_read_b64_tr_b16 v[20:21], v16 offset:5280
	v_lshl_add_u64 v[14:15], v[0:1], 0, v[14:15]
	v_lshl_add_u64 v[0:1], v[0:1], 0, v[2:3]
	s_waitcnt lgkmcnt(0)
	v_mfma_f32_16x16x32_bf16 v[4:7], v[8:11], v[18:21], v[4:7]
	s_nop 7
	v_cvt_pk_bf16_f32 v4, v4, v5
	v_cvt_pk_bf16_f32 v5, v6, v7
	v_lshl_add_u64 v[6:7], v[26:27], 0, v[2:3]
	flat_store_dwordx2 v[6:7], v[4:5]
	ds_read_b64_tr_b16 v[4:5], v16 offset:9312
	ds_read_b64_tr_b16 v[6:7], v16 offset:9888
	ds_read_b64_tr_b16 v[8:9], v16 offset:13920
	ds_read_b64_tr_b16 v[10:11], v16 offset:14496
	ds_read_b64_tr_b16 v[18:19], v16
	ds_read_b64_tr_b16 v[20:21], v16 offset:576
	ds_read_b64_tr_b16 v[22:23], v16 offset:4608
	ds_read_b64_tr_b16 v[24:25], v16 offset:5184
	s_waitcnt lgkmcnt(0)
	v_mfma_f32_16x16x32_bf16 v[18:21], v[4:7], v[18:21], 0
	v_mfma_f32_16x16x32_bf16 v[18:21], v[8:11], v[22:25], v[18:21]
	s_nop 7
	v_cvt_pk_bf16_f32 v18, v18, v19
	v_cvt_pk_bf16_f32 v19, v20, v21
	flat_store_dwordx2 v[12:13], v[18:19] offset:96
	ds_read_b64_tr_b16 v[18:19], v16 offset:32
	ds_read_b64_tr_b16 v[20:21], v16 offset:608
	ds_read_b64_tr_b16 v[22:23], v16 offset:4640
	ds_read_b64_tr_b16 v[24:25], v16 offset:5216
	s_waitcnt lgkmcnt(0)
	v_mfma_f32_16x16x32_bf16 v[18:21], v[4:7], v[18:21], 0
	v_mfma_f32_16x16x32_bf16 v[18:21], v[8:11], v[22:25], v[18:21]
	s_nop 7
	v_cvt_pk_bf16_f32 v18, v18, v19
	v_cvt_pk_bf16_f32 v19, v20, v21
	flat_store_dwordx2 v[12:13], v[18:19] offset:2144
	ds_read_b64_tr_b16 v[18:19], v16 offset:64
	ds_read_b64_tr_b16 v[20:21], v16 offset:640
	ds_read_b64_tr_b16 v[22:23], v16 offset:4672
	ds_read_b64_tr_b16 v[24:25], v16 offset:5248
	s_waitcnt lgkmcnt(0)
	v_mfma_f32_16x16x32_bf16 v[18:21], v[4:7], v[18:21], 0
	v_mfma_f32_16x16x32_bf16 v[18:21], v[8:11], v[22:25], v[18:21]
	s_nop 7
	v_cvt_pk_bf16_f32 v12, v18, v19
	v_cvt_pk_bf16_f32 v13, v20, v21
	flat_store_dwordx2 v[14:15], v[12:13]
	ds_read_b64_tr_b16 v[12:13], v16 offset:96
	ds_read_b64_tr_b16 v[14:15], v16 offset:672
	s_waitcnt lgkmcnt(0)
	v_mfma_f32_16x16x32_bf16 v[4:7], v[4:7], v[12:15], 0
	ds_read_b64_tr_b16 v[12:13], v16 offset:4704
	ds_read_b64_tr_b16 v[14:15], v16 offset:5280
	s_waitcnt lgkmcnt(0)
	v_mfma_f32_16x16x32_bf16 v[4:7], v[8:11], v[12:15], v[4:7]
	s_nop 7
	v_cvt_pk_bf16_f32 v4, v4, v5
	v_cvt_pk_bf16_f32 v5, v6, v7
	flat_store_dwordx2 v[0:1], v[4:5]
	s_waitcnt lgkmcnt(0)
	s_branch .LBB0_515

; #define LAS __attribute__((address_space(3)))
; __device__ __forceinline__ void ld8bf(const bf16_t* p, float (&o)[8]) { unpack8(*(const u32x4*)p, o); }
; __device__ __forceinline__ const float* in_ptr(const Args& a, int i) { asm volatile("" : "+s"(i)); return a.in[i]; }
; __device__ __forceinline__ void w_lru_m1(const Args& a, int l, unsigned char* ws, const bf16_t* proj, bf16_t* y, LAS unsigned char* wl, int b, int ck_, int h, int lane) {
;     LAS float* xcf = (LAS float*)wl;
;     const int row0 = b * SEQ + 64 * ck_, lo = lane & 15, fq = lane >> 4;
;     const float* cw = in_ptr(a, I_LCW) + (size_t)l * 4 * 512; const float* cbias = in_ptr(a, I_LCB) + l * 512;
;     const bf16_t* gwt = (const bf16_t*)(ws + WS_GATE) + (size_t)l * 65536;
;     const bf16_t* waT = gwt + h * 4096; const bf16_t* wxT = gwt + 32768 + h * 4096;
;     const float* ba = in_ptr(a, I_BA) + l * 512 + 64 * h; const float* bx = in_ptr(a, I_BX) + l * 512 + 64 * h; const float* lam = in_ptr(a, I_LAM) + l * 512 + 64 * h;
;     bf16x8 nWa[2], nWx[2]; f32x4 nba, nbx, nlam;
; #pragma unroll
;     for (int kk = 0; kk < 2; ++kk) { nWa[kk] = *(const bf16x8*)(waT + lo * 64 + 32 * kk + 8 * fq); nWx[kk] = *(const bf16x8*)(wxT + lo * 64 + 32 * kk + 8 * fq); }
;     nba = *(const f32x4*)(ba + 4 * fq); nbx = *(const f32x4*)(bx + 4 * fq); nlam = *(const f32x4*)(lam + 4 * fq);
;     bf16x8 Xf[4][2];
; #pragma unroll
;     for (int kk = 0; kk < 2; ++kk) { const int ch0 = 64 * h + 32 * kk + 8 * fq; float w[4][8], bs[8];
; #pragma unroll
;         for (int j = 0; j < 8; ++j) { bs[j] = cbias[ch0 + j];
; #pragma unroll
;             for (int k = 0; k < 4; ++k) w[k][j] = cw[k * 512 + ch0 + j]; }
; #pragma unroll
;         for (int tb = 0; tb < 4; ++tb) { const int tok = 16 * tb + lo, t = 64 * ck_ + tok; float s[8];
; #pragma unroll
;             for (int j = 0; j < 8; ++j) s[j] = bs[j];
; #pragma unroll
;             for (int k = 0; k < 4; ++k) { const int tt = t - 3 + k; float x[8];
;                 ld8bf(proj + (size_t)(b * SEQ + (tt >= 0 ? tt : 0)) * NIN + C_LX + ch0, x);
; #pragma unroll
;                 for (int j = 0; j < 8; ++j) s[j] += (tt >= 0 ? w[k][j] : 0.f) * x[j]; }
;             Xf[tb][kk] = pack_frag(s);
; #pragma unroll
;             for (int j = 0; j < 8; ++j) xcf[tok * 65 + 32 * kk + 8 * fq + j] = s[j]; }
.LBB0_520:
	s_setprio 2
	s_lshr_b32 s20, s24, 8
	s_lshr_b32 s21, s24, 9
	s_add_i32 s20, s20, s24
	s_and_b32 s21, s21, 12
	s_add_i32 s20, s20, s21
	s_and_b32 s91, s20, 15
	s_cmp_gt_u32 s91, 7
	s_cbranch_scc1 .LBB0_519
	s_ashr_i32 s20, s24, 31
	s_ashr_i32 s90, s24, 4
	s_lshr_b32 s20, s20, 25
	s_add_i32 s27, s90, s20
	s_and_b32 s20, s27, 0xffffff80
	v_mov_b32_e32 v122, v144
	s_mov_b32 s34, 3
	s_sub_i32 s46, s90, s20
	s_ashr_i32 s35, s34, 31
	s_lshl_b32 s20, s46, 6
	s_lshl_b64 s[34:35], s[34:35], 3
	s_add_u32 s34, s0, s34
	s_addc_u32 s35, s1, s35
	s_load_dwordx2 s[40:41], s[34:35], 0x0
	s_mov_b32 s34, 4
	s_ashr_i32 s35, s34, 31
	s_lshl_b64 s[34:35], s[34:35], 3
	s_add_u32 s34, s0, s34
	s_addc_u32 s35, s1, s35
	s_lshl_b32 s21, s91, 13
	s_add_u32 s92, s2, s21
	s_addc_u32 s93, s3, 0
	s_load_dwordx2 s[42:43], s[34:35], 0x0
	s_add_u32 s34, s68, s21
	s_mov_b32 s44, 6
	s_addc_u32 s35, s70, 0
	s_ashr_i32 s45, s44, 31
	s_lshl_b64 s[44:45], s[44:45], 3
	s_add_u32 s44, s0, s44
	s_addc_u32 s45, s1, s45
	s_waitcnt lgkmcnt(0)
	s_mov_b32 s48, 8
	s_load_dwordx2 s[44:45], s[44:45], 0x0
	s_ashr_i32 s49, s48, 31
	s_lshl_b32 s21, s91, 6
	s_lshl_b64 s[48:49], s[48:49], 3
	s_add_u32 s48, s0, s48
	s_addc_u32 s49, s1, s49
	s_load_dwordx2 s[48:49], s[48:49], 0x0
	v_ashrrev_i32_e32 v8, 4, v122
	v_and_b32_e32 v136, 15, v122
	v_lshlrev_b32_e32 v4, 3, v8
	v_lshlrev_b32_e32 v2, 7, v136
	s_waitcnt lgkmcnt(0)
	s_add_u32 s47, s48, s88
	s_mov_b32 s48, 9
	s_addc_u32 s50, s49, s89
	s_ashr_i32 s49, s48, 31
	s_lshl_b64 s[48:49], s[48:49], 3
	s_add_u32 s48, s0, s48
	s_addc_u32 s49, s1, s49
	s_add_u32 s48, s78, 0x3b00000
	s_addc_u32 s49, s79, 0x0
	v_ashrrev_i32_e32 v5, 31, v4
	v_lshl_add_u64 v[0:1], s[92:93], 0, v[2:3]
	v_lshlrev_b64 v[100:101], 1, v[4:5]
	v_lshl_add_u64 v[0:1], v[0:1], 0, v[100:101]
	s_waitcnt lgkmcnt(0)
	s_add_u32 s51, s48, s88
	s_addc_u32 s52, s49, s89
	s_lshl_b32 s27, s27, 6
	s_and_b32 s27, s27, 0xffffe000
	s_add_u32 s48, s40, s96
	s_addc_u32 s49, s41, s97
	s_add_u32 s42, s42, s88
	s_addc_u32 s43, s43, s89
	s_add_u32 s40, s44, s88
	s_addc_u32 s41, s45, s89
	s_lshl_b32 s53, s91, 8
	s_add_u32 s40, s40, s53
	v_lshl_add_u64 v[6:7], s[34:35], 0, v[2:3]
	s_addc_u32 s41, s41, 0
	v_lshl_add_u64 v[6:7], v[6:7], 0, v[100:101]
	global_load_dwordx4 v[52:55], v[0:1], off
	global_load_dwordx4 v[56:59], v[6:7], off
	global_load_dwordx4 v[60:63], v[0:1], off offset:64
	global_load_dwordx4 v[64:67], v[6:7], off offset:64
	s_add_u32 s44, s47, s53
	v_lshlrev_b32_e32 v0, 2, v8
	s_addc_u32 s45, s50, 0
	v_ashrrev_i32_e32 v1, 31, v0
	s_add_u32 s50, s51, s53
	v_lshlrev_b64 v[6:7], 2, v[0:1]
	s_addc_u32 s51, s52, 0
	v_lshl_add_u64 v[108:109], s[40:41], 0, v[6:7]
	s_add_i32 s40, s20, -3
	v_add_u32_e32 v78, s21, v4
	v_lshl_add_u64 v[110:111], s[44:45], 0, v[6:7]
	v_lshl_add_u64 v[112:113], s[50:51], 0, v[6:7]
	v_ashrrev_i32_e32 v79, 31, v78
	v_add_u32_e32 v6, s40, v136
	v_lshlrev_b64 v[4:5], 2, v[78:79]
	v_cmp_lt_i32_e64 s[50:51], -1, v6
	v_lshl_add_u64 v[76:77], s[42:43], 0, v[4:5]
	v_lshl_add_u64 v[86:87], s[48:49], 0, v[4:5]
	v_mul_u32_u24_e32 v186, 0x7e0, v8
	v_lshl_add_u32 v186, v136, 4, v186
	v_mov_b32_e32 v187, 0
	v_lshl_add_u64 v[188:189], v[86:87], 0, v[186:187]
	global_load_dwordx4 v[146:149], v[188:189], off
	v_lshlrev_b32_e32 v186, 4, v136
	v_lshlrev_b32_e32 v187, 5, v8
	v_sub_u32_e32 v186, v186, v187
	v_ashrrev_i32_e32 v187, 31, v186
	v_lshl_add_u64 v[188:189], v[76:77], 0, v[186:187]
	global_load_dwordx4 v[150:153], v[188:189], off
	s_mov_b64 s[42:43], 0x1000
	v_cndmask_b32_e64 v4, 0, v6, s[50:51]
	v_lshl_add_u64 v[36:37], v[86:87], 0, s[42:43]
	s_mov_b64 s[42:43], 0x1800
	v_lshl_add_u64 v[80:81], v[78:79], 1, s[8:9]
	v_add_u32_e32 v79, s27, v4
	v_lshl_add_u64 v[82:83], v[86:87], 0, s[42:43]
	v_max_i32_e32 v4, -1, v6
	s_or_b32 s80, s27, 1
	v_add_u32_e32 v92, s80, v4
	v_max_i32_e32 v4, -2, v6
	s_or_b32 s81, s27, 2
	v_add_u32_e32 v93, s81, v4
	s_cmp_gt_i32 s46, -1
	v_or_b32_e32 v4, s20, v136
	s_cselect_b64 s[42:43], -1, 0
	v_cndmask_b32_e64 v4, 0, v4, s[42:43]
	v_add_u32_e32 v94, s27, v4
	global_load_dwordx4 v[48:51], v[108:109], off
	global_load_dwordx4 v[44:47], v[110:111], off
	global_load_dwordx4 v[88:91], v[112:113], off
	v_lshl_add_u32 v95, v8, 5, s6
	v_cmp_lt_i32_e64 s[48:49], -2, v6
	v_cmp_lt_i32_e64 s[44:45], -3, v6
	s_nop 0
	v_add_co_u32_e32 v96, vcc, s73, v86
	v_mad_u32_u24 v121, v136, s76, v95
	s_nop 0
	v_addc_co_u32_e32 v97, vcc, 0, v87, vcc
	s_nop 0
	s_nop 0
	v_add_u32_e32 v186, s20, v136
	v_add_u32_e32 v187, -16, v186
	v_max_i32_e32 v187, 0, v187
	v_add_u32_e32 v187, s27, v187
	v_add_u32_e32 v186, s27, v186
	v_mad_i64_i32 v[188:189], s[46:47], v187, s72, v[80:81]
	global_load_dwordx4 v[222:225], v[188:189], off
	global_load_dwordx4 v[242:245], v[188:189], off offset:64
	v_mad_i64_i32 v[188:189], s[46:47], v186, s72, v[80:81]
	global_load_dwordx4 v[226:229], v[188:189], off
	global_load_dwordx4 v[246:249], v[188:189], off offset:64
	v_add_u32_e32 v187, 16, v186
	v_mad_i64_i32 v[188:189], s[46:47], v187, s72, v[80:81]
	global_load_dwordx4 v[230:233], v[188:189], off
	global_load_dwordx4 v[250:253], v[188:189], off offset:64
	v_add_u32_e32 v187, 32, v186
	v_mad_i64_i32 v[188:189], s[46:47], v187, s72, v[80:81]
	global_load_dwordx4 v[234:237], v[188:189], off
	global_load_dwordx4 v[190:193], v[188:189], off offset:64
	v_add_u32_e32 v187, 48, v186
	v_mad_i64_i32 v[188:189], s[46:47], v187, s72, v[80:81]
	global_load_dwordx4 v[238:241], v[188:189], off
	global_load_dwordx4 v[194:197], v[188:189], off offset:64
	v_or_b32_e32 v140, 16, v136
	v_or_b32_e32 v139, 32, v136
	v_or_b32_e32 v137, 48, v136
	v_mov_b64_e32 v[102:103], s[8:9]
	s_waitcnt vmcnt(13)
; __device__ __forceinline__ void ld8bf(const bf16_t* p, float (&o)[8]) { unpack8(*(const u32x4*)p, o); }
; __device__ __forceinline__ bf16x8 pack_frag(const float (&v)[8]) { return __builtin_bit_cast(bf16x8, pack8(v)); }
; __device__ __forceinline__ void w_lru_m1(const Args& a, int l, unsigned char* ws, const bf16_t* proj, bf16_t* y, LAS unsigned char* wl, int b, int ck_, int h, int lane) {
;     ...
;     for (int kk = 0; kk < 2; ++kk) { const int ch0 = 64 * h + 32 * kk + 8 * fq; float w[4][8], bs[8];
; #pragma unroll
;         for (int j = 0; j < 8; ++j) { bs[j] = cbias[ch0 + j];
; #pragma unroll
;             for (int k = 0; k < 4; ++k) w[k][j] = cw[k * 512 + ch0 + j]; }
; #pragma unroll
;         for (int tb = 0; tb < 4; ++tb) { const int tok = 16 * tb + lo, t = 64 * ck_ + tok; float s[8];
; #pragma unroll
;             for (int j = 0; j < 8; ++j) s[j] = bs[j];
; #pragma unroll
;             for (int k = 0; k < 4; ++k) { const int tt = t - 3 + k; float x[8];
;                 ld8bf(proj + (size_t)(b * SEQ + (tt >= 0 ? tt : 0)) * NIN + C_LX + ch0, x);
; #pragma unroll
;                 for (int j = 0; j < 8; ++j) s[j] += (tt >= 0 ? w[k][j] : 0.f) * x[j]; }
;             Xf[tb][kk] = pack_frag(s);
; #pragma unroll
;             for (int j = 0; j < 8; ++j) xcf[tok * 65 + 32 * kk + 8 * fq + j] = s[j]; }
	v_lshl_add_u32 v198, v144, 4, s6
	v_lshl_add_u32 v154, v136, 4, s6
	v_mov_b32_e32 v199, v95
	ds_write_b128 v198, v[146:149] offset:16640
	ds_write_b128 v154, v[150:153] offset:17664
	ds_read_b128 v[32:35], v199 offset:16640
	ds_read_b128 v[24:27], v199 offset:16656
	ds_read_b128 v[40:43], v199 offset:16896
	ds_read_b128 v[28:31], v199 offset:16912
	ds_read_b128 v[68:71], v199 offset:17152
	ds_read_b128 v[36:39], v199 offset:17168
	ds_read_b128 v[104:107], v199 offset:17408
	ds_read_b128 v[114:117], v199 offset:17424
	ds_read_b128 v[4:7], v199 offset:17664
	ds_read_b128 v[20:23], v199 offset:17680
	s_waitcnt vmcnt(0) lgkmcnt(0)
	v_mov_b32_dpp v72, v222 row_ror:3 row_mask:0xf bank_mask:0xf
	v_mov_b32_dpp v73, v223 row_ror:3 row_mask:0xf bank_mask:0xf
	v_mov_b32_dpp v74, v224 row_ror:3 row_mask:0xf bank_mask:0xf
	v_mov_b32_dpp v75, v225 row_ror:3 row_mask:0xf bank_mask:0xf
	v_mov_b32_dpp v72, v226 row_shr:3 row_mask:0xf bank_mask:0xf
	v_mov_b32_dpp v73, v227 row_shr:3 row_mask:0xf bank_mask:0xf
	v_mov_b32_dpp v74, v228 row_shr:3 row_mask:0xf bank_mask:0xf
	v_mov_b32_dpp v75, v229 row_shr:3 row_mask:0xf bank_mask:0xf
	v_mov_b32_dpp v16, v222 row_ror:2 row_mask:0xf bank_mask:0xf
	v_mov_b32_dpp v17, v223 row_ror:2 row_mask:0xf bank_mask:0xf
	v_mov_b32_dpp v18, v224 row_ror:2 row_mask:0xf bank_mask:0xf
	v_mov_b32_dpp v19, v225 row_ror:2 row_mask:0xf bank_mask:0xf
	v_mov_b32_dpp v16, v226 row_shr:2 row_mask:0xf bank_mask:0xf
	v_mov_b32_dpp v17, v227 row_shr:2 row_mask:0xf bank_mask:0xf
	v_mov_b32_dpp v18, v228 row_shr:2 row_mask:0xf bank_mask:0xf
	v_mov_b32_dpp v19, v229 row_shr:2 row_mask:0xf bank_mask:0xf
	v_mov_b32_dpp v12, v222 row_ror:1 row_mask:0xf bank_mask:0xf
	v_mov_b32_dpp v13, v223 row_ror:1 row_mask:0xf bank_mask:0xf
	v_mov_b32_dpp v14, v224 row_ror:1 row_mask:0xf bank_mask:0xf
	v_mov_b32_dpp v15, v225 row_ror:1 row_mask:0xf bank_mask:0xf
	v_mov_b32_dpp v12, v226 row_shr:1 row_mask:0xf bank_mask:0xf
	v_mov_b32_dpp v13, v227 row_shr:1 row_mask:0xf bank_mask:0xf
	v_mov_b32_dpp v14, v228 row_shr:1 row_mask:0xf bank_mask:0xf
	v_mov_b32_dpp v15, v229 row_shr:1 row_mask:0xf bank_mask:0xf
	v_mov_b64_e32 v[8:9], v[226:227]
	v_mov_b64_e32 v[10:11], v[228:229]
	v_lshlrev_b32_e32 v82, 16, v72
	v_lshlrev_b32_e32 v84, 16, v73
	v_and_b32_e32 v83, 0xffff0000, v72
	v_and_b32_e32 v85, 0xffff0000, v73
	v_cndmask_b32_e64 v73, 0, v33, s[50:51]
	v_cndmask_b32_e64 v72, 0, v32, s[50:51]
	v_cndmask_b32_e64 v99, 0, v35, s[50:51]
	v_cndmask_b32_e64 v98, 0, v34, s[50:51]
	v_pk_fma_f32 v[84:85], v[98:99], v[84:85], v[6:7]
	v_pk_fma_f32 v[72:73], v[72:73], v[82:83], v[4:5]
	v_lshlrev_b32_e32 v82, 16, v17
	v_lshlrev_b32_e32 v98, 16, v16
	v_and_b32_e32 v83, 0xffff0000, v17
	v_and_b32_e32 v99, 0xffff0000, v16
	v_cndmask_b32_e64 v17, 0, v43, s[48:49]
	v_cndmask_b32_e64 v16, 0, v42, s[48:49]
	v_cndmask_b32_e64 v119, 0, v41, s[48:49]
	v_cndmask_b32_e64 v118, 0, v40, s[48:49]
	v_pk_fma_f32 v[72:73], v[118:119], v[98:99], v[72:73]
	v_pk_fma_f32 v[16:17], v[16:17], v[82:83], v[84:85]
	v_lshlrev_b32_e32 v82, 16, v12
	v_lshlrev_b32_e32 v84, 16, v13
	v_and_b32_e32 v83, 0xffff0000, v12
	v_and_b32_e32 v85, 0xffff0000, v13
	v_cndmask_b32_e64 v13, 0, v69, s[44:45]
	v_cndmask_b32_e64 v12, 0, v68, s[44:45]
	v_cndmask_b32_e64 v99, 0, v71, s[44:45]
	v_cndmask_b32_e64 v98, 0, v70, s[44:45]
	v_pk_fma_f32 v[16:17], v[98:99], v[84:85], v[16:17]
	v_pk_fma_f32 v[12:13], v[12:13], v[82:83], v[72:73]
	v_lshlrev_b32_e32 v84, 16, v9
	v_lshlrev_b32_e32 v98, 16, v8
	v_and_b32_e32 v85, 0xffff0000, v9
	v_and_b32_e32 v99, 0xffff0000, v8
	v_cndmask_b32_e64 v73, 0, v107, s[42:43]
	v_cndmask_b32_e64 v72, 0, v106, s[42:43]
	v_cndmask_b32_e64 v83, 0, v105, s[42:43]
	v_cndmask_b32_e64 v82, 0, v104, s[42:43]
	v_pk_fma_f32 v[8:9], v[82:83], v[98:99], v[12:13]
	v_pk_fma_f32 v[12:13], v[72:73], v[84:85], v[16:17]
	v_cvt_pk_bf16_f32 v16, v8, v9
	v_cvt_pk_bf16_f32 v17, v12, v13
	ds_write2_b32 v121, v12, v13 offset0:2 offset1:3
	ds_write2_b32 v121, v8, v9 offset1:1
	v_lshlrev_b32_e32 v8, 16, v74
	v_lshlrev_b32_e32 v12, 16, v75
	v_and_b32_e32 v9, 0xffff0000, v74
	v_and_b32_e32 v13, 0xffff0000, v75
	v_cndmask_b32_e64 v75, 0, v25, s[50:51]
	v_cndmask_b32_e64 v74, 0, v24, s[50:51]
	v_cndmask_b32_e64 v85, 0, v27, s[50:51]
	v_cndmask_b32_e64 v84, 0, v26, s[50:51]
	v_pk_fma_f32 v[12:13], v[84:85], v[12:13], v[22:23]
	v_pk_fma_f32 v[8:9], v[74:75], v[8:9], v[20:21]
	v_lshlrev_b32_e32 v74, 16, v19
	v_lshlrev_b32_e32 v84, 16, v18
	v_and_b32_e32 v75, 0xffff0000, v19
	v_and_b32_e32 v85, 0xffff0000, v18
	v_cndmask_b32_e64 v19, 0, v31, s[48:49]
	v_cndmask_b32_e64 v18, 0, v30, s[48:49]
	v_cndmask_b32_e64 v99, 0, v29, s[48:49]
	v_cndmask_b32_e64 v98, 0, v28, s[48:49]
	v_pk_fma_f32 v[8:9], v[98:99], v[84:85], v[8:9]
	v_pk_fma_f32 v[12:13], v[18:19], v[74:75], v[12:13]
	v_lshlrev_b32_e32 v18, 16, v14
	v_lshlrev_b32_e32 v74, 16, v15
	v_and_b32_e32 v19, 0xffff0000, v14
	v_and_b32_e32 v75, 0xffff0000, v15
	v_cndmask_b32_e64 v15, 0, v37, s[44:45]
	v_cndmask_b32_e64 v14, 0, v36, s[44:45]
	v_cndmask_b32_e64 v85, 0, v39, s[44:45]
	v_cndmask_b32_e64 v84, 0, v38, s[44:45]
	v_pk_fma_f32 v[12:13], v[84:85], v[74:75], v[12:13]
	v_pk_fma_f32 v[8:9], v[14:15], v[18:19], v[8:9]
	v_lshlrev_b32_e32 v14, 16, v11
	v_lshlrev_b32_e32 v18, 16, v10
	v_and_b32_e32 v15, 0xffff0000, v11
	v_and_b32_e32 v19, 0xffff0000, v10
	v_cndmask_b32_e64 v75, 0, v117, s[42:43]
	v_cndmask_b32_e64 v74, 0, v116, s[42:43]
	v_cndmask_b32_e64 v85, 0, v115, s[42:43]
	v_cndmask_b32_e64 v84, 0, v114, s[42:43]
	v_add_u32_e32 v98, s40, v140
	v_pk_fma_f32 v[8:9], v[84:85], v[18:19], v[8:9]
	v_pk_fma_f32 v[10:11], v[74:75], v[14:15], v[12:13]
	v_cmp_lt_i32_e64 s[62:63], -1, v98
; __device__ __forceinline__ void ld8bf(const bf16_t* p, float (&o)[8]) { unpack8(*(const u32x4*)p, o); }
; __device__ __forceinline__ bf16x8 pack_frag(const float (&v)[8]) { return __builtin_bit_cast(bf16x8, pack8(v)); }
; __device__ __forceinline__ void w_lru_m1(const Args& a, int l, unsigned char* ws, const bf16_t* proj, bf16_t* y, LAS unsigned char* wl, int b, int ck_, int h, int lane) {
;     ...
;     for (int kk = 0; kk < 2; ++kk) { const int ch0 = 64 * h + 32 * kk + 8 * fq; float w[4][8], bs[8];
; #pragma unroll
;         for (int j = 0; j < 8; ++j) { bs[j] = cbias[ch0 + j];
; #pragma unroll
;             for (int k = 0; k < 4; ++k) w[k][j] = cw[k * 512 + ch0 + j]; }
; #pragma unroll
;         for (int tb = 0; tb < 4; ++tb) { const int tok = 16 * tb + lo, t = 64 * ck_ + tok; float s[8];
; #pragma unroll
;             for (int j = 0; j < 8; ++j) s[j] = bs[j];
; #pragma unroll
;             for (int k = 0; k < 4; ++k) { const int tt = t - 3 + k; float x[8];
;                 ld8bf(proj + (size_t)(b * SEQ + (tt >= 0 ? tt : 0)) * NIN + C_LX + ch0, x);
; #pragma unroll
;                 for (int j = 0; j < 8; ++j) s[j] += (tt >= 0 ? w[k][j] : 0.f) * x[j]; }
;             Xf[tb][kk] = pack_frag(s);
; #pragma unroll
;             for (int j = 0; j < 8; ++j) xcf[tok * 65 + 32 * kk + 8 * fq + j] = s[j]; }
	v_cvt_pk_bf16_f32 v18, v8, v9
	ds_write2_b32 v121, v10, v11 offset0:6 offset1:7
	ds_write2_b32 v121, v8, v9 offset0:4 offset1:5
	v_cndmask_b32_e64 v8, 0, v98, s[62:63]
	v_cmp_lt_i32_e64 s[60:61], -2, v98
	v_max_i32_e32 v12, -1, v98
	v_cmp_lt_i32_e64 s[58:59], -3, v98
	v_max_i32_e32 v98, -2, v98
	v_add_u32_e32 v142, s81, v98
	v_add_u32_e32 v134, s27, v8
	v_add_u32_e32 v135, s80, v12
	v_mov_b32_dpp v104, v226 row_ror:1 row_mask:0xf bank_mask:0xf
	v_mov_b32_dpp v105, v227 row_ror:1 row_mask:0xf bank_mask:0xf
	v_mov_b32_dpp v106, v228 row_ror:1 row_mask:0xf bank_mask:0xf
	v_mov_b32_dpp v107, v229 row_ror:1 row_mask:0xf bank_mask:0xf
	v_mov_b32_dpp v104, v230 row_shr:1 row_mask:0xf bank_mask:0xf
	v_mov_b32_dpp v105, v231 row_shr:1 row_mask:0xf bank_mask:0xf
	v_mov_b32_dpp v106, v232 row_shr:1 row_mask:0xf bank_mask:0xf
	v_mov_b32_dpp v107, v233 row_shr:1 row_mask:0xf bank_mask:0xf
	v_or_b32_e32 v98, s20, v140
	v_cvt_pk_bf16_f32 v19, v10, v11
	v_mov_b32_dpp v8, v226 row_ror:3 row_mask:0xf bank_mask:0xf
	v_mov_b32_dpp v9, v227 row_ror:3 row_mask:0xf bank_mask:0xf
	v_mov_b32_dpp v10, v228 row_ror:3 row_mask:0xf bank_mask:0xf
	v_mov_b32_dpp v11, v229 row_ror:3 row_mask:0xf bank_mask:0xf
	v_mov_b32_dpp v8, v230 row_shr:3 row_mask:0xf bank_mask:0xf
	v_mov_b32_dpp v9, v231 row_shr:3 row_mask:0xf bank_mask:0xf
	v_mov_b32_dpp v10, v232 row_shr:3 row_mask:0xf bank_mask:0xf
	v_mov_b32_dpp v11, v233 row_shr:3 row_mask:0xf bank_mask:0xf
	v_cndmask_b32_e64 v98, 0, v98, s[42:43]
	v_mov_b32_dpp v12, v226 row_ror:2 row_mask:0xf bank_mask:0xf
	v_mov_b32_dpp v13, v227 row_ror:2 row_mask:0xf bank_mask:0xf
	v_mov_b32_dpp v14, v228 row_ror:2 row_mask:0xf bank_mask:0xf
	v_mov_b32_dpp v15, v229 row_ror:2 row_mask:0xf bank_mask:0xf
	v_mov_b32_dpp v12, v230 row_shr:2 row_mask:0xf bank_mask:0xf
	v_mov_b32_dpp v13, v231 row_shr:2 row_mask:0xf bank_mask:0xf
	v_mov_b32_dpp v14, v232 row_shr:2 row_mask:0xf bank_mask:0xf
	v_mov_b32_dpp v15, v233 row_shr:2 row_mask:0xf bank_mask:0xf
	v_add_u32_e32 v143, s27, v98
	v_mov_b64_e32 v[114:115], v[230:231]
	v_mov_b64_e32 v[116:117], v[232:233]
	v_mov_b32_e32 v98, 0x1040
	v_mad_u32_u24 v123, v136, s76, v98
	v_cndmask_b32_e64 v127, 0, v35, s[62:63]
	v_cndmask_b32_e64 v126, 0, v34, s[62:63]
	v_cndmask_b32_e64 v129, 0, v41, s[60:61]
	v_cndmask_b32_e64 v128, 0, v40, s[60:61]
	v_add_u32_e32 v125, v95, v123
	s_waitcnt vmcnt(0) lgkmcnt(0)
	v_lshlrev_b32_e32 v98, 16, v8
	v_lshlrev_b32_e32 v118, 16, v9
	v_and_b32_e32 v99, 0xffff0000, v8
	v_and_b32_e32 v119, 0xffff0000, v9
	v_cndmask_b32_e64 v9, 0, v33, s[62:63]
	v_cndmask_b32_e64 v8, 0, v32, s[62:63]
	v_pk_fma_f32 v[118:119], v[126:127], v[118:119], v[6:7]
	v_pk_fma_f32 v[8:9], v[8:9], v[98:99], v[4:5]
	v_lshlrev_b32_e32 v98, 16, v13
	v_lshlrev_b32_e32 v126, 16, v12
	v_and_b32_e32 v99, 0xffff0000, v13
	v_and_b32_e32 v127, 0xffff0000, v12
	v_cndmask_b32_e64 v13, 0, v43, s[60:61]
	v_cndmask_b32_e64 v12, 0, v42, s[60:61]
	v_pk_fma_f32 v[8:9], v[128:129], v[126:127], v[8:9]
	v_pk_fma_f32 v[12:13], v[12:13], v[98:99], v[118:119]
	v_lshlrev_b32_e32 v98, 16, v104
	v_lshlrev_b32_e32 v118, 16, v105
	v_and_b32_e32 v99, 0xffff0000, v104
	v_and_b32_e32 v119, 0xffff0000, v105
	v_cndmask_b32_e64 v105, 0, v69, s[58:59]
	v_cndmask_b32_e64 v104, 0, v68, s[58:59]
	v_cndmask_b32_e64 v127, 0, v71, s[58:59]
	v_cndmask_b32_e64 v126, 0, v70, s[58:59]
	v_pk_fma_f32 v[12:13], v[126:127], v[118:119], v[12:13]
	v_pk_fma_f32 v[8:9], v[104:105], v[98:99], v[8:9]
	v_lshlrev_b32_e32 v98, 16, v115
	v_lshlrev_b32_e32 v104, 16, v114
	v_and_b32_e32 v99, 0xffff0000, v115
	v_and_b32_e32 v105, 0xffff0000, v114
	v_pk_fma_f32 v[8:9], v[82:83], v[104:105], v[8:9]
	v_pk_fma_f32 v[98:99], v[72:73], v[98:99], v[12:13]
	v_cvt_pk_bf16_f32 v12, v8, v9
	v_cvt_pk_bf16_f32 v13, v98, v99
	ds_write2_b32 v125, v98, v99 offset0:2 offset1:3
	ds_write2_b32 v125, v8, v9 offset1:1
	v_lshlrev_b32_e32 v8, 16, v10
	v_lshlrev_b32_e32 v98, 16, v11
	v_and_b32_e32 v9, 0xffff0000, v10
	v_and_b32_e32 v99, 0xffff0000, v11
	v_cndmask_b32_e64 v11, 0, v25, s[62:63]
	v_cndmask_b32_e64 v10, 0, v24, s[62:63]
	v_cndmask_b32_e64 v105, 0, v27, s[62:63]
	v_cndmask_b32_e64 v104, 0, v26, s[62:63]
	v_pk_fma_f32 v[98:99], v[104:105], v[98:99], v[22:23]
	v_pk_fma_f32 v[8:9], v[10:11], v[8:9], v[20:21]
	v_lshlrev_b32_e32 v10, 16, v15
	v_lshlrev_b32_e32 v104, 16, v14
	v_and_b32_e32 v11, 0xffff0000, v15
	v_and_b32_e32 v105, 0xffff0000, v14
	v_cndmask_b32_e64 v15, 0, v31, s[60:61]
	v_cndmask_b32_e64 v14, 0, v30, s[60:61]
	v_cndmask_b32_e64 v115, 0, v29, s[60:61]
	v_cndmask_b32_e64 v114, 0, v28, s[60:61]
	v_pk_fma_f32 v[8:9], v[114:115], v[104:105], v[8:9]
	v_pk_fma_f32 v[10:11], v[14:15], v[10:11], v[98:99]
	v_lshlrev_b32_e32 v14, 16, v106
	v_lshlrev_b32_e32 v98, 16, v107
	v_and_b32_e32 v15, 0xffff0000, v106
	v_and_b32_e32 v99, 0xffff0000, v107
	v_cndmask_b32_e64 v105, 0, v37, s[58:59]
	v_cndmask_b32_e64 v104, 0, v36, s[58:59]
	v_cndmask_b32_e64 v107, 0, v39, s[58:59]
	v_cndmask_b32_e64 v106, 0, v38, s[58:59]
	v_pk_fma_f32 v[10:11], v[106:107], v[98:99], v[10:11]
	v_pk_fma_f32 v[8:9], v[104:105], v[14:15], v[8:9]
	v_lshlrev_b32_e32 v14, 16, v117
	v_lshlrev_b32_e32 v98, 16, v116
	v_and_b32_e32 v15, 0xffff0000, v117
	v_and_b32_e32 v99, 0xffff0000, v116
	v_add_u32_e32 v114, s40, v139
	v_pk_fma_f32 v[8:9], v[84:85], v[98:99], v[8:9]
	v_pk_fma_f32 v[10:11], v[74:75], v[14:15], v[10:11]
	v_cmp_lt_i32_e64 s[56:57], -1, v114
	v_cvt_pk_bf16_f32 v14, v8, v9
	ds_write2_b32 v125, v10, v11 offset0:6 offset1:7
	ds_write2_b32 v125, v8, v9 offset0:4 offset1:5
	v_cndmask_b32_e64 v8, 0, v114, s[56:57]
	v_max_i32_e32 v98, -1, v114
	v_add_u32_e32 v130, s27, v8
	v_add_u32_e32 v131, s80, v98
; __device__ __forceinline__ void ld8bf(const bf16_t* p, float (&o)[8]) { unpack8(*(const u32x4*)p, o); }
; __device__ __forceinline__ bf16x8 pack_frag(const float (&v)[8]) { return __builtin_bit_cast(bf16x8, pack8(v)); }
; __device__ __forceinline__ void w_lru_m1(const Args& a, int l, unsigned char* ws, const bf16_t* proj, bf16_t* y, LAS unsigned char* wl, int b, int ck_, int h, int lane) {
;     ...
;     for (int kk = 0; kk < 2; ++kk) { const int ch0 = 64 * h + 32 * kk + 8 * fq; float w[4][8], bs[8];
; #pragma unroll
;         for (int j = 0; j < 8; ++j) { bs[j] = cbias[ch0 + j];
; #pragma unroll
;             for (int k = 0; k < 4; ++k) w[k][j] = cw[k * 512 + ch0 + j]; }
; #pragma unroll
;         for (int tb = 0; tb < 4; ++tb) { const int tok = 16 * tb + lo, t = 64 * ck_ + tok; float s[8];
; #pragma unroll
;             for (int j = 0; j < 8; ++j) s[j] = bs[j];
; #pragma unroll
;             for (int k = 0; k < 4; ++k) { const int tt = t - 3 + k; float x[8];
;                 ld8bf(proj + (size_t)(b * SEQ + (tt >= 0 ? tt : 0)) * NIN + C_LX + ch0, x);
; #pragma unroll
;                 for (int j = 0; j < 8; ++j) s[j] += (tt >= 0 ? w[k][j] : 0.f) * x[j]; }
;             Xf[tb][kk] = pack_frag(s);
; #pragma unroll
;             for (int j = 0; j < 8; ++j) xcf[tok * 65 + 32 * kk + 8 * fq + j] = s[j]; }
	v_cvt_pk_bf16_f32 v15, v10, v11
	v_mov_b32_dpp v8, v230 row_ror:3 row_mask:0xf bank_mask:0xf
	v_mov_b32_dpp v9, v231 row_ror:3 row_mask:0xf bank_mask:0xf
	v_mov_b32_dpp v10, v232 row_ror:3 row_mask:0xf bank_mask:0xf
	v_mov_b32_dpp v11, v233 row_ror:3 row_mask:0xf bank_mask:0xf
	v_mov_b32_dpp v8, v234 row_shr:3 row_mask:0xf bank_mask:0xf
	v_mov_b32_dpp v9, v235 row_shr:3 row_mask:0xf bank_mask:0xf
	v_mov_b32_dpp v10, v236 row_shr:3 row_mask:0xf bank_mask:0xf
	v_mov_b32_dpp v11, v237 row_shr:3 row_mask:0xf bank_mask:0xf
	v_cmp_lt_i32_e64 s[54:55], -2, v114
	v_mov_b32_dpp v104, v230 row_ror:2 row_mask:0xf bank_mask:0xf
	v_mov_b32_dpp v105, v231 row_ror:2 row_mask:0xf bank_mask:0xf
	v_mov_b32_dpp v106, v232 row_ror:2 row_mask:0xf bank_mask:0xf
	v_mov_b32_dpp v107, v233 row_ror:2 row_mask:0xf bank_mask:0xf
	v_mov_b32_dpp v104, v234 row_shr:2 row_mask:0xf bank_mask:0xf
	v_mov_b32_dpp v105, v235 row_shr:2 row_mask:0xf bank_mask:0xf
	v_mov_b32_dpp v106, v236 row_shr:2 row_mask:0xf bank_mask:0xf
	v_mov_b32_dpp v107, v237 row_shr:2 row_mask:0xf bank_mask:0xf
	v_max_i32_e32 v98, -2, v114
	v_add_u32_e32 v132, s81, v98
	v_cmp_lt_i32_e64 s[52:53], -3, v114
	v_mov_b32_dpp v114, v230 row_ror:1 row_mask:0xf bank_mask:0xf
	v_mov_b32_dpp v115, v231 row_ror:1 row_mask:0xf bank_mask:0xf
	v_mov_b32_dpp v116, v232 row_ror:1 row_mask:0xf bank_mask:0xf
	v_mov_b32_dpp v117, v233 row_ror:1 row_mask:0xf bank_mask:0xf
	v_mov_b32_dpp v114, v234 row_shr:1 row_mask:0xf bank_mask:0xf
	v_mov_b32_dpp v115, v235 row_shr:1 row_mask:0xf bank_mask:0xf
	v_mov_b32_dpp v116, v236 row_shr:1 row_mask:0xf bank_mask:0xf
	v_mov_b32_dpp v117, v237 row_shr:1 row_mask:0xf bank_mask:0xf
	v_or_b32_e32 v98, s20, v139
	v_cndmask_b32_e64 v98, 0, v98, s[42:43]
	v_add_u32_e32 v133, s27, v98
	v_mov_b64_e32 v[126:127], v[234:235]
	v_mov_b64_e32 v[128:129], v[236:237]
	v_mov_b32_e32 v98, 0x2080
	v_mad_u32_u24 v141, v136, s76, v98
	v_cndmask_b32_e64 v147, 0, v35, s[56:57]
	v_cndmask_b32_e64 v146, 0, v34, s[56:57]
	v_cndmask_b32_e64 v149, 0, v41, s[54:55]
	v_cndmask_b32_e64 v148, 0, v40, s[54:55]
	v_add_u32_e32 v124, v95, v141
	s_waitcnt vmcnt(0) lgkmcnt(0)
	v_lshlrev_b32_e32 v98, 16, v8
	v_lshlrev_b32_e32 v118, 16, v9
	v_and_b32_e32 v99, 0xffff0000, v8
	v_and_b32_e32 v119, 0xffff0000, v9
	v_cndmask_b32_e64 v9, 0, v33, s[56:57]
	v_cndmask_b32_e64 v8, 0, v32, s[56:57]
	v_pk_fma_f32 v[118:119], v[146:147], v[118:119], v[6:7]
	v_pk_fma_f32 v[8:9], v[8:9], v[98:99], v[4:5]
	v_lshlrev_b32_e32 v98, 16, v105
	v_lshlrev_b32_e32 v146, 16, v104
	v_and_b32_e32 v99, 0xffff0000, v105
	v_and_b32_e32 v147, 0xffff0000, v104
	v_cndmask_b32_e64 v105, 0, v43, s[54:55]
	v_cndmask_b32_e64 v104, 0, v42, s[54:55]
	v_pk_fma_f32 v[8:9], v[148:149], v[146:147], v[8:9]
	v_pk_fma_f32 v[98:99], v[104:105], v[98:99], v[118:119]
	v_lshlrev_b32_e32 v104, 16, v114
	v_lshlrev_b32_e32 v118, 16, v115
	v_and_b32_e32 v105, 0xffff0000, v114
	v_and_b32_e32 v119, 0xffff0000, v115
	v_cndmask_b32_e64 v115, 0, v69, s[52:53]
	v_cndmask_b32_e64 v114, 0, v68, s[52:53]
	v_cndmask_b32_e64 v147, 0, v71, s[52:53]
	v_cndmask_b32_e64 v146, 0, v70, s[52:53]
	v_pk_fma_f32 v[98:99], v[146:147], v[118:119], v[98:99]
	v_pk_fma_f32 v[8:9], v[114:115], v[104:105], v[8:9]
	v_lshlrev_b32_e32 v104, 16, v127
	v_lshlrev_b32_e32 v114, 16, v126
	v_and_b32_e32 v105, 0xffff0000, v127
	v_and_b32_e32 v115, 0xffff0000, v126
	v_pk_fma_f32 v[114:115], v[82:83], v[114:115], v[8:9]
	v_pk_fma_f32 v[98:99], v[72:73], v[104:105], v[98:99]
	v_cvt_pk_bf16_f32 v8, v114, v115
	v_cvt_pk_bf16_f32 v9, v98, v99
	ds_write2_b32 v124, v98, v99 offset0:2 offset1:3
	ds_write2_b32 v124, v114, v115 offset1:1
	v_lshlrev_b32_e32 v98, 16, v10
	v_lshlrev_b32_e32 v104, 16, v11
	v_and_b32_e32 v99, 0xffff0000, v10
	v_and_b32_e32 v105, 0xffff0000, v11
	v_cndmask_b32_e64 v11, 0, v25, s[56:57]
	v_cndmask_b32_e64 v10, 0, v24, s[56:57]
	v_cndmask_b32_e64 v115, 0, v27, s[56:57]
	v_cndmask_b32_e64 v114, 0, v26, s[56:57]
	v_pk_fma_f32 v[104:105], v[114:115], v[104:105], v[22:23]
	v_pk_fma_f32 v[10:11], v[10:11], v[98:99], v[20:21]
	v_lshlrev_b32_e32 v98, 16, v107
	v_lshlrev_b32_e32 v114, 16, v106
	v_and_b32_e32 v99, 0xffff0000, v107
	v_and_b32_e32 v115, 0xffff0000, v106
	v_cndmask_b32_e64 v107, 0, v31, s[54:55]
	v_cndmask_b32_e64 v106, 0, v30, s[54:55]
	v_cndmask_b32_e64 v119, 0, v29, s[54:55]
	v_cndmask_b32_e64 v118, 0, v28, s[54:55]
	v_pk_fma_f32 v[10:11], v[118:119], v[114:115], v[10:11]
	v_pk_fma_f32 v[98:99], v[106:107], v[98:99], v[104:105]
	v_lshlrev_b32_e32 v104, 16, v116
	v_lshlrev_b32_e32 v106, 16, v117
	v_and_b32_e32 v105, 0xffff0000, v116
	v_and_b32_e32 v107, 0xffff0000, v117
	v_cndmask_b32_e64 v115, 0, v37, s[52:53]
	v_cndmask_b32_e64 v114, 0, v36, s[52:53]
	v_cndmask_b32_e64 v117, 0, v39, s[52:53]
	v_cndmask_b32_e64 v116, 0, v38, s[52:53]
	v_pk_fma_f32 v[98:99], v[116:117], v[106:107], v[98:99]
	v_pk_fma_f32 v[10:11], v[114:115], v[104:105], v[10:11]
	v_lshlrev_b32_e32 v104, 16, v129
	v_and_b32_e32 v105, 0xffff0000, v129
	v_add_u32_e32 v118, s40, v137
	v_lshlrev_b32_e32 v106, 16, v128
	v_and_b32_e32 v107, 0xffff0000, v128
	v_pk_fma_f32 v[98:99], v[74:75], v[104:105], v[98:99]
	v_cmp_lt_i32_e64 s[46:47], -1, v118
	v_pk_fma_f32 v[106:107], v[84:85], v[106:107], v[10:11]
	v_cvt_pk_bf16_f32 v11, v98, v99
	ds_write2_b32 v124, v98, v99 offset0:6 offset1:7
	ds_write2_b32 v124, v106, v107 offset0:4 offset1:5
	v_cndmask_b32_e64 v98, 0, v118, s[46:47]
	v_add_u32_e32 v126, s27, v98
	v_cvt_pk_bf16_f32 v10, v106, v107
	v_mov_b32_dpp v104, v234 row_ror:3 row_mask:0xf bank_mask:0xf
	v_mov_b32_dpp v105, v235 row_ror:3 row_mask:0xf bank_mask:0xf
	v_mov_b32_dpp v106, v236 row_ror:3 row_mask:0xf bank_mask:0xf
; __device__ __forceinline__ void ld8bf(const bf16_t* p, float (&o)[8]) { unpack8(*(const u32x4*)p, o); }
; __device__ __forceinline__ bf16x8 pack_frag(const float (&v)[8]) { return __builtin_bit_cast(bf16x8, pack8(v)); }
; __device__ __forceinline__ void w_lru_m1(const Args& a, int l, unsigned char* ws, const bf16_t* proj, bf16_t* y, LAS unsigned char* wl, int b, int ck_, int h, int lane) {
;     ...
;     for (int kk = 0; kk < 2; ++kk) { const int ch0 = 64 * h + 32 * kk + 8 * fq; float w[4][8], bs[8];
; #pragma unroll
;         for (int j = 0; j < 8; ++j) { bs[j] = cbias[ch0 + j];
; #pragma unroll
;             for (int k = 0; k < 4; ++k) w[k][j] = cw[k * 512 + ch0 + j]; }
; #pragma unroll
;         for (int tb = 0; tb < 4; ++tb) { const int tok = 16 * tb + lo, t = 64 * ck_ + tok; float s[8];
; #pragma unroll
;             for (int j = 0; j < 8; ++j) s[j] = bs[j];
; #pragma unroll
;             for (int k = 0; k < 4; ++k) { const int tt = t - 3 + k; float x[8];
;                 ld8bf(proj + (size_t)(b * SEQ + (tt >= 0 ? tt : 0)) * NIN + C_LX + ch0, x);
; #pragma unroll
;                 for (int j = 0; j < 8; ++j) s[j] += (tt >= 0 ? w[k][j] : 0.f) * x[j]; }
;             Xf[tb][kk] = pack_frag(s);
; #pragma unroll
;             for (int j = 0; j < 8; ++j) xcf[tok * 65 + 32 * kk + 8 * fq + j] = s[j]; }
	v_mov_b32_dpp v107, v237 row_ror:3 row_mask:0xf bank_mask:0xf
	v_mov_b32_dpp v104, v238 row_shr:3 row_mask:0xf bank_mask:0xf
	v_mov_b32_dpp v105, v239 row_shr:3 row_mask:0xf bank_mask:0xf
	v_mov_b32_dpp v106, v240 row_shr:3 row_mask:0xf bank_mask:0xf
	v_mov_b32_dpp v107, v241 row_shr:3 row_mask:0xf bank_mask:0xf
	v_max_i32_e32 v98, -1, v118
	v_add_u32_e32 v127, s80, v98
	v_mov_b32_dpp v114, v234 row_ror:2 row_mask:0xf bank_mask:0xf
	v_mov_b32_dpp v115, v235 row_ror:2 row_mask:0xf bank_mask:0xf
	v_mov_b32_dpp v116, v236 row_ror:2 row_mask:0xf bank_mask:0xf
	v_mov_b32_dpp v117, v237 row_ror:2 row_mask:0xf bank_mask:0xf
	v_mov_b32_dpp v114, v238 row_shr:2 row_mask:0xf bank_mask:0xf
	v_mov_b32_dpp v115, v239 row_shr:2 row_mask:0xf bank_mask:0xf
	v_mov_b32_dpp v116, v240 row_shr:2 row_mask:0xf bank_mask:0xf
	v_mov_b32_dpp v117, v241 row_shr:2 row_mask:0xf bank_mask:0xf
	v_max_i32_e32 v98, -2, v118
	v_add_u32_e32 v128, s81, v98
	v_mov_b32_dpp v146, v234 row_ror:1 row_mask:0xf bank_mask:0xf
	v_mov_b32_dpp v147, v235 row_ror:1 row_mask:0xf bank_mask:0xf
	v_mov_b32_dpp v148, v236 row_ror:1 row_mask:0xf bank_mask:0xf
	v_mov_b32_dpp v149, v237 row_ror:1 row_mask:0xf bank_mask:0xf
	v_mov_b32_dpp v146, v238 row_shr:1 row_mask:0xf bank_mask:0xf
	v_mov_b32_dpp v147, v239 row_shr:1 row_mask:0xf bank_mask:0xf
	v_mov_b32_dpp v148, v240 row_shr:1 row_mask:0xf bank_mask:0xf
	v_mov_b32_dpp v149, v241 row_shr:1 row_mask:0xf bank_mask:0xf
	v_or_b32_e32 v98, s20, v137
	v_cndmask_b32_e64 v98, 0, v98, s[42:43]
	v_add_u32_e32 v129, s27, v98
	v_mov_b64_e32 v[150:151], v[238:239]
	v_mov_b64_e32 v[152:153], v[240:241]
	v_mov_b32_e32 v80, 0x30c0
	v_cmp_lt_i32_e64 s[40:41], -2, v118
	v_mad_u32_u24 v138, v136, s76, v80
	v_cndmask_b32_e64 v33, 0, v33, s[46:47]
	v_cndmask_b32_e64 v32, 0, v32, s[46:47]
	v_cndmask_b32_e64 v35, 0, v35, s[46:47]
	v_cndmask_b32_e64 v34, 0, v34, s[46:47]
	v_cmp_lt_i32_e32 vcc, -3, v118
	v_cndmask_b32_e64 v43, 0, v43, s[40:41]
	v_cndmask_b32_e64 v42, 0, v42, s[40:41]
	v_cndmask_b32_e64 v41, 0, v41, s[40:41]
	v_cndmask_b32_e64 v40, 0, v40, s[40:41]
	v_add_u32_e32 v120, v95, v138
	v_cndmask_b32_e64 v25, 0, v25, s[46:47]
	v_cndmask_b32_e64 v24, 0, v24, s[46:47]
	v_cndmask_b32_e64 v27, 0, v27, s[46:47]
	v_cndmask_b32_e64 v26, 0, v26, s[46:47]
	v_cndmask_b32_e64 v29, 0, v29, s[40:41]
	v_cndmask_b32_e64 v28, 0, v28, s[40:41]
	s_mov_b64 s[80:81], 0x1080
	s_waitcnt vmcnt(0) lgkmcnt(0)
	v_lshlrev_b32_e32 v80, 16, v104
	v_lshlrev_b32_e32 v98, 16, v105
	v_and_b32_e32 v81, 0xffff0000, v104
	v_and_b32_e32 v99, 0xffff0000, v105
	v_pk_fma_f32 v[6:7], v[34:35], v[98:99], v[6:7]
	v_pk_fma_f32 v[4:5], v[32:33], v[80:81], v[4:5]
	v_lshlrev_b32_e32 v32, 16, v115
	v_lshlrev_b32_e32 v34, 16, v114
	v_and_b32_e32 v33, 0xffff0000, v115
	v_and_b32_e32 v35, 0xffff0000, v114
	v_pk_fma_f32 v[4:5], v[40:41], v[34:35], v[4:5]
	v_pk_fma_f32 v[6:7], v[42:43], v[32:33], v[6:7]
	v_lshlrev_b32_e32 v32, 16, v146
	v_lshlrev_b32_e32 v34, 16, v147
	v_and_b32_e32 v33, 0xffff0000, v146
	v_and_b32_e32 v35, 0xffff0000, v147
	v_cndmask_b32_e32 v41, 0, v69, vcc
	v_cndmask_b32_e32 v40, 0, v68, vcc
	v_cndmask_b32_e32 v43, 0, v71, vcc
	v_cndmask_b32_e32 v42, 0, v70, vcc
	v_pk_fma_f32 v[6:7], v[42:43], v[34:35], v[6:7]
	v_pk_fma_f32 v[4:5], v[40:41], v[32:33], v[4:5]
	v_lshlrev_b32_e32 v32, 16, v151
	v_and_b32_e32 v33, 0xffff0000, v151
	v_lshlrev_b32_e32 v34, 16, v150
	v_and_b32_e32 v35, 0xffff0000, v150
	v_pk_fma_f32 v[6:7], v[72:73], v[32:33], v[6:7]
	v_pk_fma_f32 v[34:35], v[82:83], v[34:35], v[4:5]
	v_cvt_pk_bf16_f32 v5, v6, v7
	ds_write2_b32 v120, v6, v7 offset0:2 offset1:3
	ds_write2_b32 v120, v34, v35 offset1:1
	v_lshlrev_b32_e32 v6, 16, v106
	v_lshlrev_b32_e32 v32, 16, v107
	v_and_b32_e32 v7, 0xffff0000, v106
	v_and_b32_e32 v33, 0xffff0000, v107
	v_pk_fma_f32 v[22:23], v[26:27], v[32:33], v[22:23]
	v_pk_fma_f32 v[6:7], v[24:25], v[6:7], v[20:21]
	v_lshlrev_b32_e32 v20, 16, v117
	v_lshlrev_b32_e32 v24, 16, v116
	v_and_b32_e32 v21, 0xffff0000, v117
	v_and_b32_e32 v25, 0xffff0000, v116
	v_cndmask_b32_e64 v27, 0, v31, s[40:41]
	v_cndmask_b32_e64 v26, 0, v30, s[40:41]
	v_pk_fma_f32 v[6:7], v[28:29], v[24:25], v[6:7]
	v_pk_fma_f32 v[20:21], v[26:27], v[20:21], v[22:23]
	v_lshlrev_b32_e32 v22, 16, v148
	v_lshlrev_b32_e32 v24, 16, v149
	v_and_b32_e32 v23, 0xffff0000, v148
	v_and_b32_e32 v25, 0xffff0000, v149
	v_cndmask_b32_e32 v27, 0, v37, vcc
	v_cndmask_b32_e32 v26, 0, v36, vcc
	v_cndmask_b32_e32 v29, 0, v39, vcc
	v_cndmask_b32_e32 v28, 0, v38, vcc
	v_pk_fma_f32 v[20:21], v[28:29], v[24:25], v[20:21]
	v_pk_fma_f32 v[6:7], v[26:27], v[22:23], v[6:7]
	v_lshlrev_b32_e32 v22, 16, v153
	v_and_b32_e32 v23, 0xffff0000, v153
	v_lshlrev_b32_e32 v24, 16, v152
	v_and_b32_e32 v25, 0xffff0000, v152
	v_pk_fma_f32 v[20:21], v[74:75], v[22:23], v[20:21]
	v_pk_fma_f32 v[24:25], v[84:85], v[24:25], v[6:7]
	v_cvt_pk_bf16_f32 v7, v20, v21
	ds_write2_b32 v120, v20, v21 offset0:6 offset1:7
	ds_write2_b32 v120, v24, v25 offset0:4 offset1:5
	v_add_u32_e32 v20, 32, v78
	v_ashrrev_i32_e32 v21, 31, v20
	v_lshl_add_u64 v[84:85], v[86:87], 0, s[80:81]
	s_mov_b64 s[80:81], 0x1880
	v_lshl_add_u64 v[106:107], v[86:87], 0, s[80:81]
	v_lshlrev_b64 v[104:105], 1, v[20:21]
	v_mov_b32_dpp v80, v242 row_ror:3 row_mask:0xf bank_mask:0xf
	v_mov_b32_dpp v81, v243 row_ror:3 row_mask:0xf bank_mask:0xf
	v_mov_b32_dpp v82, v244 row_ror:3 row_mask:0xf bank_mask:0xf
	v_mov_b32_dpp v83, v245 row_ror:3 row_mask:0xf bank_mask:0xf
	v_mov_b32_dpp v80, v246 row_shr:3 row_mask:0xf bank_mask:0xf
	v_mov_b32_dpp v81, v247 row_shr:3 row_mask:0xf bank_mask:0xf
	v_mov_b32_dpp v82, v248 row_shr:3 row_mask:0xf bank_mask:0xf
; __device__ __forceinline__ void ld8bf(const bf16_t* p, float (&o)[8]) { unpack8(*(const u32x4*)p, o); }
; __device__ __forceinline__ bf16x8 pack_frag(const float (&v)[8]) { return __builtin_bit_cast(bf16x8, pack8(v)); }
; __device__ __forceinline__ void w_lru_m1(const Args& a, int l, unsigned char* ws, const bf16_t* proj, bf16_t* y, LAS unsigned char* wl, int b, int ck_, int h, int lane) {
;     ...
;         for (int tb = 0; tb < 4; ++tb) { const int tok = 16 * tb + lo, t = 64 * ck_ + tok; float s[8];
; #pragma unroll
;             for (int j = 0; j < 8; ++j) s[j] = bs[j];
; #pragma unroll
;             for (int k = 0; k < 4; ++k) { const int tt = t - 3 + k; float x[8];
;                 ld8bf(proj + (size_t)(b * SEQ + (tt >= 0 ? tt : 0)) * NIN + C_LX + ch0, x);
; #pragma unroll
;                 for (int j = 0; j < 8; ++j) s[j] += (tt >= 0 ? w[k][j] : 0.f) * x[j]; }
;             Xf[tb][kk] = pack_frag(s);
; #pragma unroll
;             for (int j = 0; j < 8; ++j) xcf[tok * 65 + 32 * kk + 8 * fq + j] = s[j]; }
	v_mov_b32_dpp v83, v249 row_shr:3 row_mask:0xf bank_mask:0xf
	v_cvt_pk_bf16_f32 v4, v34, v35
	v_mov_b32_dpp v32, v242 row_ror:2 row_mask:0xf bank_mask:0xf
	v_mov_b32_dpp v33, v243 row_ror:2 row_mask:0xf bank_mask:0xf
	v_mov_b32_dpp v34, v244 row_ror:2 row_mask:0xf bank_mask:0xf
	v_mov_b32_dpp v35, v245 row_ror:2 row_mask:0xf bank_mask:0xf
	v_mov_b32_dpp v32, v246 row_shr:2 row_mask:0xf bank_mask:0xf
	v_mov_b32_dpp v33, v247 row_shr:2 row_mask:0xf bank_mask:0xf
	v_mov_b32_dpp v34, v248 row_shr:2 row_mask:0xf bank_mask:0xf
	v_mov_b32_dpp v35, v249 row_shr:2 row_mask:0xf bank_mask:0xf
	v_mov_b32_dpp v28, v242 row_ror:1 row_mask:0xf bank_mask:0xf
	v_mov_b32_dpp v29, v243 row_ror:1 row_mask:0xf bank_mask:0xf
	v_mov_b32_dpp v30, v244 row_ror:1 row_mask:0xf bank_mask:0xf
	v_mov_b32_dpp v31, v245 row_ror:1 row_mask:0xf bank_mask:0xf
	v_mov_b32_dpp v28, v246 row_shr:1 row_mask:0xf bank_mask:0xf
	v_mov_b32_dpp v29, v247 row_shr:1 row_mask:0xf bank_mask:0xf
	v_mov_b32_dpp v30, v248 row_shr:1 row_mask:0xf bank_mask:0xf
	v_mov_b32_dpp v31, v249 row_shr:1 row_mask:0xf bank_mask:0xf
	v_cvt_pk_bf16_f32 v6, v24, v25
	v_mov_b64_e32 v[24:25], v[246:247]
	v_mov_b64_e32 v[26:27], v[248:249]
	ds_read_b128 v[40:43], v199 offset:17808
	ds_read_b128 v[72:75], v199 offset:17792
	ds_read_b128 v[68:71], v199 offset:16784
	s_nop 0
	ds_read_b128 v[76:79], v199 offset:16768
	ds_read_b128 v[36:39], v199 offset:17040
	ds_read_b128 v[20:23], v199 offset:17024
	ds_read_b128 v[92:95], v199 offset:17280
	s_nop 0
	ds_read_b128 v[84:87], v199 offset:17296
	s_nop 0
	ds_read_b128 v[96:99], v199 offset:17536
	s_nop 0
	ds_read_b128 v[146:149], v199 offset:17552
	s_waitcnt vmcnt(0) lgkmcnt(0)
	v_lshlrev_b32_e32 v106, 16, v80
	v_lshlrev_b32_e32 v114, 16, v81
	v_and_b32_e32 v107, 0xffff0000, v80
	v_and_b32_e32 v115, 0xffff0000, v81
	v_cndmask_b32_e64 v81, 0, v77, s[50:51]
	v_cndmask_b32_e64 v80, 0, v76, s[50:51]
	v_cndmask_b32_e64 v117, 0, v79, s[50:51]
	v_cndmask_b32_e64 v116, 0, v78, s[50:51]
	v_pk_fma_f32 v[114:115], v[116:117], v[114:115], v[74:75]
	v_pk_fma_f32 v[80:81], v[80:81], v[106:107], v[72:73]
	v_lshlrev_b32_e32 v106, 16, v33
	v_lshlrev_b32_e32 v116, 16, v32
	v_and_b32_e32 v107, 0xffff0000, v33
	v_and_b32_e32 v117, 0xffff0000, v32
	v_cndmask_b32_e64 v33, 0, v23, s[48:49]
	v_cndmask_b32_e64 v32, 0, v22, s[48:49]
	v_cndmask_b32_e64 v119, 0, v21, s[48:49]
	v_cndmask_b32_e64 v118, 0, v20, s[48:49]
	v_pk_fma_f32 v[80:81], v[118:119], v[116:117], v[80:81]
	v_pk_fma_f32 v[32:33], v[32:33], v[106:107], v[114:115]
	v_lshlrev_b32_e32 v106, 16, v28
	v_lshlrev_b32_e32 v114, 16, v29
	v_and_b32_e32 v107, 0xffff0000, v28
	v_and_b32_e32 v115, 0xffff0000, v29
	v_cndmask_b32_e64 v29, 0, v93, s[44:45]
	v_cndmask_b32_e64 v28, 0, v92, s[44:45]
	v_cndmask_b32_e64 v117, 0, v95, s[44:45]
	v_cndmask_b32_e64 v116, 0, v94, s[44:45]
	v_pk_fma_f32 v[32:33], v[116:117], v[114:115], v[32:33]
	v_pk_fma_f32 v[28:29], v[28:29], v[106:107], v[80:81]
	v_lshlrev_b32_e32 v80, 16, v25
	v_lshlrev_b32_e32 v116, 16, v24
	v_and_b32_e32 v81, 0xffff0000, v25
	v_and_b32_e32 v117, 0xffff0000, v24
	v_cndmask_b32_e64 v107, 0, v99, s[42:43]
	v_cndmask_b32_e64 v106, 0, v98, s[42:43]
	v_cndmask_b32_e64 v115, 0, v97, s[42:43]
	v_cndmask_b32_e64 v114, 0, v96, s[42:43]
	v_pk_fma_f32 v[24:25], v[114:115], v[116:117], v[28:29]
	v_pk_fma_f32 v[28:29], v[106:107], v[80:81], v[32:33]
	v_cvt_pk_bf16_f32 v32, v24, v25
	v_cvt_pk_bf16_f32 v33, v28, v29
	ds_write2_b32 v121, v28, v29 offset0:34 offset1:35
	ds_write2_b32 v121, v24, v25 offset0:32 offset1:33
	v_lshlrev_b32_e32 v24, 16, v82
	v_lshlrev_b32_e32 v28, 16, v83
	v_and_b32_e32 v25, 0xffff0000, v82
	v_and_b32_e32 v29, 0xffff0000, v83
	v_cndmask_b32_e64 v81, 0, v69, s[50:51]
	v_cndmask_b32_e64 v80, 0, v68, s[50:51]
	v_cndmask_b32_e64 v83, 0, v71, s[50:51]
	v_cndmask_b32_e64 v82, 0, v70, s[50:51]
	v_pk_fma_f32 v[28:29], v[82:83], v[28:29], v[42:43]
	v_pk_fma_f32 v[24:25], v[80:81], v[24:25], v[40:41]
	v_lshlrev_b32_e32 v80, 16, v35
	v_lshlrev_b32_e32 v82, 16, v34
	v_and_b32_e32 v81, 0xffff0000, v35
	v_and_b32_e32 v83, 0xffff0000, v34
	v_cndmask_b32_e64 v35, 0, v39, s[48:49]
	v_cndmask_b32_e64 v34, 0, v38, s[48:49]
	v_cndmask_b32_e64 v97, 0, v37, s[48:49]
	v_cndmask_b32_e64 v96, 0, v36, s[48:49]
	v_pk_fma_f32 v[24:25], v[96:97], v[82:83], v[24:25]
	v_pk_fma_f32 v[28:29], v[34:35], v[80:81], v[28:29]
	v_lshlrev_b32_e32 v34, 16, v30
	v_lshlrev_b32_e32 v80, 16, v31
	v_and_b32_e32 v35, 0xffff0000, v30
	v_and_b32_e32 v81, 0xffff0000, v31
	v_cndmask_b32_e64 v31, 0, v85, s[44:45]
	v_cndmask_b32_e64 v30, 0, v84, s[44:45]
	v_cndmask_b32_e64 v83, 0, v87, s[44:45]
	v_cndmask_b32_e64 v82, 0, v86, s[44:45]
	v_pk_fma_f32 v[28:29], v[82:83], v[80:81], v[28:29]
	v_pk_fma_f32 v[24:25], v[30:31], v[34:35], v[24:25]
	v_lshlrev_b32_e32 v30, 16, v27
	v_lshlrev_b32_e32 v34, 16, v26
	v_and_b32_e32 v31, 0xffff0000, v27
	v_and_b32_e32 v35, 0xffff0000, v26
	v_cndmask_b32_e64 v117, 0, v149, s[42:43]
	v_cndmask_b32_e64 v116, 0, v148, s[42:43]
	v_cndmask_b32_e64 v119, 0, v147, s[42:43]
	v_cndmask_b32_e64 v118, 0, v146, s[42:43]
	v_pk_fma_f32 v[24:25], v[118:119], v[34:35], v[24:25]
	v_pk_fma_f32 v[26:27], v[116:117], v[30:31], v[28:29]
	v_cvt_pk_bf16_f32 v34, v24, v25
	ds_write2_b32 v121, v26, v27 offset0:38 offset1:39
	ds_write2_b32 v121, v24, v25 offset0:36 offset1:37
	v_cvt_pk_bf16_f32 v35, v26, v27
	v_mov_b32_dpp v24, v246 row_ror:3 row_mask:0xf bank_mask:0xf
	v_mov_b32_dpp v25, v247 row_ror:3 row_mask:0xf bank_mask:0xf
	v_mov_b32_dpp v26, v248 row_ror:3 row_mask:0xf bank_mask:0xf
	v_mov_b32_dpp v27, v249 row_ror:3 row_mask:0xf bank_mask:0xf
	v_mov_b32_dpp v24, v250 row_shr:3 row_mask:0xf bank_mask:0xf
; __device__ __forceinline__ void ld8bf(const bf16_t* p, float (&o)[8]) { unpack8(*(const u32x4*)p, o); }
; __device__ __forceinline__ bf16x8 pack_frag(const float (&v)[8]) { return __builtin_bit_cast(bf16x8, pack8(v)); }
; __device__ __forceinline__ void w_lru_m1(const Args& a, int l, unsigned char* ws, const bf16_t* proj, bf16_t* y, LAS unsigned char* wl, int b, int ck_, int h, int lane) {
;     ...
;         for (int tb = 0; tb < 4; ++tb) { const int tok = 16 * tb + lo, t = 64 * ck_ + tok; float s[8];
; #pragma unroll
;             for (int j = 0; j < 8; ++j) s[j] = bs[j];
; #pragma unroll
;             for (int k = 0; k < 4; ++k) { const int tt = t - 3 + k; float x[8];
;                 ld8bf(proj + (size_t)(b * SEQ + (tt >= 0 ? tt : 0)) * NIN + C_LX + ch0, x);
; #pragma unroll
;                 for (int j = 0; j < 8; ++j) s[j] += (tt >= 0 ? w[k][j] : 0.f) * x[j]; }
;             Xf[tb][kk] = pack_frag(s);
; #pragma unroll
;             for (int j = 0; j < 8; ++j) xcf[tok * 65 + 32 * kk + 8 * fq + j] = s[j]; }
	v_mov_b32_dpp v25, v251 row_shr:3 row_mask:0xf bank_mask:0xf
	v_mov_b32_dpp v26, v252 row_shr:3 row_mask:0xf bank_mask:0xf
	v_mov_b32_dpp v27, v253 row_shr:3 row_mask:0xf bank_mask:0xf
	v_mov_b32_dpp v28, v246 row_ror:2 row_mask:0xf bank_mask:0xf
	v_mov_b32_dpp v29, v247 row_ror:2 row_mask:0xf bank_mask:0xf
	v_mov_b32_dpp v30, v248 row_ror:2 row_mask:0xf bank_mask:0xf
	v_mov_b32_dpp v31, v249 row_ror:2 row_mask:0xf bank_mask:0xf
	v_mov_b32_dpp v28, v250 row_shr:2 row_mask:0xf bank_mask:0xf
	v_mov_b32_dpp v29, v251 row_shr:2 row_mask:0xf bank_mask:0xf
	v_mov_b32_dpp v30, v252 row_shr:2 row_mask:0xf bank_mask:0xf
	v_mov_b32_dpp v31, v253 row_shr:2 row_mask:0xf bank_mask:0xf
	v_mov_b32_dpp v80, v246 row_ror:1 row_mask:0xf bank_mask:0xf
	v_mov_b32_dpp v81, v247 row_ror:1 row_mask:0xf bank_mask:0xf
	v_mov_b32_dpp v82, v248 row_ror:1 row_mask:0xf bank_mask:0xf
	v_mov_b32_dpp v83, v249 row_ror:1 row_mask:0xf bank_mask:0xf
	v_mov_b32_dpp v80, v250 row_shr:1 row_mask:0xf bank_mask:0xf
	v_mov_b32_dpp v81, v251 row_shr:1 row_mask:0xf bank_mask:0xf
	v_mov_b32_dpp v82, v252 row_shr:1 row_mask:0xf bank_mask:0xf
	v_mov_b32_dpp v83, v253 row_shr:1 row_mask:0xf bank_mask:0xf
	v_mov_b64_e32 v[96:97], v[250:251]
	v_mov_b64_e32 v[98:99], v[252:253]
	v_cndmask_b32_e64 v147, 0, v79, s[62:63]
	v_cndmask_b32_e64 v146, 0, v78, s[62:63]
	v_cndmask_b32_e64 v149, 0, v21, s[60:61]
	v_cndmask_b32_e64 v148, 0, v20, s[60:61]
	s_add_i32 s48, s20, s27
	s_lshl_b32 s20, s91, 7
	s_add_u32 s44, s10, s20
	s_addc_u32 s45, s11, 0
	s_waitcnt vmcnt(0) lgkmcnt(0)
	v_lshlrev_b32_e32 v134, 16, v24
	v_lshlrev_b32_e32 v142, 16, v25
	v_and_b32_e32 v135, 0xffff0000, v24
	v_and_b32_e32 v143, 0xffff0000, v25
	v_cndmask_b32_e64 v25, 0, v77, s[62:63]
	v_cndmask_b32_e64 v24, 0, v76, s[62:63]
	v_pk_fma_f32 v[142:143], v[146:147], v[142:143], v[74:75]
	v_pk_fma_f32 v[24:25], v[24:25], v[134:135], v[72:73]
	v_lshlrev_b32_e32 v134, 16, v29
	v_lshlrev_b32_e32 v146, 16, v28
	v_and_b32_e32 v135, 0xffff0000, v29
	v_and_b32_e32 v147, 0xffff0000, v28
	v_cndmask_b32_e64 v29, 0, v23, s[60:61]
	v_cndmask_b32_e64 v28, 0, v22, s[60:61]
	v_pk_fma_f32 v[24:25], v[148:149], v[146:147], v[24:25]
	v_pk_fma_f32 v[28:29], v[28:29], v[134:135], v[142:143]
	v_lshlrev_b32_e32 v134, 16, v80
	v_lshlrev_b32_e32 v142, 16, v81
	v_and_b32_e32 v135, 0xffff0000, v80
	v_and_b32_e32 v143, 0xffff0000, v81
	v_cndmask_b32_e64 v81, 0, v93, s[58:59]
	v_cndmask_b32_e64 v80, 0, v92, s[58:59]
	v_cndmask_b32_e64 v147, 0, v95, s[58:59]
	v_cndmask_b32_e64 v146, 0, v94, s[58:59]
	v_pk_fma_f32 v[28:29], v[146:147], v[142:143], v[28:29]
	v_pk_fma_f32 v[24:25], v[80:81], v[134:135], v[24:25]
	v_lshlrev_b32_e32 v80, 16, v97
	v_lshlrev_b32_e32 v134, 16, v96
	v_and_b32_e32 v81, 0xffff0000, v97
	v_and_b32_e32 v135, 0xffff0000, v96
	v_pk_fma_f32 v[24:25], v[114:115], v[134:135], v[24:25]
	v_pk_fma_f32 v[80:81], v[106:107], v[80:81], v[28:29]
	v_cvt_pk_bf16_f32 v28, v24, v25
	v_cvt_pk_bf16_f32 v29, v80, v81
	ds_write2_b32 v125, v80, v81 offset0:34 offset1:35
	ds_write2_b32 v125, v24, v25 offset0:32 offset1:33
	v_lshlrev_b32_e32 v24, 16, v26
	v_lshlrev_b32_e32 v80, 16, v27
	v_and_b32_e32 v25, 0xffff0000, v26
	v_and_b32_e32 v81, 0xffff0000, v27
	v_cndmask_b32_e64 v27, 0, v69, s[62:63]
	v_cndmask_b32_e64 v26, 0, v68, s[62:63]
	v_cndmask_b32_e64 v97, 0, v71, s[62:63]
	v_cndmask_b32_e64 v96, 0, v70, s[62:63]
	v_pk_fma_f32 v[80:81], v[96:97], v[80:81], v[42:43]
	v_pk_fma_f32 v[24:25], v[26:27], v[24:25], v[40:41]
	v_lshlrev_b32_e32 v26, 16, v31
	v_lshlrev_b32_e32 v96, 16, v30
	v_and_b32_e32 v27, 0xffff0000, v31
	v_and_b32_e32 v97, 0xffff0000, v30
	v_cndmask_b32_e64 v31, 0, v39, s[60:61]
	v_cndmask_b32_e64 v30, 0, v38, s[60:61]
	v_cndmask_b32_e64 v135, 0, v37, s[60:61]
	v_cndmask_b32_e64 v134, 0, v36, s[60:61]
	v_pk_fma_f32 v[24:25], v[134:135], v[96:97], v[24:25]
	v_pk_fma_f32 v[26:27], v[30:31], v[26:27], v[80:81]
	v_lshlrev_b32_e32 v30, 16, v82
	v_lshlrev_b32_e32 v80, 16, v83
	v_and_b32_e32 v31, 0xffff0000, v82
	v_and_b32_e32 v81, 0xffff0000, v83
	v_cndmask_b32_e64 v83, 0, v85, s[58:59]
	v_cndmask_b32_e64 v82, 0, v84, s[58:59]
	v_cndmask_b32_e64 v97, 0, v87, s[58:59]
	v_cndmask_b32_e64 v96, 0, v86, s[58:59]
	v_pk_fma_f32 v[26:27], v[96:97], v[80:81], v[26:27]
	v_pk_fma_f32 v[24:25], v[82:83], v[30:31], v[24:25]
	v_lshlrev_b32_e32 v30, 16, v99
	v_lshlrev_b32_e32 v80, 16, v98
	v_and_b32_e32 v31, 0xffff0000, v99
	v_and_b32_e32 v81, 0xffff0000, v98
	v_pk_fma_f32 v[24:25], v[118:119], v[80:81], v[24:25]
	v_pk_fma_f32 v[26:27], v[116:117], v[30:31], v[26:27]
	v_cvt_pk_bf16_f32 v30, v24, v25
	ds_write2_b32 v125, v26, v27 offset0:38 offset1:39
	ds_write2_b32 v125, v24, v25 offset0:36 offset1:37
	v_cvt_pk_bf16_f32 v31, v26, v27
	v_mov_b32_dpp v24, v250 row_ror:3 row_mask:0xf bank_mask:0xf
	v_mov_b32_dpp v25, v251 row_ror:3 row_mask:0xf bank_mask:0xf
	v_mov_b32_dpp v26, v252 row_ror:3 row_mask:0xf bank_mask:0xf
	v_mov_b32_dpp v27, v253 row_ror:3 row_mask:0xf bank_mask:0xf
	v_mov_b32_dpp v24, v190 row_shr:3 row_mask:0xf bank_mask:0xf
	v_mov_b32_dpp v25, v191 row_shr:3 row_mask:0xf bank_mask:0xf
	v_mov_b32_dpp v26, v192 row_shr:3 row_mask:0xf bank_mask:0xf
	v_mov_b32_dpp v27, v193 row_shr:3 row_mask:0xf bank_mask:0xf
	v_mov_b32_dpp v80, v250 row_ror:2 row_mask:0xf bank_mask:0xf
	v_mov_b32_dpp v81, v251 row_ror:2 row_mask:0xf bank_mask:0xf
	v_mov_b32_dpp v82, v252 row_ror:2 row_mask:0xf bank_mask:0xf
	v_mov_b32_dpp v83, v253 row_ror:2 row_mask:0xf bank_mask:0xf
	v_mov_b32_dpp v80, v190 row_shr:2 row_mask:0xf bank_mask:0xf
	v_mov_b32_dpp v81, v191 row_shr:2 row_mask:0xf bank_mask:0xf
	v_mov_b32_dpp v82, v192 row_shr:2 row_mask:0xf bank_mask:0xf
	v_mov_b32_dpp v83, v193 row_shr:2 row_mask:0xf bank_mask:0xf
	v_mov_b32_dpp v96, v250 row_ror:1 row_mask:0xf bank_mask:0xf
	v_mov_b32_dpp v97, v251 row_ror:1 row_mask:0xf bank_mask:0xf
	v_mov_b32_dpp v98, v252 row_ror:1 row_mask:0xf bank_mask:0xf
	v_mov_b32_dpp v99, v253 row_ror:1 row_mask:0xf bank_mask:0xf
	v_mov_b32_dpp v96, v190 row_shr:1 row_mask:0xf bank_mask:0xf
	v_mov_b32_dpp v97, v191 row_shr:1 row_mask:0xf bank_mask:0xf
	v_mov_b32_dpp v98, v192 row_shr:1 row_mask:0xf bank_mask:0xf
	v_mov_b32_dpp v99, v193 row_shr:1 row_mask:0xf bank_mask:0xf
	v_mov_b64_e32 v[130:131], v[190:191]
	v_mov_b64_e32 v[132:133], v[192:193]
	v_cndmask_b32_e64 v147, 0, v79, s[56:57]
	v_cndmask_b32_e64 v146, 0, v78, s[56:57]
	v_cndmask_b32_e64 v149, 0, v21, s[54:55]
	v_cndmask_b32_e64 v148, 0, v20, s[54:55]
	v_cndmask_b32_e64 v79, 0, v79, s[46:47]
	v_cndmask_b32_e64 v78, 0, v78, s[46:47]
	v_cndmask_b32_e64 v21, 0, v21, s[40:41]
	v_cndmask_b32_e64 v20, 0, v20, s[40:41]
	s_waitcnt vmcnt(0) lgkmcnt(0)
; __device__ __forceinline__ void ld8bf(const bf16_t* p, float (&o)[8]) { unpack8(*(const u32x4*)p, o); }
; __device__ __forceinline__ bf16x8 pack_frag(const float (&v)[8]) { return __builtin_bit_cast(bf16x8, pack8(v)); }
; __device__ __forceinline__ void w_lru_m1(const Args& a, int l, unsigned char* ws, const bf16_t* proj, bf16_t* y, LAS unsigned char* wl, int b, int ck_, int h, int lane) {
;     ...
;         for (int tb = 0; tb < 4; ++tb) { const int tok = 16 * tb + lo, t = 64 * ck_ + tok; float s[8];
; #pragma unroll
;             for (int j = 0; j < 8; ++j) s[j] = bs[j];
; #pragma unroll
;             for (int k = 0; k < 4; ++k) { const int tt = t - 3 + k; float x[8];
;                 ld8bf(proj + (size_t)(b * SEQ + (tt >= 0 ? tt : 0)) * NIN + C_LX + ch0, x);
; #pragma unroll
;                 for (int j = 0; j < 8; ++j) s[j] += (tt >= 0 ? w[k][j] : 0.f) * x[j]; }
;             Xf[tb][kk] = pack_frag(s);
; #pragma unroll
;             for (int j = 0; j < 8; ++j) xcf[tok * 65 + 32 * kk + 8 * fq + j] = s[j]; }
	v_lshlrev_b32_e32 v134, 16, v24
	v_lshlrev_b32_e32 v142, 16, v25
	v_and_b32_e32 v135, 0xffff0000, v24
	v_and_b32_e32 v143, 0xffff0000, v25
	v_cndmask_b32_e64 v25, 0, v77, s[56:57]
	v_cndmask_b32_e64 v24, 0, v76, s[56:57]
	v_pk_fma_f32 v[142:143], v[146:147], v[142:143], v[74:75]
	v_pk_fma_f32 v[24:25], v[24:25], v[134:135], v[72:73]
	v_lshlrev_b32_e32 v134, 16, v81
	v_lshlrev_b32_e32 v146, 16, v80
	v_and_b32_e32 v135, 0xffff0000, v81
	v_and_b32_e32 v147, 0xffff0000, v80
	v_cndmask_b32_e64 v81, 0, v23, s[54:55]
	v_cndmask_b32_e64 v80, 0, v22, s[54:55]
	v_pk_fma_f32 v[24:25], v[148:149], v[146:147], v[24:25]
	v_pk_fma_f32 v[80:81], v[80:81], v[134:135], v[142:143]
	v_lshlrev_b32_e32 v134, 16, v96
	v_lshlrev_b32_e32 v142, 16, v97
	v_and_b32_e32 v135, 0xffff0000, v96
	v_and_b32_e32 v143, 0xffff0000, v97
	v_cndmask_b32_e64 v97, 0, v93, s[52:53]
	v_cndmask_b32_e64 v96, 0, v92, s[52:53]
	v_cndmask_b32_e64 v147, 0, v95, s[52:53]
	v_cndmask_b32_e64 v146, 0, v94, s[52:53]
	v_pk_fma_f32 v[80:81], v[146:147], v[142:143], v[80:81]
	v_pk_fma_f32 v[24:25], v[96:97], v[134:135], v[24:25]
	v_lshlrev_b32_e32 v96, 16, v131
	v_lshlrev_b32_e32 v134, 16, v130
	v_and_b32_e32 v97, 0xffff0000, v131
	v_and_b32_e32 v135, 0xffff0000, v130
	v_pk_fma_f32 v[130:131], v[114:115], v[134:135], v[24:25]
	v_pk_fma_f32 v[80:81], v[106:107], v[96:97], v[80:81]
	v_cvt_pk_bf16_f32 v24, v130, v131
	v_cvt_pk_bf16_f32 v25, v80, v81
	ds_write2_b32 v124, v80, v81 offset0:34 offset1:35
	ds_write2_b32 v124, v130, v131 offset0:32 offset1:33
	v_lshlrev_b32_e32 v80, 16, v26
	v_lshlrev_b32_e32 v96, 16, v27
	v_and_b32_e32 v81, 0xffff0000, v26
	v_and_b32_e32 v97, 0xffff0000, v27
	v_cndmask_b32_e64 v27, 0, v69, s[56:57]
	v_cndmask_b32_e64 v26, 0, v68, s[56:57]
	v_cndmask_b32_e64 v131, 0, v71, s[56:57]
	v_cndmask_b32_e64 v130, 0, v70, s[56:57]
	v_pk_fma_f32 v[96:97], v[130:131], v[96:97], v[42:43]
	v_pk_fma_f32 v[26:27], v[26:27], v[80:81], v[40:41]
	v_lshlrev_b32_e32 v80, 16, v83
	v_lshlrev_b32_e32 v130, 16, v82
	v_and_b32_e32 v81, 0xffff0000, v83
	v_and_b32_e32 v131, 0xffff0000, v82
	v_cndmask_b32_e64 v83, 0, v39, s[54:55]
	v_cndmask_b32_e64 v82, 0, v38, s[54:55]
	v_cndmask_b32_e64 v135, 0, v37, s[54:55]
	v_cndmask_b32_e64 v134, 0, v36, s[54:55]
	v_pk_fma_f32 v[26:27], v[134:135], v[130:131], v[26:27]
	v_pk_fma_f32 v[80:81], v[82:83], v[80:81], v[96:97]
	v_lshlrev_b32_e32 v82, 16, v98
	v_lshlrev_b32_e32 v96, 16, v99
	v_and_b32_e32 v83, 0xffff0000, v98
	v_and_b32_e32 v97, 0xffff0000, v99
	v_cndmask_b32_e64 v99, 0, v85, s[52:53]
	v_cndmask_b32_e64 v98, 0, v84, s[52:53]
	v_cndmask_b32_e64 v131, 0, v87, s[52:53]
	v_cndmask_b32_e64 v130, 0, v86, s[52:53]
	v_pk_fma_f32 v[80:81], v[130:131], v[96:97], v[80:81]
	v_pk_fma_f32 v[26:27], v[98:99], v[82:83], v[26:27]
	v_lshlrev_b32_e32 v82, 16, v133
	v_and_b32_e32 v83, 0xffff0000, v133
	v_lshlrev_b32_e32 v96, 16, v132
	v_and_b32_e32 v97, 0xffff0000, v132
	v_pk_fma_f32 v[80:81], v[116:117], v[82:83], v[80:81]
	v_pk_fma_f32 v[96:97], v[118:119], v[96:97], v[26:27]
	v_cvt_pk_bf16_f32 v27, v80, v81
	ds_write2_b32 v124, v80, v81 offset0:38 offset1:39
	ds_write2_b32 v124, v96, v97 offset0:36 offset1:37
	v_mov_b32_dpp v130, v190 row_ror:3 row_mask:0xf bank_mask:0xf
	v_mov_b32_dpp v131, v191 row_ror:3 row_mask:0xf bank_mask:0xf
	v_mov_b32_dpp v132, v192 row_ror:3 row_mask:0xf bank_mask:0xf
	v_mov_b32_dpp v133, v193 row_ror:3 row_mask:0xf bank_mask:0xf
	v_mov_b32_dpp v130, v194 row_shr:3 row_mask:0xf bank_mask:0xf
	v_mov_b32_dpp v131, v195 row_shr:3 row_mask:0xf bank_mask:0xf
	v_mov_b32_dpp v132, v196 row_shr:3 row_mask:0xf bank_mask:0xf
	v_mov_b32_dpp v133, v197 row_shr:3 row_mask:0xf bank_mask:0xf
	v_mov_b32_dpp v124, v190 row_ror:2 row_mask:0xf bank_mask:0xf
	v_mov_b32_dpp v125, v191 row_ror:2 row_mask:0xf bank_mask:0xf
	v_mov_b32_dpp v126, v192 row_ror:2 row_mask:0xf bank_mask:0xf
	v_mov_b32_dpp v127, v193 row_ror:2 row_mask:0xf bank_mask:0xf
	v_mov_b32_dpp v124, v194 row_shr:2 row_mask:0xf bank_mask:0xf
	v_mov_b32_dpp v125, v195 row_shr:2 row_mask:0xf bank_mask:0xf
	v_mov_b32_dpp v126, v196 row_shr:2 row_mask:0xf bank_mask:0xf
	v_mov_b32_dpp v127, v197 row_shr:2 row_mask:0xf bank_mask:0xf
	v_cvt_pk_bf16_f32 v26, v96, v97
	v_mov_b32_dpp v96, v190 row_ror:1 row_mask:0xf bank_mask:0xf
	v_mov_b32_dpp v97, v191 row_ror:1 row_mask:0xf bank_mask:0xf
	v_mov_b32_dpp v98, v192 row_ror:1 row_mask:0xf bank_mask:0xf
	v_mov_b32_dpp v99, v193 row_ror:1 row_mask:0xf bank_mask:0xf
	v_mov_b32_dpp v96, v194 row_shr:1 row_mask:0xf bank_mask:0xf
	v_mov_b32_dpp v97, v195 row_shr:1 row_mask:0xf bank_mask:0xf
	v_mov_b32_dpp v98, v196 row_shr:1 row_mask:0xf bank_mask:0xf
	v_mov_b32_dpp v99, v197 row_shr:1 row_mask:0xf bank_mask:0xf
	v_mov_b64_e32 v[80:81], v[194:195]
	v_mov_b64_e32 v[82:83], v[196:197]
	v_cndmask_b32_e64 v77, 0, v77, s[46:47]
	v_cndmask_b32_e64 v76, 0, v76, s[46:47]
	v_cndmask_b32_e64 v23, 0, v23, s[40:41]
	v_cndmask_b32_e64 v22, 0, v22, s[40:41]
	v_cndmask_b32_e64 v69, 0, v69, s[46:47]
	v_cndmask_b32_e64 v68, 0, v68, s[46:47]
	v_cndmask_b32_e64 v71, 0, v71, s[46:47]
	v_cndmask_b32_e64 v70, 0, v70, s[46:47]
	v_cndmask_b32_e64 v39, 0, v39, s[40:41]
	v_cndmask_b32_e64 v38, 0, v38, s[40:41]
	v_cndmask_b32_e64 v37, 0, v37, s[40:41]
	v_cndmask_b32_e64 v36, 0, v36, s[40:41]
	s_add_u32 s46, s71, s20
	s_addc_u32 s47, s64, 0
	s_ashr_i32 s91, s90, 31
	s_lshl_b64 s[42:43], s[90:91], 9
	s_or_b32 s42, s42, s21
	s_waitcnt vmcnt(0) lgkmcnt(0)
; __device__ __forceinline__ void w_lru_m1(const Args& a, int l, unsigned char* ws, const bf16_t* proj, bf16_t* y, LAS unsigned char* wl, int b, int ck_, int h, int lane) {
;     ...
;         for (int tb = 0; tb < 4; ++tb) { const int tok = 16 * tb + lo, t = 64 * ck_ + tok; float s[8];
; #pragma unroll
;             for (int j = 0; j < 8; ++j) s[j] = bs[j];
; #pragma unroll
;             for (int k = 0; k < 4; ++k) { const int tt = t - 3 + k; float x[8];
;                 ld8bf(proj + (size_t)(b * SEQ + (tt >= 0 ? tt : 0)) * NIN + C_LX + ch0, x);
; #pragma unroll
;                 for (int j = 0; j < 8; ++j) s[j] += (tt >= 0 ? w[k][j] : 0.f) * x[j]; }
;             Xf[tb][kk] = pack_frag(s);
; #pragma unroll
;             for (int j = 0; j < 8; ++j) xcf[tok * 65 + 32 * kk + 8 * fq + j] = s[j]; }
;     ...
;     for (int jb = 0; jb < 4; ++jb) {
;         bf16x8 WaF[2], WxF[2]; f32x4 pba, pbx, plam;
; #pragma unroll
;         for (int kk = 0; kk < 2; ++kk) { WaF[kk] = nWa[kk]; WxF[kk] = nWx[kk]; }
;         pba = nba; pbx = nbx; plam = nlam;
;         if (jb < 3) {
; #pragma unroll
;             for (int kk = 0; kk < 2; ++kk) { nWa[kk] = *(const bf16x8*)(waT + (16 * (jb + 1) + lo) * 64 + 32 * kk + 8 * fq); nWx[kk] = *(const bf16x8*)(wxT + (16 * (jb + 1) + lo) * 64 + 32 * kk + 8 * fq); }
;             nba = *(const f32x4*)(ba + 16 * (jb + 1) + 4 * fq); nbx = *(const f32x4*)(bx + 16 * (jb + 1) + 4 * fq); nlam = *(const f32x4*)(lam + 16 * (jb + 1) + 4 * fq);
;         }
;         const int j0 = 16 * jb + 4 * fq;
;         float bav[4], bxv[4], sp[4], hc[4], Pc[4];
; #pragma unroll
;         for (int r = 0; r < 4; ++r) { bav[r] = pba[r]; bxv[r] = pbx[r]; sp[r] = log1pf(__expf(-plam[r])); hc[r] = 0.f; Pc[r] = 1.f; }
; #pragma unroll
;         for (int tb = 0; tb < 4; ++tb) { const int tok = 16 * tb + lo;
;             f32x4 ga = {0.f, 0.f, 0.f, 0.f}, gx = {0.f, 0.f, 0.f, 0.f};
; #pragma unroll
;             for (int kk = 0; kk < 2; ++kk) { ga = __builtin_amdgcn_mfma_f32_16x16x32_bf16(WaF[kk], Xf[tb][kk], ga, 0, 0, 0); gx = __builtin_amdgcn_mfma_f32_16x16x32_bf16(WxF[kk], Xf[tb][kk], gx, 0, 0, 0); }
;             float hv[4], pv[4];
; #pragma unroll
;             for (int r = 0; r < 4; ++r) {
;                 const float rg = sigmoidf_(ga[r] + bav[r]), ig = sigmoidf_(gx[r] + bxv[r]);
;                 const float la = -8.0f * rg * sp[r]; float A = __expf(la);
	v_lshlrev_b32_e32 v102, 16, v130
	v_lshlrev_b32_e32 v104, 16, v131
	v_and_b32_e32 v103, 0xffff0000, v130
	v_and_b32_e32 v105, 0xffff0000, v131
	v_pk_fma_f32 v[74:75], v[78:79], v[104:105], v[74:75]
	v_pk_fma_f32 v[72:73], v[76:77], v[102:103], v[72:73]
	v_lshlrev_b32_e32 v76, 16, v125
	v_lshlrev_b32_e32 v78, 16, v124
	v_and_b32_e32 v77, 0xffff0000, v125
	v_and_b32_e32 v79, 0xffff0000, v124
	v_pk_fma_f32 v[20:21], v[20:21], v[78:79], v[72:73]
	v_pk_fma_f32 v[22:23], v[22:23], v[76:77], v[74:75]
	v_lshlrev_b32_e32 v72, 16, v96
	v_lshlrev_b32_e32 v74, 16, v97
	v_and_b32_e32 v73, 0xffff0000, v96
	v_and_b32_e32 v75, 0xffff0000, v97
	v_cndmask_b32_e32 v77, 0, v93, vcc
	v_cndmask_b32_e32 v76, 0, v92, vcc
	v_cndmask_b32_e32 v79, 0, v95, vcc
	v_cndmask_b32_e32 v78, 0, v94, vcc
	v_pk_fma_f32 v[22:23], v[78:79], v[74:75], v[22:23]
	v_pk_fma_f32 v[20:21], v[76:77], v[72:73], v[20:21]
	v_lshlrev_b32_e32 v72, 16, v81
	v_and_b32_e32 v73, 0xffff0000, v81
	v_lshlrev_b32_e32 v74, 16, v80
	v_and_b32_e32 v75, 0xffff0000, v80
	v_pk_fma_f32 v[22:23], v[106:107], v[72:73], v[22:23]
	v_pk_fma_f32 v[74:75], v[114:115], v[74:75], v[20:21]
	v_cvt_pk_bf16_f32 v21, v22, v23
	ds_write2_b32 v120, v22, v23 offset0:34 offset1:35
	ds_write2_b32 v120, v74, v75 offset0:32 offset1:33
	v_lshlrev_b32_e32 v22, 16, v132
	v_lshlrev_b32_e32 v72, 16, v133
	v_and_b32_e32 v23, 0xffff0000, v132
	v_and_b32_e32 v73, 0xffff0000, v133
	v_pk_fma_f32 v[42:43], v[70:71], v[72:73], v[42:43]
	v_pk_fma_f32 v[22:23], v[68:69], v[22:23], v[40:41]
	v_lshlrev_b32_e32 v40, 16, v127
	v_lshlrev_b32_e32 v68, 16, v126
	v_and_b32_e32 v41, 0xffff0000, v127
	v_and_b32_e32 v69, 0xffff0000, v126
	v_pk_fma_f32 v[22:23], v[36:37], v[68:69], v[22:23]
	v_pk_fma_f32 v[36:37], v[38:39], v[40:41], v[42:43]
	v_lshlrev_b32_e32 v38, 16, v98
	v_lshlrev_b32_e32 v40, 16, v99
	v_and_b32_e32 v39, 0xffff0000, v98
	v_and_b32_e32 v41, 0xffff0000, v99
	v_cndmask_b32_e32 v43, 0, v85, vcc
	v_cndmask_b32_e32 v42, 0, v84, vcc
	v_cndmask_b32_e32 v69, 0, v87, vcc
	v_cndmask_b32_e32 v68, 0, v86, vcc
	v_pk_fma_f32 v[36:37], v[68:69], v[40:41], v[36:37]
	v_pk_fma_f32 v[22:23], v[42:43], v[38:39], v[22:23]
	v_lshlrev_b32_e32 v38, 16, v83
	v_and_b32_e32 v39, 0xffff0000, v83
	v_lshlrev_b32_e32 v40, 16, v82
	v_and_b32_e32 v41, 0xffff0000, v82
	v_pk_fma_f32 v[36:37], v[116:117], v[38:39], v[36:37]
	v_pk_fma_f32 v[40:41], v[118:119], v[40:41], v[22:23]
	v_cvt_pk_bf16_f32 v23, v36, v37
	ds_write2_b32 v120, v36, v37 offset0:38 offset1:39
	ds_write2_b32 v120, v40, v41 offset0:36 offset1:37
	v_lshlrev_b32_e32 v36, 2, v122
	v_lshl_add_u64 v[118:119], s[92:93], 0, v[100:101]
	v_lshl_add_u64 v[120:121], s[34:35], 0, v[100:101]
	v_and_b32_e32 v143, 0xc0, v36
	v_lshl_add_u64 v[36:37], v[118:119], 0, v[2:3]
	v_lshl_add_u64 v[38:39], v[120:121], 0, v[2:3]
	s_nop 7
	s_waitcnt lgkmcnt(0)
	v_cvt_pk_bf16_f32 v20, v74, v75
	v_cvt_pk_bf16_f32 v22, v40, v41
	s_nop 7
	global_load_dwordx4 v[68:71], v[36:37], off offset:2048
	global_load_dwordx4 v[72:75], v[38:39], off offset:2048
	global_load_dwordx4 v[76:79], v[36:37], off offset:2112
	global_load_dwordx4 v[80:83], v[38:39], off offset:2112
	global_load_dwordx4 v[40:43], v[108:109], off offset:64
	s_nop 7
	global_load_dwordx4 v[36:39], v[110:111], off offset:64
	global_load_dwordx4 v[84:87], v[112:113], off offset:64
	s_nop 7
	v_mov_b32_e32 v104, 1.0
	s_nop 7
	v_mov_b32_e32 v105, 1.0
	s_nop 7
	v_cmp_eq_u32_e32 vcc, 0, v136
	s_nop 7
	v_mov_b32_e32 v145, v88
	s_nop 7
	v_mov_b32_e32 v147, v89
	s_nop 7
	v_mov_b32_e32 v103, 1.0
	s_nop 7
	v_mov_b32_e32 v2, v90
	s_nop 7
	v_mov_b32_e32 v100, 1.0
	s_nop 7
	v_mov_b32_e32 v101, 1.0
	s_nop 7
	v_mfma_f32_16x16x32_bf16 v[92:95], v[56:59], v[16:19], 0
	v_mov_b32_e32 v98, 1.0
	s_nop 7
	v_mfma_f32_16x16x32_bf16 v[92:95], v[64:67], v[32:35], v[92:95]
	v_mov_b32_e32 v99, 1.0
	s_nop 7
	v_mov_b32_e32 v146, v91
	v_and_b32_e32 v88, -16, v122
	v_add_u32_e32 v142, s6, v88
	v_lshlrev_b64 v[88:89], 1, v[0:1]
	v_lshl_add_u64 v[114:115], s[44:45], 0, v[88:89]
	v_lshl_add_u64 v[116:117], s[46:47], 0, v[88:89]
	v_and_b32_e32 v198, 16, v144
	v_lshrrev_b32_e32 v199, 1, v198
	v_add_u32_e32 v198, v198, v199
	v_mov_b32_e32 v199, 0
	v_lshl_add_u64 v[114:115], v[114:115], 0, v[198:199]
	v_lshl_add_u64 v[116:117], v[116:117], 0, v[198:199]
	v_mfma_f32_16x16x32_bf16 v[88:91], v[52:55], v[16:19], 0
	v_mad_u32_u24 v122, v136, s76, v142
	ds_read2_b32 v[124:125], v122 offset1:1
	ds_read2_b32 v[128:129], v122 offset0:2 offset1:3
	v_mfma_f32_16x16x32_bf16 v[88:91], v[60:63], v[32:35], v[88:91]
	v_mov_b32_e32 v102, 1.0
	v_add_u32_e32 v148, v142, v123
	v_add_u32_e32 v150, v142, v141
	s_nop 4
	v_add_f32_e32 v88, v48, v88
	v_add_f32_e32 v89, v49, v89
	v_mul_f32_e32 v88, 0xbfb8aa3b, v88
	v_mul_f32_e32 v89, 0xbfb8aa3b, v89
	v_exp_f32_e32 v88, v88
	v_exp_f32_e32 v89, v89
	v_add_f32_e32 v90, v50, v90
	v_mul_f32_e32 v90, 0xbfb8aa3b, v90
	v_add_f32_e32 v88, 1.0, v88
	v_add_f32_e32 v89, 1.0, v89
	v_rcp_f32_e32 v96, v88
	v_rcp_f32_e32 v97, v89
	v_add_f32_e32 v88, v44, v92
	v_add_f32_e32 v89, v45, v93
	v_mul_f32_e32 v92, 0xc1000000, v96
	v_mul_f32_e32 v93, 0xc1000000, v97
	v_mul_f32_e32 v88, 0xbfb8aa3b, v88
	v_mul_f32_e32 v92, v145, v92
	v_mul_f32_e32 v89, 0xbfb8aa3b, v89
	v_mul_f32_e32 v93, v147, v93
	v_exp_f32_e32 v88, v88
	v_mul_f32_e32 v92, 0x3fb8aa3b, v92
	v_exp_f32_e32 v89, v89
	v_mul_f32_e32 v93, 0x3fb8aa3b, v93
	v_exp_f32_e32 v92, v92
	v_exp_f32_e32 v93, v93
	v_add_f32_e32 v88, 1.0, v88
	v_add_f32_e32 v89, 1.0, v89
	v_rcp_f32_e32 v88, v88
	v_fma_f32 v96, -v92, v92, 1.0
	v_rcp_f32_e32 v89, v89
	v_fma_f32 v97, -v93, v93, 1.0
	v_sqrt_f32_e32 v96, v96
	v_sqrt_f32_e32 v97, v97
	s_waitcnt lgkmcnt(0)
; __device__ __forceinline__ unsigned pk2(float lo, float hi) { const f32x2_t v = {lo, hi}; const bf16x2_t b = __builtin_convertvector(v, bf16x2_t); return __builtin_bit_cast(unsigned, b); }
; __device__ __forceinline__ float sigmoidf_(float x) { return __builtin_amdgcn_rcpf(1.0f + __expf(-x)); }
; __device__ __forceinline__ float bcast15(float v, int lane) { return bperm_f((lane & 48) | 15, v); }
; __device__ __forceinline__ void w_lru_m1(const Args& a, int l, unsigned char* ws, const bf16_t* proj, bf16_t* y, LAS unsigned char* wl, int b, int ck_, int h, int lane) {
;     ...
;         for (int tb = 0; tb < 4; ++tb) { const int tok = 16 * tb + lo;
;             f32x4 ga = {0.f, 0.f, 0.f, 0.f}, gx = {0.f, 0.f, 0.f, 0.f};
; #pragma unroll
;             for (int kk = 0; kk < 2; ++kk) { ga = __builtin_amdgcn_mfma_f32_16x16x32_bf16(WaF[kk], Xf[tb][kk], ga, 0, 0, 0); gx = __builtin_amdgcn_mfma_f32_16x16x32_bf16(WxF[kk], Xf[tb][kk], gx, 0, 0, 0); }
;             float hv[4], pv[4];
; #pragma unroll
;             for (int r = 0; r < 4; ++r) {
;                 const float rg = sigmoidf_(ga[r] + bav[r]), ig = sigmoidf_(gx[r] + bxv[r]);
;                 const float la = -8.0f * rg * sp[r]; float A = __expf(la);
;                 float U = __builtin_amdgcn_sqrtf(1.0f - A * A) * (ig * xcf[tok * 65 + j0 + r]);
;                 { const float As = dpp_shr1<1>(A), Us = dpp_shr0<1>(U); U = A * Us + U; A = A * As; }
;                 { const float As = dpp_shr1<2>(A), Us = dpp_shr0<2>(U); U = A * Us + U; A = A * As; }
;                 { const float As = dpp_shr1<4>(A), Us = dpp_shr0<4>(U); U = A * Us + U; A = A * As; }
;                 { const float As = dpp_shr1<8>(A), Us = dpp_shr0<8>(U); U = A * Us + U; A = A * As; }
;                 const float hh = U + A * hc[r], PP = A * Pc[r];
;                 hc[r] = bcast15(hh, lane); Pc[r] = bcast15(PP, lane); hv[r] = hh; pv[r] = PP; }
;             *(unsigned long long*)(y + (size_t)(row0 + tok) * DM + 64 * h + j0) = (unsigned long long)pk2(hv[0], hv[1]) | ((unsigned long long)pk2(hv[2], hv[3]) << 32);
;             *(unsigned long long*)((bf16_t*)(ws + WS_P) + (size_t)(row0 + tok) * 512 + 64 * h + j0) = (unsigned long long)pk2(pv[0], pv[1]) | ((unsigned long long)pk2(pv[2], pv[3]) << 32);
	v_pk_mul_f32 v[88:89], v[124:125], v[88:89]
	v_mov_b32_dpp v98, v92 row_shr:1 row_mask:0xf bank_mask:0xf
	v_mov_b32_dpp v99, v93 row_shr:1 row_mask:0xf bank_mask:0xf
	v_pk_mul_f32 v[88:89], v[88:89], v[96:97]
	v_pk_mul_f32 v[98:99], v[92:93], v[98:99]
	v_exp_f32_e32 v90, v90
	v_mov_b32_dpp v96, v88 row_shr:1 row_mask:0xf bank_mask:0xf bound_ctrl:1
	v_mov_b32_dpp v97, v89 row_shr:1 row_mask:0xf bank_mask:0xf bound_ctrl:1
	v_pk_fma_f32 v[88:89], v[92:93], v[96:97], v[88:89]
	v_mov_b32_dpp v100, v98 row_shr:2 row_mask:0xf bank_mask:0xf
	v_mov_b32_dpp v101, v99 row_shr:2 row_mask:0xf bank_mask:0xf
	v_mov_b32_dpp v92, v88 row_shr:2 row_mask:0xf bank_mask:0xf bound_ctrl:1
	v_mov_b32_dpp v93, v89 row_shr:2 row_mask:0xf bank_mask:0xf bound_ctrl:1
	v_pk_fma_f32 v[88:89], v[98:99], v[92:93], v[88:89]
	v_pk_mul_f32 v[100:101], v[98:99], v[100:101]
	v_add_f32_e32 v90, 1.0, v90
	v_mov_b32_dpp v92, v88 row_shr:4 row_mask:0xf bank_mask:0xf bound_ctrl:1
	v_mov_b32_dpp v93, v89 row_shr:4 row_mask:0xf bank_mask:0xf bound_ctrl:1
	v_mov_b32_dpp v102, v100 row_shr:4 row_mask:0xf bank_mask:0xf
	v_mov_b32_dpp v103, v101 row_shr:4 row_mask:0xf bank_mask:0xf
	v_pk_fma_f32 v[88:89], v[100:101], v[92:93], v[88:89]
	v_pk_mul_f32 v[102:103], v[100:101], v[102:103]
	v_add_f32_e32 v91, v51, v91
	v_mov_b32_dpp v92, v88 row_shr:8 row_mask:0xf bank_mask:0xf bound_ctrl:1
	v_mov_b32_dpp v93, v89 row_shr:8 row_mask:0xf bank_mask:0xf bound_ctrl:1
	v_pk_fma_f32 v[88:89], v[102:103], v[92:93], v[88:89]
	v_rcp_f32_e32 v92, v90
	v_mul_f32_e32 v91, 0xbfb8aa3b, v91
	v_exp_f32_e32 v91, v91
	v_add_f32_e32 v90, v46, v94
	v_mul_f32_e32 v92, 0xc1000000, v92
	v_mul_f32_e32 v92, v2, v92
	v_mul_f32_e32 v92, 0x3fb8aa3b, v92
	v_exp_f32_e32 v92, v92
	v_add_f32_e32 v91, 1.0, v91
	v_mul_f32_e32 v90, 0xbfb8aa3b, v90
	v_exp_f32_e32 v90, v90
	v_fma_f32 v93, -v92, v92, 1.0
	v_sqrt_f32_e32 v94, v93
	v_rcp_f32_e32 v93, v91
	v_add_f32_e32 v91, v47, v95
	v_mul_f32_e32 v91, 0xbfb8aa3b, v91
	v_exp_f32_e32 v91, v91
	v_mul_f32_e32 v93, 0xc1000000, v93
	v_mul_f32_e32 v93, v146, v93
	v_mul_f32_e32 v93, 0x3fb8aa3b, v93
	v_exp_f32_e32 v93, v93
	v_add_f32_e32 v90, 1.0, v90
	v_add_f32_e32 v91, 1.0, v91
	v_rcp_f32_e32 v90, v90
	v_rcp_f32_e32 v91, v91
	v_fma_f32 v95, -v93, v93, 1.0
	v_sqrt_f32_e32 v95, v95
	v_mov_b32_e32 v96, 1.0
	v_pk_mul_f32 v[90:91], v[90:91], v[128:129]
	v_mov_b32_e32 v97, 1.0
	v_pk_mul_f32 v[90:91], v[94:95], v[90:91]
	v_mov_b32_dpp v96, v92 row_shr:1 row_mask:0xf bank_mask:0xf
	v_mov_b32_dpp v97, v93 row_shr:1 row_mask:0xf bank_mask:0xf
	v_mov_b32_dpp v94, v90 row_shr:1 row_mask:0xf bank_mask:0xf bound_ctrl:1
	v_mov_b32_dpp v95, v91 row_shr:1 row_mask:0xf bank_mask:0xf bound_ctrl:1
	v_pk_mul_f32 v[96:97], v[92:93], v[96:97]
	v_mov_b32_e32 v100, 1.0
	v_mov_b32_e32 v101, 1.0
	v_pk_fma_f32 v[90:91], v[92:93], v[94:95], v[90:91]
	v_mov_b32_dpp v104, v102 row_shr:8 row_mask:0xf bank_mask:0xf
	v_mov_b32_dpp v105, v103 row_shr:8 row_mask:0xf bank_mask:0xf
	v_mov_b32_dpp v100, v96 row_shr:2 row_mask:0xf bank_mask:0xf
	v_mov_b32_dpp v101, v97 row_shr:2 row_mask:0xf bank_mask:0xf
	v_mov_b32_dpp v92, v90 row_shr:2 row_mask:0xf bank_mask:0xf bound_ctrl:1
	v_mov_b32_dpp v93, v91 row_shr:2 row_mask:0xf bank_mask:0xf bound_ctrl:1
	v_pk_mul_f32 v[106:107], v[102:103], v[104:105]
	v_pk_mul_f32 v[100:101], v[96:97], v[100:101]
	v_mov_b32_e32 v102, 1.0
	v_mov_b32_e32 v103, 1.0
	v_pk_fma_f32 v[90:91], v[96:97], v[92:93], v[90:91]
	v_mov_b32_dpp v102, v100 row_shr:4 row_mask:0xf bank_mask:0xf
	v_mov_b32_dpp v103, v101 row_shr:4 row_mask:0xf bank_mask:0xf
	v_mov_b32_dpp v92, v90 row_shr:4 row_mask:0xf bank_mask:0xf bound_ctrl:1
	v_mov_b32_dpp v93, v91 row_shr:4 row_mask:0xf bank_mask:0xf bound_ctrl:1
	v_pk_mul_f32 v[102:103], v[100:101], v[102:103]
	v_mov_b32_e32 v124, 1.0
	v_mov_b32_e32 v125, 1.0
	v_pk_fma_f32 v[90:91], v[100:101], v[92:93], v[90:91]
	v_mov_b32_dpp v124, v102 row_shr:8 row_mask:0xf bank_mask:0xf
	v_mov_b32_dpp v125, v103 row_shr:8 row_mask:0xf bank_mask:0xf
	v_mov_b32_dpp v92, v90 row_shr:8 row_mask:0xf bank_mask:0xf bound_ctrl:1
	v_mov_b32_dpp v93, v91 row_shr:8 row_mask:0xf bank_mask:0xf bound_ctrl:1
	v_pk_mul_f32 v[126:127], v[102:103], v[124:125]
	v_pk_fma_f32 v[90:91], v[102:103], v[92:93], v[90:91]
	v_pk_fma_f32 v[88:89], v[106:107], 0, v[88:89] op_sel_hi:[1,0,1]
	v_pk_fma_f32 v[90:91], v[126:127], 0, v[90:91] op_sel_hi:[1,0,1]
	ds_bpermute_b32 v98, v143, v88 offset:60
	ds_bpermute_b32 v99, v143, v89 offset:60
	ds_bpermute_b32 v96, v143, v90 offset:60
	v_cvt_pk_bf16_f32 v88, v88, v89
	v_cvt_pk_bf16_f32 v89, v90, v91
	v_or_b32_e32 v90, s48, v136
	ds_bpermute_b32 v97, v143, v91 offset:60
	v_ashrrev_i32_e32 v91, 31, v90
	v_lshlrev_b64 v[92:93], 11, v[90:91]
	v_lshl_add_u64 v[100:101], v[114:115], 0, v[92:93]
	v_lshlrev_b64 v[90:91], 10, v[90:91]
	v_mov_b64_e32 v[222:223], v[88:89]
	v_cvt_pk_bf16_f32 v88, v106, v107
	v_cvt_pk_bf16_f32 v89, v126, v127
	v_lshl_add_u64 v[102:103], v[116:117], 0, v[90:91]
	v_mov_b64_e32 v[226:227], v[88:89]
	v_mfma_f32_16x16x32_bf16 v[88:91], v[52:55], v[12:15], 0
	ds_bpermute_b32 v124, v143, v126 offset:60
	ds_bpermute_b32 v125, v143, v127 offset:60
	ds_bpermute_b32 v104, v143, v106 offset:60
	v_mfma_f32_16x16x32_bf16 v[126:129], v[56:59], v[12:15], 0
	ds_bpermute_b32 v105, v143, v107 offset:60
	v_mfma_f32_16x16x32_bf16 v[92:95], v[60:63], v[28:31], v[88:91]
	v_mfma_f32_16x16x32_bf16 v[88:91], v[64:67], v[28:31], v[126:129]
	s_nop 6
	v_add_f32_e32 v92, v48, v92
	v_mul_f32_e32 v92, 0xbfb8aa3b, v92
	v_exp_f32_e32 v92, v92
	v_add_f32_e32 v88, v44, v88
	v_mul_f32_e32 v88, 0xbfb8aa3b, v88
	v_exp_f32_e32 v88, v88
	v_add_f32_e32 v92, 1.0, v92
	v_rcp_f32_e32 v92, v92
; __device__ __forceinline__ float sigmoidf_(float x) { return __builtin_amdgcn_rcpf(1.0f + __expf(-x)); }
; __device__ __forceinline__ float bcast15(float v, int lane) { return bperm_f((lane & 48) | 15, v); }
; __device__ __forceinline__ void w_lru_m1(const Args& a, int l, unsigned char* ws, const bf16_t* proj, bf16_t* y, LAS unsigned char* wl, int b, int ck_, int h, int lane) {
;     ...
;         for (int tb = 0; tb < 4; ++tb) { const int tok = 16 * tb + lo;
;             f32x4 ga = {0.f, 0.f, 0.f, 0.f}, gx = {0.f, 0.f, 0.f, 0.f};
; #pragma unroll
;             for (int kk = 0; kk < 2; ++kk) { ga = __builtin_amdgcn_mfma_f32_16x16x32_bf16(WaF[kk], Xf[tb][kk], ga, 0, 0, 0); gx = __builtin_amdgcn_mfma_f32_16x16x32_bf16(WxF[kk], Xf[tb][kk], gx, 0, 0, 0); }
;             float hv[4], pv[4];
; #pragma unroll
;             for (int r = 0; r < 4; ++r) {
;                 const float rg = sigmoidf_(ga[r] + bav[r]), ig = sigmoidf_(gx[r] + bxv[r]);
;                 const float la = -8.0f * rg * sp[r]; float A = __expf(la);
;                 float U = __builtin_amdgcn_sqrtf(1.0f - A * A) * (ig * xcf[tok * 65 + j0 + r]);
;                 { const float As = dpp_shr1<1>(A), Us = dpp_shr0<1>(U); U = A * Us + U; A = A * As; }
;                 { const float As = dpp_shr1<2>(A), Us = dpp_shr0<2>(U); U = A * Us + U; A = A * As; }
;                 { const float As = dpp_shr1<4>(A), Us = dpp_shr0<4>(U); U = A * Us + U; A = A * As; }
;                 { const float As = dpp_shr1<8>(A), Us = dpp_shr0<8>(U); U = A * Us + U; A = A * As; }
;                 const float hh = U + A * hc[r], PP = A * Pc[r];
;                 hc[r] = bcast15(hh, lane); Pc[r] = bcast15(PP, lane); hv[r] = hh; pv[r] = PP; }
	v_add_f32_e32 v89, v45, v89
	v_add_f32_e32 v88, 1.0, v88
	v_rcp_f32_e32 v106, v88
	v_mul_f32_e32 v88, 0xc1000000, v92
	v_add_f32_e32 v92, v49, v93
	v_mul_f32_e32 v92, 0xbfb8aa3b, v92
	v_exp_f32_e32 v92, v92
	v_mul_f32_e32 v89, 0xbfb8aa3b, v89
	v_exp_f32_e32 v89, v89
	v_mul_f32_e32 v88, v145, v88
	v_add_f32_e32 v92, 1.0, v92
	v_rcp_f32_e32 v92, v92
	v_add_f32_e32 v89, 1.0, v89
	v_rcp_f32_e32 v107, v89
	v_mul_f32_e32 v88, 0x3fb8aa3b, v88
	v_mul_f32_e32 v89, 0xc1000000, v92
	v_mul_f32_e32 v89, v147, v89
	v_mul_f32_e32 v89, 0x3fb8aa3b, v89
	v_exp_f32_e32 v122, v88
	v_exp_f32_e32 v123, v89
	v_add_f32_e32 v94, v50, v94
	v_add_f32_e32 v95, v51, v95
	v_fma_f32 v88, -v122, v122, 1.0
	v_fma_f32 v89, -v123, v123, 1.0
	v_sqrt_f32_e32 v126, v88
	v_mov_b32_e32 v88, 1.0
	v_sqrt_f32_e32 v127, v89
	v_mov_b32_e32 v89, 1.0
	v_mov_b32_dpp v88, v122 row_shr:1 row_mask:0xf bank_mask:0xf
	v_mul_f32_e32 v94, 0xbfb8aa3b, v94
	v_mov_b32_dpp v89, v123 row_shr:1 row_mask:0xf bank_mask:0xf
	v_pk_mul_f32 v[128:129], v[122:123], v[88:89]
	v_mov_b32_e32 v88, 1.0
	v_mov_b32_e32 v89, 1.0
	v_mul_f32_e32 v95, 0xbfb8aa3b, v95
	v_mov_b32_dpp v88, v128 row_shr:2 row_mask:0xf bank_mask:0xf
	v_mov_b32_dpp v89, v129 row_shr:2 row_mask:0xf bank_mask:0xf
	v_pk_mul_f32 v[130:131], v[128:129], v[88:89]
	v_mov_b32_e32 v88, 1.0
	v_mov_b32_e32 v89, 1.0
	v_exp_f32_e32 v94, v94
	v_mov_b32_dpp v88, v130 row_shr:4 row_mask:0xf bank_mask:0xf
	v_mov_b32_dpp v89, v131 row_shr:4 row_mask:0xf bank_mask:0xf
	v_pk_mul_f32 v[132:133], v[130:131], v[88:89]
	v_mov_b32_e32 v88, 1.0
	v_mov_b32_e32 v89, 1.0
	v_exp_f32_e32 v95, v95
	v_mov_b32_dpp v88, v132 row_shr:8 row_mask:0xf bank_mask:0xf
	v_mov_b32_dpp v89, v133 row_shr:8 row_mask:0xf bank_mask:0xf
	v_pk_mul_f32 v[134:135], v[132:133], v[88:89]
	v_add_f32_e32 v90, v46, v90
	s_waitcnt lgkmcnt(0)
	v_pk_mul_f32 v[92:93], v[134:135], v[104:105]
	ds_read2_b32 v[104:105], v148 offset1:1
	v_add_f32_e32 v91, v47, v91
	v_mul_f32_e32 v90, 0xbfb8aa3b, v90
	v_mul_f32_e32 v91, 0xbfb8aa3b, v91
	v_add_f32_e32 v94, 1.0, v94
	s_waitcnt lgkmcnt(0)
	v_pk_mul_f32 v[104:105], v[104:105], v[106:107]
	v_exp_f32_e32 v90, v90
	v_pk_mul_f32 v[104:105], v[104:105], v[126:127]
	v_add_f32_e32 v95, 1.0, v95
	v_exp_f32_e32 v91, v91
	v_mov_b32_dpp v106, v104 row_shr:1 row_mask:0xf bank_mask:0xf bound_ctrl:1
	v_mov_b32_dpp v107, v105 row_shr:1 row_mask:0xf bank_mask:0xf bound_ctrl:1
	v_pk_fma_f32 v[104:105], v[122:123], v[106:107], v[104:105]
	v_rcp_f32_e32 v94, v94
	v_rcp_f32_e32 v95, v95
	v_mov_b32_dpp v106, v104 row_shr:2 row_mask:0xf bank_mask:0xf bound_ctrl:1
	v_mov_b32_dpp v107, v105 row_shr:2 row_mask:0xf bank_mask:0xf bound_ctrl:1
	v_pk_fma_f32 v[104:105], v[128:129], v[106:107], v[104:105]
	v_add_f32_e32 v90, 1.0, v90
	v_add_f32_e32 v91, 1.0, v91
	v_mov_b32_dpp v106, v104 row_shr:4 row_mask:0xf bank_mask:0xf bound_ctrl:1
	v_mov_b32_dpp v107, v105 row_shr:4 row_mask:0xf bank_mask:0xf bound_ctrl:1
	v_pk_fma_f32 v[104:105], v[130:131], v[106:107], v[104:105]
	ds_bpermute_b32 v88, v143, v92 offset:60
	ds_bpermute_b32 v89, v143, v93 offset:60
	v_mov_b32_dpp v106, v104 row_shr:8 row_mask:0xf bank_mask:0xf bound_ctrl:1
	v_mov_b32_dpp v107, v105 row_shr:8 row_mask:0xf bank_mask:0xf bound_ctrl:1
	v_pk_fma_f32 v[104:105], v[132:133], v[106:107], v[104:105]
	v_rcp_f32_e32 v106, v90
	v_mul_f32_e32 v90, 0xc1000000, v94
	v_rcp_f32_e32 v107, v91
	v_mul_f32_e32 v91, 0xc1000000, v95
	v_mul_f32_e32 v90, v2, v90
	v_mul_f32_e32 v91, v146, v91
	v_mul_f32_e32 v90, 0x3fb8aa3b, v90
	v_mul_f32_e32 v91, 0x3fb8aa3b, v91
	v_exp_f32_e32 v94, v90
	v_exp_f32_e32 v95, v91
	v_pk_fma_f32 v[104:105], v[134:135], v[98:99], v[104:105]
	ds_read2_b32 v[134:135], v148 offset0:2 offset1:3
	v_fma_f32 v90, -v94, v94, 1.0
	v_fma_f32 v91, -v95, v95, 1.0
	v_sqrt_f32_e32 v122, v90
	v_sqrt_f32_e32 v123, v91
	s_waitcnt lgkmcnt(0)
	v_pk_mul_f32 v[106:107], v[106:107], v[134:135]
	v_mov_b32_e32 v90, 1.0
	v_mov_b32_e32 v91, 1.0
	v_pk_mul_f32 v[106:107], v[122:123], v[106:107]
	v_mov_b32_dpp v90, v94 row_shr:1 row_mask:0xf bank_mask:0xf
	v_mov_b32_dpp v91, v95 row_shr:1 row_mask:0xf bank_mask:0xf
	v_mov_b32_dpp v122, v106 row_shr:1 row_mask:0xf bank_mask:0xf bound_ctrl:1
	v_mov_b32_dpp v123, v107 row_shr:1 row_mask:0xf bank_mask:0xf bound_ctrl:1
	v_pk_mul_f32 v[126:127], v[94:95], v[90:91]
	v_mov_b32_e32 v90, 1.0
	v_mov_b32_e32 v91, 1.0
	v_pk_fma_f32 v[94:95], v[94:95], v[122:123], v[106:107]
	v_mov_b32_dpp v90, v126 row_shr:2 row_mask:0xf bank_mask:0xf
	v_mov_b32_dpp v91, v127 row_shr:2 row_mask:0xf bank_mask:0xf
	v_mov_b32_dpp v106, v94 row_shr:2 row_mask:0xf bank_mask:0xf bound_ctrl:1
	v_mov_b32_dpp v107, v95 row_shr:2 row_mask:0xf bank_mask:0xf bound_ctrl:1
	v_pk_mul_f32 v[128:129], v[126:127], v[90:91]
	v_mov_b32_e32 v90, 1.0
	v_mov_b32_e32 v91, 1.0
	v_pk_fma_f32 v[94:95], v[126:127], v[106:107], v[94:95]
	v_mov_b32_dpp v90, v128 row_shr:4 row_mask:0xf bank_mask:0xf
	v_mov_b32_dpp v91, v129 row_shr:4 row_mask:0xf bank_mask:0xf
	v_mov_b32_dpp v106, v94 row_shr:4 row_mask:0xf bank_mask:0xf bound_ctrl:1
	v_mov_b32_dpp v107, v95 row_shr:4 row_mask:0xf bank_mask:0xf bound_ctrl:1
	v_pk_mul_f32 v[130:131], v[128:129], v[90:91]
	v_mov_b32_e32 v90, 1.0
	v_mov_b32_e32 v91, 1.0
	v_pk_fma_f32 v[94:95], v[128:129], v[106:107], v[94:95]
	v_mov_b32_dpp v90, v130 row_shr:8 row_mask:0xf bank_mask:0xf
	v_mov_b32_dpp v91, v131 row_shr:8 row_mask:0xf bank_mask:0xf
	v_mov_b32_dpp v106, v94 row_shr:8 row_mask:0xf bank_mask:0xf bound_ctrl:1
	v_mov_b32_dpp v107, v95 row_shr:8 row_mask:0xf bank_mask:0xf bound_ctrl:1
	v_pk_mul_f32 v[132:133], v[130:131], v[90:91]
	v_pk_fma_f32 v[94:95], v[130:131], v[106:107], v[94:95]
; __device__ __forceinline__ unsigned pk2(float lo, float hi) { const f32x2_t v = {lo, hi}; const bf16x2_t b = __builtin_convertvector(v, bf16x2_t); return __builtin_bit_cast(unsigned, b); }
; __device__ __forceinline__ float sigmoidf_(float x) { return __builtin_amdgcn_rcpf(1.0f + __expf(-x)); }
; __device__ __forceinline__ float bcast15(float v, int lane) { return bperm_f((lane & 48) | 15, v); }
; __device__ __forceinline__ void w_lru_m1(const Args& a, int l, unsigned char* ws, const bf16_t* proj, bf16_t* y, LAS unsigned char* wl, int b, int ck_, int h, int lane) {
;     ...
;         for (int tb = 0; tb < 4; ++tb) { const int tok = 16 * tb + lo;
;             f32x4 ga = {0.f, 0.f, 0.f, 0.f}, gx = {0.f, 0.f, 0.f, 0.f};
; #pragma unroll
;             for (int kk = 0; kk < 2; ++kk) { ga = __builtin_amdgcn_mfma_f32_16x16x32_bf16(WaF[kk], Xf[tb][kk], ga, 0, 0, 0); gx = __builtin_amdgcn_mfma_f32_16x16x32_bf16(WxF[kk], Xf[tb][kk], gx, 0, 0, 0); }
;             float hv[4], pv[4];
; #pragma unroll
;             for (int r = 0; r < 4; ++r) {
;                 const float rg = sigmoidf_(ga[r] + bav[r]), ig = sigmoidf_(gx[r] + bxv[r]);
;                 const float la = -8.0f * rg * sp[r]; float A = __expf(la);
;                 float U = __builtin_amdgcn_sqrtf(1.0f - A * A) * (ig * xcf[tok * 65 + j0 + r]);
;                 { const float As = dpp_shr1<1>(A), Us = dpp_shr0<1>(U); U = A * Us + U; A = A * As; }
;                 { const float As = dpp_shr1<2>(A), Us = dpp_shr0<2>(U); U = A * Us + U; A = A * As; }
;                 { const float As = dpp_shr1<4>(A), Us = dpp_shr0<4>(U); U = A * Us + U; A = A * As; }
;                 { const float As = dpp_shr1<8>(A), Us = dpp_shr0<8>(U); U = A * Us + U; A = A * As; }
;                 const float hh = U + A * hc[r], PP = A * Pc[r];
;                 hc[r] = bcast15(hh, lane); Pc[r] = bcast15(PP, lane); hv[r] = hh; pv[r] = PP; }
;             *(unsigned long long*)(y + (size_t)(row0 + tok) * DM + 64 * h + j0) = (unsigned long long)pk2(hv[0], hv[1]) | ((unsigned long long)pk2(hv[2], hv[3]) << 32);
;             *(unsigned long long*)((bf16_t*)(ws + WS_P) + (size_t)(row0 + tok) * 512 + 64 * h + j0) = (unsigned long long)pk2(pv[0], pv[1]) | ((unsigned long long)pk2(pv[2], pv[3]) << 32);
	ds_bpermute_b32 v98, v143, v104 offset:60
	v_pk_fma_f32 v[94:95], v[132:133], v[96:97], v[94:95]
	ds_bpermute_b32 v96, v143, v94 offset:60
	v_cvt_pk_bf16_f32 v107, v94, v95
	v_or_b32_e32 v94, s48, v140
	ds_bpermute_b32 v97, v143, v95 offset:60
	v_ashrrev_i32_e32 v95, 31, v94
	ds_bpermute_b32 v99, v143, v105 offset:60
	v_cvt_pk_bf16_f32 v106, v104, v105
	v_lshlrev_b64 v[104:105], 11, v[94:95]
	v_pk_mul_f32 v[124:125], v[132:133], v[124:125]
	v_lshl_add_u64 v[104:105], v[114:115], 0, v[104:105]
	v_lshlrev_b64 v[94:95], 10, v[94:95]
	v_mov_b64_e32 v[230:231], v[106:107]
	v_cvt_pk_bf16_f32 v92, v92, v93
	v_cvt_pk_bf16_f32 v93, v124, v125
	v_lshl_add_u64 v[106:107], v[116:117], 0, v[94:95]
	v_mov_b64_e32 v[234:235], v[92:93]
	v_mfma_f32_16x16x32_bf16 v[92:95], v[52:55], v[8:11], 0
	ds_bpermute_b32 v90, v143, v124 offset:60
	ds_bpermute_b32 v91, v143, v125 offset:60
	v_mfma_f32_16x16x32_bf16 v[126:129], v[60:63], v[24:27], v[92:95]
	v_mfma_f32_16x16x32_bf16 v[122:125], v[56:59], v[8:11], 0
	v_mfma_f32_16x16x32_bf16 v[122:125], v[64:67], v[24:27], v[122:125]
	s_nop 5
	v_add_f32_e32 v92, v48, v126
	v_mul_f32_e32 v92, 0xbfb8aa3b, v92
	v_exp_f32_e32 v92, v92
	v_mfma_f32_16x16x32_bf16 v[52:55], v[52:55], v[4:7], 0
	v_add_f32_e32 v92, 1.0, v92
	v_rcp_f32_e32 v93, v92
	v_add_f32_e32 v92, v44, v122
	v_mov_b32_e32 v122, 1.0
	v_mul_f32_e32 v92, 0xbfb8aa3b, v92
	v_mul_f32_e32 v93, 0xc1000000, v93
	v_mul_f32_e32 v93, v145, v93
	v_mul_f32_e32 v93, 0x3fb8aa3b, v93
	v_exp_f32_e32 v94, v93
	v_exp_f32_e32 v92, v92
	v_fma_f32 v93, -v94, v94, 1.0
	v_sqrt_f32_e32 v126, v93
	v_add_f32_e32 v93, v49, v127
	v_mul_f32_e32 v93, 0xbfb8aa3b, v93
	v_exp_f32_e32 v93, v93
	v_mov_b32_dpp v122, v94 row_shr:1 row_mask:0xf bank_mask:0xf
	v_add_f32_e32 v92, 1.0, v92
	v_rcp_f32_e32 v92, v92
	v_add_f32_e32 v93, 1.0, v93
	v_rcp_f32_e32 v95, v93
	v_add_f32_e32 v93, v45, v123
	v_mul_f32_e32 v93, 0xbfb8aa3b, v93
	v_exp_f32_e32 v93, v93
	v_mul_f32_e32 v95, 0xc1000000, v95
	v_mul_f32_e32 v95, v147, v95
	v_mul_f32_e32 v95, 0x3fb8aa3b, v95
	v_exp_f32_e32 v95, v95
	v_add_f32_e32 v93, 1.0, v93
	v_rcp_f32_e32 v93, v93
	v_fma_f32 v123, -v95, v95, 1.0
	v_sqrt_f32_e32 v127, v123
	v_mov_b32_e32 v123, 1.0
	s_nop 1
	v_mov_b32_dpp v123, v95 row_shr:1 row_mask:0xf bank_mask:0xf
	v_pk_mul_f32 v[130:131], v[94:95], v[122:123]
	v_mov_b32_e32 v122, 1.0
	v_mov_b32_e32 v123, 1.0
	s_nop 0
	v_mov_b32_dpp v122, v130 row_shr:2 row_mask:0xf bank_mask:0xf
	v_mov_b32_dpp v123, v131 row_shr:2 row_mask:0xf bank_mask:0xf
	v_pk_mul_f32 v[132:133], v[130:131], v[122:123]
	v_mov_b32_e32 v122, 1.0
	v_mov_b32_e32 v123, 1.0
	s_nop 0
	v_mov_b32_dpp v122, v132 row_shr:4 row_mask:0xf bank_mask:0xf
	v_mov_b32_dpp v123, v133 row_shr:4 row_mask:0xf bank_mask:0xf
	v_pk_mul_f32 v[134:135], v[132:133], v[122:123]
	v_mov_b32_e32 v122, 1.0
	v_mov_b32_e32 v123, 1.0
	s_nop 0
	v_mov_b32_dpp v122, v134 row_shr:8 row_mask:0xf bank_mask:0xf
	v_mov_b32_dpp v123, v135 row_shr:8 row_mask:0xf bank_mask:0xf
	v_pk_mul_f32 v[140:141], v[134:135], v[122:123]
	s_nop 0
	v_pk_mul_f32 v[148:149], v[140:141], v[88:89]
	ds_read2_b32 v[88:89], v150 offset1:1
	ds_bpermute_b32 v122, v143, v148 offset:60
	ds_bpermute_b32 v123, v143, v149 offset:60
	s_waitcnt lgkmcnt(0)
	v_pk_mul_f32 v[88:89], v[88:89], v[92:93]
	s_nop 0
	v_pk_mul_f32 v[88:89], v[88:89], v[126:127]
	s_nop 1
	v_mov_b32_dpp v92, v88 row_shr:1 row_mask:0xf bank_mask:0xf bound_ctrl:1
	v_mov_b32_dpp v93, v89 row_shr:1 row_mask:0xf bank_mask:0xf bound_ctrl:1
	v_pk_fma_f32 v[88:89], v[94:95], v[92:93], v[88:89]
	s_nop 1
	v_mov_b32_dpp v92, v88 row_shr:2 row_mask:0xf bank_mask:0xf bound_ctrl:1
	v_mov_b32_dpp v93, v89 row_shr:2 row_mask:0xf bank_mask:0xf bound_ctrl:1
	v_pk_fma_f32 v[88:89], v[130:131], v[92:93], v[88:89]
	s_nop 1
	v_mov_b32_dpp v92, v88 row_shr:4 row_mask:0xf bank_mask:0xf bound_ctrl:1
	v_mov_b32_dpp v93, v89 row_shr:4 row_mask:0xf bank_mask:0xf bound_ctrl:1
	v_pk_fma_f32 v[88:89], v[132:133], v[92:93], v[88:89]
	s_nop 1
	v_mov_b32_dpp v92, v88 row_shr:8 row_mask:0xf bank_mask:0xf bound_ctrl:1
	v_mov_b32_dpp v93, v89 row_shr:8 row_mask:0xf bank_mask:0xf bound_ctrl:1
	v_pk_fma_f32 v[88:89], v[134:135], v[92:93], v[88:89]
	v_mov_b32_e32 v92, 1.0
	v_pk_fma_f32 v[98:99], v[140:141], v[98:99], v[88:89]
	v_add_f32_e32 v88, v50, v128
	v_mul_f32_e32 v88, 0xbfb8aa3b, v88
	v_exp_f32_e32 v88, v88
	ds_read2_b32 v[140:141], v150 offset0:2 offset1:3
	ds_bpermute_b32 v94, v143, v98 offset:60
	ds_bpermute_b32 v95, v143, v99 offset:60
	v_add_f32_e32 v88, 1.0, v88
	v_rcp_f32_e32 v89, v88
	v_add_f32_e32 v88, v46, v124
	v_mul_f32_e32 v88, 0xbfb8aa3b, v88
	v_exp_f32_e32 v88, v88
	v_mul_f32_e32 v89, 0xc1000000, v89
	v_mul_f32_e32 v89, v2, v89
	v_mul_f32_e32 v89, 0x3fb8aa3b, v89
	v_exp_f32_e32 v124, v89
	v_add_f32_e32 v88, 1.0, v88
	v_rcp_f32_e32 v88, v88
	v_cvt_pk_bf16_f32 v98, v98, v99
	v_fma_f32 v89, -v124, v124, 1.0
	v_sqrt_f32_e32 v126, v89
	v_add_f32_e32 v89, v51, v129
	v_mul_f32_e32 v89, 0xbfb8aa3b, v89
	v_exp_f32_e32 v89, v89
	v_mov_b32_dpp v92, v124 row_shr:1 row_mask:0xf bank_mask:0xf
	v_add_f32_e32 v89, 1.0, v89
	v_rcp_f32_e32 v93, v89
	v_add_f32_e32 v89, v47, v125
	v_mul_f32_e32 v89, 0xbfb8aa3b, v89
	v_exp_f32_e32 v89, v89
	v_mul_f32_e32 v93, 0xc1000000, v93
	v_mul_f32_e32 v93, v146, v93
	v_mul_f32_e32 v93, 0x3fb8aa3b, v93
	v_exp_f32_e32 v125, v93
	v_add_f32_e32 v89, 1.0, v89
	v_rcp_f32_e32 v89, v89
	v_fma_f32 v93, -v125, v125, 1.0
	v_sqrt_f32_e32 v127, v93
	s_waitcnt lgkmcnt(0)
; __device__ __forceinline__ unsigned pk2(float lo, float hi) { const f32x2_t v = {lo, hi}; const bf16x2_t b = __builtin_convertvector(v, bf16x2_t); return __builtin_bit_cast(unsigned, b); }
; __device__ __forceinline__ float sigmoidf_(float x) { return __builtin_amdgcn_rcpf(1.0f + __expf(-x)); }
; __device__ __forceinline__ float bcast15(float v, int lane) { return bperm_f((lane & 48) | 15, v); }
; __device__ __forceinline__ void w_lru_m1(const Args& a, int l, unsigned char* ws, const bf16_t* proj, bf16_t* y, LAS unsigned char* wl, int b, int ck_, int h, int lane) {
;     ...
;         for (int tb = 0; tb < 4; ++tb) { const int tok = 16 * tb + lo;
;             f32x4 ga = {0.f, 0.f, 0.f, 0.f}, gx = {0.f, 0.f, 0.f, 0.f};
; #pragma unroll
;             for (int kk = 0; kk < 2; ++kk) { ga = __builtin_amdgcn_mfma_f32_16x16x32_bf16(WaF[kk], Xf[tb][kk], ga, 0, 0, 0); gx = __builtin_amdgcn_mfma_f32_16x16x32_bf16(WxF[kk], Xf[tb][kk], gx, 0, 0, 0); }
;             float hv[4], pv[4];
; #pragma unroll
;             for (int r = 0; r < 4; ++r) {
;                 const float rg = sigmoidf_(ga[r] + bav[r]), ig = sigmoidf_(gx[r] + bxv[r]);
;                 const float la = -8.0f * rg * sp[r]; float A = __expf(la);
;                 float U = __builtin_amdgcn_sqrtf(1.0f - A * A) * (ig * xcf[tok * 65 + j0 + r]);
;                 { const float As = dpp_shr1<1>(A), Us = dpp_shr0<1>(U); U = A * Us + U; A = A * As; }
;                 { const float As = dpp_shr1<2>(A), Us = dpp_shr0<2>(U); U = A * Us + U; A = A * As; }
;                 { const float As = dpp_shr1<4>(A), Us = dpp_shr0<4>(U); U = A * Us + U; A = A * As; }
;                 { const float As = dpp_shr1<8>(A), Us = dpp_shr0<8>(U); U = A * Us + U; A = A * As; }
;                 const float hh = U + A * hc[r], PP = A * Pc[r];
;                 hc[r] = bcast15(hh, lane); Pc[r] = bcast15(PP, lane); hv[r] = hh; pv[r] = PP; }
;             *(unsigned long long*)(y + (size_t)(row0 + tok) * DM + 64 * h + j0) = (unsigned long long)pk2(hv[0], hv[1]) | ((unsigned long long)pk2(hv[2], hv[3]) << 32);
;             *(unsigned long long*)((bf16_t*)(ws + WS_P) + (size_t)(row0 + tok) * 512 + 64 * h + j0) = (unsigned long long)pk2(pv[0], pv[1]) | ((unsigned long long)pk2(pv[2], pv[3]) << 32);
	v_pk_mul_f32 v[88:89], v[88:89], v[140:141]
	v_mov_b32_e32 v93, 1.0
	v_pk_mul_f32 v[88:89], v[126:127], v[88:89]
	s_nop 0
	v_mov_b32_dpp v93, v125 row_shr:1 row_mask:0xf bank_mask:0xf
	v_mov_b32_dpp v126, v88 row_shr:1 row_mask:0xf bank_mask:0xf bound_ctrl:1
	v_mov_b32_dpp v127, v89 row_shr:1 row_mask:0xf bank_mask:0xf bound_ctrl:1
	v_pk_mul_f32 v[128:129], v[124:125], v[92:93]
	v_mov_b32_e32 v92, 1.0
	v_mov_b32_e32 v93, 1.0
	v_pk_fma_f32 v[88:89], v[124:125], v[126:127], v[88:89]
	v_mov_b32_dpp v92, v128 row_shr:2 row_mask:0xf bank_mask:0xf
	v_mov_b32_dpp v93, v129 row_shr:2 row_mask:0xf bank_mask:0xf
	v_mov_b32_dpp v124, v88 row_shr:2 row_mask:0xf bank_mask:0xf bound_ctrl:1
	v_mov_b32_dpp v125, v89 row_shr:2 row_mask:0xf bank_mask:0xf bound_ctrl:1
	v_pk_mul_f32 v[130:131], v[128:129], v[92:93]
	v_mov_b32_e32 v92, 1.0
	v_mov_b32_e32 v93, 1.0
	v_pk_fma_f32 v[88:89], v[128:129], v[124:125], v[88:89]
	v_mov_b32_dpp v92, v130 row_shr:4 row_mask:0xf bank_mask:0xf
	v_mov_b32_dpp v93, v131 row_shr:4 row_mask:0xf bank_mask:0xf
	v_mov_b32_dpp v124, v88 row_shr:4 row_mask:0xf bank_mask:0xf bound_ctrl:1
	v_mov_b32_dpp v125, v89 row_shr:4 row_mask:0xf bank_mask:0xf bound_ctrl:1
	v_pk_mul_f32 v[132:133], v[130:131], v[92:93]
	v_mov_b32_e32 v92, 1.0
	v_mov_b32_e32 v93, 1.0
	v_pk_fma_f32 v[88:89], v[130:131], v[124:125], v[88:89]
	v_mov_b32_dpp v92, v132 row_shr:8 row_mask:0xf bank_mask:0xf
	v_mov_b32_dpp v93, v133 row_shr:8 row_mask:0xf bank_mask:0xf
	v_mov_b32_dpp v124, v88 row_shr:8 row_mask:0xf bank_mask:0xf bound_ctrl:1
	v_mov_b32_dpp v125, v89 row_shr:8 row_mask:0xf bank_mask:0xf bound_ctrl:1
	v_pk_mul_f32 v[134:135], v[132:133], v[92:93]
	v_pk_fma_f32 v[88:89], v[132:133], v[124:125], v[88:89]
	v_or_b32_e32 v124, s48, v139
	v_pk_fma_f32 v[96:97], v[134:135], v[96:97], v[88:89]
	v_ashrrev_i32_e32 v125, 31, v124
	v_pk_mul_f32 v[90:91], v[134:135], v[90:91]
	ds_bpermute_b32 v88, v143, v96 offset:60
	ds_bpermute_b32 v89, v143, v97 offset:60
	v_cvt_pk_bf16_f32 v99, v96, v97
	v_lshlrev_b64 v[96:97], 11, v[124:125]
	ds_bpermute_b32 v92, v143, v90 offset:60
	ds_bpermute_b32 v93, v143, v91 offset:60
	v_lshl_add_u64 v[96:97], v[114:115], 0, v[96:97]
	v_cvt_pk_bf16_f32 v127, v90, v91
	v_lshlrev_b64 v[90:91], 10, v[124:125]
	v_mov_b64_e32 v[238:239], v[98:99]
	v_cvt_pk_bf16_f32 v126, v148, v149
	v_lshl_add_u64 v[98:99], v[116:117], 0, v[90:91]
	v_mov_b64_e32 v[242:243], v[126:127]
	v_mfma_f32_16x16x32_bf16 v[124:127], v[56:59], v[4:7], 0
	v_mfma_f32_16x16x32_bf16 v[56:59], v[60:63], v[20:23], v[52:55]
	v_mfma_f32_16x16x32_bf16 v[52:55], v[64:67], v[20:23], v[124:127]
	s_nop 5
	v_add_u32_e32 v124, v142, v138
	v_add_f32_e32 v48, v48, v56
	v_add_f32_e32 v49, v49, v57
	v_mul_f32_e32 v48, 0xbfb8aa3b, v48
	v_mul_f32_e32 v49, 0xbfb8aa3b, v49
	v_exp_f32_e32 v48, v48
	v_exp_f32_e32 v49, v49
	v_add_f32_e32 v44, v44, v52
	v_add_f32_e32 v45, v45, v53
	v_mul_f32_e32 v44, 0xbfb8aa3b, v44
	v_mul_f32_e32 v45, 0xbfb8aa3b, v45
	v_add_f32_e32 v48, 1.0, v48
	v_exp_f32_e32 v44, v44
	v_add_f32_e32 v49, 1.0, v49
	v_exp_f32_e32 v45, v45
	v_rcp_f32_e32 v56, v48
	v_rcp_f32_e32 v52, v49
	v_add_f32_e32 v44, 1.0, v44
	v_add_f32_e32 v45, 1.0, v45
	v_rcp_f32_e32 v48, v44
	v_mul_f32_e32 v44, 0xc1000000, v56
	v_rcp_f32_e32 v49, v45
	v_mul_f32_e32 v45, 0xc1000000, v52
	v_mul_f32_e32 v44, v145, v44
	v_mul_f32_e32 v45, v147, v45
	v_mul_f32_e32 v44, 0x3fb8aa3b, v44
	v_mul_f32_e32 v45, 0x3fb8aa3b, v45
	v_exp_f32_e32 v56, v44
	v_exp_f32_e32 v57, v45
	v_add_f32_e32 v50, v50, v58
	v_mul_f32_e32 v50, 0xbfb8aa3b, v50
	v_fma_f32 v44, -v56, v56, 1.0
	v_fma_f32 v45, -v57, v57, 1.0
	v_sqrt_f32_e32 v60, v44
	v_mov_b32_e32 v44, 1.0
	v_sqrt_f32_e32 v61, v45
	v_mov_b32_e32 v45, 1.0
	v_exp_f32_e32 v50, v50
	v_mov_b32_dpp v44, v56 row_shr:1 row_mask:0xf bank_mask:0xf
	v_mov_b32_dpp v45, v57 row_shr:1 row_mask:0xf bank_mask:0xf
	v_pk_mul_f32 v[62:63], v[56:57], v[44:45]
	v_mov_b32_e32 v44, 1.0
	v_mov_b32_e32 v45, 1.0
	v_add_f32_e32 v46, v46, v54
	v_mov_b32_dpp v44, v62 row_shr:2 row_mask:0xf bank_mask:0xf
	v_mov_b32_dpp v45, v63 row_shr:2 row_mask:0xf bank_mask:0xf
	v_mul_f32_e32 v46, 0xbfb8aa3b, v46
	v_pk_mul_f32 v[64:65], v[62:63], v[44:45]
	v_mov_b32_e32 v44, 1.0
	v_mov_b32_e32 v45, 1.0
	v_add_f32_e32 v50, 1.0, v50
	v_exp_f32_e32 v46, v46
	v_mov_b32_dpp v44, v64 row_shr:4 row_mask:0xf bank_mask:0xf
	v_mov_b32_dpp v45, v65 row_shr:4 row_mask:0xf bank_mask:0xf
	v_rcp_f32_e32 v50, v50
	v_pk_mul_f32 v[66:67], v[64:65], v[44:45]
	v_mov_b32_e32 v44, 1.0
	v_mov_b32_e32 v45, 1.0
	v_add_f32_e32 v46, 1.0, v46
	v_mov_b32_dpp v44, v66 row_shr:8 row_mask:0xf bank_mask:0xf
	v_mov_b32_dpp v45, v67 row_shr:8 row_mask:0xf bank_mask:0xf
	v_pk_mul_f32 v[90:91], v[66:67], v[44:45]
	v_rcp_f32_e32 v54, v46
	v_pk_mul_f32 v[52:53], v[90:91], v[122:123]
	ds_read2_b32 v[122:123], v124 offset1:1
	v_mul_f32_e32 v46, 0xc1000000, v50
	v_mul_f32_e32 v2, v2, v46
	v_mul_f32_e32 v2, 0x3fb8aa3b, v2
	v_exp_f32_e32 v50, v2
	s_waitcnt lgkmcnt(0)
; __device__ __forceinline__ unsigned pk2(float lo, float hi) { const f32x2_t v = {lo, hi}; const bf16x2_t b = __builtin_convertvector(v, bf16x2_t); return __builtin_bit_cast(unsigned, b); }
; __device__ __forceinline__ float sigmoidf_(float x) { return __builtin_amdgcn_rcpf(1.0f + __expf(-x)); }
; __device__ __forceinline__ void w_lru_m1(const Args& a, int l, unsigned char* ws, const bf16_t* proj, bf16_t* y, LAS unsigned char* wl, int b, int ck_, int h, int lane) {
;     ...
;         for (int tb = 0; tb < 4; ++tb) { const int tok = 16 * tb + lo;
;             f32x4 ga = {0.f, 0.f, 0.f, 0.f}, gx = {0.f, 0.f, 0.f, 0.f};
; #pragma unroll
;             for (int kk = 0; kk < 2; ++kk) { ga = __builtin_amdgcn_mfma_f32_16x16x32_bf16(WaF[kk], Xf[tb][kk], ga, 0, 0, 0); gx = __builtin_amdgcn_mfma_f32_16x16x32_bf16(WxF[kk], Xf[tb][kk], gx, 0, 0, 0); }
;             float hv[4], pv[4];
; #pragma unroll
;             for (int r = 0; r < 4; ++r) {
;                 const float rg = sigmoidf_(ga[r] + bav[r]), ig = sigmoidf_(gx[r] + bxv[r]);
;                 const float la = -8.0f * rg * sp[r]; float A = __expf(la);
;                 float U = __builtin_amdgcn_sqrtf(1.0f - A * A) * (ig * xcf[tok * 65 + j0 + r]);
;                 { const float As = dpp_shr1<1>(A), Us = dpp_shr0<1>(U); U = A * Us + U; A = A * As; }
;                 { const float As = dpp_shr1<2>(A), Us = dpp_shr0<2>(U); U = A * Us + U; A = A * As; }
;                 { const float As = dpp_shr1<4>(A), Us = dpp_shr0<4>(U); U = A * Us + U; A = A * As; }
;                 { const float As = dpp_shr1<8>(A), Us = dpp_shr0<8>(U); U = A * Us + U; A = A * As; }
;                 const float hh = U + A * hc[r], PP = A * Pc[r];
;                 hc[r] = bcast15(hh, lane); Pc[r] = bcast15(PP, lane); hv[r] = hh; pv[r] = PP; }
;             *(unsigned long long*)(y + (size_t)(row0 + tok) * DM + 64 * h + j0) = (unsigned long long)pk2(hv[0], hv[1]) | ((unsigned long long)pk2(hv[2], hv[3]) << 32);
;             *(unsigned long long*)((bf16_t*)(ws + WS_P) + (size_t)(row0 + tok) * 512 + 64 * h + j0) = (unsigned long long)pk2(pv[0], pv[1]) | ((unsigned long long)pk2(pv[2], pv[3]) << 32);
;         }
;         if (lo == 0) { const size_t so = (size_t)(b * NCH + ck_) * 512 + 64 * h + j0;
; #pragma unroll
;             for (int r = 0; r < 4; ++r) { ((float*)(ws + WS_LRUA))[so + r] = Pc[r]; ((float*)(ws + WS_LRUH))[so + r] = hc[r]; } }
	v_pk_mul_f32 v[48:49], v[122:123], v[48:49]
	v_add_f32_e32 v47, v47, v55
	v_pk_mul_f32 v[48:49], v[48:49], v[60:61]
	v_fma_f32 v2, -v50, v50, 1.0
	v_mul_f32_e32 v47, 0xbfb8aa3b, v47
	v_mov_b32_dpp v60, v48 row_shr:1 row_mask:0xf bank_mask:0xf bound_ctrl:1
	v_mov_b32_dpp v61, v49 row_shr:1 row_mask:0xf bank_mask:0xf bound_ctrl:1
	v_pk_fma_f32 v[48:49], v[56:57], v[60:61], v[48:49]
	v_sqrt_f32_e32 v60, v2
	v_add_f32_e32 v2, v51, v59
	v_mul_f32_e32 v2, 0xbfb8aa3b, v2
	v_exp_f32_e32 v2, v2
	v_exp_f32_e32 v47, v47
	v_mov_b32_e32 v46, 1.0
	v_mov_b32_dpp v56, v48 row_shr:2 row_mask:0xf bank_mask:0xf bound_ctrl:1
	v_add_f32_e32 v2, 1.0, v2
	v_rcp_f32_e32 v2, v2
	v_add_f32_e32 v47, 1.0, v47
	v_rcp_f32_e32 v55, v47
	v_mov_b32_e32 v47, 1.0
	v_mul_f32_e32 v2, 0xc1000000, v2
	v_mul_f32_e32 v2, v146, v2
	v_mul_f32_e32 v2, 0x3fb8aa3b, v2
	v_exp_f32_e32 v51, v2
	v_mov_b32_dpp v57, v49 row_shr:2 row_mask:0xf bank_mask:0xf bound_ctrl:1
	v_mov_b32_dpp v46, v50 row_shr:1 row_mask:0xf bank_mask:0xf
	v_pk_fma_f32 v[48:49], v[62:63], v[56:57], v[48:49]
	v_mov_b32_dpp v47, v51 row_shr:1 row_mask:0xf bank_mask:0xf
	v_pk_mul_f32 v[62:63], v[50:51], v[46:47]
	v_mov_b32_e32 v46, 1.0
	v_mov_b32_e32 v47, 1.0
	v_mov_b32_dpp v56, v48 row_shr:4 row_mask:0xf bank_mask:0xf bound_ctrl:1
	v_mov_b32_dpp v57, v49 row_shr:4 row_mask:0xf bank_mask:0xf bound_ctrl:1
	v_mov_b32_dpp v46, v62 row_shr:2 row_mask:0xf bank_mask:0xf
	v_mov_b32_dpp v47, v63 row_shr:2 row_mask:0xf bank_mask:0xf
	v_pk_fma_f32 v[48:49], v[64:65], v[56:57], v[48:49]
	v_pk_mul_f32 v[64:65], v[62:63], v[46:47]
	v_mov_b32_e32 v46, 1.0
	v_mov_b32_e32 v47, 1.0
	v_mov_b32_dpp v56, v48 row_shr:8 row_mask:0xf bank_mask:0xf bound_ctrl:1
	v_mov_b32_dpp v57, v49 row_shr:8 row_mask:0xf bank_mask:0xf bound_ctrl:1
	v_mov_b32_dpp v46, v64 row_shr:4 row_mask:0xf bank_mask:0xf
	v_mov_b32_dpp v47, v65 row_shr:4 row_mask:0xf bank_mask:0xf
	v_pk_fma_f32 v[48:49], v[66:67], v[56:57], v[48:49]
	v_pk_mul_f32 v[66:67], v[64:65], v[46:47]
	v_mov_b32_e32 v46, 1.0
	v_mov_b32_e32 v47, 1.0
	v_pk_fma_f32 v[56:57], v[90:91], v[94:95], v[48:49]
	v_mov_b32_dpp v46, v66 row_shr:8 row_mask:0xf bank_mask:0xf
	v_mov_b32_dpp v47, v67 row_shr:8 row_mask:0xf bank_mask:0xf
	v_pk_mul_f32 v[90:91], v[66:67], v[46:47]
	v_fma_f32 v2, -v51, v51, 1.0
	v_pk_mul_f32 v[58:59], v[90:91], v[92:93]
	ds_read2_b32 v[92:93], v124 offset0:2 offset1:3
	v_sqrt_f32_e32 v61, v2
	ds_bpermute_b32 v44, v143, v52 offset:60
	ds_bpermute_b32 v48, v143, v56 offset:60
	ds_bpermute_b32 v49, v143, v57 offset:60
	s_waitcnt lgkmcnt(0)
	v_pk_mul_f32 v[54:55], v[54:55], v[92:93]
	ds_bpermute_b32 v45, v143, v53 offset:60
	v_pk_mul_f32 v[54:55], v[60:61], v[54:55]
	ds_bpermute_b32 v46, v143, v58 offset:60
	ds_bpermute_b32 v47, v143, v59 offset:60
	v_mov_b32_dpp v60, v54 row_shr:1 row_mask:0xf bank_mask:0xf bound_ctrl:1
	v_mov_b32_dpp v61, v55 row_shr:1 row_mask:0xf bank_mask:0xf bound_ctrl:1
	v_pk_fma_f32 v[50:51], v[50:51], v[60:61], v[54:55]
	v_cvt_pk_bf16_f32 v56, v56, v57
	v_cvt_pk_bf16_f32 v52, v52, v53
	v_mov_b32_dpp v54, v50 row_shr:2 row_mask:0xf bank_mask:0xf bound_ctrl:1
	v_mov_b32_dpp v55, v51 row_shr:2 row_mask:0xf bank_mask:0xf bound_ctrl:1
	v_pk_fma_f32 v[50:51], v[62:63], v[54:55], v[50:51]
	v_cvt_pk_bf16_f32 v53, v58, v59
	s_nop 0
	v_mov_b32_dpp v54, v50 row_shr:4 row_mask:0xf bank_mask:0xf bound_ctrl:1
	v_mov_b32_dpp v55, v51 row_shr:4 row_mask:0xf bank_mask:0xf bound_ctrl:1
	v_pk_fma_f32 v[50:51], v[64:65], v[54:55], v[50:51]
	s_nop 1
	v_mov_b32_dpp v54, v50 row_shr:8 row_mask:0xf bank_mask:0xf bound_ctrl:1
	v_mov_b32_dpp v55, v51 row_shr:8 row_mask:0xf bank_mask:0xf bound_ctrl:1
	v_pk_fma_f32 v[50:51], v[66:67], v[54:55], v[50:51]
	s_nop 0
	v_pk_fma_f32 v[54:55], v[90:91], v[88:89], v[50:51]
	ds_bpermute_b32 v50, v143, v54 offset:60
	ds_bpermute_b32 v51, v143, v55 offset:60
	v_cvt_pk_bf16_f32 v57, v54, v55
	v_or_b32_e32 v54, s48, v137
	v_ashrrev_i32_e32 v55, 31, v54
	v_lshlrev_b64 v[60:61], 11, v[54:55]
	v_lshlrev_b64 v[54:55], 10, v[54:55]
	v_lshl_add_u64 v[114:115], v[114:115], 0, v[60:61]
	v_lshl_add_u64 v[116:117], v[116:117], 0, v[54:55]
	v_mov_b64_e32 v[246:247], v[56:57]
	v_mov_b64_e32 v[250:251], v[52:53]
	s_and_saveexec_b64 s[34:35], vcc
	s_cbranch_execz .LBB0_523
	v_lshl_add_u64 v[52:53], s[42:43], 0, v[0:1]
	v_lshlrev_b64 v[52:53], 2, v[52:53]
	v_lshl_add_u64 v[54:55], s[84:85], 0, v[52:53]
	v_lshl_add_u64 v[52:53], s[86:87], 0, v[52:53]
	s_waitcnt lgkmcnt(0)
	global_store_dwordx4 v[54:55], v[44:47], off
	global_store_dwordx4 v[52:53], v[48:51], off

; __device__ __forceinline__ void ld8bf(const bf16_t* p, float (&o)[8]) { unpack8(*(const u32x4*)p, o); }
; __device__ __forceinline__ void w_hg_m1(const Args& a, int l, unsigned char* ws, const bf16_t* proj, LAS unsigned char* wl, int b, int ck_, int h, int lane) {
;     ...
;     for (int kk = 0; kk < 2; ++kk) { float bb[4][8], r31[8], r63[8], lbv[8];
; #pragma unroll
;         for (int j = 0; j < 8; ++j) lbv[j] = hg_lb(a, l, 64 * h + 32 * kk + 8 * fq + j);
;         const bf16_t* fsrc = proj + (size_t)row0 * NIN + C_HF + 64 * h + 32 * kk + 8 * fq;
;         w_hg_scan(lbv, fsrc, lane, bb, r31, r63);
; #pragma unroll
;         for (int tb = 0; tb < 4; ++tb) { float fp[8]; ld8bf(fsrc + (size_t)(16 * tb + lo) * NIN, fp);
.LBB0_531:
	s_setprio 0
	s_lshr_b32 s20, s90, 8
	s_lshr_b32 s21, s90, 9
	s_add_i32 s20, s20, s90
	s_and_b32 s21, s21, 12
	s_add_i32 s20, s20, s21
	s_and_b32 s20, s20, 15
	s_cmp_lt_u32 s20, 12
	s_cbranch_scc1 .LBB0_530
	v_mov_b32_e32 v33, v144
	s_add_i32 s20, s20, -12
	v_ashrrev_i32_e32 v32, 4, v33
	s_lshl_b32 s34, s20, 6
	v_lshlrev_b32_e32 v0, 3, v32
	v_add_u32_e32 v12, s34, v0
	v_mov_b32_e32 v23, 0
	s_ashr_i32 s21, s90, 31
	s_ashr_i32 s27, s90, 4
	s_lshr_b32 s21, s21, 25
	s_add_i32 s35, s27, s21
	s_ashr_i32 s21, s35, 7
	s_and_b32 s35, s35, 0xffffff80
	s_sub_i32 s27, s27, s35
	s_lshl_b32 s35, s21, 13
	s_lshl_b32 s38, s27, 6
	s_add_i32 s35, s38, s35
	s_mul_hi_i32 s38, s35, 0x1800
	s_mulk_i32 s35, 0x1800
	s_add_u32 s91, s8, s35
	s_addc_u32 s92, s9, s38
	s_lshl_b32 s93, s34, 1
	s_add_i32 s38, s93, 0x1200
	v_and_b32_e32 v196, 15, v33
	v_lshrrev_b32_e32 v197, 4, v33
	v_mul_u32_u24_e32 v196, 0x1800, v196
	v_lshl_add_u32 v196, v197, 4, v196
	v_add_u32_e32 v196, s38, v196
	v_add_co_u32_e32 v198, vcc, s91, v196
	v_mov_b32_e32 v199, s92
	s_nop 0
	v_addc_co_u32_e32 v199, vcc, 0, v199, vcc
	global_load_dwordx4 v[222:225], v[198:199], off
	global_load_dwordx4 v[238:241], v[198:199], off offset:64
	v_add_u32_e32 v196, 0x18000, v196
	v_add_co_u32_e32 v198, vcc, s91, v196
	v_mov_b32_e32 v199, s92
	s_nop 0
	v_addc_co_u32_e32 v199, vcc, 0, v199, vcc
	global_load_dwordx4 v[226:229], v[198:199], off
	global_load_dwordx4 v[242:245], v[198:199], off offset:64
	v_add_u32_e32 v196, 0x18000, v196
	v_add_co_u32_e32 v198, vcc, s91, v196
	v_mov_b32_e32 v199, s92
	s_nop 0
	v_addc_co_u32_e32 v199, vcc, 0, v199, vcc
	global_load_dwordx4 v[230:233], v[198:199], off
	global_load_dwordx4 v[246:249], v[198:199], off offset:64
	v_add_u32_e32 v196, 0x18000, v196
	v_add_co_u32_e32 v198, vcc, s91, v196
	v_mov_b32_e32 v199, s92
	s_nop 0
	v_addc_co_u32_e32 v199, vcc, 0, v199, vcc
	global_load_dwordx4 v[234:237], v[198:199], off
	global_load_dwordx4 v[250:253], v[198:199], off offset:64
	s_and_b64 vcc, exec, s[36:37]
	v_ashrrev_i32_e32 v13, 31, v12
	v_mov_b32_e32 v22, 0
	s_cbranch_vccnz .LBB0_810
	v_cndmask_b32_e64 v1, 0, 1, s[36:37]
	v_cmp_ne_u32_e64 s[40:41], 1, v1
	s_andn2_b64 vcc, exec, s[36:37]
	s_cbranch_vccz .LBB0_811
